# v15 + 8-byte instruction alignment of the hand-written GEMM k-loops (loop heads 64-byte aligned, no 8-byte instruction straddling)
# speedup vs baseline: 1.0123x; 1.0054x over previous
; #define LAS __attribute__((address_space(3)))
; DEVI int xcd_first_tile() { return (blockIdx.x & 7) * (gridDim.x >> 3) + (blockIdx.x >> 3); }
;     ...
;   const int nk = (nk_part < 0) ? (K >> 5) : nk_part;
;   const int lrow = tid >> 2, lpc = tid & 3;
;   const int lch = lpc ^ ((0x78 >> (((lrow >> 2) & 3) * 2)) & 3);
;   const u16* ga = A + (size_t)(m0 + lrow) * lda + kbeg + lch * 8;
;   const u16* gb = Bt + (size_t)(n0 + lrow) * K + kbeg + lch * 8;
;   const size_t ga1 = (size_t)64 * lda, gb1 = (size_t)64 * K;
;   const unsigned lds0 = (unsigned)(uintptr_t)(LAS char*)smem + (unsigned)__builtin_amdgcn_readfirstlane(wid) * 1024u;
;     ...
;   __syncthreads();
;   G2_STAGE(0); G2_STAGE(1);
; DEVI void run_phase(const Params& p, int ph, char* smem) {
;     ...
;       for (int t = xcd_first_tile(); t < 512 + 16 * 11; t += xcd_tile_step()) {
;         if (t < 512) {
;           int mt_, nt_; tile_coords(t, 64, 8, mt_, nt_);
;           gemm_tile256<EPI_RESID>(p, hb, DFF, Bt, DFF, mt_ * 256, nt_ * 128, nullptr, 0, smem);
;         } else {
;           const int u_ = t - 512, tl_ = u_ / 11, q_ = u_ - tl_ * 11;
;           gemm_tile256<EPI_RESID_ATOMIC>(p, hb, DFF, Bt, DFF, (64 + (tl_ & 1)) * 256, (tl_ >> 1) * 128, nullptr, 0, smem, q_ * 256, 8, q_);
;         }
.LBB0_42:
	s_cmpk_gt_i32 s38, 0x1ff
	s_mov_b64 s[2:3], -1
	s_cbranch_scc0 .LBB0_116
	s_sub_i32 s46, s38, 512
	s_mul_i32 s45, s46, 373
	s_lshr_b32 s45, s45, 12
	s_mul_i32 s47, s45, 11
	s_sub_i32 s47, s46, s47
	s_lshr_b32 s42, s45, 1
	s_and_b32 s45, s45, 1
	s_add_i32 s45, s45, 64
	s_cmp_lt_u32 s45, 64
	s_cselect_b32 s44, 1, 0
	v_readlane_b32 s2, v250, 5
	v_readlane_b32 s3, v250, 6
	v_readlane_b32 s46, v254, 62
	s_mul_i32 s40, s45, 0x160000
	s_add_u32 s4, s2, s40
	s_addc_u32 s5, s3, 0
	s_add_u32 s4, s4, 0xef40000
	s_addc_u32 s5, s5, 0
	s_mul_i32 s40, s46, 0x580000
	s_mul_i32 s41, s42, 0xb0000
	s_add_i32 s40, s40, s41
	s_add_u32 s10, s2, s40
	s_addc_u32 s11, s3, 0
	s_add_u32 s10, s10, 0x19a00000
	s_addc_u32 s11, s11, 0
	s_mul_i32 s40, s47, 512
	s_add_u32 s4, s4, s40
	s_addc_u32 s5, s5, 0
	s_mul_i32 s40, s47, 1024
	s_add_u32 s10, s10, s40
	s_addc_u32 s11, s11, 0
	s_movk_i32 s39, 0x78
	v_lshrrev_b32_e32 v0, 2, v145
	v_and_b32_e32 v131, 3, v145
	v_bfe_u32 v136, v145, 4, 2
	v_lshlrev_b32_e32 v136, 1, v136
	v_lshrrev_b32_e64 v136, v136, s39
	v_and_b32_e32 v136, 3, v136
	v_xor_b32_e32 v131, v131, v136
	v_lshlrev_b32_e32 v131, 4, v131
	s_movk_i32 s41, 0x1600
	v_mad_u32_u24 v0, v0, s41, v131
	v_bfe_u32 v137, v145, 2, 1
	s_movk_i32 s41, 0x15c0
	v_mul_u32_u24_e32 v136, s41, v137
	v_sub_u32_e32 v136, v0, v136
	v_mov_b32_e32 v137, 0
	v_lshl_add_u64 v[134:135], s[10:11], 0, v[136:137]
	v_bfe_u32 v137, v145, 2, 1
	s_mul_i32 s41, s44, 0x15c0
	v_mul_u32_u24_e32 v136, s41, v137
	v_sub_u32_e32 v0, v0, v136
	s_lshl_b32 s12, s44, 6
	s_add_i32 s12, s12, 64
	s_mov_b32 s13, 0
	v_lshl_add_u64 v[132:133], s[4:5], 0, v[0:1]
	v_bfe_u32 v136, v145, 2, 2
	v_lshlrev_b32_e32 v136, 1, v136
	v_lshrrev_b32_e64 v136, v136, s39
	v_and_b32_e32 v136, 3, v136
	v_bfe_u32 v137, v145, 4, 2
	v_xor_b32_e32 v136, v136, v137
	v_lshlrev_b32_e32 v136, 4, v136
	v_and_b32_e32 v131, 15, v145
	v_lshl_or_b32 v136, v131, 6, v136
	v_bfe_u32 v137, v145, 6, 1
	v_lshl_or_b32 v137, v137, 12, v136
	v_lshrrev_b32_e32 v0, 7, v145
	v_lshl_or_b32 v136, v0, 13, v136
	v_and_b32_e32 v140, 1, v131
	v_lshl_or_b32 v131, v0, 7, v131
	v_bfe_u32 v0, v145, 4, 2
	v_lshlrev_b32_e32 v0, 3, v0
	v_bfe_u32 v141, v145, 6, 1
	s_lshl_b32 s40, s45, 19
	s_lshl_b32 s41, s42, 8
	s_add_i32 s40, s40, s41
	s_add_u32 s4, s2, s40
	s_addc_u32 s5, s3, 0
	s_add_u32 s4, s4, 0x4200000
	s_addc_u32 s5, s5, 0
	v_lshlrev_b32_e32 v138, 11, v131
	v_lshl_add_u32 v138, v141, 7, v138
	v_bfe_u32 v139, v145, 4, 1
	v_lshl_add_u32 v138, v139, 5, v138
	v_bfe_u32 v139, v145, 5, 1
	v_lshl_add_u32 v138, v139, 4, v138
	v_mov_b32_e32 v139, 0
	v_lshl_add_u64 v[138:139], s[4:5], 0, v[138:139]
	s_and_b32 s40, s45, 1
	s_lshl_b32 s40, s40, 20
	s_lshl_b32 s41, s47, 21
	s_add_i32 s40, s40, s41
	s_lshl_b32 s41, s42, 9
	s_add_i32 s40, s40, s41
	s_add_u32 s10, s2, s40
	s_addc_u32 s11, s3, 0
	s_add_u32 s10, s10, 0x1dcc0000
	s_addc_u32 s11, s11, 0
	v_lshlrev_b32_e32 v140, 12, v131
	v_lshl_add_u32 v140, v141, 8, v140
	v_lshl_add_u32 v140, v0, 1, v140
	v_mov_b32_e32 v141, 0
	v_lshl_add_u64 v[140:141], s[10:11], 0, v[140:141]
	s_mov_b32 s2, 0x58000
	s_mov_b32 s3, 0
	v_lshrrev_b32_e32 v0, 6, v145
	v_lshlrev_b32_e32 v0, 10, v0
	s_nop 0
	v_readfirstlane_b32 s46, v0
	s_mov_b32 s43, m0
	s_mov_b32 s4, 128
	s_mov_b32 s5, 0
	s_barrier
	s_add_i32 s42, s46, 0x0
	s_mov_b32 m0, s42
	v_lshl_add_u64 v[142:143], v[132:133], 0, s[2:3]
	global_load_lds_dwordx4 v[132:133], off
	s_add_i32 m0, m0, 0x1000
	s_nop 0
	global_load_lds_dwordx4 v[142:143], off
	v_lshl_add_u64 v[142:143], v[142:143], 0, s[2:3]
	s_add_i32 m0, m0, 0x1000
	s_nop 0
	global_load_lds_dwordx4 v[142:143], off
	v_lshl_add_u64 v[142:143], v[142:143], 0, s[2:3]
	s_add_i32 m0, m0, 0x1000
	s_nop 0
	global_load_lds_dwordx4 v[142:143], off
	s_add_i32 m0, m0, 0x1000
	v_lshl_add_u64 v[142:143], v[134:135], 0, s[2:3]
	s_nop 0
	global_load_lds_dwordx4 v[134:135], off
	s_add_i32 m0, m0, 0x1000
	v_lshl_add_u64 v[132:133], v[132:133], 0, s[12:13]
	s_nop 0
	global_load_lds_dwordx4 v[142:143], off
	v_lshl_add_u64 v[134:135], v[134:135], 0, s[4:5]
	s_nop 0
	s_add_i32 s42, s46, 0x6000
	s_mov_b32 m0, s42
	v_lshl_add_u64 v[142:143], v[132:133], 0, s[2:3]
	global_load_lds_dwordx4 v[132:133], off
	s_add_i32 m0, m0, 0x1000
	s_nop 0
	global_load_lds_dwordx4 v[142:143], off
	v_lshl_add_u64 v[142:143], v[142:143], 0, s[2:3]
	s_add_i32 m0, m0, 0x1000
	s_nop 0
	global_load_lds_dwordx4 v[142:143], off
	v_lshl_add_u64 v[142:143], v[142:143], 0, s[2:3]
	s_add_i32 m0, m0, 0x1000
	s_nop 0
	global_load_lds_dwordx4 v[142:143], off
	s_add_i32 m0, m0, 0x1000
	v_lshl_add_u64 v[142:143], v[134:135], 0, s[2:3]
	s_nop 0
	global_load_lds_dwordx4 v[134:135], off
	s_add_i32 m0, m0, 0x1000
	v_lshl_add_u64 v[132:133], v[132:133], 0, s[12:13]
	s_nop 0
	global_load_lds_dwordx4 v[142:143], off
	v_lshl_add_u64 v[134:135], v[134:135], 0, s[4:5]
	s_nop 0
	s_add_i32 s42, s46, 0xc000
	s_mov_b32 m0, s42
	v_lshl_add_u64 v[142:143], v[132:133], 0, s[2:3]
	global_load_lds_dwordx4 v[132:133], off
	s_add_i32 m0, m0, 0x1000
	s_nop 0
	global_load_lds_dwordx4 v[142:143], off
	v_lshl_add_u64 v[142:143], v[142:143], 0, s[2:3]
	s_add_i32 m0, m0, 0x1000
	s_nop 0
	global_load_lds_dwordx4 v[142:143], off
	v_lshl_add_u64 v[142:143], v[142:143], 0, s[2:3]
	s_add_i32 m0, m0, 0x1000
	s_nop 0
	global_load_lds_dwordx4 v[142:143], off
	s_add_i32 m0, m0, 0x1000
	v_lshl_add_u64 v[142:143], v[134:135], 0, s[2:3]
	s_nop 0
	global_load_lds_dwordx4 v[134:135], off
	s_add_i32 m0, m0, 0x1000
	v_lshl_add_u64 v[132:133], v[132:133], 0, s[12:13]
	s_nop 0
	global_load_lds_dwordx4 v[142:143], off
	v_lshl_add_u64 v[134:135], v[134:135], 0, s[4:5]
	s_nop 0
	v_mov_b32_e32 v2, 0
	v_mov_b32_e32 v3, 0
; #define LAS __attribute__((address_space(3)))
;     ...
;   f32x4 acc[4][8];
; #pragma unroll
;   for (int i = 0; i < 4; i++)
; #pragma unroll
;     for (int j = 0; j < 8; j++) acc[i][j] = (f32x4){0.f, 0.f, 0.f, 0.f};
;   const int nk = (nk_part < 0) ? (K >> 5) : nk_part;
;   const int lrow = tid >> 2, lpc = tid & 3;
;   const int lch = lpc ^ ((0x78 >> (((lrow >> 2) & 3) * 2)) & 3);
;   const u16* ga = A + (size_t)(m0 + lrow) * lda + kbeg + lch * 8;
;   const u16* gb = Bt + (size_t)(n0 + lrow) * K + kbeg + lch * 8;
;   const size_t ga1 = (size_t)64 * lda, gb1 = (size_t)64 * K;
;   const unsigned lds0 = (unsigned)(uintptr_t)(LAS char*)smem + (unsigned)__builtin_amdgcn_readfirstlane(wid) * 1024u;
;     ...
;   __syncthreads();
;   G2_STAGE(0); G2_STAGE(1);
;   const int fsw = (0x78 >> (((r16 >> 2) & 3) * 2)) & 3;
;   const int aoff = (wm * 128 + r16) * 64 + ((quad ^ fsw) << 4);
;   const int boff = 16384 + (wn * 64 + r16) * 64 + ((quad ^ fsw) << 4);
;   for (int kt = 0; kt < nk; kt++) {
;     if (kt + 1 < nk) asm volatile("s_waitcnt vmcnt(6)" ::: "memory");
;     else asm volatile("s_waitcnt vmcnt(0)" ::: "memory");
;     __builtin_amdgcn_s_barrier();
;     asm volatile("" ::: "memory");
;     if (kt + 2 < nk) G2_STAGE(kt + 2);
;     const char* cS = smem + (kt % 3) * 24576;
;     bf16x8 xa[8], wb[4];
; #pragma unroll
;     for (int f = 0; f < 8; f++) xa[f] = *(const bf16x8*)(cS + aoff + f * 1024);
; #pragma unroll
;     for (int f = 0; f < 4; f++) wb[f] = *(const bf16x8*)(cS + boff + f * 1024);
; #pragma unroll
;     for (int nf = 0; nf < 4; nf++)
; #pragma unroll
;       for (int mf = 0; mf < 8; mf++)
;         acc[nf][mf] = __builtin_amdgcn_mfma_f32_16x16x32_bf16(wb[nf], xa[mf], acc[nf][mf], 0, 0, 0);
;   }
	v_mov_b32_e32 v4, 0
	v_mov_b32_e32 v5, 0
	v_mov_b32_e32 v6, 0
	v_mov_b32_e32 v7, 0
	v_mov_b32_e32 v8, 0
	v_mov_b32_e32 v9, 0
	v_mov_b32_e32 v10, 0
	v_mov_b32_e32 v11, 0
	v_mov_b32_e32 v12, 0
	v_mov_b32_e32 v13, 0
	v_mov_b32_e32 v14, 0
	v_mov_b32_e32 v15, 0
	v_mov_b32_e32 v16, 0
	v_mov_b32_e32 v17, 0
	v_mov_b32_e32 v18, 0
	v_mov_b32_e32 v19, 0
	v_mov_b32_e32 v20, 0
	v_mov_b32_e32 v21, 0
	v_mov_b32_e32 v22, 0
	v_mov_b32_e32 v23, 0
	v_mov_b32_e32 v24, 0
	v_mov_b32_e32 v25, 0
	v_mov_b32_e32 v26, 0
	v_mov_b32_e32 v27, 0
	v_mov_b32_e32 v28, 0
	v_mov_b32_e32 v29, 0
	v_mov_b32_e32 v30, 0
	v_mov_b32_e32 v31, 0
	v_mov_b32_e32 v32, 0
	v_mov_b32_e32 v33, 0
	v_mov_b32_e32 v34, 0
	v_mov_b32_e32 v35, 0
	v_mov_b32_e32 v36, 0
	v_mov_b32_e32 v37, 0
	v_mov_b32_e32 v38, 0
	v_mov_b32_e32 v39, 0
	v_mov_b32_e32 v40, 0
	v_mov_b32_e32 v41, 0
	v_mov_b32_e32 v42, 0
	v_mov_b32_e32 v43, 0
	v_mov_b32_e32 v44, 0
	v_mov_b32_e32 v45, 0
	v_mov_b32_e32 v46, 0
	v_mov_b32_e32 v47, 0
	v_mov_b32_e32 v48, 0
	v_mov_b32_e32 v49, 0
	v_mov_b32_e32 v50, 0
	v_mov_b32_e32 v51, 0
	v_mov_b32_e32 v52, 0
	v_mov_b32_e32 v53, 0
	v_mov_b32_e32 v54, 0
	v_mov_b32_e32 v55, 0
	v_mov_b32_e32 v56, 0
	v_mov_b32_e32 v57, 0
	v_mov_b32_e32 v58, 0
	v_mov_b32_e32 v59, 0
	v_mov_b32_e32 v60, 0
	v_mov_b32_e32 v61, 0
	v_mov_b32_e32 v62, 0
	v_mov_b32_e32 v63, 0
	v_mov_b32_e32 v64, 0
	v_mov_b32_e32 v65, 0
	v_mov_b32_e32 v66, 0
	v_mov_b32_e32 v67, 0
	v_mov_b32_e32 v68, 0
	v_mov_b32_e32 v69, 0
	v_mov_b32_e32 v70, 0
	v_mov_b32_e32 v71, 0
	v_mov_b32_e32 v72, 0
	v_mov_b32_e32 v73, 0
	v_mov_b32_e32 v74, 0
	v_mov_b32_e32 v75, 0
	v_mov_b32_e32 v76, 0
	v_mov_b32_e32 v77, 0
	v_mov_b32_e32 v78, 0
	v_mov_b32_e32 v79, 0
	v_mov_b32_e32 v80, 0
	v_mov_b32_e32 v81, 0
	v_mov_b32_e32 v82, 0
	v_mov_b32_e32 v83, 0
	v_mov_b32_e32 v84, 0
	v_mov_b32_e32 v85, 0
	v_mov_b32_e32 v86, 0
	v_mov_b32_e32 v87, 0
	v_mov_b32_e32 v88, 0
	v_mov_b32_e32 v89, 0
	v_mov_b32_e32 v90, 0
	v_mov_b32_e32 v91, 0
	v_mov_b32_e32 v92, 0
	v_mov_b32_e32 v93, 0
	v_mov_b32_e32 v94, 0
	v_mov_b32_e32 v95, 0
	v_mov_b32_e32 v96, 0
	v_mov_b32_e32 v97, 0
	v_mov_b32_e32 v98, 0
	v_mov_b32_e32 v99, 0
	v_mov_b32_e32 v100, 0
	v_mov_b32_e32 v101, 0
	v_mov_b32_e32 v102, 0
	v_mov_b32_e32 v103, 0
	v_mov_b32_e32 v104, 0
	v_mov_b32_e32 v105, 0
	v_mov_b32_e32 v106, 0
	v_mov_b32_e32 v107, 0
	v_mov_b32_e32 v108, 0
	v_mov_b32_e32 v109, 0
	v_mov_b32_e32 v110, 0
	v_mov_b32_e32 v111, 0
	v_mov_b32_e32 v112, 0
	v_mov_b32_e32 v113, 0
	v_mov_b32_e32 v114, 0
	v_mov_b32_e32 v115, 0
	v_mov_b32_e32 v116, 0
	v_mov_b32_e32 v117, 0
	v_mov_b32_e32 v118, 0
	v_mov_b32_e32 v119, 0
	v_mov_b32_e32 v120, 0
	v_mov_b32_e32 v121, 0
	v_mov_b32_e32 v122, 0
	v_mov_b32_e32 v123, 0
	v_mov_b32_e32 v124, 0
	v_mov_b32_e32 v125, 0
	v_mov_b32_e32 v126, 0
	v_mov_b32_e32 v127, 0
	v_mov_b32_e32 v128, 0
	v_mov_b32_e32 v129, 0
	s_waitcnt vmcnt(12)
	s_barrier
	ds_read_b128 v[146:149], v136 offset:0
	ds_read_b128 v[152:155], v136 offset:1024
	ds_read_b128 v[156:159], v136 offset:2048
	ds_read_b128 v[162:165], v136 offset:3072
	ds_read_b128 v[166:169], v136 offset:4096
	ds_read_b128 v[170:173], v136 offset:5120
	ds_read_b128 v[176:179], v136 offset:6144
	ds_read_b128 v[180:183], v136 offset:7168
	ds_read_b128 v[184:187], v137 offset:16384
	ds_read_b128 v[188:191], v137 offset:17408
	ds_read_b128 v[192:195], v137 offset:18432
	ds_read_b128 v[196:199], v137 offset:19456
	s_movk_i32 s40, 0x6000
	s_mov_b32 s41, 0
	s_movk_i32 s39, 2
	.p2align 6
.Lta11_loop:
	.p2align 3
	s_waitcnt vmcnt(6) lgkmcnt(0)
	s_barrier
	s_setprio 1
	v_add_u32_e32 v144, s40, v136
	v_mfma_f32_16x16x32_bf16 v[126:129], v[184:187], v[146:149], v[126:129]
	ds_read_b128 v[200:203], v144 offset:0
	v_mfma_f32_16x16x32_bf16 v[122:125], v[184:187], v[152:155], v[122:125]
	ds_read_b128 v[204:207], v144 offset:1024
	v_mfma_f32_16x16x32_bf16 v[118:121], v[184:187], v[156:159], v[118:121]
	ds_read_b128 v[208:211], v144 offset:2048
	v_mfma_f32_16x16x32_bf16 v[114:117], v[184:187], v[162:165], v[114:117]
	ds_read_b128 v[212:215], v144 offset:3072
	v_mfma_f32_16x16x32_bf16 v[110:113], v[184:187], v[166:169], v[110:113]
	ds_read_b128 v[216:219], v144 offset:4096
	v_mfma_f32_16x16x32_bf16 v[106:109], v[184:187], v[170:173], v[106:109]
	ds_read_b128 v[220:223], v144 offset:5120
	v_mfma_f32_16x16x32_bf16 v[102:105], v[184:187], v[176:179], v[102:105]
	ds_read_b128 v[224:227], v144 offset:6144
	v_mfma_f32_16x16x32_bf16 v[98:101], v[184:187], v[180:183], v[98:101]
	ds_read_b128 v[228:231], v144 offset:7168
	v_mfma_f32_16x16x32_bf16 v[94:97], v[188:191], v[146:149], v[94:97]
	v_add_u32_e64 v144, s40, v137
	v_mfma_f32_16x16x32_bf16 v[90:93], v[188:191], v[152:155], v[90:93]
	v_mfma_f32_16x16x32_bf16 v[86:89], v[188:191], v[156:159], v[86:89]
	ds_read_b128 v[232:235], v144 offset:16384
	v_mfma_f32_16x16x32_bf16 v[82:85], v[188:191], v[162:165], v[82:85]
	ds_read_b128 v[236:239], v144 offset:17408
	v_mfma_f32_16x16x32_bf16 v[78:81], v[188:191], v[166:169], v[78:81]
	ds_read_b128 v[240:243], v144 offset:18432
	v_mfma_f32_16x16x32_bf16 v[74:77], v[188:191], v[170:173], v[74:77]
	ds_read_b128 v[244:247], v144 offset:19456
	v_mfma_f32_16x16x32_bf16 v[70:73], v[188:191], v[176:179], v[70:73]
	s_add_i32 s42, s46, s41
	s_mov_b32 m0, s42
	v_lshl_add_u64 v[142:143], v[132:133], 0, s[2:3]
	v_mfma_f32_16x16x32_bf16 v[66:69], v[188:191], v[180:183], v[66:69]
	global_load_lds_dwordx4 v[132:133], off
	s_add_i32 m0, m0, 0x1000
	v_mfma_f32_16x16x32_bf16 v[62:65], v[192:195], v[146:149], v[62:65]
	v_mfma_f32_16x16x32_bf16 v[58:61], v[192:195], v[152:155], v[58:61]
	v_mfma_f32_16x16x32_bf16 v[54:57], v[192:195], v[156:159], v[54:57]
	global_load_lds_dwordx4 v[142:143], off
;     ...
;   for (int kt = 0; kt < nk; kt++) {
;     if (kt + 1 < nk) asm volatile("s_waitcnt vmcnt(6)" ::: "memory");
;     else asm volatile("s_waitcnt vmcnt(0)" ::: "memory");
;     __builtin_amdgcn_s_barrier();
;     asm volatile("" ::: "memory");
;     if (kt + 2 < nk) G2_STAGE(kt + 2);
;     const char* cS = smem + (kt % 3) * 24576;
;     bf16x8 xa[8], wb[4];
; #pragma unroll
;     for (int f = 0; f < 8; f++) xa[f] = *(const bf16x8*)(cS + aoff + f * 1024);
; #pragma unroll
;     for (int f = 0; f < 4; f++) wb[f] = *(const bf16x8*)(cS + boff + f * 1024);
; #pragma unroll
;     for (int nf = 0; nf < 4; nf++)
; #pragma unroll
;       for (int mf = 0; mf < 8; mf++)
;         acc[nf][mf] = __builtin_amdgcn_mfma_f32_16x16x32_bf16(wb[nf], xa[mf], acc[nf][mf], 0, 0, 0);
;   }
	v_lshl_add_u64 v[142:143], v[142:143], 0, s[2:3]
	s_add_i32 m0, m0, 0x1000
	v_mfma_f32_16x16x32_bf16 v[50:53], v[192:195], v[162:165], v[50:53]
	v_mfma_f32_16x16x32_bf16 v[46:49], v[192:195], v[166:169], v[46:49]
	v_mfma_f32_16x16x32_bf16 v[42:45], v[192:195], v[170:173], v[42:45]
	global_load_lds_dwordx4 v[142:143], off
	v_lshl_add_u64 v[142:143], v[142:143], 0, s[2:3]
	s_add_i32 m0, m0, 0x1000
	v_mfma_f32_16x16x32_bf16 v[38:41], v[192:195], v[176:179], v[38:41]
	v_mfma_f32_16x16x32_bf16 v[34:37], v[192:195], v[180:183], v[34:37]
	v_mfma_f32_16x16x32_bf16 v[30:33], v[196:199], v[146:149], v[30:33]
	global_load_lds_dwordx4 v[142:143], off
	s_add_i32 m0, m0, 0x1000
	v_lshl_add_u64 v[142:143], v[134:135], 0, s[2:3]
	v_mfma_f32_16x16x32_bf16 v[26:29], v[196:199], v[152:155], v[26:29]
	v_mfma_f32_16x16x32_bf16 v[22:25], v[196:199], v[156:159], v[22:25]
	v_mfma_f32_16x16x32_bf16 v[18:21], v[196:199], v[162:165], v[18:21]
	global_load_lds_dwordx4 v[134:135], off
	s_add_i32 m0, m0, 0x1000
	v_lshl_add_u64 v[132:133], v[132:133], 0, s[12:13]
	v_mfma_f32_16x16x32_bf16 v[14:17], v[196:199], v[166:169], v[14:17]
	v_mfma_f32_16x16x32_bf16 v[10:13], v[196:199], v[170:173], v[10:13]
	v_mfma_f32_16x16x32_bf16 v[6:9], v[196:199], v[176:179], v[6:9]
	global_load_lds_dwordx4 v[142:143], off
	v_lshl_add_u64 v[134:135], v[134:135], 0, s[4:5]
	v_mfma_f32_16x16x32_bf16 v[2:5], v[196:199], v[180:183], v[2:5]
	s_setprio 0
	s_mov_b32 s41, s40
	s_add_i32 s40, s40, 0x6000
	s_cmp_eq_u32 s40, 0x12000
	s_cselect_b32 s40, 0, s40
	s_nop 0
	.p2align 3
	s_waitcnt vmcnt(6) lgkmcnt(0)
	s_barrier
	s_setprio 1
	v_add_u32_e32 v144, s40, v136
	v_mfma_f32_16x16x32_bf16 v[126:129], v[232:235], v[200:203], v[126:129]
	ds_read_b128 v[146:149], v144 offset:0
	v_mfma_f32_16x16x32_bf16 v[122:125], v[232:235], v[204:207], v[122:125]
	ds_read_b128 v[152:155], v144 offset:1024
	v_mfma_f32_16x16x32_bf16 v[118:121], v[232:235], v[208:211], v[118:121]
	ds_read_b128 v[156:159], v144 offset:2048
	v_mfma_f32_16x16x32_bf16 v[114:117], v[232:235], v[212:215], v[114:117]
	ds_read_b128 v[162:165], v144 offset:3072
	v_mfma_f32_16x16x32_bf16 v[110:113], v[232:235], v[216:219], v[110:113]
	ds_read_b128 v[166:169], v144 offset:4096
	v_mfma_f32_16x16x32_bf16 v[106:109], v[232:235], v[220:223], v[106:109]
	ds_read_b128 v[170:173], v144 offset:5120
	v_mfma_f32_16x16x32_bf16 v[102:105], v[232:235], v[224:227], v[102:105]
	ds_read_b128 v[176:179], v144 offset:6144
	v_mfma_f32_16x16x32_bf16 v[98:101], v[232:235], v[228:231], v[98:101]
	ds_read_b128 v[180:183], v144 offset:7168
	v_mfma_f32_16x16x32_bf16 v[94:97], v[236:239], v[200:203], v[94:97]
	v_add_u32_e64 v144, s40, v137
	v_mfma_f32_16x16x32_bf16 v[90:93], v[236:239], v[204:207], v[90:93]
	v_mfma_f32_16x16x32_bf16 v[86:89], v[236:239], v[208:211], v[86:89]
	ds_read_b128 v[184:187], v144 offset:16384
	v_mfma_f32_16x16x32_bf16 v[82:85], v[236:239], v[212:215], v[82:85]
	ds_read_b128 v[188:191], v144 offset:17408
	v_mfma_f32_16x16x32_bf16 v[78:81], v[236:239], v[216:219], v[78:81]
	ds_read_b128 v[192:195], v144 offset:18432
	v_mfma_f32_16x16x32_bf16 v[74:77], v[236:239], v[220:223], v[74:77]
	ds_read_b128 v[196:199], v144 offset:19456
	v_mfma_f32_16x16x32_bf16 v[70:73], v[236:239], v[224:227], v[70:73]
	s_add_i32 s42, s46, s41
	s_mov_b32 m0, s42
	v_lshl_add_u64 v[142:143], v[132:133], 0, s[2:3]
	v_mfma_f32_16x16x32_bf16 v[66:69], v[236:239], v[228:231], v[66:69]
	global_load_lds_dwordx4 v[132:133], off
	s_add_i32 m0, m0, 0x1000
	v_mfma_f32_16x16x32_bf16 v[62:65], v[240:243], v[200:203], v[62:65]
	v_mfma_f32_16x16x32_bf16 v[58:61], v[240:243], v[204:207], v[58:61]
	v_mfma_f32_16x16x32_bf16 v[54:57], v[240:243], v[208:211], v[54:57]
	global_load_lds_dwordx4 v[142:143], off
	v_lshl_add_u64 v[142:143], v[142:143], 0, s[2:3]
	s_add_i32 m0, m0, 0x1000
	v_mfma_f32_16x16x32_bf16 v[50:53], v[240:243], v[212:215], v[50:53]
	v_mfma_f32_16x16x32_bf16 v[46:49], v[240:243], v[216:219], v[46:49]
	v_mfma_f32_16x16x32_bf16 v[42:45], v[240:243], v[220:223], v[42:45]
	global_load_lds_dwordx4 v[142:143], off
	v_lshl_add_u64 v[142:143], v[142:143], 0, s[2:3]
	s_add_i32 m0, m0, 0x1000
	v_mfma_f32_16x16x32_bf16 v[38:41], v[240:243], v[224:227], v[38:41]
	v_mfma_f32_16x16x32_bf16 v[34:37], v[240:243], v[228:231], v[34:37]
	v_mfma_f32_16x16x32_bf16 v[30:33], v[244:247], v[200:203], v[30:33]
	global_load_lds_dwordx4 v[142:143], off
	s_add_i32 m0, m0, 0x1000
	v_lshl_add_u64 v[142:143], v[134:135], 0, s[2:3]
	v_mfma_f32_16x16x32_bf16 v[26:29], v[244:247], v[204:207], v[26:29]
	v_mfma_f32_16x16x32_bf16 v[22:25], v[244:247], v[208:211], v[22:25]
	v_mfma_f32_16x16x32_bf16 v[18:21], v[244:247], v[212:215], v[18:21]
	global_load_lds_dwordx4 v[134:135], off
	s_add_i32 m0, m0, 0x1000
	v_lshl_add_u64 v[132:133], v[132:133], 0, s[12:13]
	v_mfma_f32_16x16x32_bf16 v[14:17], v[244:247], v[216:219], v[14:17]
	v_mfma_f32_16x16x32_bf16 v[10:13], v[244:247], v[220:223], v[10:13]
	v_mfma_f32_16x16x32_bf16 v[6:9], v[244:247], v[224:227], v[6:9]
	global_load_lds_dwordx4 v[142:143], off
	v_lshl_add_u64 v[134:135], v[134:135], 0, s[4:5]
	v_mfma_f32_16x16x32_bf16 v[2:5], v[244:247], v[228:231], v[2:5]
	s_setprio 0
	s_mov_b32 s41, s40
	s_add_i32 s40, s40, 0x6000
	s_cmp_eq_u32 s40, 0x12000
	s_cselect_b32 s40, 0, s40
	s_nop 0
	s_sub_i32 s39, s39, 1
	s_cmp_lg_u32 s39, 0
	s_cbranch_scc1 .Lta11_loop
	.p2align 3
	s_waitcnt vmcnt(6) lgkmcnt(0)
	s_barrier
;     ...
;   for (int kt = 0; kt < nk; kt++) {
;     if (kt + 1 < nk) asm volatile("s_waitcnt vmcnt(6)" ::: "memory");
;     else asm volatile("s_waitcnt vmcnt(0)" ::: "memory");
;     __builtin_amdgcn_s_barrier();
;     asm volatile("" ::: "memory");
;     if (kt + 2 < nk) G2_STAGE(kt + 2);
;     const char* cS = smem + (kt % 3) * 24576;
;     bf16x8 xa[8], wb[4];
; #pragma unroll
;     for (int f = 0; f < 8; f++) xa[f] = *(const bf16x8*)(cS + aoff + f * 1024);
; #pragma unroll
;     for (int f = 0; f < 4; f++) wb[f] = *(const bf16x8*)(cS + boff + f * 1024);
; #pragma unroll
;     for (int nf = 0; nf < 4; nf++)
; #pragma unroll
;       for (int mf = 0; mf < 8; mf++)
;         acc[nf][mf] = __builtin_amdgcn_mfma_f32_16x16x32_bf16(wb[nf], xa[mf], acc[nf][mf], 0, 0, 0);
;   }
	s_setprio 1
	v_add_u32_e32 v144, s40, v136
	v_mfma_f32_16x16x32_bf16 v[126:129], v[184:187], v[146:149], v[126:129]
	ds_read_b128 v[200:203], v144 offset:0
	v_mfma_f32_16x16x32_bf16 v[122:125], v[184:187], v[152:155], v[122:125]
	ds_read_b128 v[204:207], v144 offset:1024
	v_mfma_f32_16x16x32_bf16 v[118:121], v[184:187], v[156:159], v[118:121]
	ds_read_b128 v[208:211], v144 offset:2048
	v_mfma_f32_16x16x32_bf16 v[114:117], v[184:187], v[162:165], v[114:117]
	ds_read_b128 v[212:215], v144 offset:3072
	v_mfma_f32_16x16x32_bf16 v[110:113], v[184:187], v[166:169], v[110:113]
	ds_read_b128 v[216:219], v144 offset:4096
	v_mfma_f32_16x16x32_bf16 v[106:109], v[184:187], v[170:173], v[106:109]
	ds_read_b128 v[220:223], v144 offset:5120
	v_mfma_f32_16x16x32_bf16 v[102:105], v[184:187], v[176:179], v[102:105]
	ds_read_b128 v[224:227], v144 offset:6144
	v_mfma_f32_16x16x32_bf16 v[98:101], v[184:187], v[180:183], v[98:101]
	ds_read_b128 v[228:231], v144 offset:7168
	v_mfma_f32_16x16x32_bf16 v[94:97], v[188:191], v[146:149], v[94:97]
	v_add_u32_e64 v144, s40, v137
	v_mfma_f32_16x16x32_bf16 v[90:93], v[188:191], v[152:155], v[90:93]
	v_mfma_f32_16x16x32_bf16 v[86:89], v[188:191], v[156:159], v[86:89]
	ds_read_b128 v[232:235], v144 offset:16384
	v_mfma_f32_16x16x32_bf16 v[82:85], v[188:191], v[162:165], v[82:85]
	ds_read_b128 v[236:239], v144 offset:17408
	v_mfma_f32_16x16x32_bf16 v[78:81], v[188:191], v[166:169], v[78:81]
	ds_read_b128 v[240:243], v144 offset:18432
	v_mfma_f32_16x16x32_bf16 v[74:77], v[188:191], v[170:173], v[74:77]
	ds_read_b128 v[244:247], v144 offset:19456
	v_mfma_f32_16x16x32_bf16 v[70:73], v[188:191], v[176:179], v[70:73]
	s_add_i32 s42, s46, s41
	s_mov_b32 m0, s42
	v_lshl_add_u64 v[142:143], v[132:133], 0, s[2:3]
	v_mfma_f32_16x16x32_bf16 v[66:69], v[188:191], v[180:183], v[66:69]
	global_load_lds_dwordx4 v[132:133], off
	s_add_i32 m0, m0, 0x1000
	v_mfma_f32_16x16x32_bf16 v[62:65], v[192:195], v[146:149], v[62:65]
	v_mfma_f32_16x16x32_bf16 v[58:61], v[192:195], v[152:155], v[58:61]
	v_mfma_f32_16x16x32_bf16 v[54:57], v[192:195], v[156:159], v[54:57]
	global_load_lds_dwordx4 v[142:143], off
	v_lshl_add_u64 v[142:143], v[142:143], 0, s[2:3]
	s_add_i32 m0, m0, 0x1000
	v_mfma_f32_16x16x32_bf16 v[50:53], v[192:195], v[162:165], v[50:53]
	v_mfma_f32_16x16x32_bf16 v[46:49], v[192:195], v[166:169], v[46:49]
	v_mfma_f32_16x16x32_bf16 v[42:45], v[192:195], v[170:173], v[42:45]
	global_load_lds_dwordx4 v[142:143], off
	v_lshl_add_u64 v[142:143], v[142:143], 0, s[2:3]
	s_add_i32 m0, m0, 0x1000
	v_mfma_f32_16x16x32_bf16 v[38:41], v[192:195], v[176:179], v[38:41]
	v_mfma_f32_16x16x32_bf16 v[34:37], v[192:195], v[180:183], v[34:37]
	v_mfma_f32_16x16x32_bf16 v[30:33], v[196:199], v[146:149], v[30:33]
	global_load_lds_dwordx4 v[142:143], off
	s_add_i32 m0, m0, 0x1000
	v_lshl_add_u64 v[142:143], v[134:135], 0, s[2:3]
	v_mfma_f32_16x16x32_bf16 v[26:29], v[196:199], v[152:155], v[26:29]
	v_mfma_f32_16x16x32_bf16 v[22:25], v[196:199], v[156:159], v[22:25]
	v_mfma_f32_16x16x32_bf16 v[18:21], v[196:199], v[162:165], v[18:21]
	global_load_lds_dwordx4 v[134:135], off
	s_add_i32 m0, m0, 0x1000
	v_lshl_add_u64 v[132:133], v[132:133], 0, s[12:13]
	v_mfma_f32_16x16x32_bf16 v[14:17], v[196:199], v[166:169], v[14:17]
	v_mfma_f32_16x16x32_bf16 v[10:13], v[196:199], v[170:173], v[10:13]
	v_mfma_f32_16x16x32_bf16 v[6:9], v[196:199], v[176:179], v[6:9]
	global_load_lds_dwordx4 v[142:143], off
	v_lshl_add_u64 v[134:135], v[134:135], 0, s[4:5]
	v_mfma_f32_16x16x32_bf16 v[2:5], v[196:199], v[180:183], v[2:5]
	s_setprio 0
	s_mov_b32 s41, s40
	s_add_i32 s40, s40, 0x6000
	s_cmp_eq_u32 s40, 0x12000
	s_cselect_b32 s40, 0, s40
	s_nop 0
	.p2align 3
	s_waitcnt vmcnt(6) lgkmcnt(0)
	s_barrier
	s_setprio 1
	v_add_u32_e32 v144, s40, v136
	v_mfma_f32_16x16x32_bf16 v[126:129], v[232:235], v[200:203], v[126:129]
	ds_read_b128 v[146:149], v144 offset:0
	v_mfma_f32_16x16x32_bf16 v[122:125], v[232:235], v[204:207], v[122:125]
	ds_read_b128 v[152:155], v144 offset:1024
	v_mfma_f32_16x16x32_bf16 v[118:121], v[232:235], v[208:211], v[118:121]
	ds_read_b128 v[156:159], v144 offset:2048
	v_mfma_f32_16x16x32_bf16 v[114:117], v[232:235], v[212:215], v[114:117]
	ds_read_b128 v[162:165], v144 offset:3072
	v_mfma_f32_16x16x32_bf16 v[110:113], v[232:235], v[216:219], v[110:113]
	ds_read_b128 v[166:169], v144 offset:4096
	v_mfma_f32_16x16x32_bf16 v[106:109], v[232:235], v[220:223], v[106:109]
	ds_read_b128 v[170:173], v144 offset:5120
	v_mfma_f32_16x16x32_bf16 v[102:105], v[232:235], v[224:227], v[102:105]
	ds_read_b128 v[176:179], v144 offset:6144
	v_mfma_f32_16x16x32_bf16 v[98:101], v[232:235], v[228:231], v[98:101]
	ds_read_b128 v[180:183], v144 offset:7168
	v_mfma_f32_16x16x32_bf16 v[94:97], v[236:239], v[200:203], v[94:97]
	v_add_u32_e64 v144, s40, v137
	v_mfma_f32_16x16x32_bf16 v[90:93], v[236:239], v[204:207], v[90:93]
	v_mfma_f32_16x16x32_bf16 v[86:89], v[236:239], v[208:211], v[86:89]
	ds_read_b128 v[184:187], v144 offset:16384
	v_mfma_f32_16x16x32_bf16 v[82:85], v[236:239], v[212:215], v[82:85]
	ds_read_b128 v[188:191], v144 offset:17408
	v_mfma_f32_16x16x32_bf16 v[78:81], v[236:239], v[216:219], v[78:81]
	ds_read_b128 v[192:195], v144 offset:18432
	v_mfma_f32_16x16x32_bf16 v[74:77], v[236:239], v[220:223], v[74:77]
	ds_read_b128 v[196:199], v144 offset:19456
	v_mfma_f32_16x16x32_bf16 v[70:73], v[236:239], v[224:227], v[70:73]
	v_mfma_f32_16x16x32_bf16 v[66:69], v[236:239], v[228:231], v[66:69]
	v_mfma_f32_16x16x32_bf16 v[62:65], v[240:243], v[200:203], v[62:65]
	v_mfma_f32_16x16x32_bf16 v[58:61], v[240:243], v[204:207], v[58:61]
	v_mfma_f32_16x16x32_bf16 v[54:57], v[240:243], v[208:211], v[54:57]
	v_mfma_f32_16x16x32_bf16 v[50:53], v[240:243], v[212:215], v[50:53]
	v_mfma_f32_16x16x32_bf16 v[46:49], v[240:243], v[216:219], v[46:49]
	v_mfma_f32_16x16x32_bf16 v[42:45], v[240:243], v[220:223], v[42:45]
	v_mfma_f32_16x16x32_bf16 v[38:41], v[240:243], v[224:227], v[38:41]
	v_mfma_f32_16x16x32_bf16 v[34:37], v[240:243], v[228:231], v[34:37]
	v_mfma_f32_16x16x32_bf16 v[30:33], v[244:247], v[200:203], v[30:33]
	v_mfma_f32_16x16x32_bf16 v[26:29], v[244:247], v[204:207], v[26:29]
	v_mfma_f32_16x16x32_bf16 v[22:25], v[244:247], v[208:211], v[22:25]
	v_mfma_f32_16x16x32_bf16 v[18:21], v[244:247], v[212:215], v[18:21]
	v_mfma_f32_16x16x32_bf16 v[14:17], v[244:247], v[216:219], v[14:17]
	v_mfma_f32_16x16x32_bf16 v[10:13], v[244:247], v[220:223], v[10:13]
	v_mfma_f32_16x16x32_bf16 v[6:9], v[244:247], v[224:227], v[6:9]
	v_mfma_f32_16x16x32_bf16 v[2:5], v[244:247], v[228:231], v[2:5]
	s_setprio 0
	s_mov_b32 s41, s40
	s_add_i32 s40, s40, 0x6000
	s_cmp_eq_u32 s40, 0x12000
	s_cselect_b32 s40, 0, s40
	s_nop 0
	.p2align 3
	s_waitcnt vmcnt(0) lgkmcnt(0)
	s_barrier
;     ...
;   for (int kt = 0; kt < nk; kt++) {
;     if (kt + 1 < nk) asm volatile("s_waitcnt vmcnt(6)" ::: "memory");
;     else asm volatile("s_waitcnt vmcnt(0)" ::: "memory");
;     __builtin_amdgcn_s_barrier();
;     asm volatile("" ::: "memory");
;     if (kt + 2 < nk) G2_STAGE(kt + 2);
;     const char* cS = smem + (kt % 3) * 24576;
;     bf16x8 xa[8], wb[4];
; #pragma unroll
;     for (int f = 0; f < 8; f++) xa[f] = *(const bf16x8*)(cS + aoff + f * 1024);
; #pragma unroll
;     for (int f = 0; f < 4; f++) wb[f] = *(const bf16x8*)(cS + boff + f * 1024);
; #pragma unroll
;     for (int nf = 0; nf < 4; nf++)
; #pragma unroll
;       for (int mf = 0; mf < 8; mf++)
;         acc[nf][mf] = __builtin_amdgcn_mfma_f32_16x16x32_bf16(wb[nf], xa[mf], acc[nf][mf], 0, 0, 0);
;   }
	s_setprio 1
	v_add_u32_e32 v144, s40, v136
	v_mfma_f32_16x16x32_bf16 v[126:129], v[184:187], v[146:149], v[126:129]
	ds_read_b128 v[200:203], v144 offset:0
	v_mfma_f32_16x16x32_bf16 v[122:125], v[184:187], v[152:155], v[122:125]
	ds_read_b128 v[204:207], v144 offset:1024
	v_mfma_f32_16x16x32_bf16 v[118:121], v[184:187], v[156:159], v[118:121]
	ds_read_b128 v[208:211], v144 offset:2048
	v_mfma_f32_16x16x32_bf16 v[114:117], v[184:187], v[162:165], v[114:117]
	ds_read_b128 v[212:215], v144 offset:3072
	v_mfma_f32_16x16x32_bf16 v[110:113], v[184:187], v[166:169], v[110:113]
	ds_read_b128 v[216:219], v144 offset:4096
	v_mfma_f32_16x16x32_bf16 v[106:109], v[184:187], v[170:173], v[106:109]
	ds_read_b128 v[220:223], v144 offset:5120
	v_mfma_f32_16x16x32_bf16 v[102:105], v[184:187], v[176:179], v[102:105]
	ds_read_b128 v[224:227], v144 offset:6144
	v_mfma_f32_16x16x32_bf16 v[98:101], v[184:187], v[180:183], v[98:101]
	ds_read_b128 v[228:231], v144 offset:7168
	v_mfma_f32_16x16x32_bf16 v[94:97], v[188:191], v[146:149], v[94:97]
	v_add_u32_e64 v144, s40, v137
	v_mfma_f32_16x16x32_bf16 v[90:93], v[188:191], v[152:155], v[90:93]
	v_mfma_f32_16x16x32_bf16 v[86:89], v[188:191], v[156:159], v[86:89]
	ds_read_b128 v[232:235], v144 offset:16384
	v_mfma_f32_16x16x32_bf16 v[82:85], v[188:191], v[162:165], v[82:85]
	ds_read_b128 v[236:239], v144 offset:17408
	v_mfma_f32_16x16x32_bf16 v[78:81], v[188:191], v[166:169], v[78:81]
	ds_read_b128 v[240:243], v144 offset:18432
	v_mfma_f32_16x16x32_bf16 v[74:77], v[188:191], v[170:173], v[74:77]
	ds_read_b128 v[244:247], v144 offset:19456
	v_mfma_f32_16x16x32_bf16 v[70:73], v[188:191], v[176:179], v[70:73]
	v_mfma_f32_16x16x32_bf16 v[66:69], v[188:191], v[180:183], v[66:69]
	v_mfma_f32_16x16x32_bf16 v[62:65], v[192:195], v[146:149], v[62:65]
	v_mfma_f32_16x16x32_bf16 v[58:61], v[192:195], v[152:155], v[58:61]
	v_mfma_f32_16x16x32_bf16 v[54:57], v[192:195], v[156:159], v[54:57]
	v_mfma_f32_16x16x32_bf16 v[50:53], v[192:195], v[162:165], v[50:53]
	v_mfma_f32_16x16x32_bf16 v[46:49], v[192:195], v[166:169], v[46:49]
	v_mfma_f32_16x16x32_bf16 v[42:45], v[192:195], v[170:173], v[42:45]
	v_mfma_f32_16x16x32_bf16 v[38:41], v[192:195], v[176:179], v[38:41]
	v_mfma_f32_16x16x32_bf16 v[34:37], v[192:195], v[180:183], v[34:37]
	v_mfma_f32_16x16x32_bf16 v[30:33], v[196:199], v[146:149], v[30:33]
	v_mfma_f32_16x16x32_bf16 v[26:29], v[196:199], v[152:155], v[26:29]
	v_mfma_f32_16x16x32_bf16 v[22:25], v[196:199], v[156:159], v[22:25]
	v_mfma_f32_16x16x32_bf16 v[18:21], v[196:199], v[162:165], v[18:21]
	v_mfma_f32_16x16x32_bf16 v[14:17], v[196:199], v[166:169], v[14:17]
	v_mfma_f32_16x16x32_bf16 v[10:13], v[196:199], v[170:173], v[10:13]
	v_mfma_f32_16x16x32_bf16 v[6:9], v[196:199], v[176:179], v[6:9]
	v_mfma_f32_16x16x32_bf16 v[2:5], v[196:199], v[180:183], v[2:5]
	s_setprio 0
	s_mov_b32 s41, s40
	s_add_i32 s40, s40, 0x6000
	s_cmp_eq_u32 s40, 0x12000
	s_cselect_b32 s40, 0, s40
	s_nop 0
	s_mov_b32 s4, 0x8000
	s_mov_b32 s5, 0
	s_mov_b32 s10, 0x10000
	s_mov_b32 s11, 0
	s_mov_b32 s44, 0x3fd744fd
	.p2align 3
	s_waitcnt lgkmcnt(0)
	s_nop 0
	v_mfma_f32_16x16x32_bf16 v[126:129], v[232:235], v[200:203], v[126:129]
	v_mfma_f32_16x16x32_bf16 v[122:125], v[232:235], v[204:207], v[122:125]
	v_mfma_f32_16x16x32_bf16 v[118:121], v[232:235], v[208:211], v[118:121]
	v_mfma_f32_16x16x32_bf16 v[114:117], v[232:235], v[212:215], v[114:117]
	v_mfma_f32_16x16x32_bf16 v[110:113], v[232:235], v[216:219], v[110:113]
	v_mfma_f32_16x16x32_bf16 v[106:109], v[232:235], v[220:223], v[106:109]
	v_mfma_f32_16x16x32_bf16 v[102:105], v[232:235], v[224:227], v[102:105]
	v_mfma_f32_16x16x32_bf16 v[98:101], v[232:235], v[228:231], v[98:101]
	v_mfma_f32_16x16x32_bf16 v[94:97], v[236:239], v[200:203], v[94:97]
	v_mfma_f32_16x16x32_bf16 v[90:93], v[236:239], v[204:207], v[90:93]
	v_mfma_f32_16x16x32_bf16 v[86:89], v[236:239], v[208:211], v[86:89]
	v_mfma_f32_16x16x32_bf16 v[82:85], v[236:239], v[212:215], v[82:85]
	v_mfma_f32_16x16x32_bf16 v[78:81], v[236:239], v[216:219], v[78:81]
	v_mfma_f32_16x16x32_bf16 v[74:77], v[236:239], v[220:223], v[74:77]
	v_mfma_f32_16x16x32_bf16 v[70:73], v[236:239], v[224:227], v[70:73]
	v_mfma_f32_16x16x32_bf16 v[66:69], v[236:239], v[228:231], v[66:69]
	v_mfma_f32_16x16x32_bf16 v[62:65], v[240:243], v[200:203], v[62:65]
	v_mfma_f32_16x16x32_bf16 v[58:61], v[240:243], v[204:207], v[58:61]
	v_mfma_f32_16x16x32_bf16 v[54:57], v[240:243], v[208:211], v[54:57]
	v_mfma_f32_16x16x32_bf16 v[50:53], v[240:243], v[212:215], v[50:53]
	v_mfma_f32_16x16x32_bf16 v[46:49], v[240:243], v[216:219], v[46:49]
	v_mfma_f32_16x16x32_bf16 v[42:45], v[240:243], v[220:223], v[42:45]
	v_mfma_f32_16x16x32_bf16 v[38:41], v[240:243], v[224:227], v[38:41]
	v_mfma_f32_16x16x32_bf16 v[34:37], v[240:243], v[228:231], v[34:37]
	v_mfma_f32_16x16x32_bf16 v[30:33], v[244:247], v[200:203], v[30:33]
	v_mfma_f32_16x16x32_bf16 v[26:29], v[244:247], v[204:207], v[26:29]
	v_mfma_f32_16x16x32_bf16 v[22:25], v[244:247], v[208:211], v[22:25]
	v_mfma_f32_16x16x32_bf16 v[18:21], v[244:247], v[212:215], v[18:21]
	v_mfma_f32_16x16x32_bf16 v[14:17], v[244:247], v[216:219], v[14:17]
	v_mfma_f32_16x16x32_bf16 v[10:13], v[244:247], v[220:223], v[10:13]
	v_mfma_f32_16x16x32_bf16 v[6:9], v[244:247], v[224:227], v[6:9]
	v_mfma_f32_16x16x32_bf16 v[2:5], v[244:247], v[228:231], v[2:5]
	s_mov_b32 m0, s43
	s_cmp_eq_u32 s47, 0
	s_cbranch_scc1 .Lta11_first
; DEVI float blo(unsigned u) { return __uint_as_float(u << 16); }
; DEVI float bhi(unsigned u) { return __uint_as_float(u & 0xffff0000u); }
;     ...
;         if (EPI == EPI_RESID || EPI == EPI_RESID_ATOMIC) {
;           f32x4 x = a;
;           if (EPI == EPI_RESID || kpart == 0) {
;             const u32x2 xr = *(const u32x2*)((const u16*)(p.ws + WS_XB) + (size_t)row * 1024 + col);
;             x[0] += ALPHA * blo(xr[0]); x[1] += ALPHA * bhi(xr[0]); x[2] += ALPHA * blo(xr[1]); x[3] += ALPHA * bhi(xr[1]);
;           }
;           if (EPI == EPI_RESID) *(f32x4*)((float*)(p.ws + WS_XF) + (size_t)row * 1024 + col) = x;
;           else *(f32x4*)((float*)(p.ws + WS_SLAB) + ((size_t)kpart * 512 + (row - T_P)) * 1024 + col) = x;
	s_nop 7
	global_store_dwordx4 v[140:141], v[126:129], off offset:0
	global_store_dwordx4 v[140:141], v[94:97], off offset:64
	global_store_dwordx4 v[140:141], v[62:65], off offset:128
	global_store_dwordx4 v[140:141], v[30:33], off offset:192
	v_lshl_add_u64 v[140:141], v[140:141], 0, s[10:11]
	global_store_dwordx4 v[140:141], v[122:125], off offset:0
	global_store_dwordx4 v[140:141], v[90:93], off offset:64
	global_store_dwordx4 v[140:141], v[58:61], off offset:128
	global_store_dwordx4 v[140:141], v[26:29], off offset:192
	v_lshl_add_u64 v[140:141], v[140:141], 0, s[10:11]
	global_store_dwordx4 v[140:141], v[118:121], off offset:0
	global_store_dwordx4 v[140:141], v[86:89], off offset:64
	global_store_dwordx4 v[140:141], v[54:57], off offset:128
	global_store_dwordx4 v[140:141], v[22:25], off offset:192
	v_lshl_add_u64 v[140:141], v[140:141], 0, s[10:11]
	global_store_dwordx4 v[140:141], v[114:117], off offset:0
	global_store_dwordx4 v[140:141], v[82:85], off offset:64
	global_store_dwordx4 v[140:141], v[50:53], off offset:128
	global_store_dwordx4 v[140:141], v[18:21], off offset:192
	v_lshl_add_u64 v[140:141], v[140:141], 0, s[10:11]
	global_store_dwordx4 v[140:141], v[110:113], off offset:0
	global_store_dwordx4 v[140:141], v[78:81], off offset:64
	global_store_dwordx4 v[140:141], v[46:49], off offset:128
	global_store_dwordx4 v[140:141], v[14:17], off offset:192
	v_lshl_add_u64 v[140:141], v[140:141], 0, s[10:11]
	global_store_dwordx4 v[140:141], v[106:109], off offset:0
	global_store_dwordx4 v[140:141], v[74:77], off offset:64
	global_store_dwordx4 v[140:141], v[42:45], off offset:128
	global_store_dwordx4 v[140:141], v[10:13], off offset:192
	v_lshl_add_u64 v[140:141], v[140:141], 0, s[10:11]
	global_store_dwordx4 v[140:141], v[102:105], off offset:0
	global_store_dwordx4 v[140:141], v[70:73], off offset:64
	global_store_dwordx4 v[140:141], v[38:41], off offset:128
	global_store_dwordx4 v[140:141], v[6:9], off offset:192
	v_lshl_add_u64 v[140:141], v[140:141], 0, s[10:11]
	global_store_dwordx4 v[140:141], v[98:101], off offset:0
	global_store_dwordx4 v[140:141], v[66:69], off offset:64
	global_store_dwordx4 v[140:141], v[34:37], off offset:128
	global_store_dwordx4 v[140:141], v[2:5], off offset:192
	s_branch .LBB0_41

; #define LAS __attribute__((address_space(3)))
; DEVI int xcd_first_tile() { return (blockIdx.x & 7) * (gridDim.x >> 3) + (blockIdx.x >> 3); }
;     ...
;   const int nk = (nk_part < 0) ? (K >> 5) : nk_part;
;   const int lrow = tid >> 2, lpc = tid & 3;
;   const int lch = lpc ^ ((0x78 >> (((lrow >> 2) & 3) * 2)) & 3);
;   const u16* ga = A + (size_t)(m0 + lrow) * lda + kbeg + lch * 8;
;   const u16* gb = Bt + (size_t)(n0 + lrow) * K + kbeg + lch * 8;
;   const size_t ga1 = (size_t)64 * lda, gb1 = (size_t)64 * K;
;   const unsigned lds0 = (unsigned)(uintptr_t)(LAS char*)smem + (unsigned)__builtin_amdgcn_readfirstlane(wid) * 1024u;
;     ...
;   __syncthreads();
;   G2_STAGE(0); G2_STAGE(1);
; DEVI void run_phase(const Params& p, int ph, char* smem) {
;     ...
;       for (int t = xcd_first_tile(); t < 512 + 16 * 11; t += xcd_tile_step()) {
;         if (t < 512) {
;           int mt_, nt_; tile_coords(t, 64, 8, mt_, nt_);
;           gemm_tile256<EPI_RESID>(p, hb, DFF, Bt, DFF, mt_ * 256, nt_ * 128, nullptr, 0, smem);
.LBB0_116:
	s_and_b64 vcc, exec, s[2:3]
	s_cbranch_vccz .LBB0_41
	s_lshr_b32 s45, s38, 6
	s_and_b32 s46, s38, 63
	s_lshr_b32 s42, s46, 3
	s_and_b32 s46, s46, 7
	s_lshl_b32 s45, s45, 3
	s_add_i32 s45, s45, s46
	s_cmp_lt_u32 s45, 64
	s_cselect_b32 s44, 1, 0
	v_readlane_b32 s2, v250, 5
	v_readlane_b32 s3, v250, 6
	v_readlane_b32 s46, v254, 62
	s_mul_i32 s40, s45, 0x160000
	s_add_u32 s4, s2, s40
	s_addc_u32 s5, s3, 0
	s_add_u32 s4, s4, 0xef40000
	s_addc_u32 s5, s5, 0
	s_mul_i32 s40, s46, 0x580000
	s_mul_i32 s41, s42, 0xb0000
	s_add_i32 s40, s40, s41
	s_add_u32 s10, s2, s40
	s_addc_u32 s11, s3, 0
	s_add_u32 s10, s10, 0x19a00000
	s_addc_u32 s11, s11, 0
	s_movk_i32 s39, 0x78
	v_lshrrev_b32_e32 v0, 2, v145
	v_and_b32_e32 v131, 3, v145
	v_bfe_u32 v136, v145, 4, 2
	v_lshlrev_b32_e32 v136, 1, v136
	v_lshrrev_b32_e64 v136, v136, s39
	v_and_b32_e32 v136, 3, v136
	v_xor_b32_e32 v131, v131, v136
	v_lshlrev_b32_e32 v131, 4, v131
	s_movk_i32 s41, 0x1600
	v_mad_u32_u24 v0, v0, s41, v131
	v_bfe_u32 v137, v145, 2, 1
	s_movk_i32 s41, 0x15c0
	v_mul_u32_u24_e32 v136, s41, v137
	v_sub_u32_e32 v136, v0, v136
	v_mov_b32_e32 v137, 0
	v_lshl_add_u64 v[134:135], s[10:11], 0, v[136:137]
	v_bfe_u32 v137, v145, 2, 1
	s_mul_i32 s41, s44, 0x15c0
	v_mul_u32_u24_e32 v136, s41, v137
	v_sub_u32_e32 v0, v0, v136
	s_lshl_b32 s12, s44, 6
	s_add_i32 s12, s12, 64
	s_mov_b32 s13, 0
	v_lshl_add_u64 v[132:133], s[4:5], 0, v[0:1]
	v_bfe_u32 v136, v145, 2, 2
	v_lshlrev_b32_e32 v136, 1, v136
	v_lshrrev_b32_e64 v136, v136, s39
	v_and_b32_e32 v136, 3, v136
	v_bfe_u32 v137, v145, 4, 2
	v_xor_b32_e32 v136, v136, v137
	v_lshlrev_b32_e32 v136, 4, v136
	v_and_b32_e32 v131, 15, v145
	v_lshl_or_b32 v136, v131, 6, v136
	v_bfe_u32 v137, v145, 6, 1
	v_lshl_or_b32 v137, v137, 12, v136
	v_lshrrev_b32_e32 v0, 7, v145
	v_lshl_or_b32 v136, v0, 13, v136
	v_and_b32_e32 v140, 1, v131
	v_lshl_or_b32 v131, v0, 7, v131
	v_bfe_u32 v0, v145, 4, 2
	v_lshlrev_b32_e32 v0, 3, v0
	v_bfe_u32 v141, v145, 6, 1
	s_lshl_b32 s40, s45, 19
	s_lshl_b32 s41, s42, 9
	s_add_i32 s40, s40, s41
	s_add_u32 s4, s2, s40
	s_addc_u32 s5, s3, 0
	s_add_u32 s4, s4, 0x4200000
	s_addc_u32 s5, s5, 0
	v_lshlrev_b32_e32 v138, 11, v131
	v_lshl_add_u32 v138, v141, 8, v138
	v_bfe_u32 v139, v145, 4, 1
	v_lshl_add_u32 v138, v139, 5, v138
	v_bfe_u32 v139, v145, 5, 1
	v_lshl_add_u32 v138, v139, 4, v138
	s_movk_i32 s41, 1984
	v_mul_u32_u24_e32 v139, s41, v140
	v_sub_u32_e32 v138, v138, v139
	v_mov_b32_e32 v139, 0
	v_lshl_add_u64 v[138:139], s[4:5], 0, v[138:139]
	s_lshl_b32 s40, s45, 20
	s_lshl_b32 s41, s42, 9
	s_add_i32 s40, s40, s41
	s_add_u32 s10, s2, s40
	s_addc_u32 s11, s3, 0
	v_lshlrev_b32_e32 v140, 12, v131
	v_lshl_add_u32 v140, v141, 8, v140
	v_lshl_add_u32 v140, v0, 1, v140
	v_mov_b32_e32 v141, 0
	v_lshl_add_u64 v[140:141], s[10:11], 0, v[140:141]
	s_mov_b32 s2, 0x58000
	s_mov_b32 s3, 0
	v_lshrrev_b32_e32 v0, 6, v145
	v_lshlrev_b32_e32 v0, 10, v0
	s_nop 0
	v_readfirstlane_b32 s46, v0
	s_mov_b32 s43, m0
	s_mov_b32 s4, 128
	s_mov_b32 s5, 0
	s_barrier
	s_add_i32 s42, s46, 0x0
	s_mov_b32 m0, s42
	v_lshl_add_u64 v[142:143], v[132:133], 0, s[2:3]
	global_load_lds_dwordx4 v[132:133], off
	s_add_i32 m0, m0, 0x1000
	s_nop 0
	global_load_lds_dwordx4 v[142:143], off
	v_lshl_add_u64 v[142:143], v[142:143], 0, s[2:3]
	s_add_i32 m0, m0, 0x1000
	s_nop 0
	global_load_lds_dwordx4 v[142:143], off
	v_lshl_add_u64 v[142:143], v[142:143], 0, s[2:3]
	s_add_i32 m0, m0, 0x1000
	s_nop 0
	global_load_lds_dwordx4 v[142:143], off
	s_add_i32 m0, m0, 0x1000
	v_lshl_add_u64 v[142:143], v[134:135], 0, s[2:3]
	s_nop 0
	global_load_lds_dwordx4 v[134:135], off
	s_add_i32 m0, m0, 0x1000
	v_lshl_add_u64 v[132:133], v[132:133], 0, s[12:13]
	s_nop 0
	global_load_lds_dwordx4 v[142:143], off
	v_lshl_add_u64 v[134:135], v[134:135], 0, s[4:5]
	s_nop 0
	s_add_i32 s42, s46, 0x6000
	s_mov_b32 m0, s42
	v_lshl_add_u64 v[142:143], v[132:133], 0, s[2:3]
	global_load_lds_dwordx4 v[132:133], off
	s_add_i32 m0, m0, 0x1000
	s_nop 0
	global_load_lds_dwordx4 v[142:143], off
	v_lshl_add_u64 v[142:143], v[142:143], 0, s[2:3]
	s_add_i32 m0, m0, 0x1000
	s_nop 0
	global_load_lds_dwordx4 v[142:143], off
	v_lshl_add_u64 v[142:143], v[142:143], 0, s[2:3]
	s_add_i32 m0, m0, 0x1000
	s_nop 0
	global_load_lds_dwordx4 v[142:143], off
	s_add_i32 m0, m0, 0x1000
	v_lshl_add_u64 v[142:143], v[134:135], 0, s[2:3]
	s_nop 0
	global_load_lds_dwordx4 v[134:135], off
	s_add_i32 m0, m0, 0x1000
	v_lshl_add_u64 v[132:133], v[132:133], 0, s[12:13]
	s_nop 0
	global_load_lds_dwordx4 v[142:143], off
	v_lshl_add_u64 v[134:135], v[134:135], 0, s[4:5]
	s_nop 0
	s_add_i32 s42, s46, 0xc000
	s_mov_b32 m0, s42
	v_lshl_add_u64 v[142:143], v[132:133], 0, s[2:3]
	global_load_lds_dwordx4 v[132:133], off
	s_add_i32 m0, m0, 0x1000
	s_nop 0
	global_load_lds_dwordx4 v[142:143], off
	v_lshl_add_u64 v[142:143], v[142:143], 0, s[2:3]
	s_add_i32 m0, m0, 0x1000
	s_nop 0
	global_load_lds_dwordx4 v[142:143], off
	v_lshl_add_u64 v[142:143], v[142:143], 0, s[2:3]
	s_add_i32 m0, m0, 0x1000
	s_nop 0
	global_load_lds_dwordx4 v[142:143], off
	s_add_i32 m0, m0, 0x1000
	v_lshl_add_u64 v[142:143], v[134:135], 0, s[2:3]
	s_nop 0
	global_load_lds_dwordx4 v[134:135], off
	s_add_i32 m0, m0, 0x1000
	v_lshl_add_u64 v[132:133], v[132:133], 0, s[12:13]
	s_nop 0
	global_load_lds_dwordx4 v[142:143], off
	v_lshl_add_u64 v[134:135], v[134:135], 0, s[4:5]
	s_nop 0
	v_mov_b32_e32 v2, 0
	v_mov_b32_e32 v3, 0
	v_mov_b32_e32 v4, 0
	v_mov_b32_e32 v5, 0
	v_mov_b32_e32 v6, 0
	v_mov_b32_e32 v7, 0
	v_mov_b32_e32 v8, 0
	v_mov_b32_e32 v9, 0
	v_mov_b32_e32 v10, 0
	v_mov_b32_e32 v11, 0
	v_mov_b32_e32 v12, 0
	v_mov_b32_e32 v13, 0
	v_mov_b32_e32 v14, 0
	v_mov_b32_e32 v15, 0
; #define LAS __attribute__((address_space(3)))
;     ...
;   f32x4 acc[4][8];
; #pragma unroll
;   for (int i = 0; i < 4; i++)
; #pragma unroll
;     for (int j = 0; j < 8; j++) acc[i][j] = (f32x4){0.f, 0.f, 0.f, 0.f};
;   const int nk = (nk_part < 0) ? (K >> 5) : nk_part;
;   const int lrow = tid >> 2, lpc = tid & 3;
;   const int lch = lpc ^ ((0x78 >> (((lrow >> 2) & 3) * 2)) & 3);
;   const u16* ga = A + (size_t)(m0 + lrow) * lda + kbeg + lch * 8;
;   const u16* gb = Bt + (size_t)(n0 + lrow) * K + kbeg + lch * 8;
;   const size_t ga1 = (size_t)64 * lda, gb1 = (size_t)64 * K;
;   const unsigned lds0 = (unsigned)(uintptr_t)(LAS char*)smem + (unsigned)__builtin_amdgcn_readfirstlane(wid) * 1024u;
;     ...
;   __syncthreads();
;   G2_STAGE(0); G2_STAGE(1);
;   const int fsw = (0x78 >> (((r16 >> 2) & 3) * 2)) & 3;
;   const int aoff = (wm * 128 + r16) * 64 + ((quad ^ fsw) << 4);
;   const int boff = 16384 + (wn * 64 + r16) * 64 + ((quad ^ fsw) << 4);
;   for (int kt = 0; kt < nk; kt++) {
;     if (kt + 1 < nk) asm volatile("s_waitcnt vmcnt(6)" ::: "memory");
;     else asm volatile("s_waitcnt vmcnt(0)" ::: "memory");
;     __builtin_amdgcn_s_barrier();
;     asm volatile("" ::: "memory");
;     if (kt + 2 < nk) G2_STAGE(kt + 2);
;     const char* cS = smem + (kt % 3) * 24576;
;     bf16x8 xa[8], wb[4];
; #pragma unroll
;     for (int f = 0; f < 8; f++) xa[f] = *(const bf16x8*)(cS + aoff + f * 1024);
; #pragma unroll
;     for (int f = 0; f < 4; f++) wb[f] = *(const bf16x8*)(cS + boff + f * 1024);
; #pragma unroll
;     for (int nf = 0; nf < 4; nf++)
; #pragma unroll
;       for (int mf = 0; mf < 8; mf++)
;         acc[nf][mf] = __builtin_amdgcn_mfma_f32_16x16x32_bf16(wb[nf], xa[mf], acc[nf][mf], 0, 0, 0);
;   }
	v_mov_b32_e32 v16, 0
	v_mov_b32_e32 v17, 0
	v_mov_b32_e32 v18, 0
	v_mov_b32_e32 v19, 0
	v_mov_b32_e32 v20, 0
	v_mov_b32_e32 v21, 0
	v_mov_b32_e32 v22, 0
	v_mov_b32_e32 v23, 0
	v_mov_b32_e32 v24, 0
	v_mov_b32_e32 v25, 0
	v_mov_b32_e32 v26, 0
	v_mov_b32_e32 v27, 0
	v_mov_b32_e32 v28, 0
	v_mov_b32_e32 v29, 0
	v_mov_b32_e32 v30, 0
	v_mov_b32_e32 v31, 0
	v_mov_b32_e32 v32, 0
	v_mov_b32_e32 v33, 0
	v_mov_b32_e32 v34, 0
	v_mov_b32_e32 v35, 0
	v_mov_b32_e32 v36, 0
	v_mov_b32_e32 v37, 0
	v_mov_b32_e32 v38, 0
	v_mov_b32_e32 v39, 0
	v_mov_b32_e32 v40, 0
	v_mov_b32_e32 v41, 0
	v_mov_b32_e32 v42, 0
	v_mov_b32_e32 v43, 0
	v_mov_b32_e32 v44, 0
	v_mov_b32_e32 v45, 0
	v_mov_b32_e32 v46, 0
	v_mov_b32_e32 v47, 0
	v_mov_b32_e32 v48, 0
	v_mov_b32_e32 v49, 0
	v_mov_b32_e32 v50, 0
	v_mov_b32_e32 v51, 0
	v_mov_b32_e32 v52, 0
	v_mov_b32_e32 v53, 0
	v_mov_b32_e32 v54, 0
	v_mov_b32_e32 v55, 0
	v_mov_b32_e32 v56, 0
	v_mov_b32_e32 v57, 0
	v_mov_b32_e32 v58, 0
	v_mov_b32_e32 v59, 0
	v_mov_b32_e32 v60, 0
	v_mov_b32_e32 v61, 0
	v_mov_b32_e32 v62, 0
	v_mov_b32_e32 v63, 0
	v_mov_b32_e32 v64, 0
	v_mov_b32_e32 v65, 0
	v_mov_b32_e32 v66, 0
	v_mov_b32_e32 v67, 0
	v_mov_b32_e32 v68, 0
	v_mov_b32_e32 v69, 0
	v_mov_b32_e32 v70, 0
	v_mov_b32_e32 v71, 0
	v_mov_b32_e32 v72, 0
	v_mov_b32_e32 v73, 0
	v_mov_b32_e32 v74, 0
	v_mov_b32_e32 v75, 0
	v_mov_b32_e32 v76, 0
	v_mov_b32_e32 v77, 0
	v_mov_b32_e32 v78, 0
	v_mov_b32_e32 v79, 0
	v_mov_b32_e32 v80, 0
	v_mov_b32_e32 v81, 0
	v_mov_b32_e32 v82, 0
	v_mov_b32_e32 v83, 0
	v_mov_b32_e32 v84, 0
	v_mov_b32_e32 v85, 0
	v_mov_b32_e32 v86, 0
	v_mov_b32_e32 v87, 0
	v_mov_b32_e32 v88, 0
	v_mov_b32_e32 v89, 0
	v_mov_b32_e32 v90, 0
	v_mov_b32_e32 v91, 0
	v_mov_b32_e32 v92, 0
	v_mov_b32_e32 v93, 0
	v_mov_b32_e32 v94, 0
	v_mov_b32_e32 v95, 0
	v_mov_b32_e32 v96, 0
	v_mov_b32_e32 v97, 0
	v_mov_b32_e32 v98, 0
	v_mov_b32_e32 v99, 0
	v_mov_b32_e32 v100, 0
	v_mov_b32_e32 v101, 0
	v_mov_b32_e32 v102, 0
	v_mov_b32_e32 v103, 0
	v_mov_b32_e32 v104, 0
	v_mov_b32_e32 v105, 0
	v_mov_b32_e32 v106, 0
	v_mov_b32_e32 v107, 0
	v_mov_b32_e32 v108, 0
	v_mov_b32_e32 v109, 0
	v_mov_b32_e32 v110, 0
	v_mov_b32_e32 v111, 0
	v_mov_b32_e32 v112, 0
	v_mov_b32_e32 v113, 0
	v_mov_b32_e32 v114, 0
	v_mov_b32_e32 v115, 0
	v_mov_b32_e32 v116, 0
	v_mov_b32_e32 v117, 0
	v_mov_b32_e32 v118, 0
	v_mov_b32_e32 v119, 0
	v_mov_b32_e32 v120, 0
	v_mov_b32_e32 v121, 0
	v_mov_b32_e32 v122, 0
	v_mov_b32_e32 v123, 0
	v_mov_b32_e32 v124, 0
	v_mov_b32_e32 v125, 0
	v_mov_b32_e32 v126, 0
	v_mov_b32_e32 v127, 0
	v_mov_b32_e32 v128, 0
	v_mov_b32_e32 v129, 0
	s_waitcnt vmcnt(12)
	s_barrier
	ds_read_b128 v[146:149], v136 offset:0
	ds_read_b128 v[152:155], v136 offset:1024
	ds_read_b128 v[156:159], v136 offset:2048
	ds_read_b128 v[162:165], v136 offset:3072
	ds_read_b128 v[166:169], v136 offset:4096
	ds_read_b128 v[170:173], v136 offset:5120
	ds_read_b128 v[176:179], v136 offset:6144
	ds_read_b128 v[180:183], v136 offset:7168
	ds_read_b128 v[184:187], v137 offset:16384
	ds_read_b128 v[188:191], v137 offset:17408
	ds_read_b128 v[192:195], v137 offset:18432
	ds_read_b128 v[196:199], v137 offset:19456
	s_movk_i32 s40, 0x6000
	s_mov_b32 s41, 0
	s_movk_i32 s39, 42
	.p2align 6
.Lt11_loop:
	.p2align 3
	s_waitcnt vmcnt(6) lgkmcnt(0)
	s_barrier
	s_setprio 1
	v_add_u32_e32 v144, s40, v136
	v_mfma_f32_16x16x32_bf16 v[126:129], v[184:187], v[146:149], v[126:129]
	ds_read_b128 v[200:203], v144 offset:0
	v_mfma_f32_16x16x32_bf16 v[122:125], v[184:187], v[152:155], v[122:125]
	ds_read_b128 v[204:207], v144 offset:1024
	v_mfma_f32_16x16x32_bf16 v[118:121], v[184:187], v[156:159], v[118:121]
	ds_read_b128 v[208:211], v144 offset:2048
	v_mfma_f32_16x16x32_bf16 v[114:117], v[184:187], v[162:165], v[114:117]
	ds_read_b128 v[212:215], v144 offset:3072
	v_mfma_f32_16x16x32_bf16 v[110:113], v[184:187], v[166:169], v[110:113]
	ds_read_b128 v[216:219], v144 offset:4096
	v_mfma_f32_16x16x32_bf16 v[106:109], v[184:187], v[170:173], v[106:109]
	ds_read_b128 v[220:223], v144 offset:5120
	v_mfma_f32_16x16x32_bf16 v[102:105], v[184:187], v[176:179], v[102:105]
	ds_read_b128 v[224:227], v144 offset:6144
	v_mfma_f32_16x16x32_bf16 v[98:101], v[184:187], v[180:183], v[98:101]
	ds_read_b128 v[228:231], v144 offset:7168
	v_mfma_f32_16x16x32_bf16 v[94:97], v[188:191], v[146:149], v[94:97]
	v_add_u32_e64 v144, s40, v137
	v_mfma_f32_16x16x32_bf16 v[90:93], v[188:191], v[152:155], v[90:93]
	v_mfma_f32_16x16x32_bf16 v[86:89], v[188:191], v[156:159], v[86:89]
	ds_read_b128 v[232:235], v144 offset:16384
	v_mfma_f32_16x16x32_bf16 v[82:85], v[188:191], v[162:165], v[82:85]
	ds_read_b128 v[236:239], v144 offset:17408
	v_mfma_f32_16x16x32_bf16 v[78:81], v[188:191], v[166:169], v[78:81]
	ds_read_b128 v[240:243], v144 offset:18432
	v_mfma_f32_16x16x32_bf16 v[74:77], v[188:191], v[170:173], v[74:77]
	ds_read_b128 v[244:247], v144 offset:19456
	v_mfma_f32_16x16x32_bf16 v[70:73], v[188:191], v[176:179], v[70:73]
	s_add_i32 s42, s46, s41
	s_mov_b32 m0, s42
	v_lshl_add_u64 v[142:143], v[132:133], 0, s[2:3]
	v_mfma_f32_16x16x32_bf16 v[66:69], v[188:191], v[180:183], v[66:69]
	global_load_lds_dwordx4 v[132:133], off
	s_add_i32 m0, m0, 0x1000
	v_mfma_f32_16x16x32_bf16 v[62:65], v[192:195], v[146:149], v[62:65]
	v_mfma_f32_16x16x32_bf16 v[58:61], v[192:195], v[152:155], v[58:61]
	v_mfma_f32_16x16x32_bf16 v[54:57], v[192:195], v[156:159], v[54:57]
	global_load_lds_dwordx4 v[142:143], off
	v_lshl_add_u64 v[142:143], v[142:143], 0, s[2:3]
	s_add_i32 m0, m0, 0x1000
	v_mfma_f32_16x16x32_bf16 v[50:53], v[192:195], v[162:165], v[50:53]
	v_mfma_f32_16x16x32_bf16 v[46:49], v[192:195], v[166:169], v[46:49]
	v_mfma_f32_16x16x32_bf16 v[42:45], v[192:195], v[170:173], v[42:45]
	global_load_lds_dwordx4 v[142:143], off
	v_lshl_add_u64 v[142:143], v[142:143], 0, s[2:3]
	s_add_i32 m0, m0, 0x1000
	v_mfma_f32_16x16x32_bf16 v[38:41], v[192:195], v[176:179], v[38:41]
	v_mfma_f32_16x16x32_bf16 v[34:37], v[192:195], v[180:183], v[34:37]
	v_mfma_f32_16x16x32_bf16 v[30:33], v[196:199], v[146:149], v[30:33]
	global_load_lds_dwordx4 v[142:143], off
	s_add_i32 m0, m0, 0x1000
	v_lshl_add_u64 v[142:143], v[134:135], 0, s[2:3]
	v_mfma_f32_16x16x32_bf16 v[26:29], v[196:199], v[152:155], v[26:29]
	v_mfma_f32_16x16x32_bf16 v[22:25], v[196:199], v[156:159], v[22:25]
	v_mfma_f32_16x16x32_bf16 v[18:21], v[196:199], v[162:165], v[18:21]
	global_load_lds_dwordx4 v[134:135], off
	s_add_i32 m0, m0, 0x1000
	v_lshl_add_u64 v[132:133], v[132:133], 0, s[12:13]
	v_mfma_f32_16x16x32_bf16 v[14:17], v[196:199], v[166:169], v[14:17]
	v_mfma_f32_16x16x32_bf16 v[10:13], v[196:199], v[170:173], v[10:13]
	v_mfma_f32_16x16x32_bf16 v[6:9], v[196:199], v[176:179], v[6:9]
	global_load_lds_dwordx4 v[142:143], off
	v_lshl_add_u64 v[134:135], v[134:135], 0, s[4:5]
	v_mfma_f32_16x16x32_bf16 v[2:5], v[196:199], v[180:183], v[2:5]
	s_setprio 0
	s_mov_b32 s41, s40
	s_add_i32 s40, s40, 0x6000
	s_cmp_eq_u32 s40, 0x12000
	s_cselect_b32 s40, 0, s40
	s_nop 0
	.p2align 3
	s_waitcnt vmcnt(6) lgkmcnt(0)
	s_barrier
;     ...
;   for (int kt = 0; kt < nk; kt++) {
;     if (kt + 1 < nk) asm volatile("s_waitcnt vmcnt(6)" ::: "memory");
;     else asm volatile("s_waitcnt vmcnt(0)" ::: "memory");
;     __builtin_amdgcn_s_barrier();
;     asm volatile("" ::: "memory");
;     if (kt + 2 < nk) G2_STAGE(kt + 2);
;     const char* cS = smem + (kt % 3) * 24576;
;     bf16x8 xa[8], wb[4];
; #pragma unroll
;     for (int f = 0; f < 8; f++) xa[f] = *(const bf16x8*)(cS + aoff + f * 1024);
; #pragma unroll
;     for (int f = 0; f < 4; f++) wb[f] = *(const bf16x8*)(cS + boff + f * 1024);
; #pragma unroll
;     for (int nf = 0; nf < 4; nf++)
; #pragma unroll
;       for (int mf = 0; mf < 8; mf++)
;         acc[nf][mf] = __builtin_amdgcn_mfma_f32_16x16x32_bf16(wb[nf], xa[mf], acc[nf][mf], 0, 0, 0);
;   }
	s_setprio 1
	v_add_u32_e32 v144, s40, v136
	v_mfma_f32_16x16x32_bf16 v[126:129], v[232:235], v[200:203], v[126:129]
	ds_read_b128 v[146:149], v144 offset:0
	v_mfma_f32_16x16x32_bf16 v[122:125], v[232:235], v[204:207], v[122:125]
	ds_read_b128 v[152:155], v144 offset:1024
	v_mfma_f32_16x16x32_bf16 v[118:121], v[232:235], v[208:211], v[118:121]
	ds_read_b128 v[156:159], v144 offset:2048
	v_mfma_f32_16x16x32_bf16 v[114:117], v[232:235], v[212:215], v[114:117]
	ds_read_b128 v[162:165], v144 offset:3072
	v_mfma_f32_16x16x32_bf16 v[110:113], v[232:235], v[216:219], v[110:113]
	ds_read_b128 v[166:169], v144 offset:4096
	v_mfma_f32_16x16x32_bf16 v[106:109], v[232:235], v[220:223], v[106:109]
	ds_read_b128 v[170:173], v144 offset:5120
	v_mfma_f32_16x16x32_bf16 v[102:105], v[232:235], v[224:227], v[102:105]
	ds_read_b128 v[176:179], v144 offset:6144
	v_mfma_f32_16x16x32_bf16 v[98:101], v[232:235], v[228:231], v[98:101]
	ds_read_b128 v[180:183], v144 offset:7168
	v_mfma_f32_16x16x32_bf16 v[94:97], v[236:239], v[200:203], v[94:97]
	v_add_u32_e64 v144, s40, v137
	v_mfma_f32_16x16x32_bf16 v[90:93], v[236:239], v[204:207], v[90:93]
	v_mfma_f32_16x16x32_bf16 v[86:89], v[236:239], v[208:211], v[86:89]
	ds_read_b128 v[184:187], v144 offset:16384
	v_mfma_f32_16x16x32_bf16 v[82:85], v[236:239], v[212:215], v[82:85]
	ds_read_b128 v[188:191], v144 offset:17408
	v_mfma_f32_16x16x32_bf16 v[78:81], v[236:239], v[216:219], v[78:81]
	ds_read_b128 v[192:195], v144 offset:18432
	v_mfma_f32_16x16x32_bf16 v[74:77], v[236:239], v[220:223], v[74:77]
	ds_read_b128 v[196:199], v144 offset:19456
	v_mfma_f32_16x16x32_bf16 v[70:73], v[236:239], v[224:227], v[70:73]
	s_add_i32 s42, s46, s41
	s_mov_b32 m0, s42
	v_lshl_add_u64 v[142:143], v[132:133], 0, s[2:3]
	v_mfma_f32_16x16x32_bf16 v[66:69], v[236:239], v[228:231], v[66:69]
	global_load_lds_dwordx4 v[132:133], off
	s_add_i32 m0, m0, 0x1000
	v_mfma_f32_16x16x32_bf16 v[62:65], v[240:243], v[200:203], v[62:65]
	v_mfma_f32_16x16x32_bf16 v[58:61], v[240:243], v[204:207], v[58:61]
	v_mfma_f32_16x16x32_bf16 v[54:57], v[240:243], v[208:211], v[54:57]
	global_load_lds_dwordx4 v[142:143], off
	v_lshl_add_u64 v[142:143], v[142:143], 0, s[2:3]
	s_add_i32 m0, m0, 0x1000
	v_mfma_f32_16x16x32_bf16 v[50:53], v[240:243], v[212:215], v[50:53]
	v_mfma_f32_16x16x32_bf16 v[46:49], v[240:243], v[216:219], v[46:49]
	v_mfma_f32_16x16x32_bf16 v[42:45], v[240:243], v[220:223], v[42:45]
	global_load_lds_dwordx4 v[142:143], off
	v_lshl_add_u64 v[142:143], v[142:143], 0, s[2:3]
	s_add_i32 m0, m0, 0x1000
	v_mfma_f32_16x16x32_bf16 v[38:41], v[240:243], v[224:227], v[38:41]
	v_mfma_f32_16x16x32_bf16 v[34:37], v[240:243], v[228:231], v[34:37]
	v_mfma_f32_16x16x32_bf16 v[30:33], v[244:247], v[200:203], v[30:33]
	global_load_lds_dwordx4 v[142:143], off
	s_add_i32 m0, m0, 0x1000
	v_lshl_add_u64 v[142:143], v[134:135], 0, s[2:3]
	v_mfma_f32_16x16x32_bf16 v[26:29], v[244:247], v[204:207], v[26:29]
	v_mfma_f32_16x16x32_bf16 v[22:25], v[244:247], v[208:211], v[22:25]
	v_mfma_f32_16x16x32_bf16 v[18:21], v[244:247], v[212:215], v[18:21]
	global_load_lds_dwordx4 v[134:135], off
	s_add_i32 m0, m0, 0x1000
	v_lshl_add_u64 v[132:133], v[132:133], 0, s[12:13]
	v_mfma_f32_16x16x32_bf16 v[14:17], v[244:247], v[216:219], v[14:17]
	v_mfma_f32_16x16x32_bf16 v[10:13], v[244:247], v[220:223], v[10:13]
	v_mfma_f32_16x16x32_bf16 v[6:9], v[244:247], v[224:227], v[6:9]
	global_load_lds_dwordx4 v[142:143], off
	v_lshl_add_u64 v[134:135], v[134:135], 0, s[4:5]
	v_mfma_f32_16x16x32_bf16 v[2:5], v[244:247], v[228:231], v[2:5]
	s_setprio 0
	s_mov_b32 s41, s40
	s_add_i32 s40, s40, 0x6000
	s_cmp_eq_u32 s40, 0x12000
	s_cselect_b32 s40, 0, s40
	s_nop 0
	s_sub_i32 s39, s39, 1
	s_cmp_lg_u32 s39, 0
	s_cbranch_scc1 .Lt11_loop
	.p2align 3
	s_waitcnt vmcnt(6) lgkmcnt(0)
	s_barrier
	s_setprio 1
	v_add_u32_e32 v144, s40, v136
	v_mfma_f32_16x16x32_bf16 v[126:129], v[184:187], v[146:149], v[126:129]
	ds_read_b128 v[200:203], v144 offset:0
	v_mfma_f32_16x16x32_bf16 v[122:125], v[184:187], v[152:155], v[122:125]
	ds_read_b128 v[204:207], v144 offset:1024
	v_mfma_f32_16x16x32_bf16 v[118:121], v[184:187], v[156:159], v[118:121]
	ds_read_b128 v[208:211], v144 offset:2048
	v_mfma_f32_16x16x32_bf16 v[114:117], v[184:187], v[162:165], v[114:117]
	ds_read_b128 v[212:215], v144 offset:3072
	v_mfma_f32_16x16x32_bf16 v[110:113], v[184:187], v[166:169], v[110:113]
	ds_read_b128 v[216:219], v144 offset:4096
	v_mfma_f32_16x16x32_bf16 v[106:109], v[184:187], v[170:173], v[106:109]
	ds_read_b128 v[220:223], v144 offset:5120
	v_mfma_f32_16x16x32_bf16 v[102:105], v[184:187], v[176:179], v[102:105]
	ds_read_b128 v[224:227], v144 offset:6144
	v_mfma_f32_16x16x32_bf16 v[98:101], v[184:187], v[180:183], v[98:101]
	ds_read_b128 v[228:231], v144 offset:7168
	v_mfma_f32_16x16x32_bf16 v[94:97], v[188:191], v[146:149], v[94:97]
	v_add_u32_e64 v144, s40, v137
	v_mfma_f32_16x16x32_bf16 v[90:93], v[188:191], v[152:155], v[90:93]
	v_mfma_f32_16x16x32_bf16 v[86:89], v[188:191], v[156:159], v[86:89]
	ds_read_b128 v[232:235], v144 offset:16384
	v_mfma_f32_16x16x32_bf16 v[82:85], v[188:191], v[162:165], v[82:85]
	ds_read_b128 v[236:239], v144 offset:17408
	v_mfma_f32_16x16x32_bf16 v[78:81], v[188:191], v[166:169], v[78:81]
	ds_read_b128 v[240:243], v144 offset:18432
	v_mfma_f32_16x16x32_bf16 v[74:77], v[188:191], v[170:173], v[74:77]
	ds_read_b128 v[244:247], v144 offset:19456
	v_mfma_f32_16x16x32_bf16 v[70:73], v[188:191], v[176:179], v[70:73]
	s_add_i32 s42, s46, s41
	s_mov_b32 m0, s42
	v_lshl_add_u64 v[142:143], v[132:133], 0, s[2:3]
	v_mfma_f32_16x16x32_bf16 v[66:69], v[188:191], v[180:183], v[66:69]
	global_load_lds_dwordx4 v[132:133], off
;     ...
;   for (int kt = 0; kt < nk; kt++) {
;     if (kt + 1 < nk) asm volatile("s_waitcnt vmcnt(6)" ::: "memory");
;     else asm volatile("s_waitcnt vmcnt(0)" ::: "memory");
;     __builtin_amdgcn_s_barrier();
;     asm volatile("" ::: "memory");
;     if (kt + 2 < nk) G2_STAGE(kt + 2);
;     const char* cS = smem + (kt % 3) * 24576;
;     bf16x8 xa[8], wb[4];
; #pragma unroll
;     for (int f = 0; f < 8; f++) xa[f] = *(const bf16x8*)(cS + aoff + f * 1024);
; #pragma unroll
;     for (int f = 0; f < 4; f++) wb[f] = *(const bf16x8*)(cS + boff + f * 1024);
; #pragma unroll
;     for (int nf = 0; nf < 4; nf++)
; #pragma unroll
;       for (int mf = 0; mf < 8; mf++)
;         acc[nf][mf] = __builtin_amdgcn_mfma_f32_16x16x32_bf16(wb[nf], xa[mf], acc[nf][mf], 0, 0, 0);
;   }
	s_add_i32 m0, m0, 0x1000
	v_mfma_f32_16x16x32_bf16 v[62:65], v[192:195], v[146:149], v[62:65]
	v_mfma_f32_16x16x32_bf16 v[58:61], v[192:195], v[152:155], v[58:61]
	v_mfma_f32_16x16x32_bf16 v[54:57], v[192:195], v[156:159], v[54:57]
	global_load_lds_dwordx4 v[142:143], off
	v_lshl_add_u64 v[142:143], v[142:143], 0, s[2:3]
	s_add_i32 m0, m0, 0x1000
	v_mfma_f32_16x16x32_bf16 v[50:53], v[192:195], v[162:165], v[50:53]
	v_mfma_f32_16x16x32_bf16 v[46:49], v[192:195], v[166:169], v[46:49]
	v_mfma_f32_16x16x32_bf16 v[42:45], v[192:195], v[170:173], v[42:45]
	global_load_lds_dwordx4 v[142:143], off
	v_lshl_add_u64 v[142:143], v[142:143], 0, s[2:3]
	s_add_i32 m0, m0, 0x1000
	v_mfma_f32_16x16x32_bf16 v[38:41], v[192:195], v[176:179], v[38:41]
	v_mfma_f32_16x16x32_bf16 v[34:37], v[192:195], v[180:183], v[34:37]
	v_mfma_f32_16x16x32_bf16 v[30:33], v[196:199], v[146:149], v[30:33]
	global_load_lds_dwordx4 v[142:143], off
	s_add_i32 m0, m0, 0x1000
	v_lshl_add_u64 v[142:143], v[134:135], 0, s[2:3]
	v_mfma_f32_16x16x32_bf16 v[26:29], v[196:199], v[152:155], v[26:29]
	v_mfma_f32_16x16x32_bf16 v[22:25], v[196:199], v[156:159], v[22:25]
	v_mfma_f32_16x16x32_bf16 v[18:21], v[196:199], v[162:165], v[18:21]
	global_load_lds_dwordx4 v[134:135], off
	s_add_i32 m0, m0, 0x1000
	v_lshl_add_u64 v[132:133], v[132:133], 0, s[12:13]
	v_mfma_f32_16x16x32_bf16 v[14:17], v[196:199], v[166:169], v[14:17]
	v_mfma_f32_16x16x32_bf16 v[10:13], v[196:199], v[170:173], v[10:13]
	v_mfma_f32_16x16x32_bf16 v[6:9], v[196:199], v[176:179], v[6:9]
	global_load_lds_dwordx4 v[142:143], off
	v_lshl_add_u64 v[134:135], v[134:135], 0, s[4:5]
	v_mfma_f32_16x16x32_bf16 v[2:5], v[196:199], v[180:183], v[2:5]
	s_setprio 0
	s_mov_b32 s41, s40
	s_add_i32 s40, s40, 0x6000
	s_cmp_eq_u32 s40, 0x12000
	s_cselect_b32 s40, 0, s40
	s_nop 0
	.p2align 3
	s_waitcnt vmcnt(6) lgkmcnt(0)
	s_barrier
	s_setprio 1
	v_add_u32_e32 v144, s40, v136
	v_mfma_f32_16x16x32_bf16 v[126:129], v[232:235], v[200:203], v[126:129]
	ds_read_b128 v[146:149], v144 offset:0
	v_mfma_f32_16x16x32_bf16 v[122:125], v[232:235], v[204:207], v[122:125]
	ds_read_b128 v[152:155], v144 offset:1024
	v_mfma_f32_16x16x32_bf16 v[118:121], v[232:235], v[208:211], v[118:121]
	ds_read_b128 v[156:159], v144 offset:2048
	v_mfma_f32_16x16x32_bf16 v[114:117], v[232:235], v[212:215], v[114:117]
	ds_read_b128 v[162:165], v144 offset:3072
	v_mfma_f32_16x16x32_bf16 v[110:113], v[232:235], v[216:219], v[110:113]
	ds_read_b128 v[166:169], v144 offset:4096
	v_mfma_f32_16x16x32_bf16 v[106:109], v[232:235], v[220:223], v[106:109]
	ds_read_b128 v[170:173], v144 offset:5120
	v_mfma_f32_16x16x32_bf16 v[102:105], v[232:235], v[224:227], v[102:105]
	ds_read_b128 v[176:179], v144 offset:6144
	v_mfma_f32_16x16x32_bf16 v[98:101], v[232:235], v[228:231], v[98:101]
	ds_read_b128 v[180:183], v144 offset:7168
	v_mfma_f32_16x16x32_bf16 v[94:97], v[236:239], v[200:203], v[94:97]
	v_add_u32_e64 v144, s40, v137
	v_mfma_f32_16x16x32_bf16 v[90:93], v[236:239], v[204:207], v[90:93]
	v_mfma_f32_16x16x32_bf16 v[86:89], v[236:239], v[208:211], v[86:89]
	ds_read_b128 v[184:187], v144 offset:16384
	v_mfma_f32_16x16x32_bf16 v[82:85], v[236:239], v[212:215], v[82:85]
	ds_read_b128 v[188:191], v144 offset:17408
	v_mfma_f32_16x16x32_bf16 v[78:81], v[236:239], v[216:219], v[78:81]
	ds_read_b128 v[192:195], v144 offset:18432
	v_mfma_f32_16x16x32_bf16 v[74:77], v[236:239], v[220:223], v[74:77]
	ds_read_b128 v[196:199], v144 offset:19456
	v_mfma_f32_16x16x32_bf16 v[70:73], v[236:239], v[224:227], v[70:73]
	v_mfma_f32_16x16x32_bf16 v[66:69], v[236:239], v[228:231], v[66:69]
	v_mfma_f32_16x16x32_bf16 v[62:65], v[240:243], v[200:203], v[62:65]
	v_mfma_f32_16x16x32_bf16 v[58:61], v[240:243], v[204:207], v[58:61]
	v_mfma_f32_16x16x32_bf16 v[54:57], v[240:243], v[208:211], v[54:57]
	v_mfma_f32_16x16x32_bf16 v[50:53], v[240:243], v[212:215], v[50:53]
	v_mfma_f32_16x16x32_bf16 v[46:49], v[240:243], v[216:219], v[46:49]
	v_mfma_f32_16x16x32_bf16 v[42:45], v[240:243], v[220:223], v[42:45]
	v_mfma_f32_16x16x32_bf16 v[38:41], v[240:243], v[224:227], v[38:41]
	v_mfma_f32_16x16x32_bf16 v[34:37], v[240:243], v[228:231], v[34:37]
	v_mfma_f32_16x16x32_bf16 v[30:33], v[244:247], v[200:203], v[30:33]
	v_mfma_f32_16x16x32_bf16 v[26:29], v[244:247], v[204:207], v[26:29]
	v_mfma_f32_16x16x32_bf16 v[22:25], v[244:247], v[208:211], v[22:25]
	v_mfma_f32_16x16x32_bf16 v[18:21], v[244:247], v[212:215], v[18:21]
	v_mfma_f32_16x16x32_bf16 v[14:17], v[244:247], v[216:219], v[14:17]
	v_mfma_f32_16x16x32_bf16 v[10:13], v[244:247], v[220:223], v[10:13]
	v_mfma_f32_16x16x32_bf16 v[6:9], v[244:247], v[224:227], v[6:9]
	v_mfma_f32_16x16x32_bf16 v[2:5], v[244:247], v[228:231], v[2:5]
	s_setprio 0
	s_mov_b32 s41, s40
	s_add_i32 s40, s40, 0x6000
	s_cmp_eq_u32 s40, 0x12000
	s_cselect_b32 s40, 0, s40
	s_nop 0
	.p2align 3
	s_waitcnt vmcnt(0) lgkmcnt(0)
	s_barrier
; DEVI float blo(unsigned u) { return __uint_as_float(u << 16); }
; DEVI float bhi(unsigned u) { return __uint_as_float(u & 0xffff0000u); }
;     ...
;     for (int f = 0; f < 8; f++) xa[f] = *(const bf16x8*)(cS + aoff + f * 1024);
; #pragma unroll
;     for (int f = 0; f < 4; f++) wb[f] = *(const bf16x8*)(cS + boff + f * 1024);
; #pragma unroll
;     for (int nf = 0; nf < 4; nf++)
; #pragma unroll
;       for (int mf = 0; mf < 8; mf++)
;         acc[nf][mf] = __builtin_amdgcn_mfma_f32_16x16x32_bf16(wb[nf], xa[mf], acc[nf][mf], 0, 0, 0);
;     ...
;         if (EPI == EPI_RESID || EPI == EPI_RESID_ATOMIC) {
;           f32x4 x = a;
;           if (EPI == EPI_RESID || kpart == 0) {
;             const u32x2 xr = *(const u32x2*)((const u16*)(p.ws + WS_XB) + (size_t)row * 1024 + col);
;             x[0] += ALPHA * blo(xr[0]); x[1] += ALPHA * bhi(xr[0]); x[2] += ALPHA * blo(xr[1]); x[3] += ALPHA * bhi(xr[1]);
;           }
;           if (EPI == EPI_RESID) *(f32x4*)((float*)(p.ws + WS_XF) + (size_t)row * 1024 + col) = x;
	s_setprio 1
	v_add_u32_e32 v144, s40, v136
	v_mfma_f32_16x16x32_bf16 v[126:129], v[184:187], v[146:149], v[126:129]
	ds_read_b128 v[200:203], v144 offset:0
	v_mfma_f32_16x16x32_bf16 v[122:125], v[184:187], v[152:155], v[122:125]
	ds_read_b128 v[204:207], v144 offset:1024
	v_mfma_f32_16x16x32_bf16 v[118:121], v[184:187], v[156:159], v[118:121]
	ds_read_b128 v[208:211], v144 offset:2048
	v_mfma_f32_16x16x32_bf16 v[114:117], v[184:187], v[162:165], v[114:117]
	ds_read_b128 v[212:215], v144 offset:3072
	v_mfma_f32_16x16x32_bf16 v[110:113], v[184:187], v[166:169], v[110:113]
	ds_read_b128 v[216:219], v144 offset:4096
	v_mfma_f32_16x16x32_bf16 v[106:109], v[184:187], v[170:173], v[106:109]
	ds_read_b128 v[220:223], v144 offset:5120
	v_mfma_f32_16x16x32_bf16 v[102:105], v[184:187], v[176:179], v[102:105]
	ds_read_b128 v[224:227], v144 offset:6144
	v_mfma_f32_16x16x32_bf16 v[98:101], v[184:187], v[180:183], v[98:101]
	ds_read_b128 v[228:231], v144 offset:7168
	v_mfma_f32_16x16x32_bf16 v[94:97], v[188:191], v[146:149], v[94:97]
	v_add_u32_e64 v144, s40, v137
	v_mfma_f32_16x16x32_bf16 v[90:93], v[188:191], v[152:155], v[90:93]
	v_mfma_f32_16x16x32_bf16 v[86:89], v[188:191], v[156:159], v[86:89]
	ds_read_b128 v[232:235], v144 offset:16384
	v_mfma_f32_16x16x32_bf16 v[82:85], v[188:191], v[162:165], v[82:85]
	ds_read_b128 v[236:239], v144 offset:17408
	v_mfma_f32_16x16x32_bf16 v[78:81], v[188:191], v[166:169], v[78:81]
	ds_read_b128 v[240:243], v144 offset:18432
	v_mfma_f32_16x16x32_bf16 v[74:77], v[188:191], v[170:173], v[74:77]
	ds_read_b128 v[244:247], v144 offset:19456
	v_mfma_f32_16x16x32_bf16 v[70:73], v[188:191], v[176:179], v[70:73]
	v_mfma_f32_16x16x32_bf16 v[66:69], v[188:191], v[180:183], v[66:69]
	v_mfma_f32_16x16x32_bf16 v[62:65], v[192:195], v[146:149], v[62:65]
	v_mfma_f32_16x16x32_bf16 v[58:61], v[192:195], v[152:155], v[58:61]
	v_mfma_f32_16x16x32_bf16 v[54:57], v[192:195], v[156:159], v[54:57]
	v_mfma_f32_16x16x32_bf16 v[50:53], v[192:195], v[162:165], v[50:53]
	v_mfma_f32_16x16x32_bf16 v[46:49], v[192:195], v[166:169], v[46:49]
	v_mfma_f32_16x16x32_bf16 v[42:45], v[192:195], v[170:173], v[42:45]
	v_mfma_f32_16x16x32_bf16 v[38:41], v[192:195], v[176:179], v[38:41]
	v_mfma_f32_16x16x32_bf16 v[34:37], v[192:195], v[180:183], v[34:37]
	v_mfma_f32_16x16x32_bf16 v[30:33], v[196:199], v[146:149], v[30:33]
	v_mfma_f32_16x16x32_bf16 v[26:29], v[196:199], v[152:155], v[26:29]
	v_mfma_f32_16x16x32_bf16 v[22:25], v[196:199], v[156:159], v[22:25]
	v_mfma_f32_16x16x32_bf16 v[18:21], v[196:199], v[162:165], v[18:21]
	v_mfma_f32_16x16x32_bf16 v[14:17], v[196:199], v[166:169], v[14:17]
	v_mfma_f32_16x16x32_bf16 v[10:13], v[196:199], v[170:173], v[10:13]
	v_mfma_f32_16x16x32_bf16 v[6:9], v[196:199], v[176:179], v[6:9]
	v_mfma_f32_16x16x32_bf16 v[2:5], v[196:199], v[180:183], v[2:5]
	s_setprio 0
	s_mov_b32 s41, s40
	s_add_i32 s40, s40, 0x6000
	s_cmp_eq_u32 s40, 0x12000
	s_cselect_b32 s40, 0, s40
	s_nop 0
	s_mov_b32 s4, 0x8000
	s_mov_b32 s5, 0
	s_mov_b32 s10, 0x10000
	s_mov_b32 s11, 0
	s_mov_b32 s44, 0x3fd744fd
	.p2align 3
	s_waitcnt lgkmcnt(0)
	s_nop 0
	v_mfma_f32_16x16x32_bf16 v[126:129], v[232:235], v[200:203], v[126:129]
	v_mfma_f32_16x16x32_bf16 v[122:125], v[232:235], v[204:207], v[122:125]
	v_mfma_f32_16x16x32_bf16 v[118:121], v[232:235], v[208:211], v[118:121]
	v_mfma_f32_16x16x32_bf16 v[114:117], v[232:235], v[212:215], v[114:117]
	v_mfma_f32_16x16x32_bf16 v[110:113], v[232:235], v[216:219], v[110:113]
	global_load_dwordx4 v[146:149], v[138:139], off offset:0
	v_mfma_f32_16x16x32_bf16 v[106:109], v[232:235], v[220:223], v[106:109]
	v_mfma_f32_16x16x32_bf16 v[102:105], v[232:235], v[224:227], v[102:105]
	global_load_dwordx4 v[152:155], v[138:139], off offset:128
	v_mfma_f32_16x16x32_bf16 v[98:101], v[232:235], v[228:231], v[98:101]
	v_lshl_add_u64 v[138:139], v[138:139], 0, s[4:5]
	v_mfma_f32_16x16x32_bf16 v[94:97], v[236:239], v[200:203], v[94:97]
	global_load_dwordx4 v[156:159], v[138:139], off offset:0
	v_mfma_f32_16x16x32_bf16 v[90:93], v[236:239], v[204:207], v[90:93]
	v_mfma_f32_16x16x32_bf16 v[86:89], v[236:239], v[208:211], v[86:89]
	global_load_dwordx4 v[162:165], v[138:139], off offset:128
	v_mfma_f32_16x16x32_bf16 v[82:85], v[236:239], v[212:215], v[82:85]
	v_lshl_add_u64 v[138:139], v[138:139], 0, s[4:5]
	v_mfma_f32_16x16x32_bf16 v[78:81], v[236:239], v[216:219], v[78:81]
	global_load_dwordx4 v[166:169], v[138:139], off offset:0
	v_mfma_f32_16x16x32_bf16 v[74:77], v[236:239], v[220:223], v[74:77]
	v_mfma_f32_16x16x32_bf16 v[70:73], v[236:239], v[224:227], v[70:73]
	global_load_dwordx4 v[170:173], v[138:139], off offset:128
	v_mfma_f32_16x16x32_bf16 v[66:69], v[236:239], v[228:231], v[66:69]
	v_lshl_add_u64 v[138:139], v[138:139], 0, s[4:5]
	v_mfma_f32_16x16x32_bf16 v[62:65], v[240:243], v[200:203], v[62:65]
	global_load_dwordx4 v[176:179], v[138:139], off offset:0
	v_mfma_f32_16x16x32_bf16 v[58:61], v[240:243], v[204:207], v[58:61]
	v_mfma_f32_16x16x32_bf16 v[54:57], v[240:243], v[208:211], v[54:57]
	global_load_dwordx4 v[180:183], v[138:139], off offset:128
	v_mfma_f32_16x16x32_bf16 v[50:53], v[240:243], v[212:215], v[50:53]
	v_lshl_add_u64 v[138:139], v[138:139], 0, s[4:5]
	v_mfma_f32_16x16x32_bf16 v[46:49], v[240:243], v[216:219], v[46:49]
	global_load_dwordx4 v[184:187], v[138:139], off offset:0
	v_mfma_f32_16x16x32_bf16 v[42:45], v[240:243], v[220:223], v[42:45]
	v_mfma_f32_16x16x32_bf16 v[38:41], v[240:243], v[224:227], v[38:41]
	global_load_dwordx4 v[188:191], v[138:139], off offset:128
	v_mfma_f32_16x16x32_bf16 v[34:37], v[240:243], v[228:231], v[34:37]
	v_lshl_add_u64 v[138:139], v[138:139], 0, s[4:5]
	v_mfma_f32_16x16x32_bf16 v[30:33], v[244:247], v[200:203], v[30:33]
	global_load_dwordx4 v[192:195], v[138:139], off offset:0
	v_mfma_f32_16x16x32_bf16 v[26:29], v[244:247], v[204:207], v[26:29]
	v_mfma_f32_16x16x32_bf16 v[22:25], v[244:247], v[208:211], v[22:25]
	global_load_dwordx4 v[196:199], v[138:139], off offset:128
	v_mfma_f32_16x16x32_bf16 v[18:21], v[244:247], v[212:215], v[18:21]
	v_lshl_add_u64 v[138:139], v[138:139], 0, s[4:5]
	v_mfma_f32_16x16x32_bf16 v[14:17], v[244:247], v[216:219], v[14:17]
	v_mfma_f32_16x16x32_bf16 v[10:13], v[244:247], v[220:223], v[10:13]
	v_mfma_f32_16x16x32_bf16 v[6:9], v[244:247], v[224:227], v[6:9]
	v_mfma_f32_16x16x32_bf16 v[2:5], v[244:247], v[228:231], v[2:5]
	s_mov_b32 m0, s43
	global_load_dwordx4 v[200:203], v[138:139], off offset:0
	global_load_dwordx4 v[204:207], v[138:139], off offset:128
	v_lshl_add_u64 v[138:139], v[138:139], 0, s[4:5]
	global_load_dwordx4 v[208:211], v[138:139], off offset:0
	global_load_dwordx4 v[212:215], v[138:139], off offset:128
	v_lshl_add_u64 v[138:139], v[138:139], 0, s[4:5]
	s_nop 7
	s_waitcnt vmcnt(15)
; DEVI float blo(unsigned u) { return __uint_as_float(u << 16); }
; DEVI float bhi(unsigned u) { return __uint_as_float(u & 0xffff0000u); }
;     ...
;         if (EPI == EPI_RESID || EPI == EPI_RESID_ATOMIC) {
;           f32x4 x = a;
;           if (EPI == EPI_RESID || kpart == 0) {
;             const u32x2 xr = *(const u32x2*)((const u16*)(p.ws + WS_XB) + (size_t)row * 1024 + col);
;             x[0] += ALPHA * blo(xr[0]); x[1] += ALPHA * bhi(xr[0]); x[2] += ALPHA * blo(xr[1]); x[3] += ALPHA * bhi(xr[1]);
;           }
;           if (EPI == EPI_RESID) *(f32x4*)((float*)(p.ws + WS_XF) + (size_t)row * 1024 + col) = x;
	v_permlane16_swap_b32_e32 v146, v148
	v_permlane16_swap_b32_e32 v147, v149
	v_lshlrev_b32_e32 v216, 16, v146
	v_and_b32_e32 v146, 0xffff0000, v146
	v_lshlrev_b32_e32 v217, 16, v147
	v_and_b32_e32 v147, 0xffff0000, v147
	v_fmac_f32_e32 v126, s44, v216
	v_fmac_f32_e32 v127, s44, v146
	v_fmac_f32_e32 v128, s44, v217
	v_fmac_f32_e32 v129, s44, v147
	global_store_dwordx4 v[140:141], v[126:129], off offset:0
	v_lshlrev_b32_e32 v216, 16, v148
	v_and_b32_e32 v148, 0xffff0000, v148
	v_lshlrev_b32_e32 v217, 16, v149
	v_and_b32_e32 v149, 0xffff0000, v149
	v_fmac_f32_e32 v94, s44, v216
	v_fmac_f32_e32 v95, s44, v148
	v_fmac_f32_e32 v96, s44, v217
	v_fmac_f32_e32 v97, s44, v149
	global_store_dwordx4 v[140:141], v[94:97], off offset:64
	s_waitcnt vmcnt(16)
	v_permlane16_swap_b32_e32 v152, v154
	v_permlane16_swap_b32_e32 v153, v155
	v_lshlrev_b32_e32 v216, 16, v152
	v_and_b32_e32 v152, 0xffff0000, v152
	v_lshlrev_b32_e32 v217, 16, v153
	v_and_b32_e32 v153, 0xffff0000, v153
	v_fmac_f32_e32 v62, s44, v216
	v_fmac_f32_e32 v63, s44, v152
	v_fmac_f32_e32 v64, s44, v217
	v_fmac_f32_e32 v65, s44, v153
	global_store_dwordx4 v[140:141], v[62:65], off offset:128
	v_lshlrev_b32_e32 v216, 16, v154
	v_and_b32_e32 v154, 0xffff0000, v154
	v_lshlrev_b32_e32 v217, 16, v155
	v_and_b32_e32 v155, 0xffff0000, v155
	v_fmac_f32_e32 v30, s44, v216
	v_fmac_f32_e32 v31, s44, v154
	v_fmac_f32_e32 v32, s44, v217
	v_fmac_f32_e32 v33, s44, v155
	global_store_dwordx4 v[140:141], v[30:33], off offset:192
	v_lshl_add_u64 v[140:141], v[140:141], 0, s[10:11]
	s_waitcnt vmcnt(17)
	v_permlane16_swap_b32_e32 v156, v158
	v_permlane16_swap_b32_e32 v157, v159
	v_lshlrev_b32_e32 v216, 16, v156
	v_and_b32_e32 v156, 0xffff0000, v156
	v_lshlrev_b32_e32 v217, 16, v157
	v_and_b32_e32 v157, 0xffff0000, v157
	v_fmac_f32_e32 v122, s44, v216
	v_fmac_f32_e32 v123, s44, v156
	v_fmac_f32_e32 v124, s44, v217
	v_fmac_f32_e32 v125, s44, v157
	global_store_dwordx4 v[140:141], v[122:125], off offset:0
	v_lshlrev_b32_e32 v216, 16, v158
	v_and_b32_e32 v158, 0xffff0000, v158
	v_lshlrev_b32_e32 v217, 16, v159
	v_and_b32_e32 v159, 0xffff0000, v159
	v_fmac_f32_e32 v90, s44, v216
	v_fmac_f32_e32 v91, s44, v158
	v_fmac_f32_e32 v92, s44, v217
	v_fmac_f32_e32 v93, s44, v159
	global_store_dwordx4 v[140:141], v[90:93], off offset:64
	s_waitcnt vmcnt(18)
	v_permlane16_swap_b32_e32 v162, v164
	v_permlane16_swap_b32_e32 v163, v165
	v_lshlrev_b32_e32 v216, 16, v162
	v_and_b32_e32 v162, 0xffff0000, v162
	v_lshlrev_b32_e32 v217, 16, v163
	v_and_b32_e32 v163, 0xffff0000, v163
	v_fmac_f32_e32 v58, s44, v216
	v_fmac_f32_e32 v59, s44, v162
	v_fmac_f32_e32 v60, s44, v217
	v_fmac_f32_e32 v61, s44, v163
	global_store_dwordx4 v[140:141], v[58:61], off offset:128
	v_lshlrev_b32_e32 v216, 16, v164
	v_and_b32_e32 v164, 0xffff0000, v164
	v_lshlrev_b32_e32 v217, 16, v165
	v_and_b32_e32 v165, 0xffff0000, v165
	v_fmac_f32_e32 v26, s44, v216
	v_fmac_f32_e32 v27, s44, v164
	v_fmac_f32_e32 v28, s44, v217
	v_fmac_f32_e32 v29, s44, v165
	global_store_dwordx4 v[140:141], v[26:29], off offset:192
	v_lshl_add_u64 v[140:141], v[140:141], 0, s[10:11]
	s_waitcnt vmcnt(19)
	v_permlane16_swap_b32_e32 v166, v168
	v_permlane16_swap_b32_e32 v167, v169
	v_lshlrev_b32_e32 v216, 16, v166
	v_and_b32_e32 v166, 0xffff0000, v166
	v_lshlrev_b32_e32 v217, 16, v167
	v_and_b32_e32 v167, 0xffff0000, v167
	v_fmac_f32_e32 v118, s44, v216
	v_fmac_f32_e32 v119, s44, v166
	v_fmac_f32_e32 v120, s44, v217
	v_fmac_f32_e32 v121, s44, v167
	global_store_dwordx4 v[140:141], v[118:121], off offset:0
	v_lshlrev_b32_e32 v216, 16, v168
	v_and_b32_e32 v168, 0xffff0000, v168
	v_lshlrev_b32_e32 v217, 16, v169
	v_and_b32_e32 v169, 0xffff0000, v169
	v_fmac_f32_e32 v86, s44, v216
	v_fmac_f32_e32 v87, s44, v168
	v_fmac_f32_e32 v88, s44, v217
	v_fmac_f32_e32 v89, s44, v169
	global_store_dwordx4 v[140:141], v[86:89], off offset:64
	s_waitcnt vmcnt(20)
	v_permlane16_swap_b32_e32 v170, v172
	v_permlane16_swap_b32_e32 v171, v173
	v_lshlrev_b32_e32 v216, 16, v170
	v_and_b32_e32 v170, 0xffff0000, v170
	v_lshlrev_b32_e32 v217, 16, v171
	v_and_b32_e32 v171, 0xffff0000, v171
	v_fmac_f32_e32 v54, s44, v216
	v_fmac_f32_e32 v55, s44, v170
	v_fmac_f32_e32 v56, s44, v217
	v_fmac_f32_e32 v57, s44, v171
	global_store_dwordx4 v[140:141], v[54:57], off offset:128
	v_lshlrev_b32_e32 v216, 16, v172
	v_and_b32_e32 v172, 0xffff0000, v172
	v_lshlrev_b32_e32 v217, 16, v173
	v_and_b32_e32 v173, 0xffff0000, v173
	v_fmac_f32_e32 v22, s44, v216
	v_fmac_f32_e32 v23, s44, v172
	v_fmac_f32_e32 v24, s44, v217
	v_fmac_f32_e32 v25, s44, v173
	global_store_dwordx4 v[140:141], v[22:25], off offset:192
	v_lshl_add_u64 v[140:141], v[140:141], 0, s[10:11]
	s_waitcnt vmcnt(21)
	v_permlane16_swap_b32_e32 v176, v178
	v_permlane16_swap_b32_e32 v177, v179
	v_lshlrev_b32_e32 v216, 16, v176
	v_and_b32_e32 v176, 0xffff0000, v176
	v_lshlrev_b32_e32 v217, 16, v177
	v_and_b32_e32 v177, 0xffff0000, v177
	v_fmac_f32_e32 v114, s44, v216
	v_fmac_f32_e32 v115, s44, v176
	v_fmac_f32_e32 v116, s44, v217
	v_fmac_f32_e32 v117, s44, v177
	global_store_dwordx4 v[140:141], v[114:117], off offset:0
	v_lshlrev_b32_e32 v216, 16, v178
	v_and_b32_e32 v178, 0xffff0000, v178
	v_lshlrev_b32_e32 v217, 16, v179
	v_and_b32_e32 v179, 0xffff0000, v179
	v_fmac_f32_e32 v82, s44, v216
	v_fmac_f32_e32 v83, s44, v178
	v_fmac_f32_e32 v84, s44, v217
	v_fmac_f32_e32 v85, s44, v179
	global_store_dwordx4 v[140:141], v[82:85], off offset:64
	s_waitcnt vmcnt(22)
; DEVI float blo(unsigned u) { return __uint_as_float(u << 16); }
; DEVI float bhi(unsigned u) { return __uint_as_float(u & 0xffff0000u); }
;     ...
;         if (EPI == EPI_RESID || EPI == EPI_RESID_ATOMIC) {
;           f32x4 x = a;
;           if (EPI == EPI_RESID || kpart == 0) {
;             const u32x2 xr = *(const u32x2*)((const u16*)(p.ws + WS_XB) + (size_t)row * 1024 + col);
;             x[0] += ALPHA * blo(xr[0]); x[1] += ALPHA * bhi(xr[0]); x[2] += ALPHA * blo(xr[1]); x[3] += ALPHA * bhi(xr[1]);
;           }
;           if (EPI == EPI_RESID) *(f32x4*)((float*)(p.ws + WS_XF) + (size_t)row * 1024 + col) = x;
	v_permlane16_swap_b32_e32 v180, v182
	v_permlane16_swap_b32_e32 v181, v183
	v_lshlrev_b32_e32 v216, 16, v180
	v_and_b32_e32 v180, 0xffff0000, v180
	v_lshlrev_b32_e32 v217, 16, v181
	v_and_b32_e32 v181, 0xffff0000, v181
	v_fmac_f32_e32 v50, s44, v216
	v_fmac_f32_e32 v51, s44, v180
	v_fmac_f32_e32 v52, s44, v217
	v_fmac_f32_e32 v53, s44, v181
	global_store_dwordx4 v[140:141], v[50:53], off offset:128
	v_lshlrev_b32_e32 v216, 16, v182
	v_and_b32_e32 v182, 0xffff0000, v182
	v_lshlrev_b32_e32 v217, 16, v183
	v_and_b32_e32 v183, 0xffff0000, v183
	v_fmac_f32_e32 v18, s44, v216
	v_fmac_f32_e32 v19, s44, v182
	v_fmac_f32_e32 v20, s44, v217
	v_fmac_f32_e32 v21, s44, v183
	global_store_dwordx4 v[140:141], v[18:21], off offset:192
	v_lshl_add_u64 v[140:141], v[140:141], 0, s[10:11]
	s_waitcnt vmcnt(23)
	v_permlane16_swap_b32_e32 v184, v186
	v_permlane16_swap_b32_e32 v185, v187
	v_lshlrev_b32_e32 v216, 16, v184
	v_and_b32_e32 v184, 0xffff0000, v184
	v_lshlrev_b32_e32 v217, 16, v185
	v_and_b32_e32 v185, 0xffff0000, v185
	v_fmac_f32_e32 v110, s44, v216
	v_fmac_f32_e32 v111, s44, v184
	v_fmac_f32_e32 v112, s44, v217
	v_fmac_f32_e32 v113, s44, v185
	global_store_dwordx4 v[140:141], v[110:113], off offset:0
	v_lshlrev_b32_e32 v216, 16, v186
	v_and_b32_e32 v186, 0xffff0000, v186
	v_lshlrev_b32_e32 v217, 16, v187
	v_and_b32_e32 v187, 0xffff0000, v187
	v_fmac_f32_e32 v78, s44, v216
	v_fmac_f32_e32 v79, s44, v186
	v_fmac_f32_e32 v80, s44, v217
	v_fmac_f32_e32 v81, s44, v187
	global_store_dwordx4 v[140:141], v[78:81], off offset:64
	s_waitcnt vmcnt(24)
	v_permlane16_swap_b32_e32 v188, v190
	v_permlane16_swap_b32_e32 v189, v191
	v_lshlrev_b32_e32 v216, 16, v188
	v_and_b32_e32 v188, 0xffff0000, v188
	v_lshlrev_b32_e32 v217, 16, v189
	v_and_b32_e32 v189, 0xffff0000, v189
	v_fmac_f32_e32 v46, s44, v216
	v_fmac_f32_e32 v47, s44, v188
	v_fmac_f32_e32 v48, s44, v217
	v_fmac_f32_e32 v49, s44, v189
	global_store_dwordx4 v[140:141], v[46:49], off offset:128
	v_lshlrev_b32_e32 v216, 16, v190
	v_and_b32_e32 v190, 0xffff0000, v190
	v_lshlrev_b32_e32 v217, 16, v191
	v_and_b32_e32 v191, 0xffff0000, v191
	v_fmac_f32_e32 v14, s44, v216
	v_fmac_f32_e32 v15, s44, v190
	v_fmac_f32_e32 v16, s44, v217
	v_fmac_f32_e32 v17, s44, v191
	global_store_dwordx4 v[140:141], v[14:17], off offset:192
	v_lshl_add_u64 v[140:141], v[140:141], 0, s[10:11]
	s_waitcnt vmcnt(25)
	v_permlane16_swap_b32_e32 v192, v194
	v_permlane16_swap_b32_e32 v193, v195
	v_lshlrev_b32_e32 v216, 16, v192
	v_and_b32_e32 v192, 0xffff0000, v192
	v_lshlrev_b32_e32 v217, 16, v193
	v_and_b32_e32 v193, 0xffff0000, v193
	v_fmac_f32_e32 v106, s44, v216
	v_fmac_f32_e32 v107, s44, v192
	v_fmac_f32_e32 v108, s44, v217
	v_fmac_f32_e32 v109, s44, v193
	global_store_dwordx4 v[140:141], v[106:109], off offset:0
	v_lshlrev_b32_e32 v216, 16, v194
	v_and_b32_e32 v194, 0xffff0000, v194
	v_lshlrev_b32_e32 v217, 16, v195
	v_and_b32_e32 v195, 0xffff0000, v195
	v_fmac_f32_e32 v74, s44, v216
	v_fmac_f32_e32 v75, s44, v194
	v_fmac_f32_e32 v76, s44, v217
	v_fmac_f32_e32 v77, s44, v195
	global_store_dwordx4 v[140:141], v[74:77], off offset:64
	s_waitcnt vmcnt(26)
	v_permlane16_swap_b32_e32 v196, v198
	v_permlane16_swap_b32_e32 v197, v199
	v_lshlrev_b32_e32 v216, 16, v196
	v_and_b32_e32 v196, 0xffff0000, v196
	v_lshlrev_b32_e32 v217, 16, v197
	v_and_b32_e32 v197, 0xffff0000, v197
	v_fmac_f32_e32 v42, s44, v216
	v_fmac_f32_e32 v43, s44, v196
	v_fmac_f32_e32 v44, s44, v217
	v_fmac_f32_e32 v45, s44, v197
	global_store_dwordx4 v[140:141], v[42:45], off offset:128
	v_lshlrev_b32_e32 v216, 16, v198
	v_and_b32_e32 v198, 0xffff0000, v198
	v_lshlrev_b32_e32 v217, 16, v199
	v_and_b32_e32 v199, 0xffff0000, v199
	v_fmac_f32_e32 v10, s44, v216
	v_fmac_f32_e32 v11, s44, v198
	v_fmac_f32_e32 v12, s44, v217
	v_fmac_f32_e32 v13, s44, v199
	global_store_dwordx4 v[140:141], v[10:13], off offset:192
	v_lshl_add_u64 v[140:141], v[140:141], 0, s[10:11]
	s_waitcnt vmcnt(27)
	v_permlane16_swap_b32_e32 v200, v202
	v_permlane16_swap_b32_e32 v201, v203
	v_lshlrev_b32_e32 v216, 16, v200
	v_and_b32_e32 v200, 0xffff0000, v200
	v_lshlrev_b32_e32 v217, 16, v201
	v_and_b32_e32 v201, 0xffff0000, v201
	v_fmac_f32_e32 v102, s44, v216
	v_fmac_f32_e32 v103, s44, v200
	v_fmac_f32_e32 v104, s44, v217
	v_fmac_f32_e32 v105, s44, v201
	global_store_dwordx4 v[140:141], v[102:105], off offset:0
	v_lshlrev_b32_e32 v216, 16, v202
	v_and_b32_e32 v202, 0xffff0000, v202
	v_lshlrev_b32_e32 v217, 16, v203
	v_and_b32_e32 v203, 0xffff0000, v203
	v_fmac_f32_e32 v70, s44, v216
	v_fmac_f32_e32 v71, s44, v202
	v_fmac_f32_e32 v72, s44, v217
	v_fmac_f32_e32 v73, s44, v203
	global_store_dwordx4 v[140:141], v[70:73], off offset:64
	s_waitcnt vmcnt(28)
	v_permlane16_swap_b32_e32 v204, v206
	v_permlane16_swap_b32_e32 v205, v207
	v_lshlrev_b32_e32 v216, 16, v204
	v_and_b32_e32 v204, 0xffff0000, v204
	v_lshlrev_b32_e32 v217, 16, v205
	v_and_b32_e32 v205, 0xffff0000, v205
	v_fmac_f32_e32 v38, s44, v216
	v_fmac_f32_e32 v39, s44, v204
	v_fmac_f32_e32 v40, s44, v217
	v_fmac_f32_e32 v41, s44, v205
	global_store_dwordx4 v[140:141], v[38:41], off offset:128
	v_lshlrev_b32_e32 v216, 16, v206
	v_and_b32_e32 v206, 0xffff0000, v206
	v_lshlrev_b32_e32 v217, 16, v207
	v_and_b32_e32 v207, 0xffff0000, v207
	v_fmac_f32_e32 v6, s44, v216
	v_fmac_f32_e32 v7, s44, v206
	v_fmac_f32_e32 v8, s44, v217
	v_fmac_f32_e32 v9, s44, v207
	global_store_dwordx4 v[140:141], v[6:9], off offset:192
	v_lshl_add_u64 v[140:141], v[140:141], 0, s[10:11]
	s_waitcnt vmcnt(29)
	v_permlane16_swap_b32_e32 v208, v210
	v_permlane16_swap_b32_e32 v209, v211
	v_lshlrev_b32_e32 v216, 16, v208
	v_and_b32_e32 v208, 0xffff0000, v208
	v_lshlrev_b32_e32 v217, 16, v209
	v_and_b32_e32 v209, 0xffff0000, v209
	v_fmac_f32_e32 v98, s44, v216
	v_fmac_f32_e32 v99, s44, v208
	v_fmac_f32_e32 v100, s44, v217
	v_fmac_f32_e32 v101, s44, v209
	global_store_dwordx4 v[140:141], v[98:101], off offset:0
	v_lshlrev_b32_e32 v216, 16, v210
	v_and_b32_e32 v210, 0xffff0000, v210
	v_lshlrev_b32_e32 v217, 16, v211
	v_and_b32_e32 v211, 0xffff0000, v211
	v_fmac_f32_e32 v66, s44, v216
	v_fmac_f32_e32 v67, s44, v210
	v_fmac_f32_e32 v68, s44, v217
	v_fmac_f32_e32 v69, s44, v211
	global_store_dwordx4 v[140:141], v[66:69], off offset:64
	s_waitcnt vmcnt(30)
	v_permlane16_swap_b32_e32 v212, v214
	v_permlane16_swap_b32_e32 v213, v215
	v_lshlrev_b32_e32 v216, 16, v212
	v_and_b32_e32 v212, 0xffff0000, v212
	v_lshlrev_b32_e32 v217, 16, v213
	v_and_b32_e32 v213, 0xffff0000, v213
	v_fmac_f32_e32 v34, s44, v216
	v_fmac_f32_e32 v35, s44, v212
	v_fmac_f32_e32 v36, s44, v217
	v_fmac_f32_e32 v37, s44, v213
	global_store_dwordx4 v[140:141], v[34:37], off offset:128
	v_lshlrev_b32_e32 v216, 16, v214
	v_and_b32_e32 v214, 0xffff0000, v214
	v_lshlrev_b32_e32 v217, 16, v215
	v_and_b32_e32 v215, 0xffff0000, v215
	v_fmac_f32_e32 v2, s44, v216
	v_fmac_f32_e32 v3, s44, v214
	v_fmac_f32_e32 v4, s44, v217
	v_fmac_f32_e32 v5, s44, v215
	global_store_dwordx4 v[140:141], v[2:5], off offset:192
	v_readlane_b32 s39, v250, 7
	s_cmpk_lg_u32 s39, 0x200
	s_cbranch_scc1 .LBB0_41
; DEVI int xcd_first_tile() { return (blockIdx.x & 7) * (gridDim.x >> 3) + (blockIdx.x >> 3); }
; DEVI void run_phase(const Params& p, int ph, char* smem) {
;     ...
;       for (int t = xcd_first_tile(); t < 512 + 16 * 11; t += xcd_tile_step()) {
;         if (t < 512) {
;           int mt_, nt_; tile_coords(t, 64, 8, mt_, nt_);
;           gemm_tile256<EPI_RESID>(p, hb, DFF, Bt, DFF, mt_ * 256, nt_ * 128, nullptr, 0, smem);
;         } else {
;           const int u_ = t - 512, tl_ = u_ / 11, q_ = u_ - tl_ * 11;
;           gemm_tile256<EPI_RESID_ATOMIC>(p, hb, DFF, Bt, DFF, (64 + (tl_ & 1)) * 256, (tl_ >> 1) * 128, nullptr, 0, smem, q_ * 256, 8, q_);
;         }
	v_readlane_b32 s40, v250, 0
	s_lshr_b32 s41, s40, 3
	s_and_b32 s40, s40, 7
	s_mul_i32 s40, s40, 22
	s_add_i32 s40, s40, s41
	s_cmp_lt_u32 s41, 22
	s_cselect_b32 s38, s40, 0x4000
	s_branch .LBB0_41

; #define LAS __attribute__((address_space(3)))
; DEVI int xcd_first_tile() { return (blockIdx.x & 7) * (gridDim.x >> 3) + (blockIdx.x >> 3); }
;     ...
;   const int nk = (nk_part < 0) ? (K >> 5) : nk_part;
;   const int lrow = tid >> 2, lpc = tid & 3;
;   const int lch = lpc ^ ((0x78 >> (((lrow >> 2) & 3) * 2)) & 3);
;   const u16* ga = A + (size_t)(m0 + lrow) * lda + kbeg + lch * 8;
;   const u16* gb = Bt + (size_t)(n0 + lrow) * K + kbeg + lch * 8;
;   const size_t ga1 = (size_t)64 * lda, gb1 = (size_t)64 * K;
;   const unsigned lds0 = (unsigned)(uintptr_t)(LAS char*)smem + (unsigned)__builtin_amdgcn_readfirstlane(wid) * 1024u;
;     ...
;   __syncthreads();
;   G2_STAGE(0); G2_STAGE(1);
; DEVI void run_phase(const Params& p, int ph, char* smem) {
;     ...
;       for (int t = xcd_first_tile(); t < 66 * 44; t += xcd_tile_step()) {
;         int mt_, nt_; tile_coords(t, 66, 44, mt_, nt_);
;         gemm_tile256<EPI_SWIGLU>(p, xb, 1024, Bt, 1024, mt_ * 256, nt_ * 128, hb, DFF, smem);
.Lt10_crd:
	s_cmp_lt_u32 s41, 64
	s_cselect_b32 s40, 1, 0
	v_readlane_b32 s2, v250, 5
	v_readlane_b32 s3, v250, 6
	v_readlane_b32 s43, v254, 62
	s_mul_i32 s36, s41, 0x80000
	s_add_u32 s10, s2, s36
	s_addc_u32 s11, s3, 0
	s_add_u32 s10, s10, 0x4200000
	s_addc_u32 s11, s11, 0
	s_mul_i32 s36, s43, 0xb00000
	s_mul_i32 s37, s38, 0x40000
	s_add_i32 s36, s36, s37
	s_add_u32 s12, s2, s36
	s_addc_u32 s13, s3, 0
	s_add_u32 s12, s12, 0x16e00000
	s_addc_u32 s13, s13, 0
	s_movk_i32 s9, 0x78
	v_lshrrev_b32_e32 v0, 2, v145
	v_and_b32_e32 v131, 3, v145
	v_bfe_u32 v136, v145, 4, 2
	v_lshlrev_b32_e32 v136, 1, v136
	v_lshrrev_b32_e64 v136, v136, s9
	v_and_b32_e32 v136, 3, v136
	v_xor_b32_e32 v131, v131, v136
	v_lshlrev_b32_e32 v131, 4, v131
	s_movk_i32 s37, 0x800
	v_mad_u32_u24 v0, v0, s37, v131
	v_bfe_u32 v137, v145, 2, 1
	s_movk_i32 s37, 0x7c0
	v_mul_u32_u24_e32 v136, s37, v137
	v_sub_u32_e32 v136, v0, v136
	v_mov_b32_e32 v137, 0
	v_lshl_add_u64 v[134:135], s[12:13], 0, v[136:137]
	v_bfe_u32 v137, v145, 2, 1
	s_mul_i32 s37, s40, 0x7c0
	v_mul_u32_u24_e32 v136, s37, v137
	v_sub_u32_e32 v0, v0, v136
	s_lshl_b32 s14, s40, 6
	s_add_i32 s14, s14, 64
	s_mov_b32 s15, 0
	v_lshl_add_u64 v[132:133], s[10:11], 0, v[0:1]
	v_bfe_u32 v136, v145, 2, 2
	v_lshlrev_b32_e32 v136, 1, v136
	v_lshrrev_b32_e64 v136, v136, s9
	v_and_b32_e32 v136, 3, v136
	v_bfe_u32 v137, v145, 4, 2
	v_xor_b32_e32 v136, v136, v137
	v_lshlrev_b32_e32 v136, 4, v136
	v_and_b32_e32 v131, 15, v145
	v_lshl_or_b32 v136, v131, 6, v136
	v_bfe_u32 v137, v145, 6, 1
	v_lshl_or_b32 v137, v137, 12, v136
	v_lshrrev_b32_e32 v0, 7, v145
	v_lshl_or_b32 v136, v0, 13, v136
	v_and_b32_e32 v140, 1, v131
	v_lshl_or_b32 v131, v0, 7, v131
	v_bfe_u32 v0, v145, 4, 1
	v_lshlrev_b32_e32 v0, 5, v0
	v_bfe_u32 v141, v145, 5, 1
	v_lshl_or_b32 v0, v141, 4, v0
	v_bfe_u32 v141, v145, 6, 1
	s_mul_i32 s36, s41, 0x160000
	s_lshl_b32 s37, s38, 7
	s_lshl_b32 s37, s37, s40
	s_add_i32 s36, s36, s37
	s_add_u32 s12, s2, s36
	s_addc_u32 s13, s3, 0
	s_add_u32 s12, s12, 0xef40000
	s_addc_u32 s13, s13, 0
	s_movk_i32 s37, 5632
	v_mad_u32_u24 v138, v131, s37, v0
	v_lshlrev_b32_e32 v139, 6, v141
	v_lshlrev_b32_e64 v139, s40, v139
	v_add_u32_e32 v138, v138, v139
	s_mul_i32 s37, s40, 5568
	v_mul_u32_u24_e32 v139, s37, v140
	v_sub_u32_e32 v138, v138, v139
	v_mov_b32_e32 v139, 0
	v_lshl_add_u64 v[140:141], s[12:13], 0, v[138:139]
	s_mov_b32 s2, 0x20000
	s_mov_b32 s3, 0
	v_lshrrev_b32_e32 v0, 6, v145
	v_lshlrev_b32_e32 v0, 10, v0
	s_nop 0
	v_readfirstlane_b32 s43, v0
	s_mov_b32 s39, m0
	s_mov_b32 s10, 128
	s_mov_b32 s11, 0
	s_barrier
	s_add_i32 s38, s43, 0x0
	s_mov_b32 m0, s38
	v_lshl_add_u64 v[142:143], v[132:133], 0, s[2:3]
	global_load_lds_dwordx4 v[132:133], off
	s_add_i32 m0, m0, 0x1000
	s_nop 0
	global_load_lds_dwordx4 v[142:143], off
	v_lshl_add_u64 v[142:143], v[142:143], 0, s[2:3]
	s_add_i32 m0, m0, 0x1000
	s_nop 0
	global_load_lds_dwordx4 v[142:143], off
	v_lshl_add_u64 v[142:143], v[142:143], 0, s[2:3]
	s_add_i32 m0, m0, 0x1000
	s_nop 0
	global_load_lds_dwordx4 v[142:143], off
	s_add_i32 m0, m0, 0x1000
	v_lshl_add_u64 v[142:143], v[134:135], 0, s[2:3]
	s_nop 0
	global_load_lds_dwordx4 v[134:135], off
	s_add_i32 m0, m0, 0x1000
	v_lshl_add_u64 v[132:133], v[132:133], 0, s[14:15]
	s_nop 0
	global_load_lds_dwordx4 v[142:143], off
	v_lshl_add_u64 v[134:135], v[134:135], 0, s[10:11]
	s_nop 0
	s_add_i32 s38, s43, 0x6000
	s_mov_b32 m0, s38
	v_lshl_add_u64 v[142:143], v[132:133], 0, s[2:3]
	global_load_lds_dwordx4 v[132:133], off
	s_add_i32 m0, m0, 0x1000
	s_nop 0
	global_load_lds_dwordx4 v[142:143], off
	v_lshl_add_u64 v[142:143], v[142:143], 0, s[2:3]
	s_add_i32 m0, m0, 0x1000
	s_nop 0
	global_load_lds_dwordx4 v[142:143], off
	v_lshl_add_u64 v[142:143], v[142:143], 0, s[2:3]
	s_add_i32 m0, m0, 0x1000
	s_nop 0
	global_load_lds_dwordx4 v[142:143], off
	s_add_i32 m0, m0, 0x1000
	v_lshl_add_u64 v[142:143], v[134:135], 0, s[2:3]
	s_nop 0
	global_load_lds_dwordx4 v[134:135], off
	s_add_i32 m0, m0, 0x1000
	v_lshl_add_u64 v[132:133], v[132:133], 0, s[14:15]
	s_nop 0
	global_load_lds_dwordx4 v[142:143], off
	v_lshl_add_u64 v[134:135], v[134:135], 0, s[10:11]
	s_nop 0
	s_add_i32 s38, s43, 0xc000
	s_mov_b32 m0, s38
	v_lshl_add_u64 v[142:143], v[132:133], 0, s[2:3]
	global_load_lds_dwordx4 v[132:133], off
	s_add_i32 m0, m0, 0x1000
	s_nop 0
	global_load_lds_dwordx4 v[142:143], off
	v_lshl_add_u64 v[142:143], v[142:143], 0, s[2:3]
	s_add_i32 m0, m0, 0x1000
	s_nop 0
	global_load_lds_dwordx4 v[142:143], off
	v_lshl_add_u64 v[142:143], v[142:143], 0, s[2:3]
	s_add_i32 m0, m0, 0x1000
	s_nop 0
	global_load_lds_dwordx4 v[142:143], off
	s_add_i32 m0, m0, 0x1000
	v_lshl_add_u64 v[142:143], v[134:135], 0, s[2:3]
	s_nop 0
	global_load_lds_dwordx4 v[134:135], off
	s_add_i32 m0, m0, 0x1000
	v_lshl_add_u64 v[132:133], v[132:133], 0, s[14:15]
	s_nop 0
	global_load_lds_dwordx4 v[142:143], off
	v_lshl_add_u64 v[134:135], v[134:135], 0, s[10:11]
	s_nop 0
	v_mov_b32_e32 v2, 0
	v_mov_b32_e32 v3, 0
	v_mov_b32_e32 v4, 0
	v_mov_b32_e32 v5, 0
	v_mov_b32_e32 v6, 0
	v_mov_b32_e32 v7, 0
	v_mov_b32_e32 v8, 0
	v_mov_b32_e32 v9, 0
	v_mov_b32_e32 v10, 0
	v_mov_b32_e32 v11, 0
	v_mov_b32_e32 v12, 0
	v_mov_b32_e32 v13, 0
	v_mov_b32_e32 v14, 0
	v_mov_b32_e32 v15, 0
	v_mov_b32_e32 v16, 0
	v_mov_b32_e32 v17, 0
	v_mov_b32_e32 v18, 0
	v_mov_b32_e32 v19, 0
	v_mov_b32_e32 v20, 0
	v_mov_b32_e32 v21, 0
	v_mov_b32_e32 v22, 0
	v_mov_b32_e32 v23, 0
	v_mov_b32_e32 v24, 0
	v_mov_b32_e32 v25, 0
	v_mov_b32_e32 v26, 0
	v_mov_b32_e32 v27, 0
	v_mov_b32_e32 v28, 0
	v_mov_b32_e32 v29, 0
	v_mov_b32_e32 v30, 0
	v_mov_b32_e32 v31, 0
	v_mov_b32_e32 v32, 0
	v_mov_b32_e32 v33, 0
	v_mov_b32_e32 v34, 0
	v_mov_b32_e32 v35, 0
; #define LAS __attribute__((address_space(3)))
;     ...
;   f32x4 acc[4][8];
; #pragma unroll
;   for (int i = 0; i < 4; i++)
; #pragma unroll
;     for (int j = 0; j < 8; j++) acc[i][j] = (f32x4){0.f, 0.f, 0.f, 0.f};
;   const int nk = (nk_part < 0) ? (K >> 5) : nk_part;
;   const int lrow = tid >> 2, lpc = tid & 3;
;   const int lch = lpc ^ ((0x78 >> (((lrow >> 2) & 3) * 2)) & 3);
;   const u16* ga = A + (size_t)(m0 + lrow) * lda + kbeg + lch * 8;
;   const u16* gb = Bt + (size_t)(n0 + lrow) * K + kbeg + lch * 8;
;   const size_t ga1 = (size_t)64 * lda, gb1 = (size_t)64 * K;
;   const unsigned lds0 = (unsigned)(uintptr_t)(LAS char*)smem + (unsigned)__builtin_amdgcn_readfirstlane(wid) * 1024u;
;     ...
;   __syncthreads();
;   G2_STAGE(0); G2_STAGE(1);
;   const int fsw = (0x78 >> (((r16 >> 2) & 3) * 2)) & 3;
;   const int aoff = (wm * 128 + r16) * 64 + ((quad ^ fsw) << 4);
;   const int boff = 16384 + (wn * 64 + r16) * 64 + ((quad ^ fsw) << 4);
;   for (int kt = 0; kt < nk; kt++) {
;     if (kt + 1 < nk) asm volatile("s_waitcnt vmcnt(6)" ::: "memory");
;     else asm volatile("s_waitcnt vmcnt(0)" ::: "memory");
;     __builtin_amdgcn_s_barrier();
;     asm volatile("" ::: "memory");
;     if (kt + 2 < nk) G2_STAGE(kt + 2);
;     const char* cS = smem + (kt % 3) * 24576;
;     bf16x8 xa[8], wb[4];
; #pragma unroll
;     for (int f = 0; f < 8; f++) xa[f] = *(const bf16x8*)(cS + aoff + f * 1024);
; #pragma unroll
;     for (int f = 0; f < 4; f++) wb[f] = *(const bf16x8*)(cS + boff + f * 1024);
; #pragma unroll
;     for (int nf = 0; nf < 4; nf++)
; #pragma unroll
;       for (int mf = 0; mf < 8; mf++)
;         acc[nf][mf] = __builtin_amdgcn_mfma_f32_16x16x32_bf16(wb[nf], xa[mf], acc[nf][mf], 0, 0, 0);
	v_mov_b32_e32 v36, 0
	v_mov_b32_e32 v37, 0
	v_mov_b32_e32 v38, 0
	v_mov_b32_e32 v39, 0
	v_mov_b32_e32 v40, 0
	v_mov_b32_e32 v41, 0
	v_mov_b32_e32 v42, 0
	v_mov_b32_e32 v43, 0
	v_mov_b32_e32 v44, 0
	v_mov_b32_e32 v45, 0
	v_mov_b32_e32 v46, 0
	v_mov_b32_e32 v47, 0
	v_mov_b32_e32 v48, 0
	v_mov_b32_e32 v49, 0
	v_mov_b32_e32 v50, 0
	v_mov_b32_e32 v51, 0
	v_mov_b32_e32 v52, 0
	v_mov_b32_e32 v53, 0
	v_mov_b32_e32 v54, 0
	v_mov_b32_e32 v55, 0
	v_mov_b32_e32 v56, 0
	v_mov_b32_e32 v57, 0
	v_mov_b32_e32 v58, 0
	v_mov_b32_e32 v59, 0
	v_mov_b32_e32 v60, 0
	v_mov_b32_e32 v61, 0
	v_mov_b32_e32 v62, 0
	v_mov_b32_e32 v63, 0
	v_mov_b32_e32 v64, 0
	v_mov_b32_e32 v65, 0
	v_mov_b32_e32 v66, 0
	v_mov_b32_e32 v67, 0
	v_mov_b32_e32 v68, 0
	v_mov_b32_e32 v69, 0
	v_mov_b32_e32 v70, 0
	v_mov_b32_e32 v71, 0
	v_mov_b32_e32 v72, 0
	v_mov_b32_e32 v73, 0
	v_mov_b32_e32 v74, 0
	v_mov_b32_e32 v75, 0
	v_mov_b32_e32 v76, 0
	v_mov_b32_e32 v77, 0
	v_mov_b32_e32 v78, 0
	v_mov_b32_e32 v79, 0
	v_mov_b32_e32 v80, 0
	v_mov_b32_e32 v81, 0
	v_mov_b32_e32 v82, 0
	v_mov_b32_e32 v83, 0
	v_mov_b32_e32 v84, 0
	v_mov_b32_e32 v85, 0
	v_mov_b32_e32 v86, 0
	v_mov_b32_e32 v87, 0
	v_mov_b32_e32 v88, 0
	v_mov_b32_e32 v89, 0
	v_mov_b32_e32 v90, 0
	v_mov_b32_e32 v91, 0
	v_mov_b32_e32 v92, 0
	v_mov_b32_e32 v93, 0
	v_mov_b32_e32 v94, 0
	v_mov_b32_e32 v95, 0
	v_mov_b32_e32 v96, 0
	v_mov_b32_e32 v97, 0
	v_mov_b32_e32 v98, 0
	v_mov_b32_e32 v99, 0
	v_mov_b32_e32 v100, 0
	v_mov_b32_e32 v101, 0
	v_mov_b32_e32 v102, 0
	v_mov_b32_e32 v103, 0
	v_mov_b32_e32 v104, 0
	v_mov_b32_e32 v105, 0
	v_mov_b32_e32 v106, 0
	v_mov_b32_e32 v107, 0
	v_mov_b32_e32 v108, 0
	v_mov_b32_e32 v109, 0
	v_mov_b32_e32 v110, 0
	v_mov_b32_e32 v111, 0
	v_mov_b32_e32 v112, 0
	v_mov_b32_e32 v113, 0
	v_mov_b32_e32 v114, 0
	v_mov_b32_e32 v115, 0
	v_mov_b32_e32 v116, 0
	v_mov_b32_e32 v117, 0
	v_mov_b32_e32 v118, 0
	v_mov_b32_e32 v119, 0
	v_mov_b32_e32 v120, 0
	v_mov_b32_e32 v121, 0
	v_mov_b32_e32 v122, 0
	v_mov_b32_e32 v123, 0
	v_mov_b32_e32 v124, 0
	v_mov_b32_e32 v125, 0
	v_mov_b32_e32 v126, 0
	v_mov_b32_e32 v127, 0
	v_mov_b32_e32 v128, 0
	v_mov_b32_e32 v129, 0
	s_waitcnt vmcnt(12)
	s_barrier
	ds_read_b128 v[146:149], v136 offset:0
	ds_read_b128 v[152:155], v136 offset:1024
	ds_read_b128 v[156:159], v136 offset:2048
	ds_read_b128 v[162:165], v136 offset:3072
	ds_read_b128 v[166:169], v136 offset:4096
	ds_read_b128 v[170:173], v136 offset:5120
	ds_read_b128 v[176:179], v136 offset:6144
	ds_read_b128 v[180:183], v136 offset:7168
	ds_read_b128 v[184:187], v137 offset:16384
	ds_read_b128 v[188:191], v137 offset:17408
	ds_read_b128 v[192:195], v137 offset:18432
	ds_read_b128 v[196:199], v137 offset:19456
	s_movk_i32 s36, 0x6000
	s_mov_b32 s37, 0
	s_movk_i32 s9, 14
	.p2align 6
.Lt10_loop:
	.p2align 3
	s_waitcnt vmcnt(6) lgkmcnt(0)
	s_barrier
	s_setprio 1
	v_add_u32_e32 v144, s36, v136
	v_mfma_f32_16x16x32_bf16 v[126:129], v[184:187], v[146:149], v[126:129]
	ds_read_b128 v[200:203], v144 offset:0
	v_mfma_f32_16x16x32_bf16 v[122:125], v[184:187], v[152:155], v[122:125]
	ds_read_b128 v[204:207], v144 offset:1024
	v_mfma_f32_16x16x32_bf16 v[118:121], v[184:187], v[156:159], v[118:121]
	ds_read_b128 v[208:211], v144 offset:2048
	v_mfma_f32_16x16x32_bf16 v[114:117], v[184:187], v[162:165], v[114:117]
	ds_read_b128 v[212:215], v144 offset:3072
	v_mfma_f32_16x16x32_bf16 v[110:113], v[184:187], v[166:169], v[110:113]
	ds_read_b128 v[216:219], v144 offset:4096
	v_mfma_f32_16x16x32_bf16 v[106:109], v[184:187], v[170:173], v[106:109]
	ds_read_b128 v[220:223], v144 offset:5120
	v_mfma_f32_16x16x32_bf16 v[102:105], v[184:187], v[176:179], v[102:105]
	ds_read_b128 v[224:227], v144 offset:6144
	v_mfma_f32_16x16x32_bf16 v[98:101], v[184:187], v[180:183], v[98:101]
	ds_read_b128 v[228:231], v144 offset:7168
	v_mfma_f32_16x16x32_bf16 v[94:97], v[188:191], v[146:149], v[94:97]
	v_add_u32_e64 v144, s36, v137
	v_mfma_f32_16x16x32_bf16 v[90:93], v[188:191], v[152:155], v[90:93]
	v_mfma_f32_16x16x32_bf16 v[86:89], v[188:191], v[156:159], v[86:89]
	ds_read_b128 v[232:235], v144 offset:16384
	v_mfma_f32_16x16x32_bf16 v[82:85], v[188:191], v[162:165], v[82:85]
	ds_read_b128 v[236:239], v144 offset:17408
	v_mfma_f32_16x16x32_bf16 v[78:81], v[188:191], v[166:169], v[78:81]
	ds_read_b128 v[240:243], v144 offset:18432
	v_mfma_f32_16x16x32_bf16 v[74:77], v[188:191], v[170:173], v[74:77]
	ds_read_b128 v[244:247], v144 offset:19456
	v_mfma_f32_16x16x32_bf16 v[70:73], v[188:191], v[176:179], v[70:73]
	s_add_i32 s38, s43, s37
	s_mov_b32 m0, s38
	v_lshl_add_u64 v[142:143], v[132:133], 0, s[2:3]
	v_mfma_f32_16x16x32_bf16 v[66:69], v[188:191], v[180:183], v[66:69]
	global_load_lds_dwordx4 v[132:133], off
	s_add_i32 m0, m0, 0x1000
	v_mfma_f32_16x16x32_bf16 v[62:65], v[192:195], v[146:149], v[62:65]
	v_mfma_f32_16x16x32_bf16 v[58:61], v[192:195], v[152:155], v[58:61]
	v_mfma_f32_16x16x32_bf16 v[54:57], v[192:195], v[156:159], v[54:57]
	global_load_lds_dwordx4 v[142:143], off
	v_lshl_add_u64 v[142:143], v[142:143], 0, s[2:3]
	s_add_i32 m0, m0, 0x1000
	v_mfma_f32_16x16x32_bf16 v[50:53], v[192:195], v[162:165], v[50:53]
	v_mfma_f32_16x16x32_bf16 v[46:49], v[192:195], v[166:169], v[46:49]
	v_mfma_f32_16x16x32_bf16 v[42:45], v[192:195], v[170:173], v[42:45]
	global_load_lds_dwordx4 v[142:143], off
	v_lshl_add_u64 v[142:143], v[142:143], 0, s[2:3]
	s_add_i32 m0, m0, 0x1000
	v_mfma_f32_16x16x32_bf16 v[38:41], v[192:195], v[176:179], v[38:41]
	v_mfma_f32_16x16x32_bf16 v[34:37], v[192:195], v[180:183], v[34:37]
	v_mfma_f32_16x16x32_bf16 v[30:33], v[196:199], v[146:149], v[30:33]
	global_load_lds_dwordx4 v[142:143], off
	s_add_i32 m0, m0, 0x1000
	v_lshl_add_u64 v[142:143], v[134:135], 0, s[2:3]
	v_mfma_f32_16x16x32_bf16 v[26:29], v[196:199], v[152:155], v[26:29]
	v_mfma_f32_16x16x32_bf16 v[22:25], v[196:199], v[156:159], v[22:25]
	v_mfma_f32_16x16x32_bf16 v[18:21], v[196:199], v[162:165], v[18:21]
	global_load_lds_dwordx4 v[134:135], off
	s_add_i32 m0, m0, 0x1000
	v_lshl_add_u64 v[132:133], v[132:133], 0, s[14:15]
	v_mfma_f32_16x16x32_bf16 v[14:17], v[196:199], v[166:169], v[14:17]
	v_mfma_f32_16x16x32_bf16 v[10:13], v[196:199], v[170:173], v[10:13]
	v_mfma_f32_16x16x32_bf16 v[6:9], v[196:199], v[176:179], v[6:9]
	global_load_lds_dwordx4 v[142:143], off
	v_lshl_add_u64 v[134:135], v[134:135], 0, s[10:11]
	v_mfma_f32_16x16x32_bf16 v[2:5], v[196:199], v[180:183], v[2:5]
	s_setprio 0
	s_mov_b32 s37, s36
	s_add_i32 s36, s36, 0x6000
	s_cmp_eq_u32 s36, 0x12000
	s_cselect_b32 s36, 0, s36
	s_nop 0
	.p2align 3
	s_waitcnt vmcnt(6) lgkmcnt(0)
	s_barrier
;     ...
;   for (int kt = 0; kt < nk; kt++) {
;     if (kt + 1 < nk) asm volatile("s_waitcnt vmcnt(6)" ::: "memory");
;     else asm volatile("s_waitcnt vmcnt(0)" ::: "memory");
;     __builtin_amdgcn_s_barrier();
;     asm volatile("" ::: "memory");
;     if (kt + 2 < nk) G2_STAGE(kt + 2);
;     const char* cS = smem + (kt % 3) * 24576;
;     bf16x8 xa[8], wb[4];
; #pragma unroll
;     for (int f = 0; f < 8; f++) xa[f] = *(const bf16x8*)(cS + aoff + f * 1024);
; #pragma unroll
;     for (int f = 0; f < 4; f++) wb[f] = *(const bf16x8*)(cS + boff + f * 1024);
; #pragma unroll
;     for (int nf = 0; nf < 4; nf++)
; #pragma unroll
;       for (int mf = 0; mf < 8; mf++)
;         acc[nf][mf] = __builtin_amdgcn_mfma_f32_16x16x32_bf16(wb[nf], xa[mf], acc[nf][mf], 0, 0, 0);
;   }
	s_setprio 1
	v_add_u32_e32 v144, s36, v136
	v_mfma_f32_16x16x32_bf16 v[126:129], v[232:235], v[200:203], v[126:129]
	ds_read_b128 v[146:149], v144 offset:0
	v_mfma_f32_16x16x32_bf16 v[122:125], v[232:235], v[204:207], v[122:125]
	ds_read_b128 v[152:155], v144 offset:1024
	v_mfma_f32_16x16x32_bf16 v[118:121], v[232:235], v[208:211], v[118:121]
	ds_read_b128 v[156:159], v144 offset:2048
	v_mfma_f32_16x16x32_bf16 v[114:117], v[232:235], v[212:215], v[114:117]
	ds_read_b128 v[162:165], v144 offset:3072
	v_mfma_f32_16x16x32_bf16 v[110:113], v[232:235], v[216:219], v[110:113]
	ds_read_b128 v[166:169], v144 offset:4096
	v_mfma_f32_16x16x32_bf16 v[106:109], v[232:235], v[220:223], v[106:109]
	ds_read_b128 v[170:173], v144 offset:5120
	v_mfma_f32_16x16x32_bf16 v[102:105], v[232:235], v[224:227], v[102:105]
	ds_read_b128 v[176:179], v144 offset:6144
	v_mfma_f32_16x16x32_bf16 v[98:101], v[232:235], v[228:231], v[98:101]
	ds_read_b128 v[180:183], v144 offset:7168
	v_mfma_f32_16x16x32_bf16 v[94:97], v[236:239], v[200:203], v[94:97]
	v_add_u32_e64 v144, s36, v137
	v_mfma_f32_16x16x32_bf16 v[90:93], v[236:239], v[204:207], v[90:93]
	v_mfma_f32_16x16x32_bf16 v[86:89], v[236:239], v[208:211], v[86:89]
	ds_read_b128 v[184:187], v144 offset:16384
	v_mfma_f32_16x16x32_bf16 v[82:85], v[236:239], v[212:215], v[82:85]
	ds_read_b128 v[188:191], v144 offset:17408
	v_mfma_f32_16x16x32_bf16 v[78:81], v[236:239], v[216:219], v[78:81]
	ds_read_b128 v[192:195], v144 offset:18432
	v_mfma_f32_16x16x32_bf16 v[74:77], v[236:239], v[220:223], v[74:77]
	ds_read_b128 v[196:199], v144 offset:19456
	v_mfma_f32_16x16x32_bf16 v[70:73], v[236:239], v[224:227], v[70:73]
	s_add_i32 s38, s43, s37
	s_mov_b32 m0, s38
	v_lshl_add_u64 v[142:143], v[132:133], 0, s[2:3]
	v_mfma_f32_16x16x32_bf16 v[66:69], v[236:239], v[228:231], v[66:69]
	global_load_lds_dwordx4 v[132:133], off
	s_add_i32 m0, m0, 0x1000
	v_mfma_f32_16x16x32_bf16 v[62:65], v[240:243], v[200:203], v[62:65]
	v_mfma_f32_16x16x32_bf16 v[58:61], v[240:243], v[204:207], v[58:61]
	v_mfma_f32_16x16x32_bf16 v[54:57], v[240:243], v[208:211], v[54:57]
	global_load_lds_dwordx4 v[142:143], off
	v_lshl_add_u64 v[142:143], v[142:143], 0, s[2:3]
	s_add_i32 m0, m0, 0x1000
	v_mfma_f32_16x16x32_bf16 v[50:53], v[240:243], v[212:215], v[50:53]
	v_mfma_f32_16x16x32_bf16 v[46:49], v[240:243], v[216:219], v[46:49]
	v_mfma_f32_16x16x32_bf16 v[42:45], v[240:243], v[220:223], v[42:45]
	global_load_lds_dwordx4 v[142:143], off
	v_lshl_add_u64 v[142:143], v[142:143], 0, s[2:3]
	s_add_i32 m0, m0, 0x1000
	v_mfma_f32_16x16x32_bf16 v[38:41], v[240:243], v[224:227], v[38:41]
	v_mfma_f32_16x16x32_bf16 v[34:37], v[240:243], v[228:231], v[34:37]
	v_mfma_f32_16x16x32_bf16 v[30:33], v[244:247], v[200:203], v[30:33]
	global_load_lds_dwordx4 v[142:143], off
	s_add_i32 m0, m0, 0x1000
	v_lshl_add_u64 v[142:143], v[134:135], 0, s[2:3]
	v_mfma_f32_16x16x32_bf16 v[26:29], v[244:247], v[204:207], v[26:29]
	v_mfma_f32_16x16x32_bf16 v[22:25], v[244:247], v[208:211], v[22:25]
	v_mfma_f32_16x16x32_bf16 v[18:21], v[244:247], v[212:215], v[18:21]
	global_load_lds_dwordx4 v[134:135], off
	s_add_i32 m0, m0, 0x1000
	v_lshl_add_u64 v[132:133], v[132:133], 0, s[14:15]
	v_mfma_f32_16x16x32_bf16 v[14:17], v[244:247], v[216:219], v[14:17]
	v_mfma_f32_16x16x32_bf16 v[10:13], v[244:247], v[220:223], v[10:13]
	v_mfma_f32_16x16x32_bf16 v[6:9], v[244:247], v[224:227], v[6:9]
	global_load_lds_dwordx4 v[142:143], off
	v_lshl_add_u64 v[134:135], v[134:135], 0, s[10:11]
	v_mfma_f32_16x16x32_bf16 v[2:5], v[244:247], v[228:231], v[2:5]
	s_setprio 0
	s_mov_b32 s37, s36
	s_add_i32 s36, s36, 0x6000
	s_cmp_eq_u32 s36, 0x12000
	s_cselect_b32 s36, 0, s36
	s_nop 0
	s_sub_i32 s9, s9, 1
	s_cmp_lg_u32 s9, 0
	s_cbranch_scc1 .Lt10_loop
	.p2align 3
	s_waitcnt vmcnt(6) lgkmcnt(0)
	s_barrier
	s_setprio 1
	v_add_u32_e32 v144, s36, v136
	v_mfma_f32_16x16x32_bf16 v[126:129], v[184:187], v[146:149], v[126:129]
	ds_read_b128 v[200:203], v144 offset:0
	v_mfma_f32_16x16x32_bf16 v[122:125], v[184:187], v[152:155], v[122:125]
	ds_read_b128 v[204:207], v144 offset:1024
	v_mfma_f32_16x16x32_bf16 v[118:121], v[184:187], v[156:159], v[118:121]
	ds_read_b128 v[208:211], v144 offset:2048
	v_mfma_f32_16x16x32_bf16 v[114:117], v[184:187], v[162:165], v[114:117]
	ds_read_b128 v[212:215], v144 offset:3072
	v_mfma_f32_16x16x32_bf16 v[110:113], v[184:187], v[166:169], v[110:113]
	ds_read_b128 v[216:219], v144 offset:4096
	v_mfma_f32_16x16x32_bf16 v[106:109], v[184:187], v[170:173], v[106:109]
	ds_read_b128 v[220:223], v144 offset:5120
	v_mfma_f32_16x16x32_bf16 v[102:105], v[184:187], v[176:179], v[102:105]
	ds_read_b128 v[224:227], v144 offset:6144
	v_mfma_f32_16x16x32_bf16 v[98:101], v[184:187], v[180:183], v[98:101]
	ds_read_b128 v[228:231], v144 offset:7168
	v_mfma_f32_16x16x32_bf16 v[94:97], v[188:191], v[146:149], v[94:97]
	v_add_u32_e64 v144, s36, v137
	v_mfma_f32_16x16x32_bf16 v[90:93], v[188:191], v[152:155], v[90:93]
	v_mfma_f32_16x16x32_bf16 v[86:89], v[188:191], v[156:159], v[86:89]
	ds_read_b128 v[232:235], v144 offset:16384
	v_mfma_f32_16x16x32_bf16 v[82:85], v[188:191], v[162:165], v[82:85]
	ds_read_b128 v[236:239], v144 offset:17408
	v_mfma_f32_16x16x32_bf16 v[78:81], v[188:191], v[166:169], v[78:81]
	ds_read_b128 v[240:243], v144 offset:18432
	v_mfma_f32_16x16x32_bf16 v[74:77], v[188:191], v[170:173], v[74:77]
	ds_read_b128 v[244:247], v144 offset:19456
	v_mfma_f32_16x16x32_bf16 v[70:73], v[188:191], v[176:179], v[70:73]
	s_add_i32 s38, s43, s37
	s_mov_b32 m0, s38
	v_lshl_add_u64 v[142:143], v[132:133], 0, s[2:3]
	v_mfma_f32_16x16x32_bf16 v[66:69], v[188:191], v[180:183], v[66:69]
	global_load_lds_dwordx4 v[132:133], off
;     ...
;   for (int kt = 0; kt < nk; kt++) {
;     if (kt + 1 < nk) asm volatile("s_waitcnt vmcnt(6)" ::: "memory");
;     else asm volatile("s_waitcnt vmcnt(0)" ::: "memory");
;     __builtin_amdgcn_s_barrier();
;     asm volatile("" ::: "memory");
;     if (kt + 2 < nk) G2_STAGE(kt + 2);
;     const char* cS = smem + (kt % 3) * 24576;
;     bf16x8 xa[8], wb[4];
; #pragma unroll
;     for (int f = 0; f < 8; f++) xa[f] = *(const bf16x8*)(cS + aoff + f * 1024);
; #pragma unroll
;     for (int f = 0; f < 4; f++) wb[f] = *(const bf16x8*)(cS + boff + f * 1024);
; #pragma unroll
;     for (int nf = 0; nf < 4; nf++)
; #pragma unroll
;       for (int mf = 0; mf < 8; mf++)
;         acc[nf][mf] = __builtin_amdgcn_mfma_f32_16x16x32_bf16(wb[nf], xa[mf], acc[nf][mf], 0, 0, 0);
;   }
	s_add_i32 m0, m0, 0x1000
	v_mfma_f32_16x16x32_bf16 v[62:65], v[192:195], v[146:149], v[62:65]
	v_mfma_f32_16x16x32_bf16 v[58:61], v[192:195], v[152:155], v[58:61]
	v_mfma_f32_16x16x32_bf16 v[54:57], v[192:195], v[156:159], v[54:57]
	global_load_lds_dwordx4 v[142:143], off
	v_lshl_add_u64 v[142:143], v[142:143], 0, s[2:3]
	s_add_i32 m0, m0, 0x1000
	v_mfma_f32_16x16x32_bf16 v[50:53], v[192:195], v[162:165], v[50:53]
	v_mfma_f32_16x16x32_bf16 v[46:49], v[192:195], v[166:169], v[46:49]
	v_mfma_f32_16x16x32_bf16 v[42:45], v[192:195], v[170:173], v[42:45]
	global_load_lds_dwordx4 v[142:143], off
	v_lshl_add_u64 v[142:143], v[142:143], 0, s[2:3]
	s_add_i32 m0, m0, 0x1000
	v_mfma_f32_16x16x32_bf16 v[38:41], v[192:195], v[176:179], v[38:41]
	v_mfma_f32_16x16x32_bf16 v[34:37], v[192:195], v[180:183], v[34:37]
	v_mfma_f32_16x16x32_bf16 v[30:33], v[196:199], v[146:149], v[30:33]
	global_load_lds_dwordx4 v[142:143], off
	s_add_i32 m0, m0, 0x1000
	v_lshl_add_u64 v[142:143], v[134:135], 0, s[2:3]
	v_mfma_f32_16x16x32_bf16 v[26:29], v[196:199], v[152:155], v[26:29]
	v_mfma_f32_16x16x32_bf16 v[22:25], v[196:199], v[156:159], v[22:25]
	v_mfma_f32_16x16x32_bf16 v[18:21], v[196:199], v[162:165], v[18:21]
	global_load_lds_dwordx4 v[134:135], off
	s_add_i32 m0, m0, 0x1000
	v_lshl_add_u64 v[132:133], v[132:133], 0, s[14:15]
	v_mfma_f32_16x16x32_bf16 v[14:17], v[196:199], v[166:169], v[14:17]
	v_mfma_f32_16x16x32_bf16 v[10:13], v[196:199], v[170:173], v[10:13]
	v_mfma_f32_16x16x32_bf16 v[6:9], v[196:199], v[176:179], v[6:9]
	global_load_lds_dwordx4 v[142:143], off
	v_lshl_add_u64 v[134:135], v[134:135], 0, s[10:11]
	v_mfma_f32_16x16x32_bf16 v[2:5], v[196:199], v[180:183], v[2:5]
	s_setprio 0
	s_mov_b32 s37, s36
	s_add_i32 s36, s36, 0x6000
	s_cmp_eq_u32 s36, 0x12000
	s_cselect_b32 s36, 0, s36
	s_nop 0
	.p2align 3
	s_waitcnt vmcnt(6) lgkmcnt(0)
	s_barrier
	s_setprio 1
	v_add_u32_e32 v144, s36, v136
	v_mfma_f32_16x16x32_bf16 v[126:129], v[232:235], v[200:203], v[126:129]
	ds_read_b128 v[146:149], v144 offset:0
	v_mfma_f32_16x16x32_bf16 v[122:125], v[232:235], v[204:207], v[122:125]
	ds_read_b128 v[152:155], v144 offset:1024
	v_mfma_f32_16x16x32_bf16 v[118:121], v[232:235], v[208:211], v[118:121]
	ds_read_b128 v[156:159], v144 offset:2048
	v_mfma_f32_16x16x32_bf16 v[114:117], v[232:235], v[212:215], v[114:117]
	ds_read_b128 v[162:165], v144 offset:3072
	v_mfma_f32_16x16x32_bf16 v[110:113], v[232:235], v[216:219], v[110:113]
	ds_read_b128 v[166:169], v144 offset:4096
	v_mfma_f32_16x16x32_bf16 v[106:109], v[232:235], v[220:223], v[106:109]
	ds_read_b128 v[170:173], v144 offset:5120
	v_mfma_f32_16x16x32_bf16 v[102:105], v[232:235], v[224:227], v[102:105]
	ds_read_b128 v[176:179], v144 offset:6144
	v_mfma_f32_16x16x32_bf16 v[98:101], v[232:235], v[228:231], v[98:101]
	ds_read_b128 v[180:183], v144 offset:7168
	v_mfma_f32_16x16x32_bf16 v[94:97], v[236:239], v[200:203], v[94:97]
	v_add_u32_e64 v144, s36, v137
	v_mfma_f32_16x16x32_bf16 v[90:93], v[236:239], v[204:207], v[90:93]
	v_mfma_f32_16x16x32_bf16 v[86:89], v[236:239], v[208:211], v[86:89]
	ds_read_b128 v[184:187], v144 offset:16384
	v_mfma_f32_16x16x32_bf16 v[82:85], v[236:239], v[212:215], v[82:85]
	ds_read_b128 v[188:191], v144 offset:17408
	v_mfma_f32_16x16x32_bf16 v[78:81], v[236:239], v[216:219], v[78:81]
	ds_read_b128 v[192:195], v144 offset:18432
	v_mfma_f32_16x16x32_bf16 v[74:77], v[236:239], v[220:223], v[74:77]
	ds_read_b128 v[196:199], v144 offset:19456
	v_mfma_f32_16x16x32_bf16 v[70:73], v[236:239], v[224:227], v[70:73]
	v_mfma_f32_16x16x32_bf16 v[66:69], v[236:239], v[228:231], v[66:69]
	v_mfma_f32_16x16x32_bf16 v[62:65], v[240:243], v[200:203], v[62:65]
	v_mfma_f32_16x16x32_bf16 v[58:61], v[240:243], v[204:207], v[58:61]
	v_mfma_f32_16x16x32_bf16 v[54:57], v[240:243], v[208:211], v[54:57]
	v_mfma_f32_16x16x32_bf16 v[50:53], v[240:243], v[212:215], v[50:53]
	v_mfma_f32_16x16x32_bf16 v[46:49], v[240:243], v[216:219], v[46:49]
	v_mfma_f32_16x16x32_bf16 v[42:45], v[240:243], v[220:223], v[42:45]
	v_mfma_f32_16x16x32_bf16 v[38:41], v[240:243], v[224:227], v[38:41]
	v_mfma_f32_16x16x32_bf16 v[34:37], v[240:243], v[228:231], v[34:37]
	v_mfma_f32_16x16x32_bf16 v[30:33], v[244:247], v[200:203], v[30:33]
	v_mfma_f32_16x16x32_bf16 v[26:29], v[244:247], v[204:207], v[26:29]
	v_mfma_f32_16x16x32_bf16 v[22:25], v[244:247], v[208:211], v[22:25]
	v_mfma_f32_16x16x32_bf16 v[18:21], v[244:247], v[212:215], v[18:21]
	v_mfma_f32_16x16x32_bf16 v[14:17], v[244:247], v[216:219], v[14:17]
	v_mfma_f32_16x16x32_bf16 v[10:13], v[244:247], v[220:223], v[10:13]
	v_mfma_f32_16x16x32_bf16 v[6:9], v[244:247], v[224:227], v[6:9]
	v_mfma_f32_16x16x32_bf16 v[2:5], v[244:247], v[228:231], v[2:5]
	s_setprio 0
	s_mov_b32 s37, s36
	s_add_i32 s36, s36, 0x6000
	s_cmp_eq_u32 s36, 0x12000
	s_cselect_b32 s36, 0, s36
	s_nop 0
	.p2align 3
	s_waitcnt vmcnt(0) lgkmcnt(0)
	s_barrier
; DEVI unsigned pack2(float a, float b) { return __builtin_bit_cast(unsigned, __builtin_convertvector((f32x2_t){a, b}, bf16x2_t)); }
; DEVI float siluf_(float x) { return x * __builtin_amdgcn_rcpf(1.f + __expf(-x)); }
;     ...
;     for (int f = 0; f < 8; f++) xa[f] = *(const bf16x8*)(cS + aoff + f * 1024);
; #pragma unroll
;     for (int f = 0; f < 4; f++) wb[f] = *(const bf16x8*)(cS + boff + f * 1024);
; #pragma unroll
;     for (int nf = 0; nf < 4; nf++)
; #pragma unroll
;       for (int mf = 0; mf < 8; mf++)
;         acc[nf][mf] = __builtin_amdgcn_mfma_f32_16x16x32_bf16(wb[nf], xa[mf], acc[nf][mf], 0, 0, 0);
;   }
;     ...
; #pragma unroll
;   for (int mf = 0; mf < 8; mf++) {
;     const int row = m0 + wm * 128 + mf * 16 + r16;
;     if (EPI == EPI_SWIGLU) {
; #pragma unroll
;       for (int nf = 0; nf < 2; nf++) {
;         const int hcol = (n0 >> 1) + wn * 32 + nf * 16 + quad * 4;
;         f32x4 g = acc[nf][mf], u = acc[nf + 2][mf];
;         u32x2 pk;
;         pk[0] = pack2(siluf_(g[0]) * u[0], siluf_(g[1]) * u[1]);
;         pk[1] = pack2(siluf_(g[2]) * u[2], siluf_(g[3]) * u[3]);
;         *(u32x2*)(outb + (size_t)row * DFF + hcol) = pk;
	s_setprio 1
	v_add_u32_e32 v144, s36, v136
	v_mfma_f32_16x16x32_bf16 v[126:129], v[184:187], v[146:149], v[126:129]
	ds_read_b128 v[200:203], v144 offset:0
	v_mfma_f32_16x16x32_bf16 v[122:125], v[184:187], v[152:155], v[122:125]
	ds_read_b128 v[204:207], v144 offset:1024
	v_mfma_f32_16x16x32_bf16 v[118:121], v[184:187], v[156:159], v[118:121]
	ds_read_b128 v[208:211], v144 offset:2048
	v_mfma_f32_16x16x32_bf16 v[114:117], v[184:187], v[162:165], v[114:117]
	ds_read_b128 v[212:215], v144 offset:3072
	v_mfma_f32_16x16x32_bf16 v[110:113], v[184:187], v[166:169], v[110:113]
	ds_read_b128 v[216:219], v144 offset:4096
	v_mfma_f32_16x16x32_bf16 v[106:109], v[184:187], v[170:173], v[106:109]
	ds_read_b128 v[220:223], v144 offset:5120
	v_mfma_f32_16x16x32_bf16 v[102:105], v[184:187], v[176:179], v[102:105]
	ds_read_b128 v[224:227], v144 offset:6144
	v_mfma_f32_16x16x32_bf16 v[98:101], v[184:187], v[180:183], v[98:101]
	ds_read_b128 v[228:231], v144 offset:7168
	v_mfma_f32_16x16x32_bf16 v[94:97], v[188:191], v[146:149], v[94:97]
	v_add_u32_e64 v144, s36, v137
	v_mfma_f32_16x16x32_bf16 v[90:93], v[188:191], v[152:155], v[90:93]
	v_mfma_f32_16x16x32_bf16 v[86:89], v[188:191], v[156:159], v[86:89]
	ds_read_b128 v[232:235], v144 offset:16384
	v_mfma_f32_16x16x32_bf16 v[82:85], v[188:191], v[162:165], v[82:85]
	ds_read_b128 v[236:239], v144 offset:17408
	v_mfma_f32_16x16x32_bf16 v[78:81], v[188:191], v[166:169], v[78:81]
	ds_read_b128 v[240:243], v144 offset:18432
	v_mfma_f32_16x16x32_bf16 v[74:77], v[188:191], v[170:173], v[74:77]
	ds_read_b128 v[244:247], v144 offset:19456
	v_mfma_f32_16x16x32_bf16 v[70:73], v[188:191], v[176:179], v[70:73]
	v_mfma_f32_16x16x32_bf16 v[66:69], v[188:191], v[180:183], v[66:69]
	v_mfma_f32_16x16x32_bf16 v[62:65], v[192:195], v[146:149], v[62:65]
	v_mfma_f32_16x16x32_bf16 v[58:61], v[192:195], v[152:155], v[58:61]
	v_mfma_f32_16x16x32_bf16 v[54:57], v[192:195], v[156:159], v[54:57]
	v_mfma_f32_16x16x32_bf16 v[50:53], v[192:195], v[162:165], v[50:53]
	v_mfma_f32_16x16x32_bf16 v[46:49], v[192:195], v[166:169], v[46:49]
	v_mfma_f32_16x16x32_bf16 v[42:45], v[192:195], v[170:173], v[42:45]
	v_mfma_f32_16x16x32_bf16 v[38:41], v[192:195], v[176:179], v[38:41]
	v_mfma_f32_16x16x32_bf16 v[34:37], v[192:195], v[180:183], v[34:37]
	v_mfma_f32_16x16x32_bf16 v[30:33], v[196:199], v[146:149], v[30:33]
	v_mfma_f32_16x16x32_bf16 v[26:29], v[196:199], v[152:155], v[26:29]
	v_mfma_f32_16x16x32_bf16 v[22:25], v[196:199], v[156:159], v[22:25]
	v_mfma_f32_16x16x32_bf16 v[18:21], v[196:199], v[162:165], v[18:21]
	v_mfma_f32_16x16x32_bf16 v[14:17], v[196:199], v[166:169], v[14:17]
	v_mfma_f32_16x16x32_bf16 v[10:13], v[196:199], v[170:173], v[10:13]
	v_mfma_f32_16x16x32_bf16 v[6:9], v[196:199], v[176:179], v[6:9]
	v_mfma_f32_16x16x32_bf16 v[2:5], v[196:199], v[180:183], v[2:5]
	s_setprio 0
	s_mov_b32 s37, s36
	s_add_i32 s36, s36, 0x6000
	s_cmp_eq_u32 s36, 0x12000
	s_cselect_b32 s36, 0, s36
	s_nop 0
	.p2align 3
	s_waitcnt lgkmcnt(0)
	s_nop 0
	v_mfma_f32_16x16x32_bf16 v[126:129], v[232:235], v[200:203], v[126:129]
	v_mfma_f32_16x16x32_bf16 v[122:125], v[232:235], v[204:207], v[122:125]
	v_mfma_f32_16x16x32_bf16 v[118:121], v[232:235], v[208:211], v[118:121]
	v_mfma_f32_16x16x32_bf16 v[114:117], v[232:235], v[212:215], v[114:117]
	v_mfma_f32_16x16x32_bf16 v[110:113], v[232:235], v[216:219], v[110:113]
	v_mfma_f32_16x16x32_bf16 v[106:109], v[232:235], v[220:223], v[106:109]
	v_mfma_f32_16x16x32_bf16 v[102:105], v[232:235], v[224:227], v[102:105]
	v_mfma_f32_16x16x32_bf16 v[98:101], v[232:235], v[228:231], v[98:101]
	v_mfma_f32_16x16x32_bf16 v[94:97], v[236:239], v[200:203], v[94:97]
	v_mfma_f32_16x16x32_bf16 v[90:93], v[236:239], v[204:207], v[90:93]
	v_mfma_f32_16x16x32_bf16 v[86:89], v[236:239], v[208:211], v[86:89]
	v_mfma_f32_16x16x32_bf16 v[82:85], v[236:239], v[212:215], v[82:85]
	v_mfma_f32_16x16x32_bf16 v[78:81], v[236:239], v[216:219], v[78:81]
	v_mfma_f32_16x16x32_bf16 v[74:77], v[236:239], v[220:223], v[74:77]
	v_mfma_f32_16x16x32_bf16 v[70:73], v[236:239], v[224:227], v[70:73]
	v_mfma_f32_16x16x32_bf16 v[66:69], v[236:239], v[228:231], v[66:69]
	v_mfma_f32_16x16x32_bf16 v[62:65], v[240:243], v[200:203], v[62:65]
	v_mfma_f32_16x16x32_bf16 v[58:61], v[240:243], v[204:207], v[58:61]
	v_mfma_f32_16x16x32_bf16 v[54:57], v[240:243], v[208:211], v[54:57]
	v_mfma_f32_16x16x32_bf16 v[50:53], v[240:243], v[212:215], v[50:53]
	v_mfma_f32_16x16x32_bf16 v[46:49], v[240:243], v[216:219], v[46:49]
	v_mfma_f32_16x16x32_bf16 v[42:45], v[240:243], v[220:223], v[42:45]
	v_mfma_f32_16x16x32_bf16 v[38:41], v[240:243], v[224:227], v[38:41]
	v_mfma_f32_16x16x32_bf16 v[34:37], v[240:243], v[228:231], v[34:37]
	v_mfma_f32_16x16x32_bf16 v[30:33], v[244:247], v[200:203], v[30:33]
	v_mfma_f32_16x16x32_bf16 v[26:29], v[244:247], v[204:207], v[26:29]
	v_mfma_f32_16x16x32_bf16 v[22:25], v[244:247], v[208:211], v[22:25]
	v_mfma_f32_16x16x32_bf16 v[18:21], v[244:247], v[212:215], v[18:21]
	v_mfma_f32_16x16x32_bf16 v[14:17], v[244:247], v[216:219], v[14:17]
	v_mfma_f32_16x16x32_bf16 v[10:13], v[244:247], v[220:223], v[10:13]
	v_mfma_f32_16x16x32_bf16 v[6:9], v[244:247], v[224:227], v[6:9]
	v_mfma_f32_16x16x32_bf16 v[2:5], v[244:247], v[228:231], v[2:5]
	s_mov_b32 m0, s39
	s_mov_b32 s10, 0x16000
	s_mov_b32 s11, 0
	s_mov_b32 s40, 0xbfb8aa3b
	s_nop 7
	v_mul_f32_e32 v216, s40, v126
	v_mul_f32_e32 v217, s40, v127
	v_mul_f32_e32 v218, s40, v128
	v_mul_f32_e32 v219, s40, v129
	v_exp_f32_e32 v216, v216
	v_exp_f32_e32 v217, v217
	v_exp_f32_e32 v218, v218
	v_exp_f32_e32 v219, v219
	v_add_f32_e32 v216, 1.0, v216
	v_add_f32_e32 v217, 1.0, v217
	v_add_f32_e32 v218, 1.0, v218
; DEVI unsigned pack2(float a, float b) { return __builtin_bit_cast(unsigned, __builtin_convertvector((f32x2_t){a, b}, bf16x2_t)); }
; DEVI float siluf_(float x) { return x * __builtin_amdgcn_rcpf(1.f + __expf(-x)); }
;     ...
; #pragma unroll
;   for (int mf = 0; mf < 8; mf++) {
;     const int row = m0 + wm * 128 + mf * 16 + r16;
;     if (EPI == EPI_SWIGLU) {
; #pragma unroll
;       for (int nf = 0; nf < 2; nf++) {
;         const int hcol = (n0 >> 1) + wn * 32 + nf * 16 + quad * 4;
;         f32x4 g = acc[nf][mf], u = acc[nf + 2][mf];
;         u32x2 pk;
;         pk[0] = pack2(siluf_(g[0]) * u[0], siluf_(g[1]) * u[1]);
;         pk[1] = pack2(siluf_(g[2]) * u[2], siluf_(g[3]) * u[3]);
;         *(u32x2*)(outb + (size_t)row * DFF + hcol) = pk;
;       }
	v_add_f32_e32 v219, 1.0, v219
	v_rcp_f32_e32 v216, v216
	v_rcp_f32_e32 v217, v217
	v_rcp_f32_e32 v218, v218
	v_rcp_f32_e32 v219, v219
	v_mul_f32_e32 v126, v126, v216
	v_mul_f32_e32 v127, v127, v217
	v_mul_f32_e32 v128, v128, v218
	v_mul_f32_e32 v129, v129, v219
	v_mul_f32_e32 v126, v126, v62
	v_mul_f32_e32 v127, v127, v63
	v_mul_f32_e32 v128, v128, v64
	v_mul_f32_e32 v129, v129, v65
	v_mul_f32_e32 v220, s40, v94
	v_mul_f32_e32 v221, s40, v95
	v_mul_f32_e32 v222, s40, v96
	v_mul_f32_e32 v223, s40, v97
	v_exp_f32_e32 v220, v220
	v_exp_f32_e32 v221, v221
	v_exp_f32_e32 v222, v222
	v_exp_f32_e32 v223, v223
	v_add_f32_e32 v220, 1.0, v220
	v_add_f32_e32 v221, 1.0, v221
	v_add_f32_e32 v222, 1.0, v222
	v_add_f32_e32 v223, 1.0, v223
	v_rcp_f32_e32 v220, v220
	v_rcp_f32_e32 v221, v221
	v_rcp_f32_e32 v222, v222
	v_rcp_f32_e32 v223, v223
	v_mul_f32_e32 v94, v94, v220
	v_mul_f32_e32 v95, v95, v221
	v_mul_f32_e32 v96, v96, v222
	v_mul_f32_e32 v97, v97, v223
	v_mul_f32_e32 v94, v94, v30
	v_mul_f32_e32 v95, v95, v31
	v_mul_f32_e32 v96, v96, v32
	v_mul_f32_e32 v97, v97, v33
	v_cvt_pk_bf16_f32 v126, v126, v127
	v_cvt_pk_bf16_f32 v127, v128, v129
	v_cvt_pk_bf16_f32 v128, v94, v95
	v_cvt_pk_bf16_f32 v129, v96, v97
	s_nop 1
	v_permlane16_swap_b32_e32 v126, v128
	v_permlane16_swap_b32_e32 v127, v129
	global_store_dwordx4 v[140:141], v[126:129], off
	v_lshl_add_u64 v[140:141], v[140:141], 0, s[10:11]
	v_mul_f32_e32 v216, s40, v122
	v_mul_f32_e32 v217, s40, v123
	v_mul_f32_e32 v218, s40, v124
	v_mul_f32_e32 v219, s40, v125
	v_exp_f32_e32 v216, v216
	v_exp_f32_e32 v217, v217
	v_exp_f32_e32 v218, v218
	v_exp_f32_e32 v219, v219
	v_add_f32_e32 v216, 1.0, v216
	v_add_f32_e32 v217, 1.0, v217
	v_add_f32_e32 v218, 1.0, v218
	v_add_f32_e32 v219, 1.0, v219
	v_rcp_f32_e32 v216, v216
	v_rcp_f32_e32 v217, v217
	v_rcp_f32_e32 v218, v218
	v_rcp_f32_e32 v219, v219
	v_mul_f32_e32 v122, v122, v216
	v_mul_f32_e32 v123, v123, v217
	v_mul_f32_e32 v124, v124, v218
	v_mul_f32_e32 v125, v125, v219
	v_mul_f32_e32 v122, v122, v58
	v_mul_f32_e32 v123, v123, v59
	v_mul_f32_e32 v124, v124, v60
	v_mul_f32_e32 v125, v125, v61
	v_mul_f32_e32 v220, s40, v90
	v_mul_f32_e32 v221, s40, v91
	v_mul_f32_e32 v222, s40, v92
	v_mul_f32_e32 v223, s40, v93
	v_exp_f32_e32 v220, v220
	v_exp_f32_e32 v221, v221
	v_exp_f32_e32 v222, v222
	v_exp_f32_e32 v223, v223
	v_add_f32_e32 v220, 1.0, v220
	v_add_f32_e32 v221, 1.0, v221
	v_add_f32_e32 v222, 1.0, v222
	v_add_f32_e32 v223, 1.0, v223
	v_rcp_f32_e32 v220, v220
	v_rcp_f32_e32 v221, v221
	v_rcp_f32_e32 v222, v222
	v_rcp_f32_e32 v223, v223
	v_mul_f32_e32 v90, v90, v220
	v_mul_f32_e32 v91, v91, v221
	v_mul_f32_e32 v92, v92, v222
	v_mul_f32_e32 v93, v93, v223
	v_mul_f32_e32 v90, v90, v26
	v_mul_f32_e32 v91, v91, v27
	v_mul_f32_e32 v92, v92, v28
	v_mul_f32_e32 v93, v93, v29
	v_cvt_pk_bf16_f32 v122, v122, v123
	v_cvt_pk_bf16_f32 v123, v124, v125
	v_cvt_pk_bf16_f32 v124, v90, v91
	v_cvt_pk_bf16_f32 v125, v92, v93
	s_nop 1
	v_permlane16_swap_b32_e32 v122, v124
	v_permlane16_swap_b32_e32 v123, v125
	global_store_dwordx4 v[140:141], v[122:125], off
	v_lshl_add_u64 v[140:141], v[140:141], 0, s[10:11]
	v_mul_f32_e32 v216, s40, v118
	v_mul_f32_e32 v217, s40, v119
	v_mul_f32_e32 v218, s40, v120
	v_mul_f32_e32 v219, s40, v121
	v_exp_f32_e32 v216, v216
	v_exp_f32_e32 v217, v217
	v_exp_f32_e32 v218, v218
	v_exp_f32_e32 v219, v219
	v_add_f32_e32 v216, 1.0, v216
	v_add_f32_e32 v217, 1.0, v217
	v_add_f32_e32 v218, 1.0, v218
	v_add_f32_e32 v219, 1.0, v219
	v_rcp_f32_e32 v216, v216
	v_rcp_f32_e32 v217, v217
	v_rcp_f32_e32 v218, v218
	v_rcp_f32_e32 v219, v219
	v_mul_f32_e32 v118, v118, v216
	v_mul_f32_e32 v119, v119, v217
	v_mul_f32_e32 v120, v120, v218
	v_mul_f32_e32 v121, v121, v219
	v_mul_f32_e32 v118, v118, v54
	v_mul_f32_e32 v119, v119, v55
	v_mul_f32_e32 v120, v120, v56
	v_mul_f32_e32 v121, v121, v57
	v_mul_f32_e32 v220, s40, v86
	v_mul_f32_e32 v221, s40, v87
	v_mul_f32_e32 v222, s40, v88
	v_mul_f32_e32 v223, s40, v89
	v_exp_f32_e32 v220, v220
	v_exp_f32_e32 v221, v221
	v_exp_f32_e32 v222, v222
	v_exp_f32_e32 v223, v223
	v_add_f32_e32 v220, 1.0, v220
	v_add_f32_e32 v221, 1.0, v221
	v_add_f32_e32 v222, 1.0, v222
	v_add_f32_e32 v223, 1.0, v223
	v_rcp_f32_e32 v220, v220
	v_rcp_f32_e32 v221, v221
	v_rcp_f32_e32 v222, v222
	v_rcp_f32_e32 v223, v223
	v_mul_f32_e32 v86, v86, v220
	v_mul_f32_e32 v87, v87, v221
	v_mul_f32_e32 v88, v88, v222
	v_mul_f32_e32 v89, v89, v223
	v_mul_f32_e32 v86, v86, v22
	v_mul_f32_e32 v87, v87, v23
	v_mul_f32_e32 v88, v88, v24
	v_mul_f32_e32 v89, v89, v25
	v_cvt_pk_bf16_f32 v118, v118, v119
	v_cvt_pk_bf16_f32 v119, v120, v121
	v_cvt_pk_bf16_f32 v120, v86, v87
	v_cvt_pk_bf16_f32 v121, v88, v89
	s_nop 1
	v_permlane16_swap_b32_e32 v118, v120
	v_permlane16_swap_b32_e32 v119, v121
	global_store_dwordx4 v[140:141], v[118:121], off
	v_lshl_add_u64 v[140:141], v[140:141], 0, s[10:11]
	v_mul_f32_e32 v216, s40, v114
	v_mul_f32_e32 v217, s40, v115
	v_mul_f32_e32 v218, s40, v116
	v_mul_f32_e32 v219, s40, v117
	v_exp_f32_e32 v216, v216
	v_exp_f32_e32 v217, v217
	v_exp_f32_e32 v218, v218
	v_exp_f32_e32 v219, v219
	v_add_f32_e32 v216, 1.0, v216
	v_add_f32_e32 v217, 1.0, v217
	v_add_f32_e32 v218, 1.0, v218
	v_add_f32_e32 v219, 1.0, v219
	v_rcp_f32_e32 v216, v216
	v_rcp_f32_e32 v217, v217
	v_rcp_f32_e32 v218, v218
	v_rcp_f32_e32 v219, v219
	v_mul_f32_e32 v114, v114, v216
	v_mul_f32_e32 v115, v115, v217
	v_mul_f32_e32 v116, v116, v218
	v_mul_f32_e32 v117, v117, v219
	v_mul_f32_e32 v114, v114, v50
	v_mul_f32_e32 v115, v115, v51
	v_mul_f32_e32 v116, v116, v52
	v_mul_f32_e32 v117, v117, v53
	v_mul_f32_e32 v220, s40, v82
	v_mul_f32_e32 v221, s40, v83
	v_mul_f32_e32 v222, s40, v84
; DEVI unsigned pack2(float a, float b) { return __builtin_bit_cast(unsigned, __builtin_convertvector((f32x2_t){a, b}, bf16x2_t)); }
; DEVI float siluf_(float x) { return x * __builtin_amdgcn_rcpf(1.f + __expf(-x)); }
;     ...
; #pragma unroll
;   for (int mf = 0; mf < 8; mf++) {
;     const int row = m0 + wm * 128 + mf * 16 + r16;
;     if (EPI == EPI_SWIGLU) {
; #pragma unroll
;       for (int nf = 0; nf < 2; nf++) {
;         const int hcol = (n0 >> 1) + wn * 32 + nf * 16 + quad * 4;
;         f32x4 g = acc[nf][mf], u = acc[nf + 2][mf];
;         u32x2 pk;
;         pk[0] = pack2(siluf_(g[0]) * u[0], siluf_(g[1]) * u[1]);
;         pk[1] = pack2(siluf_(g[2]) * u[2], siluf_(g[3]) * u[3]);
;         *(u32x2*)(outb + (size_t)row * DFF + hcol) = pk;
;       }
	v_mul_f32_e32 v223, s40, v85
	v_exp_f32_e32 v220, v220
	v_exp_f32_e32 v221, v221
	v_exp_f32_e32 v222, v222
	v_exp_f32_e32 v223, v223
	v_add_f32_e32 v220, 1.0, v220
	v_add_f32_e32 v221, 1.0, v221
	v_add_f32_e32 v222, 1.0, v222
	v_add_f32_e32 v223, 1.0, v223
	v_rcp_f32_e32 v220, v220
	v_rcp_f32_e32 v221, v221
	v_rcp_f32_e32 v222, v222
	v_rcp_f32_e32 v223, v223
	v_mul_f32_e32 v82, v82, v220
	v_mul_f32_e32 v83, v83, v221
	v_mul_f32_e32 v84, v84, v222
	v_mul_f32_e32 v85, v85, v223
	v_mul_f32_e32 v82, v82, v18
	v_mul_f32_e32 v83, v83, v19
	v_mul_f32_e32 v84, v84, v20
	v_mul_f32_e32 v85, v85, v21
	v_cvt_pk_bf16_f32 v114, v114, v115
	v_cvt_pk_bf16_f32 v115, v116, v117
	v_cvt_pk_bf16_f32 v116, v82, v83
	v_cvt_pk_bf16_f32 v117, v84, v85
	s_nop 1
	v_permlane16_swap_b32_e32 v114, v116
	v_permlane16_swap_b32_e32 v115, v117
	global_store_dwordx4 v[140:141], v[114:117], off
	v_lshl_add_u64 v[140:141], v[140:141], 0, s[10:11]
	v_mul_f32_e32 v216, s40, v110
	v_mul_f32_e32 v217, s40, v111
	v_mul_f32_e32 v218, s40, v112
	v_mul_f32_e32 v219, s40, v113
	v_exp_f32_e32 v216, v216
	v_exp_f32_e32 v217, v217
	v_exp_f32_e32 v218, v218
	v_exp_f32_e32 v219, v219
	v_add_f32_e32 v216, 1.0, v216
	v_add_f32_e32 v217, 1.0, v217
	v_add_f32_e32 v218, 1.0, v218
	v_add_f32_e32 v219, 1.0, v219
	v_rcp_f32_e32 v216, v216
	v_rcp_f32_e32 v217, v217
	v_rcp_f32_e32 v218, v218
	v_rcp_f32_e32 v219, v219
	v_mul_f32_e32 v110, v110, v216
	v_mul_f32_e32 v111, v111, v217
	v_mul_f32_e32 v112, v112, v218
	v_mul_f32_e32 v113, v113, v219
	v_mul_f32_e32 v110, v110, v46
	v_mul_f32_e32 v111, v111, v47
	v_mul_f32_e32 v112, v112, v48
	v_mul_f32_e32 v113, v113, v49
	v_mul_f32_e32 v220, s40, v78
	v_mul_f32_e32 v221, s40, v79
	v_mul_f32_e32 v222, s40, v80
	v_mul_f32_e32 v223, s40, v81
	v_exp_f32_e32 v220, v220
	v_exp_f32_e32 v221, v221
	v_exp_f32_e32 v222, v222
	v_exp_f32_e32 v223, v223
	v_add_f32_e32 v220, 1.0, v220
	v_add_f32_e32 v221, 1.0, v221
	v_add_f32_e32 v222, 1.0, v222
	v_add_f32_e32 v223, 1.0, v223
	v_rcp_f32_e32 v220, v220
	v_rcp_f32_e32 v221, v221
	v_rcp_f32_e32 v222, v222
	v_rcp_f32_e32 v223, v223
	v_mul_f32_e32 v78, v78, v220
	v_mul_f32_e32 v79, v79, v221
	v_mul_f32_e32 v80, v80, v222
	v_mul_f32_e32 v81, v81, v223
	v_mul_f32_e32 v78, v78, v14
	v_mul_f32_e32 v79, v79, v15
	v_mul_f32_e32 v80, v80, v16
	v_mul_f32_e32 v81, v81, v17
	v_cvt_pk_bf16_f32 v110, v110, v111
	v_cvt_pk_bf16_f32 v111, v112, v113
	v_cvt_pk_bf16_f32 v112, v78, v79
	v_cvt_pk_bf16_f32 v113, v80, v81
	s_nop 1
	v_permlane16_swap_b32_e32 v110, v112
	v_permlane16_swap_b32_e32 v111, v113
	global_store_dwordx4 v[140:141], v[110:113], off
	v_lshl_add_u64 v[140:141], v[140:141], 0, s[10:11]
	v_mul_f32_e32 v216, s40, v106
	v_mul_f32_e32 v217, s40, v107
	v_mul_f32_e32 v218, s40, v108
	v_mul_f32_e32 v219, s40, v109
	v_exp_f32_e32 v216, v216
	v_exp_f32_e32 v217, v217
	v_exp_f32_e32 v218, v218
	v_exp_f32_e32 v219, v219
	v_add_f32_e32 v216, 1.0, v216
	v_add_f32_e32 v217, 1.0, v217
	v_add_f32_e32 v218, 1.0, v218
	v_add_f32_e32 v219, 1.0, v219
	v_rcp_f32_e32 v216, v216
	v_rcp_f32_e32 v217, v217
	v_rcp_f32_e32 v218, v218
	v_rcp_f32_e32 v219, v219
	v_mul_f32_e32 v106, v106, v216
	v_mul_f32_e32 v107, v107, v217
	v_mul_f32_e32 v108, v108, v218
	v_mul_f32_e32 v109, v109, v219
	v_mul_f32_e32 v106, v106, v42
	v_mul_f32_e32 v107, v107, v43
	v_mul_f32_e32 v108, v108, v44
	v_mul_f32_e32 v109, v109, v45
	v_mul_f32_e32 v220, s40, v74
	v_mul_f32_e32 v221, s40, v75
	v_mul_f32_e32 v222, s40, v76
	v_mul_f32_e32 v223, s40, v77
	v_exp_f32_e32 v220, v220
	v_exp_f32_e32 v221, v221
	v_exp_f32_e32 v222, v222
	v_exp_f32_e32 v223, v223
	v_add_f32_e32 v220, 1.0, v220
	v_add_f32_e32 v221, 1.0, v221
	v_add_f32_e32 v222, 1.0, v222
	v_add_f32_e32 v223, 1.0, v223
	v_rcp_f32_e32 v220, v220
	v_rcp_f32_e32 v221, v221
	v_rcp_f32_e32 v222, v222
	v_rcp_f32_e32 v223, v223
	v_mul_f32_e32 v74, v74, v220
	v_mul_f32_e32 v75, v75, v221
	v_mul_f32_e32 v76, v76, v222
	v_mul_f32_e32 v77, v77, v223
; DEVI unsigned pack2(float a, float b) { return __builtin_bit_cast(unsigned, __builtin_convertvector((f32x2_t){a, b}, bf16x2_t)); }
; DEVI float siluf_(float x) { return x * __builtin_amdgcn_rcpf(1.f + __expf(-x)); }
; DEVI int xcd_first_tile() { return (blockIdx.x & 7) * (gridDim.x >> 3) + (blockIdx.x >> 3); }
;     ...
; #pragma unroll
;   for (int mf = 0; mf < 8; mf++) {
;     const int row = m0 + wm * 128 + mf * 16 + r16;
;     if (EPI == EPI_SWIGLU) {
; #pragma unroll
;       for (int nf = 0; nf < 2; nf++) {
;         const int hcol = (n0 >> 1) + wn * 32 + nf * 16 + quad * 4;
;         f32x4 g = acc[nf][mf], u = acc[nf + 2][mf];
;         u32x2 pk;
;         pk[0] = pack2(siluf_(g[0]) * u[0], siluf_(g[1]) * u[1]);
;         pk[1] = pack2(siluf_(g[2]) * u[2], siluf_(g[3]) * u[3]);
;         *(u32x2*)(outb + (size_t)row * DFF + hcol) = pk;
;       }
; DEVI void run_phase(const Params& p, int ph, char* smem) {
;     ...
;       for (int t = xcd_first_tile(); t < 66 * 44; t += xcd_tile_step()) {
;         int mt_, nt_; tile_coords(t, 66, 44, mt_, nt_);
;         gemm_tile256<EPI_SWIGLU>(p, xb, 1024, Bt, 1024, mt_ * 256, nt_ * 128, hb, DFF, smem);
	v_mul_f32_e32 v74, v74, v10
	v_mul_f32_e32 v75, v75, v11
	v_mul_f32_e32 v76, v76, v12
	v_mul_f32_e32 v77, v77, v13
	v_cvt_pk_bf16_f32 v106, v106, v107
	v_cvt_pk_bf16_f32 v107, v108, v109
	v_cvt_pk_bf16_f32 v108, v74, v75
	v_cvt_pk_bf16_f32 v109, v76, v77
	s_nop 1
	v_permlane16_swap_b32_e32 v106, v108
	v_permlane16_swap_b32_e32 v107, v109
	global_store_dwordx4 v[140:141], v[106:109], off
	v_lshl_add_u64 v[140:141], v[140:141], 0, s[10:11]
	v_mul_f32_e32 v216, s40, v102
	v_mul_f32_e32 v217, s40, v103
	v_mul_f32_e32 v218, s40, v104
	v_mul_f32_e32 v219, s40, v105
	v_exp_f32_e32 v216, v216
	v_exp_f32_e32 v217, v217
	v_exp_f32_e32 v218, v218
	v_exp_f32_e32 v219, v219
	v_add_f32_e32 v216, 1.0, v216
	v_add_f32_e32 v217, 1.0, v217
	v_add_f32_e32 v218, 1.0, v218
	v_add_f32_e32 v219, 1.0, v219
	v_rcp_f32_e32 v216, v216
	v_rcp_f32_e32 v217, v217
	v_rcp_f32_e32 v218, v218
	v_rcp_f32_e32 v219, v219
	v_mul_f32_e32 v102, v102, v216
	v_mul_f32_e32 v103, v103, v217
	v_mul_f32_e32 v104, v104, v218
	v_mul_f32_e32 v105, v105, v219
	v_mul_f32_e32 v102, v102, v38
	v_mul_f32_e32 v103, v103, v39
	v_mul_f32_e32 v104, v104, v40
	v_mul_f32_e32 v105, v105, v41
	v_mul_f32_e32 v220, s40, v70
	v_mul_f32_e32 v221, s40, v71
	v_mul_f32_e32 v222, s40, v72
	v_mul_f32_e32 v223, s40, v73
	v_exp_f32_e32 v220, v220
	v_exp_f32_e32 v221, v221
	v_exp_f32_e32 v222, v222
	v_exp_f32_e32 v223, v223
	v_add_f32_e32 v220, 1.0, v220
	v_add_f32_e32 v221, 1.0, v221
	v_add_f32_e32 v222, 1.0, v222
	v_add_f32_e32 v223, 1.0, v223
	v_rcp_f32_e32 v220, v220
	v_rcp_f32_e32 v221, v221
	v_rcp_f32_e32 v222, v222
	v_rcp_f32_e32 v223, v223
	v_mul_f32_e32 v70, v70, v220
	v_mul_f32_e32 v71, v71, v221
	v_mul_f32_e32 v72, v72, v222
	v_mul_f32_e32 v73, v73, v223
	v_mul_f32_e32 v70, v70, v6
	v_mul_f32_e32 v71, v71, v7
	v_mul_f32_e32 v72, v72, v8
	v_mul_f32_e32 v73, v73, v9
	v_cvt_pk_bf16_f32 v102, v102, v103
	v_cvt_pk_bf16_f32 v103, v104, v105
	v_cvt_pk_bf16_f32 v104, v70, v71
	v_cvt_pk_bf16_f32 v105, v72, v73
	s_nop 1
	v_permlane16_swap_b32_e32 v102, v104
	v_permlane16_swap_b32_e32 v103, v105
	global_store_dwordx4 v[140:141], v[102:105], off
	v_lshl_add_u64 v[140:141], v[140:141], 0, s[10:11]
	v_mul_f32_e32 v216, s40, v98
	v_mul_f32_e32 v217, s40, v99
	v_mul_f32_e32 v218, s40, v100
	v_mul_f32_e32 v219, s40, v101
	v_exp_f32_e32 v216, v216
	v_exp_f32_e32 v217, v217
	v_exp_f32_e32 v218, v218
	v_exp_f32_e32 v219, v219
	v_add_f32_e32 v216, 1.0, v216
	v_add_f32_e32 v217, 1.0, v217
	v_add_f32_e32 v218, 1.0, v218
	v_add_f32_e32 v219, 1.0, v219
	v_rcp_f32_e32 v216, v216
	v_rcp_f32_e32 v217, v217
	v_rcp_f32_e32 v218, v218
	v_rcp_f32_e32 v219, v219
	v_mul_f32_e32 v98, v98, v216
	v_mul_f32_e32 v99, v99, v217
	v_mul_f32_e32 v100, v100, v218
	v_mul_f32_e32 v101, v101, v219
	v_mul_f32_e32 v98, v98, v34
	v_mul_f32_e32 v99, v99, v35
	v_mul_f32_e32 v100, v100, v36
	v_mul_f32_e32 v101, v101, v37
	v_mul_f32_e32 v220, s40, v66
	v_mul_f32_e32 v221, s40, v67
	v_mul_f32_e32 v222, s40, v68
	v_mul_f32_e32 v223, s40, v69
	v_exp_f32_e32 v220, v220
	v_exp_f32_e32 v221, v221
	v_exp_f32_e32 v222, v222
	v_exp_f32_e32 v223, v223
	v_add_f32_e32 v220, 1.0, v220
	v_add_f32_e32 v221, 1.0, v221
	v_add_f32_e32 v222, 1.0, v222
	v_add_f32_e32 v223, 1.0, v223
	v_rcp_f32_e32 v220, v220
	v_rcp_f32_e32 v221, v221
	v_rcp_f32_e32 v222, v222
	v_rcp_f32_e32 v223, v223
	v_mul_f32_e32 v66, v66, v220
	v_mul_f32_e32 v67, v67, v221
	v_mul_f32_e32 v68, v68, v222
	v_mul_f32_e32 v69, v69, v223
	v_mul_f32_e32 v66, v66, v2
	v_mul_f32_e32 v67, v67, v3
	v_mul_f32_e32 v68, v68, v4
	v_mul_f32_e32 v69, v69, v5
	v_cvt_pk_bf16_f32 v98, v98, v99
	v_cvt_pk_bf16_f32 v99, v100, v101
	v_cvt_pk_bf16_f32 v100, v66, v67
	v_cvt_pk_bf16_f32 v101, v68, v69
	s_nop 1
	v_permlane16_swap_b32_e32 v98, v100
	v_permlane16_swap_b32_e32 v99, v101
	global_store_dwordx4 v[140:141], v[98:101], off
	v_readlane_b32 s42, v250, 7
	s_add_i32 s8, s8, s42
	s_cmpk_gt_i32 s8, 0xb57
	s_cbranch_scc0 .LBB0_124
	s_branch .LBB0_131

; #define LAS __attribute__((address_space(3)))
;     ...
;   const int nk = (nk_part < 0) ? (K >> 5) : nk_part;
;   const int lrow = tid >> 2, lpc = tid & 3;
;   const int lch = lpc ^ ((0x78 >> (((lrow >> 2) & 3) * 2)) & 3);
;   const u16* ga = A + (size_t)(m0 + lrow) * lda + kbeg + lch * 8;
;   const u16* gb = Bt + (size_t)(n0 + lrow) * K + kbeg + lch * 8;
;   const size_t ga1 = (size_t)64 * lda, gb1 = (size_t)64 * K;
;   const unsigned lds0 = (unsigned)(uintptr_t)(LAS char*)smem + (unsigned)__builtin_amdgcn_readfirstlane(wid) * 1024u;
;     ...
;   __syncthreads();
;   G2_STAGE(0); G2_STAGE(1);
; DEVI void run_phase(const Params& p, int ph, char* smem) {
;     ...
;           const int u_ = t - 512, tl_ = u_ / 2, q_ = u_ - tl_ * 2;
;           gemm_tile256<EPI_RESID_ATOMIC>(p, ox, 256, Bt, 256, (64 + (tl_ & 1)) * 256, (tl_ >> 1) * 128, nullptr, 0, smem, q_ * 128, 4, q_);
.LBB0_147:
	s_cmpk_gt_i32 s38, 0x1ff
	s_mov_b64 s[2:3], -1
	s_cbranch_scc0 .LBB0_208
	s_sub_i32 s98, s38, 512
	s_lshr_b32 s41, s98, 1
	s_and_b32 s99, s98, 1
	s_lshr_b32 s13, s41, 1
	s_and_b32 s41, s41, 1
	s_add_i32 s41, s41, 64
	v_readlane_b32 s2, v250, 5
	v_readlane_b32 s3, v250, 6
	v_readlane_b32 s98, v254, 62
	s_mul_i32 s1, s41, 0x20000
	s_add_u32 s4, s2, s1
	s_addc_u32 s5, s3, 0
	s_add_u32 s4, s4, 0xe700000
	s_addc_u32 s5, s5, 0
	s_mul_i32 s1, s98, 0x80000
	s_mul_i32 s12, s13, 0x10000
	s_add_i32 s1, s1, s12
	s_add_u32 s8, s2, s1
	s_addc_u32 s9, s3, 0
	s_add_u32 s8, s8, 0x16c00000
	s_addc_u32 s9, s9, 0
	s_mul_i32 s1, s99, 256
	s_add_u32 s4, s4, s1
	s_addc_u32 s5, s5, 0
	s_mul_i32 s1, s99, 512
	s_add_u32 s8, s8, s1
	s_addc_u32 s9, s9, 0
	s_movk_i32 s0, 0x78
	v_lshrrev_b32_e32 v0, 2, v145
	v_and_b32_e32 v131, 3, v145
	v_bfe_u32 v136, v145, 4, 2
	v_lshlrev_b32_e32 v136, 1, v136
	v_lshrrev_b32_e64 v136, v136, s0
	v_and_b32_e32 v136, 3, v136
	v_xor_b32_e32 v131, v131, v136
	v_lshlrev_b32_e32 v131, 4, v131
	s_movk_i32 s12, 0x200
	v_mad_u32_u24 v0, v0, s12, v131
	v_bfe_u32 v137, v145, 2, 1
	s_movk_i32 s12, 0x1c0
	v_mul_u32_u24_e32 v136, s12, v137
	v_sub_u32_e32 v136, v0, v136
	v_mov_b32_e32 v137, 0
	v_lshl_add_u64 v[134:135], s[8:9], 0, v[136:137]
	v_bfe_u32 v137, v145, 2, 1
	s_mov_b32 s10, 64
	s_mov_b32 s11, 0
	v_lshl_add_u64 v[132:133], s[4:5], 0, v[0:1]
	v_bfe_u32 v136, v145, 2, 2
	v_lshlrev_b32_e32 v136, 1, v136
	v_lshrrev_b32_e64 v136, v136, s0
	v_and_b32_e32 v136, 3, v136
	v_bfe_u32 v137, v145, 4, 2
	v_xor_b32_e32 v136, v136, v137
	v_lshlrev_b32_e32 v136, 4, v136
	v_and_b32_e32 v131, 15, v145
	v_lshl_or_b32 v136, v131, 6, v136
	v_bfe_u32 v137, v145, 6, 1
	v_lshl_or_b32 v137, v137, 12, v136
	v_lshrrev_b32_e32 v0, 7, v145
	v_lshl_or_b32 v136, v0, 13, v136
	v_and_b32_e32 v140, 1, v131
	v_lshl_or_b32 v131, v0, 7, v131
	v_bfe_u32 v0, v145, 4, 2
	v_lshlrev_b32_e32 v0, 3, v0
	v_bfe_u32 v141, v145, 6, 1
	s_lshl_b32 s1, s41, 19
	s_lshl_b32 s12, s13, 8
	s_add_i32 s1, s1, s12
	s_add_u32 s4, s2, s1
	s_addc_u32 s5, s3, 0
	s_add_u32 s4, s4, 0x4200000
	s_addc_u32 s5, s5, 0
	v_lshlrev_b32_e32 v138, 11, v131
	v_lshl_add_u32 v138, v141, 7, v138
	v_bfe_u32 v139, v145, 4, 1
	v_lshl_add_u32 v138, v139, 5, v138
	v_bfe_u32 v139, v145, 5, 1
	v_lshl_add_u32 v138, v139, 4, v138
	v_mov_b32_e32 v139, 0
	v_lshl_add_u64 v[138:139], s[4:5], 0, v[138:139]
	s_and_b32 s1, s41, 1
	s_lshl_b32 s1, s1, 20
	s_lshl_b32 s12, s99, 21
	s_add_i32 s1, s1, s12
	s_lshl_b32 s12, s13, 9
	s_add_i32 s1, s1, s12
	s_add_u32 s8, s2, s1
	s_addc_u32 s9, s3, 0
	s_add_u32 s8, s8, 0x1dcc0000
	s_addc_u32 s9, s9, 0
	v_lshlrev_b32_e32 v140, 12, v131
	v_lshl_add_u32 v140, v141, 8, v140
	v_lshl_add_u32 v140, v0, 1, v140
	v_mov_b32_e32 v141, 0
	v_lshl_add_u64 v[140:141], s[8:9], 0, v[140:141]
	s_mov_b32 s2, 0x8000
	s_mov_b32 s3, 0
	v_lshrrev_b32_e32 v0, 6, v145
	v_lshlrev_b32_e32 v0, 10, v0
	s_nop 0
	v_readfirstlane_b32 s98, v0
	s_mov_b32 s39, m0
	s_mov_b32 s4, 128
	s_mov_b32 s5, 0
	s_barrier
	s_add_i32 s13, s98, 0x0
	s_mov_b32 m0, s13
	v_lshl_add_u64 v[142:143], v[132:133], 0, s[2:3]
	global_load_lds_dwordx4 v[132:133], off
	s_add_i32 m0, m0, 0x1000
	s_nop 0
	global_load_lds_dwordx4 v[142:143], off
	v_lshl_add_u64 v[142:143], v[142:143], 0, s[2:3]
	s_add_i32 m0, m0, 0x1000
	s_nop 0
	global_load_lds_dwordx4 v[142:143], off
	v_lshl_add_u64 v[142:143], v[142:143], 0, s[2:3]
	s_add_i32 m0, m0, 0x1000
	s_nop 0
	global_load_lds_dwordx4 v[142:143], off
	s_add_i32 m0, m0, 0x1000
	v_lshl_add_u64 v[142:143], v[134:135], 0, s[2:3]
	s_nop 0
	global_load_lds_dwordx4 v[134:135], off
	s_add_i32 m0, m0, 0x1000
	v_lshl_add_u64 v[132:133], v[132:133], 0, s[10:11]
	s_nop 0
	global_load_lds_dwordx4 v[142:143], off
	v_lshl_add_u64 v[134:135], v[134:135], 0, s[4:5]
	s_nop 0
	s_add_i32 s13, s98, 0x6000
	s_mov_b32 m0, s13
	v_lshl_add_u64 v[142:143], v[132:133], 0, s[2:3]
	global_load_lds_dwordx4 v[132:133], off
	s_add_i32 m0, m0, 0x1000
	s_nop 0
	global_load_lds_dwordx4 v[142:143], off
	v_lshl_add_u64 v[142:143], v[142:143], 0, s[2:3]
	s_add_i32 m0, m0, 0x1000
	s_nop 0
	global_load_lds_dwordx4 v[142:143], off
	v_lshl_add_u64 v[142:143], v[142:143], 0, s[2:3]
	s_add_i32 m0, m0, 0x1000
	s_nop 0
	global_load_lds_dwordx4 v[142:143], off
	s_add_i32 m0, m0, 0x1000
	v_lshl_add_u64 v[142:143], v[134:135], 0, s[2:3]
	s_nop 0
	global_load_lds_dwordx4 v[134:135], off
	s_add_i32 m0, m0, 0x1000
	v_lshl_add_u64 v[132:133], v[132:133], 0, s[10:11]
	s_nop 0
	global_load_lds_dwordx4 v[142:143], off
	v_lshl_add_u64 v[134:135], v[134:135], 0, s[4:5]
	s_nop 0
	s_add_i32 s13, s98, 0xc000
	s_mov_b32 m0, s13
	v_lshl_add_u64 v[142:143], v[132:133], 0, s[2:3]
	global_load_lds_dwordx4 v[132:133], off
	s_add_i32 m0, m0, 0x1000
	s_nop 0
	global_load_lds_dwordx4 v[142:143], off
	v_lshl_add_u64 v[142:143], v[142:143], 0, s[2:3]
	s_add_i32 m0, m0, 0x1000
	s_nop 0
	global_load_lds_dwordx4 v[142:143], off
	v_lshl_add_u64 v[142:143], v[142:143], 0, s[2:3]
	s_add_i32 m0, m0, 0x1000
	s_nop 0
	global_load_lds_dwordx4 v[142:143], off
	s_add_i32 m0, m0, 0x1000
	v_lshl_add_u64 v[142:143], v[134:135], 0, s[2:3]
	s_nop 0
	global_load_lds_dwordx4 v[134:135], off
	s_add_i32 m0, m0, 0x1000
	v_lshl_add_u64 v[132:133], v[132:133], 0, s[10:11]
	s_nop 0
	global_load_lds_dwordx4 v[142:143], off
	v_lshl_add_u64 v[134:135], v[134:135], 0, s[4:5]
	s_nop 0
	v_mov_b32_e32 v2, 0
	v_mov_b32_e32 v3, 0
	v_mov_b32_e32 v4, 0
	v_mov_b32_e32 v5, 0
	v_mov_b32_e32 v6, 0
	v_mov_b32_e32 v7, 0
	v_mov_b32_e32 v8, 0
	v_mov_b32_e32 v9, 0
	v_mov_b32_e32 v10, 0
	v_mov_b32_e32 v11, 0
	v_mov_b32_e32 v12, 0
	v_mov_b32_e32 v13, 0
	v_mov_b32_e32 v14, 0
	v_mov_b32_e32 v15, 0
	v_mov_b32_e32 v16, 0
; #define LAS __attribute__((address_space(3)))
;     ...
;   f32x4 acc[4][8];
; #pragma unroll
;   for (int i = 0; i < 4; i++)
; #pragma unroll
;     for (int j = 0; j < 8; j++) acc[i][j] = (f32x4){0.f, 0.f, 0.f, 0.f};
;   const int nk = (nk_part < 0) ? (K >> 5) : nk_part;
;   const int lrow = tid >> 2, lpc = tid & 3;
;   const int lch = lpc ^ ((0x78 >> (((lrow >> 2) & 3) * 2)) & 3);
;   const u16* ga = A + (size_t)(m0 + lrow) * lda + kbeg + lch * 8;
;   const u16* gb = Bt + (size_t)(n0 + lrow) * K + kbeg + lch * 8;
;   const size_t ga1 = (size_t)64 * lda, gb1 = (size_t)64 * K;
;   const unsigned lds0 = (unsigned)(uintptr_t)(LAS char*)smem + (unsigned)__builtin_amdgcn_readfirstlane(wid) * 1024u;
;     ...
;   __syncthreads();
;   G2_STAGE(0); G2_STAGE(1);
;   const int fsw = (0x78 >> (((r16 >> 2) & 3) * 2)) & 3;
;   const int aoff = (wm * 128 + r16) * 64 + ((quad ^ fsw) << 4);
;   const int boff = 16384 + (wn * 64 + r16) * 64 + ((quad ^ fsw) << 4);
;   for (int kt = 0; kt < nk; kt++) {
;     if (kt + 1 < nk) asm volatile("s_waitcnt vmcnt(6)" ::: "memory");
;     else asm volatile("s_waitcnt vmcnt(0)" ::: "memory");
;     __builtin_amdgcn_s_barrier();
;     asm volatile("" ::: "memory");
;     if (kt + 2 < nk) G2_STAGE(kt + 2);
;     const char* cS = smem + (kt % 3) * 24576;
;     bf16x8 xa[8], wb[4];
; #pragma unroll
;     for (int f = 0; f < 8; f++) xa[f] = *(const bf16x8*)(cS + aoff + f * 1024);
; #pragma unroll
;     for (int f = 0; f < 4; f++) wb[f] = *(const bf16x8*)(cS + boff + f * 1024);
; #pragma unroll
;     for (int nf = 0; nf < 4; nf++)
; #pragma unroll
;       for (int mf = 0; mf < 8; mf++)
;         acc[nf][mf] = __builtin_amdgcn_mfma_f32_16x16x32_bf16(wb[nf], xa[mf], acc[nf][mf], 0, 0, 0);
	v_mov_b32_e32 v17, 0
	v_mov_b32_e32 v18, 0
	v_mov_b32_e32 v19, 0
	v_mov_b32_e32 v20, 0
	v_mov_b32_e32 v21, 0
	v_mov_b32_e32 v22, 0
	v_mov_b32_e32 v23, 0
	v_mov_b32_e32 v24, 0
	v_mov_b32_e32 v25, 0
	v_mov_b32_e32 v26, 0
	v_mov_b32_e32 v27, 0
	v_mov_b32_e32 v28, 0
	v_mov_b32_e32 v29, 0
	v_mov_b32_e32 v30, 0
	v_mov_b32_e32 v31, 0
	v_mov_b32_e32 v32, 0
	v_mov_b32_e32 v33, 0
	v_mov_b32_e32 v34, 0
	v_mov_b32_e32 v35, 0
	v_mov_b32_e32 v36, 0
	v_mov_b32_e32 v37, 0
	v_mov_b32_e32 v38, 0
	v_mov_b32_e32 v39, 0
	v_mov_b32_e32 v40, 0
	v_mov_b32_e32 v41, 0
	v_mov_b32_e32 v42, 0
	v_mov_b32_e32 v43, 0
	v_mov_b32_e32 v44, 0
	v_mov_b32_e32 v45, 0
	v_mov_b32_e32 v46, 0
	v_mov_b32_e32 v47, 0
	v_mov_b32_e32 v48, 0
	v_mov_b32_e32 v49, 0
	v_mov_b32_e32 v50, 0
	v_mov_b32_e32 v51, 0
	v_mov_b32_e32 v52, 0
	v_mov_b32_e32 v53, 0
	v_mov_b32_e32 v54, 0
	v_mov_b32_e32 v55, 0
	v_mov_b32_e32 v56, 0
	v_mov_b32_e32 v57, 0
	v_mov_b32_e32 v58, 0
	v_mov_b32_e32 v59, 0
	v_mov_b32_e32 v60, 0
	v_mov_b32_e32 v61, 0
	v_mov_b32_e32 v62, 0
	v_mov_b32_e32 v63, 0
	v_mov_b32_e32 v64, 0
	v_mov_b32_e32 v65, 0
	v_mov_b32_e32 v66, 0
	v_mov_b32_e32 v67, 0
	v_mov_b32_e32 v68, 0
	v_mov_b32_e32 v69, 0
	v_mov_b32_e32 v70, 0
	v_mov_b32_e32 v71, 0
	v_mov_b32_e32 v72, 0
	v_mov_b32_e32 v73, 0
	v_mov_b32_e32 v74, 0
	v_mov_b32_e32 v75, 0
	v_mov_b32_e32 v76, 0
	v_mov_b32_e32 v77, 0
	v_mov_b32_e32 v78, 0
	v_mov_b32_e32 v79, 0
	v_mov_b32_e32 v80, 0
	v_mov_b32_e32 v81, 0
	v_mov_b32_e32 v82, 0
	v_mov_b32_e32 v83, 0
	v_mov_b32_e32 v84, 0
	v_mov_b32_e32 v85, 0
	v_mov_b32_e32 v86, 0
	v_mov_b32_e32 v87, 0
	v_mov_b32_e32 v88, 0
	v_mov_b32_e32 v89, 0
	v_mov_b32_e32 v90, 0
	v_mov_b32_e32 v91, 0
	v_mov_b32_e32 v92, 0
	v_mov_b32_e32 v93, 0
	v_mov_b32_e32 v94, 0
	v_mov_b32_e32 v95, 0
	v_mov_b32_e32 v96, 0
	v_mov_b32_e32 v97, 0
	v_mov_b32_e32 v98, 0
	v_mov_b32_e32 v99, 0
	v_mov_b32_e32 v100, 0
	v_mov_b32_e32 v101, 0
	v_mov_b32_e32 v102, 0
	v_mov_b32_e32 v103, 0
	v_mov_b32_e32 v104, 0
	v_mov_b32_e32 v105, 0
	v_mov_b32_e32 v106, 0
	v_mov_b32_e32 v107, 0
	v_mov_b32_e32 v108, 0
	v_mov_b32_e32 v109, 0
	v_mov_b32_e32 v110, 0
	v_mov_b32_e32 v111, 0
	v_mov_b32_e32 v112, 0
	v_mov_b32_e32 v113, 0
	v_mov_b32_e32 v114, 0
	v_mov_b32_e32 v115, 0
	v_mov_b32_e32 v116, 0
	v_mov_b32_e32 v117, 0
	v_mov_b32_e32 v118, 0
	v_mov_b32_e32 v119, 0
	v_mov_b32_e32 v120, 0
	v_mov_b32_e32 v121, 0
	v_mov_b32_e32 v122, 0
	v_mov_b32_e32 v123, 0
	v_mov_b32_e32 v124, 0
	v_mov_b32_e32 v125, 0
	v_mov_b32_e32 v126, 0
	v_mov_b32_e32 v127, 0
	v_mov_b32_e32 v128, 0
	v_mov_b32_e32 v129, 0
	s_waitcnt vmcnt(12)
	s_barrier
	ds_read_b128 v[146:149], v136 offset:0
	ds_read_b128 v[152:155], v136 offset:1024
	ds_read_b128 v[156:159], v136 offset:2048
	ds_read_b128 v[162:165], v136 offset:3072
	ds_read_b128 v[166:169], v136 offset:4096
	ds_read_b128 v[170:173], v136 offset:5120
	ds_read_b128 v[176:179], v136 offset:6144
	ds_read_b128 v[180:183], v136 offset:7168
	ds_read_b128 v[184:187], v137 offset:16384
	ds_read_b128 v[188:191], v137 offset:17408
	ds_read_b128 v[192:195], v137 offset:18432
	ds_read_b128 v[196:199], v137 offset:19456
	s_movk_i32 s1, 0x6000
	s_mov_b32 s12, 0
	.p2align 3
	s_waitcnt vmcnt(6) lgkmcnt(0)
	s_barrier
	s_setprio 1
	v_add_u32_e32 v144, s1, v136
	v_mfma_f32_16x16x32_bf16 v[126:129], v[184:187], v[146:149], v[126:129]
	ds_read_b128 v[200:203], v144 offset:0
	v_mfma_f32_16x16x32_bf16 v[122:125], v[184:187], v[152:155], v[122:125]
	ds_read_b128 v[204:207], v144 offset:1024
	v_mfma_f32_16x16x32_bf16 v[118:121], v[184:187], v[156:159], v[118:121]
	ds_read_b128 v[208:211], v144 offset:2048
	v_mfma_f32_16x16x32_bf16 v[114:117], v[184:187], v[162:165], v[114:117]
	ds_read_b128 v[212:215], v144 offset:3072
	v_mfma_f32_16x16x32_bf16 v[110:113], v[184:187], v[166:169], v[110:113]
	ds_read_b128 v[216:219], v144 offset:4096
	v_mfma_f32_16x16x32_bf16 v[106:109], v[184:187], v[170:173], v[106:109]
	ds_read_b128 v[220:223], v144 offset:5120
	v_mfma_f32_16x16x32_bf16 v[102:105], v[184:187], v[176:179], v[102:105]
	ds_read_b128 v[224:227], v144 offset:6144
	v_mfma_f32_16x16x32_bf16 v[98:101], v[184:187], v[180:183], v[98:101]
	ds_read_b128 v[228:231], v144 offset:7168
	v_mfma_f32_16x16x32_bf16 v[94:97], v[188:191], v[146:149], v[94:97]
	v_add_u32_e64 v144, s1, v137
	v_mfma_f32_16x16x32_bf16 v[90:93], v[188:191], v[152:155], v[90:93]
	v_mfma_f32_16x16x32_bf16 v[86:89], v[188:191], v[156:159], v[86:89]
	ds_read_b128 v[232:235], v144 offset:16384
	v_mfma_f32_16x16x32_bf16 v[82:85], v[188:191], v[162:165], v[82:85]
	ds_read_b128 v[236:239], v144 offset:17408
	v_mfma_f32_16x16x32_bf16 v[78:81], v[188:191], v[166:169], v[78:81]
	ds_read_b128 v[240:243], v144 offset:18432
	v_mfma_f32_16x16x32_bf16 v[74:77], v[188:191], v[170:173], v[74:77]
	ds_read_b128 v[244:247], v144 offset:19456
	v_mfma_f32_16x16x32_bf16 v[70:73], v[188:191], v[176:179], v[70:73]
	s_add_i32 s13, s98, s12
	s_mov_b32 m0, s13
	v_lshl_add_u64 v[142:143], v[132:133], 0, s[2:3]
	v_mfma_f32_16x16x32_bf16 v[66:69], v[188:191], v[180:183], v[66:69]
	global_load_lds_dwordx4 v[132:133], off
	s_add_i32 m0, m0, 0x1000
	v_mfma_f32_16x16x32_bf16 v[62:65], v[192:195], v[146:149], v[62:65]
	v_mfma_f32_16x16x32_bf16 v[58:61], v[192:195], v[152:155], v[58:61]
	v_mfma_f32_16x16x32_bf16 v[54:57], v[192:195], v[156:159], v[54:57]
	global_load_lds_dwordx4 v[142:143], off
	v_lshl_add_u64 v[142:143], v[142:143], 0, s[2:3]
	s_add_i32 m0, m0, 0x1000
	v_mfma_f32_16x16x32_bf16 v[50:53], v[192:195], v[162:165], v[50:53]
	v_mfma_f32_16x16x32_bf16 v[46:49], v[192:195], v[166:169], v[46:49]
	v_mfma_f32_16x16x32_bf16 v[42:45], v[192:195], v[170:173], v[42:45]
	global_load_lds_dwordx4 v[142:143], off
	v_lshl_add_u64 v[142:143], v[142:143], 0, s[2:3]
	s_add_i32 m0, m0, 0x1000
	v_mfma_f32_16x16x32_bf16 v[38:41], v[192:195], v[176:179], v[38:41]
	v_mfma_f32_16x16x32_bf16 v[34:37], v[192:195], v[180:183], v[34:37]
	v_mfma_f32_16x16x32_bf16 v[30:33], v[196:199], v[146:149], v[30:33]
	global_load_lds_dwordx4 v[142:143], off
	s_add_i32 m0, m0, 0x1000
	v_lshl_add_u64 v[142:143], v[134:135], 0, s[2:3]
	v_mfma_f32_16x16x32_bf16 v[26:29], v[196:199], v[152:155], v[26:29]
	v_mfma_f32_16x16x32_bf16 v[22:25], v[196:199], v[156:159], v[22:25]
	v_mfma_f32_16x16x32_bf16 v[18:21], v[196:199], v[162:165], v[18:21]
	global_load_lds_dwordx4 v[134:135], off
	s_add_i32 m0, m0, 0x1000
	v_lshl_add_u64 v[132:133], v[132:133], 0, s[10:11]
	v_mfma_f32_16x16x32_bf16 v[14:17], v[196:199], v[166:169], v[14:17]
	v_mfma_f32_16x16x32_bf16 v[10:13], v[196:199], v[170:173], v[10:13]
	v_mfma_f32_16x16x32_bf16 v[6:9], v[196:199], v[176:179], v[6:9]
	global_load_lds_dwordx4 v[142:143], off
	v_lshl_add_u64 v[134:135], v[134:135], 0, s[4:5]
	v_mfma_f32_16x16x32_bf16 v[2:5], v[196:199], v[180:183], v[2:5]
	s_setprio 0
	s_mov_b32 s12, s1
	s_add_i32 s1, s1, 0x6000
	s_cmp_eq_u32 s1, 0x12000
	s_cselect_b32 s1, 0, s1
	s_nop 0
	.p2align 3
	s_waitcnt vmcnt(6) lgkmcnt(0)
	s_barrier
;     ...
;   for (int kt = 0; kt < nk; kt++) {
;     if (kt + 1 < nk) asm volatile("s_waitcnt vmcnt(6)" ::: "memory");
;     else asm volatile("s_waitcnt vmcnt(0)" ::: "memory");
;     __builtin_amdgcn_s_barrier();
;     asm volatile("" ::: "memory");
;     if (kt + 2 < nk) G2_STAGE(kt + 2);
;     const char* cS = smem + (kt % 3) * 24576;
;     bf16x8 xa[8], wb[4];
; #pragma unroll
;     for (int f = 0; f < 8; f++) xa[f] = *(const bf16x8*)(cS + aoff + f * 1024);
; #pragma unroll
;     for (int f = 0; f < 4; f++) wb[f] = *(const bf16x8*)(cS + boff + f * 1024);
; #pragma unroll
;     for (int nf = 0; nf < 4; nf++)
; #pragma unroll
;       for (int mf = 0; mf < 8; mf++)
;         acc[nf][mf] = __builtin_amdgcn_mfma_f32_16x16x32_bf16(wb[nf], xa[mf], acc[nf][mf], 0, 0, 0);
	s_setprio 1
	v_add_u32_e32 v144, s1, v136
	v_mfma_f32_16x16x32_bf16 v[126:129], v[232:235], v[200:203], v[126:129]
	ds_read_b128 v[146:149], v144 offset:0
	v_mfma_f32_16x16x32_bf16 v[122:125], v[232:235], v[204:207], v[122:125]
	ds_read_b128 v[152:155], v144 offset:1024
	v_mfma_f32_16x16x32_bf16 v[118:121], v[232:235], v[208:211], v[118:121]
	ds_read_b128 v[156:159], v144 offset:2048
	v_mfma_f32_16x16x32_bf16 v[114:117], v[232:235], v[212:215], v[114:117]
	ds_read_b128 v[162:165], v144 offset:3072
	v_mfma_f32_16x16x32_bf16 v[110:113], v[232:235], v[216:219], v[110:113]
	ds_read_b128 v[166:169], v144 offset:4096
	v_mfma_f32_16x16x32_bf16 v[106:109], v[232:235], v[220:223], v[106:109]
	ds_read_b128 v[170:173], v144 offset:5120
	v_mfma_f32_16x16x32_bf16 v[102:105], v[232:235], v[224:227], v[102:105]
	ds_read_b128 v[176:179], v144 offset:6144
	v_mfma_f32_16x16x32_bf16 v[98:101], v[232:235], v[228:231], v[98:101]
	ds_read_b128 v[180:183], v144 offset:7168
	v_mfma_f32_16x16x32_bf16 v[94:97], v[236:239], v[200:203], v[94:97]
	v_add_u32_e64 v144, s1, v137
	v_mfma_f32_16x16x32_bf16 v[90:93], v[236:239], v[204:207], v[90:93]
	v_mfma_f32_16x16x32_bf16 v[86:89], v[236:239], v[208:211], v[86:89]
	ds_read_b128 v[184:187], v144 offset:16384
	v_mfma_f32_16x16x32_bf16 v[82:85], v[236:239], v[212:215], v[82:85]
	ds_read_b128 v[188:191], v144 offset:17408
	v_mfma_f32_16x16x32_bf16 v[78:81], v[236:239], v[216:219], v[78:81]
	ds_read_b128 v[192:195], v144 offset:18432
	v_mfma_f32_16x16x32_bf16 v[74:77], v[236:239], v[220:223], v[74:77]
	ds_read_b128 v[196:199], v144 offset:19456
	v_mfma_f32_16x16x32_bf16 v[70:73], v[236:239], v[224:227], v[70:73]
	v_mfma_f32_16x16x32_bf16 v[66:69], v[236:239], v[228:231], v[66:69]
	v_mfma_f32_16x16x32_bf16 v[62:65], v[240:243], v[200:203], v[62:65]
	v_mfma_f32_16x16x32_bf16 v[58:61], v[240:243], v[204:207], v[58:61]
	v_mfma_f32_16x16x32_bf16 v[54:57], v[240:243], v[208:211], v[54:57]
	v_mfma_f32_16x16x32_bf16 v[50:53], v[240:243], v[212:215], v[50:53]
	v_mfma_f32_16x16x32_bf16 v[46:49], v[240:243], v[216:219], v[46:49]
	v_mfma_f32_16x16x32_bf16 v[42:45], v[240:243], v[220:223], v[42:45]
	v_mfma_f32_16x16x32_bf16 v[38:41], v[240:243], v[224:227], v[38:41]
	v_mfma_f32_16x16x32_bf16 v[34:37], v[240:243], v[228:231], v[34:37]
	v_mfma_f32_16x16x32_bf16 v[30:33], v[244:247], v[200:203], v[30:33]
	v_mfma_f32_16x16x32_bf16 v[26:29], v[244:247], v[204:207], v[26:29]
	v_mfma_f32_16x16x32_bf16 v[22:25], v[244:247], v[208:211], v[22:25]
	v_mfma_f32_16x16x32_bf16 v[18:21], v[244:247], v[212:215], v[18:21]
	v_mfma_f32_16x16x32_bf16 v[14:17], v[244:247], v[216:219], v[14:17]
	v_mfma_f32_16x16x32_bf16 v[10:13], v[244:247], v[220:223], v[10:13]
	v_mfma_f32_16x16x32_bf16 v[6:9], v[244:247], v[224:227], v[6:9]
	v_mfma_f32_16x16x32_bf16 v[2:5], v[244:247], v[228:231], v[2:5]
	s_setprio 0
	s_mov_b32 s12, s1
	s_add_i32 s1, s1, 0x6000
	s_cmp_eq_u32 s1, 0x12000
	s_cselect_b32 s1, 0, s1
	s_nop 0
	.p2align 3
	s_waitcnt vmcnt(0) lgkmcnt(0)
	s_barrier
	s_setprio 1
	v_add_u32_e32 v144, s1, v136
	v_mfma_f32_16x16x32_bf16 v[126:129], v[184:187], v[146:149], v[126:129]
	ds_read_b128 v[200:203], v144 offset:0
	v_mfma_f32_16x16x32_bf16 v[122:125], v[184:187], v[152:155], v[122:125]
	ds_read_b128 v[204:207], v144 offset:1024
	v_mfma_f32_16x16x32_bf16 v[118:121], v[184:187], v[156:159], v[118:121]
	ds_read_b128 v[208:211], v144 offset:2048
	v_mfma_f32_16x16x32_bf16 v[114:117], v[184:187], v[162:165], v[114:117]
	ds_read_b128 v[212:215], v144 offset:3072
	v_mfma_f32_16x16x32_bf16 v[110:113], v[184:187], v[166:169], v[110:113]
	ds_read_b128 v[216:219], v144 offset:4096
	v_mfma_f32_16x16x32_bf16 v[106:109], v[184:187], v[170:173], v[106:109]
	ds_read_b128 v[220:223], v144 offset:5120
	v_mfma_f32_16x16x32_bf16 v[102:105], v[184:187], v[176:179], v[102:105]
	ds_read_b128 v[224:227], v144 offset:6144
	v_mfma_f32_16x16x32_bf16 v[98:101], v[184:187], v[180:183], v[98:101]
	ds_read_b128 v[228:231], v144 offset:7168
	v_mfma_f32_16x16x32_bf16 v[94:97], v[188:191], v[146:149], v[94:97]
	v_add_u32_e64 v144, s1, v137
	v_mfma_f32_16x16x32_bf16 v[90:93], v[188:191], v[152:155], v[90:93]
	v_mfma_f32_16x16x32_bf16 v[86:89], v[188:191], v[156:159], v[86:89]
	ds_read_b128 v[232:235], v144 offset:16384
	v_mfma_f32_16x16x32_bf16 v[82:85], v[188:191], v[162:165], v[82:85]
	ds_read_b128 v[236:239], v144 offset:17408
	v_mfma_f32_16x16x32_bf16 v[78:81], v[188:191], v[166:169], v[78:81]
	ds_read_b128 v[240:243], v144 offset:18432
	v_mfma_f32_16x16x32_bf16 v[74:77], v[188:191], v[170:173], v[74:77]
	ds_read_b128 v[244:247], v144 offset:19456
	v_mfma_f32_16x16x32_bf16 v[70:73], v[188:191], v[176:179], v[70:73]
	v_mfma_f32_16x16x32_bf16 v[66:69], v[188:191], v[180:183], v[66:69]
	v_mfma_f32_16x16x32_bf16 v[62:65], v[192:195], v[146:149], v[62:65]
	v_mfma_f32_16x16x32_bf16 v[58:61], v[192:195], v[152:155], v[58:61]
	v_mfma_f32_16x16x32_bf16 v[54:57], v[192:195], v[156:159], v[54:57]
	v_mfma_f32_16x16x32_bf16 v[50:53], v[192:195], v[162:165], v[50:53]
	v_mfma_f32_16x16x32_bf16 v[46:49], v[192:195], v[166:169], v[46:49]
	v_mfma_f32_16x16x32_bf16 v[42:45], v[192:195], v[170:173], v[42:45]
	v_mfma_f32_16x16x32_bf16 v[38:41], v[192:195], v[176:179], v[38:41]
	v_mfma_f32_16x16x32_bf16 v[34:37], v[192:195], v[180:183], v[34:37]
	v_mfma_f32_16x16x32_bf16 v[30:33], v[196:199], v[146:149], v[30:33]
	v_mfma_f32_16x16x32_bf16 v[26:29], v[196:199], v[152:155], v[26:29]
	v_mfma_f32_16x16x32_bf16 v[22:25], v[196:199], v[156:159], v[22:25]
	v_mfma_f32_16x16x32_bf16 v[18:21], v[196:199], v[162:165], v[18:21]
	v_mfma_f32_16x16x32_bf16 v[14:17], v[196:199], v[166:169], v[14:17]
	v_mfma_f32_16x16x32_bf16 v[10:13], v[196:199], v[170:173], v[10:13]
	v_mfma_f32_16x16x32_bf16 v[6:9], v[196:199], v[176:179], v[6:9]
	v_mfma_f32_16x16x32_bf16 v[2:5], v[196:199], v[180:183], v[2:5]
	s_setprio 0
	s_mov_b32 s12, s1
	s_add_i32 s1, s1, 0x6000
	s_cmp_eq_u32 s1, 0x12000
	s_cselect_b32 s1, 0, s1
	s_nop 0
	s_mov_b32 s4, 0x8000
	s_mov_b32 s5, 0
	s_mov_b32 s8, 0x10000
	s_mov_b32 s9, 0
	s_mov_b32 s40, 0x3fd744fd
	.p2align 3
	s_waitcnt lgkmcnt(0)
; DEVI float blo(unsigned u) { return __uint_as_float(u << 16); }
; DEVI float bhi(unsigned u) { return __uint_as_float(u & 0xffff0000u); }
;     ...
;   for (int kt = 0; kt < nk; kt++) {
;     if (kt + 1 < nk) asm volatile("s_waitcnt vmcnt(6)" ::: "memory");
;     else asm volatile("s_waitcnt vmcnt(0)" ::: "memory");
;     __builtin_amdgcn_s_barrier();
;     asm volatile("" ::: "memory");
;     if (kt + 2 < nk) G2_STAGE(kt + 2);
;     const char* cS = smem + (kt % 3) * 24576;
;     bf16x8 xa[8], wb[4];
; #pragma unroll
;     for (int f = 0; f < 8; f++) xa[f] = *(const bf16x8*)(cS + aoff + f * 1024);
; #pragma unroll
;     for (int f = 0; f < 4; f++) wb[f] = *(const bf16x8*)(cS + boff + f * 1024);
; #pragma unroll
;     for (int nf = 0; nf < 4; nf++)
; #pragma unroll
;       for (int mf = 0; mf < 8; mf++)
;         acc[nf][mf] = __builtin_amdgcn_mfma_f32_16x16x32_bf16(wb[nf], xa[mf], acc[nf][mf], 0, 0, 0);
;     ...
;         const int col = n0 + wn * 64 + nf * 16 + quad * 4;
;         f32x4 a = acc[nf][mf];
;         if (EPI == EPI_RESID || EPI == EPI_RESID_ATOMIC) {
;           f32x4 x = a;
;           if (EPI == EPI_RESID || kpart == 0) {
;             const u32x2 xr = *(const u32x2*)((const u16*)(p.ws + WS_XB) + (size_t)row * 1024 + col);
;             x[0] += ALPHA * blo(xr[0]); x[1] += ALPHA * bhi(xr[0]); x[2] += ALPHA * blo(xr[1]); x[3] += ALPHA * bhi(xr[1]);
;           }
;           if (EPI == EPI_RESID) *(f32x4*)((float*)(p.ws + WS_XF) + (size_t)row * 1024 + col) = x;
;           else *(f32x4*)((float*)(p.ws + WS_SLAB) + ((size_t)kpart * 512 + (row - T_P)) * 1024 + col) = x;
	s_nop 0
	v_mfma_f32_16x16x32_bf16 v[126:129], v[232:235], v[200:203], v[126:129]
	v_mfma_f32_16x16x32_bf16 v[122:125], v[232:235], v[204:207], v[122:125]
	v_mfma_f32_16x16x32_bf16 v[118:121], v[232:235], v[208:211], v[118:121]
	v_mfma_f32_16x16x32_bf16 v[114:117], v[232:235], v[212:215], v[114:117]
	v_mfma_f32_16x16x32_bf16 v[110:113], v[232:235], v[216:219], v[110:113]
	v_mfma_f32_16x16x32_bf16 v[106:109], v[232:235], v[220:223], v[106:109]
	v_mfma_f32_16x16x32_bf16 v[102:105], v[232:235], v[224:227], v[102:105]
	v_mfma_f32_16x16x32_bf16 v[98:101], v[232:235], v[228:231], v[98:101]
	v_mfma_f32_16x16x32_bf16 v[94:97], v[236:239], v[200:203], v[94:97]
	v_mfma_f32_16x16x32_bf16 v[90:93], v[236:239], v[204:207], v[90:93]
	v_mfma_f32_16x16x32_bf16 v[86:89], v[236:239], v[208:211], v[86:89]
	v_mfma_f32_16x16x32_bf16 v[82:85], v[236:239], v[212:215], v[82:85]
	v_mfma_f32_16x16x32_bf16 v[78:81], v[236:239], v[216:219], v[78:81]
	v_mfma_f32_16x16x32_bf16 v[74:77], v[236:239], v[220:223], v[74:77]
	v_mfma_f32_16x16x32_bf16 v[70:73], v[236:239], v[224:227], v[70:73]
	v_mfma_f32_16x16x32_bf16 v[66:69], v[236:239], v[228:231], v[66:69]
	v_mfma_f32_16x16x32_bf16 v[62:65], v[240:243], v[200:203], v[62:65]
	v_mfma_f32_16x16x32_bf16 v[58:61], v[240:243], v[204:207], v[58:61]
	v_mfma_f32_16x16x32_bf16 v[54:57], v[240:243], v[208:211], v[54:57]
	v_mfma_f32_16x16x32_bf16 v[50:53], v[240:243], v[212:215], v[50:53]
	v_mfma_f32_16x16x32_bf16 v[46:49], v[240:243], v[216:219], v[46:49]
	v_mfma_f32_16x16x32_bf16 v[42:45], v[240:243], v[220:223], v[42:45]
	v_mfma_f32_16x16x32_bf16 v[38:41], v[240:243], v[224:227], v[38:41]
	v_mfma_f32_16x16x32_bf16 v[34:37], v[240:243], v[228:231], v[34:37]
	v_mfma_f32_16x16x32_bf16 v[30:33], v[244:247], v[200:203], v[30:33]
	v_mfma_f32_16x16x32_bf16 v[26:29], v[244:247], v[204:207], v[26:29]
	v_mfma_f32_16x16x32_bf16 v[22:25], v[244:247], v[208:211], v[22:25]
	v_mfma_f32_16x16x32_bf16 v[18:21], v[244:247], v[212:215], v[18:21]
	v_mfma_f32_16x16x32_bf16 v[14:17], v[244:247], v[216:219], v[14:17]
	v_mfma_f32_16x16x32_bf16 v[10:13], v[244:247], v[220:223], v[10:13]
	v_mfma_f32_16x16x32_bf16 v[6:9], v[244:247], v[224:227], v[6:9]
	v_mfma_f32_16x16x32_bf16 v[2:5], v[244:247], v[228:231], v[2:5]
	s_mov_b32 m0, s39
	s_cmp_eq_u32 s99, 0
	s_cbranch_scc1 .Lta8_first
	s_nop 7
	global_store_dwordx4 v[140:141], v[126:129], off offset:0
	global_store_dwordx4 v[140:141], v[94:97], off offset:64
	global_store_dwordx4 v[140:141], v[62:65], off offset:128
	global_store_dwordx4 v[140:141], v[30:33], off offset:192
	v_lshl_add_u64 v[140:141], v[140:141], 0, s[8:9]
	global_store_dwordx4 v[140:141], v[122:125], off offset:0
	global_store_dwordx4 v[140:141], v[90:93], off offset:64
	global_store_dwordx4 v[140:141], v[58:61], off offset:128
	global_store_dwordx4 v[140:141], v[26:29], off offset:192
	v_lshl_add_u64 v[140:141], v[140:141], 0, s[8:9]
	global_store_dwordx4 v[140:141], v[118:121], off offset:0
	global_store_dwordx4 v[140:141], v[86:89], off offset:64
	global_store_dwordx4 v[140:141], v[54:57], off offset:128
	global_store_dwordx4 v[140:141], v[22:25], off offset:192
	v_lshl_add_u64 v[140:141], v[140:141], 0, s[8:9]
	global_store_dwordx4 v[140:141], v[114:117], off offset:0
	global_store_dwordx4 v[140:141], v[82:85], off offset:64
	global_store_dwordx4 v[140:141], v[50:53], off offset:128
	global_store_dwordx4 v[140:141], v[18:21], off offset:192
	v_lshl_add_u64 v[140:141], v[140:141], 0, s[8:9]
	global_store_dwordx4 v[140:141], v[110:113], off offset:0
	global_store_dwordx4 v[140:141], v[78:81], off offset:64
	global_store_dwordx4 v[140:141], v[46:49], off offset:128
	global_store_dwordx4 v[140:141], v[14:17], off offset:192
	v_lshl_add_u64 v[140:141], v[140:141], 0, s[8:9]
	global_store_dwordx4 v[140:141], v[106:109], off offset:0
	global_store_dwordx4 v[140:141], v[74:77], off offset:64
	global_store_dwordx4 v[140:141], v[42:45], off offset:128
	global_store_dwordx4 v[140:141], v[10:13], off offset:192
	v_lshl_add_u64 v[140:141], v[140:141], 0, s[8:9]
	global_store_dwordx4 v[140:141], v[102:105], off offset:0
	global_store_dwordx4 v[140:141], v[70:73], off offset:64
	global_store_dwordx4 v[140:141], v[38:41], off offset:128
	global_store_dwordx4 v[140:141], v[6:9], off offset:192
	v_lshl_add_u64 v[140:141], v[140:141], 0, s[8:9]
	global_store_dwordx4 v[140:141], v[98:101], off offset:0
	global_store_dwordx4 v[140:141], v[66:69], off offset:64
	global_store_dwordx4 v[140:141], v[34:37], off offset:128
	global_store_dwordx4 v[140:141], v[2:5], off offset:192
	s_branch .LBB0_146

; #define LAS __attribute__((address_space(3)))
;     ...
;   const int nk = (nk_part < 0) ? (K >> 5) : nk_part;
;   const int lrow = tid >> 2, lpc = tid & 3;
;   const int lch = lpc ^ ((0x78 >> (((lrow >> 2) & 3) * 2)) & 3);
;   const u16* ga = A + (size_t)(m0 + lrow) * lda + kbeg + lch * 8;
;   const u16* gb = Bt + (size_t)(n0 + lrow) * K + kbeg + lch * 8;
;   const size_t ga1 = (size_t)64 * lda, gb1 = (size_t)64 * K;
;   const unsigned lds0 = (unsigned)(uintptr_t)(LAS char*)smem + (unsigned)__builtin_amdgcn_readfirstlane(wid) * 1024u;
;     ...
;   __syncthreads();
;   G2_STAGE(0); G2_STAGE(1);
; DEVI void tile_coords(int T, int MT, int NT, int& mt, int& nt) {
;   const int full = MT >> 3, band = T / (8 * NT);
;   if (band < full) { const int r = T - band * 8 * NT; nt = r >> 3; mt = band * 8 + (r & 7); }
;   else { const int MB = MT - full * 8; const int r = T - full * 8 * NT; nt = r / MB; mt = full * 8 + r % MB; }
; }
.LBB0_208:
	s_and_b64 vcc, exec, s[2:3]
	s_cbranch_vccz .LBB0_146
	s_lshr_b32 s45, s38, 6
	s_and_b32 s46, s38, 63
	s_lshr_b32 s42, s46, 3
	s_and_b32 s46, s46, 7
	s_lshl_b32 s45, s45, 3
	s_add_i32 s45, s45, s46
	v_readlane_b32 s2, v250, 5
	v_readlane_b32 s3, v250, 6
	v_readlane_b32 s46, v254, 62
	s_mul_i32 s40, s45, 0x20000
	s_add_u32 s4, s2, s40
	s_addc_u32 s5, s3, 0
	s_add_u32 s4, s4, 0xe700000
	s_addc_u32 s5, s5, 0
	s_mul_i32 s40, s46, 0x80000
	s_mul_i32 s41, s42, 0x10000
	s_add_i32 s40, s40, s41
	s_add_u32 s10, s2, s40
	s_addc_u32 s11, s3, 0
	s_add_u32 s10, s10, 0x16c00000
	s_addc_u32 s11, s11, 0
	s_movk_i32 s39, 0x78
	v_lshrrev_b32_e32 v0, 2, v145
	v_and_b32_e32 v131, 3, v145
	v_bfe_u32 v136, v145, 4, 2
	v_lshlrev_b32_e32 v136, 1, v136
	v_lshrrev_b32_e64 v136, v136, s39
	v_and_b32_e32 v136, 3, v136
	v_xor_b32_e32 v131, v131, v136
	v_lshlrev_b32_e32 v131, 4, v131
	s_movk_i32 s41, 0x200
	v_mad_u32_u24 v0, v0, s41, v131
	v_bfe_u32 v137, v145, 2, 1
	s_movk_i32 s41, 0x1c0
	v_mul_u32_u24_e32 v136, s41, v137
	v_sub_u32_e32 v136, v0, v136
	v_mov_b32_e32 v137, 0
	v_lshl_add_u64 v[134:135], s[10:11], 0, v[136:137]
	v_bfe_u32 v137, v145, 2, 1
	s_mov_b32 s12, 64
	s_mov_b32 s13, 0
	v_lshl_add_u64 v[132:133], s[4:5], 0, v[0:1]
	v_bfe_u32 v136, v145, 2, 2
	v_lshlrev_b32_e32 v136, 1, v136
	v_lshrrev_b32_e64 v136, v136, s39
	v_and_b32_e32 v136, 3, v136
	v_bfe_u32 v137, v145, 4, 2
	v_xor_b32_e32 v136, v136, v137
	v_lshlrev_b32_e32 v136, 4, v136
	v_and_b32_e32 v131, 15, v145
	v_lshl_or_b32 v136, v131, 6, v136
	v_bfe_u32 v137, v145, 6, 1
	v_lshl_or_b32 v137, v137, 12, v136
	v_lshrrev_b32_e32 v0, 7, v145
	v_lshl_or_b32 v136, v0, 13, v136
	v_and_b32_e32 v140, 1, v131
	v_lshl_or_b32 v131, v0, 7, v131
	v_bfe_u32 v0, v145, 4, 2
	v_lshlrev_b32_e32 v0, 3, v0
	v_bfe_u32 v141, v145, 6, 1
	s_lshl_b32 s40, s45, 19
	s_lshl_b32 s41, s42, 8
	s_add_i32 s40, s40, s41
	s_add_u32 s4, s2, s40
	s_addc_u32 s5, s3, 0
	s_add_u32 s4, s4, 0x4200000
	s_addc_u32 s5, s5, 0
	v_lshlrev_b32_e32 v138, 11, v131
	v_lshl_add_u32 v138, v141, 7, v138
	v_bfe_u32 v139, v145, 4, 1
	v_lshl_add_u32 v138, v139, 5, v138
	v_bfe_u32 v139, v145, 5, 1
	v_lshl_add_u32 v138, v139, 4, v138
	v_mov_b32_e32 v139, 0
	v_lshl_add_u64 v[138:139], s[4:5], 0, v[138:139]
	s_lshl_b32 s40, s45, 20
	s_lshl_b32 s41, s42, 9
	s_add_i32 s40, s40, s41
	s_add_u32 s10, s2, s40
	s_addc_u32 s11, s3, 0
	v_lshlrev_b32_e32 v140, 12, v131
	v_lshl_add_u32 v140, v141, 8, v140
	v_lshl_add_u32 v140, v0, 1, v140
	v_mov_b32_e32 v141, 0
	v_lshl_add_u64 v[140:141], s[10:11], 0, v[140:141]
	s_mov_b32 s2, 0x8000
	s_mov_b32 s3, 0
	v_lshrrev_b32_e32 v0, 6, v145
	v_lshlrev_b32_e32 v0, 10, v0
	s_nop 0
	v_readfirstlane_b32 s46, v0
	s_mov_b32 s43, m0
	s_mov_b32 s4, 128
	s_mov_b32 s5, 0
	s_barrier
	s_add_i32 s42, s46, 0x0
	s_mov_b32 m0, s42
	v_lshl_add_u64 v[142:143], v[132:133], 0, s[2:3]
	global_load_lds_dwordx4 v[132:133], off
	s_add_i32 m0, m0, 0x1000
	s_nop 0
	global_load_lds_dwordx4 v[142:143], off
	v_lshl_add_u64 v[142:143], v[142:143], 0, s[2:3]
	s_add_i32 m0, m0, 0x1000
	s_nop 0
	global_load_lds_dwordx4 v[142:143], off
	v_lshl_add_u64 v[142:143], v[142:143], 0, s[2:3]
	s_add_i32 m0, m0, 0x1000
	s_nop 0
	global_load_lds_dwordx4 v[142:143], off
	s_add_i32 m0, m0, 0x1000
	v_lshl_add_u64 v[142:143], v[134:135], 0, s[2:3]
	s_nop 0
	global_load_lds_dwordx4 v[134:135], off
	s_add_i32 m0, m0, 0x1000
	v_lshl_add_u64 v[132:133], v[132:133], 0, s[12:13]
	s_nop 0
	global_load_lds_dwordx4 v[142:143], off
	v_lshl_add_u64 v[134:135], v[134:135], 0, s[4:5]
	s_nop 0
	s_add_i32 s42, s46, 0x6000
	s_mov_b32 m0, s42
	v_lshl_add_u64 v[142:143], v[132:133], 0, s[2:3]
	global_load_lds_dwordx4 v[132:133], off
	s_add_i32 m0, m0, 0x1000
	s_nop 0
	global_load_lds_dwordx4 v[142:143], off
	v_lshl_add_u64 v[142:143], v[142:143], 0, s[2:3]
	s_add_i32 m0, m0, 0x1000
	s_nop 0
	global_load_lds_dwordx4 v[142:143], off
	v_lshl_add_u64 v[142:143], v[142:143], 0, s[2:3]
	s_add_i32 m0, m0, 0x1000
	s_nop 0
	global_load_lds_dwordx4 v[142:143], off
	s_add_i32 m0, m0, 0x1000
	v_lshl_add_u64 v[142:143], v[134:135], 0, s[2:3]
	s_nop 0
	global_load_lds_dwordx4 v[134:135], off
	s_add_i32 m0, m0, 0x1000
	v_lshl_add_u64 v[132:133], v[132:133], 0, s[12:13]
	s_nop 0
	global_load_lds_dwordx4 v[142:143], off
	v_lshl_add_u64 v[134:135], v[134:135], 0, s[4:5]
	s_nop 0
	s_add_i32 s42, s46, 0xc000
	s_mov_b32 m0, s42
	v_lshl_add_u64 v[142:143], v[132:133], 0, s[2:3]
	global_load_lds_dwordx4 v[132:133], off
	s_add_i32 m0, m0, 0x1000
	s_nop 0
	global_load_lds_dwordx4 v[142:143], off
	v_lshl_add_u64 v[142:143], v[142:143], 0, s[2:3]
	s_add_i32 m0, m0, 0x1000
	s_nop 0
	global_load_lds_dwordx4 v[142:143], off
	v_lshl_add_u64 v[142:143], v[142:143], 0, s[2:3]
	s_add_i32 m0, m0, 0x1000
	s_nop 0
	global_load_lds_dwordx4 v[142:143], off
	s_add_i32 m0, m0, 0x1000
	v_lshl_add_u64 v[142:143], v[134:135], 0, s[2:3]
	s_nop 0
	global_load_lds_dwordx4 v[134:135], off
	s_add_i32 m0, m0, 0x1000
	v_lshl_add_u64 v[132:133], v[132:133], 0, s[12:13]
	s_nop 0
	global_load_lds_dwordx4 v[142:143], off
	v_lshl_add_u64 v[134:135], v[134:135], 0, s[4:5]
	s_nop 0
	v_mov_b32_e32 v2, 0
	v_mov_b32_e32 v3, 0
	v_mov_b32_e32 v4, 0
	v_mov_b32_e32 v5, 0
	v_mov_b32_e32 v6, 0
	v_mov_b32_e32 v7, 0
	v_mov_b32_e32 v8, 0
	v_mov_b32_e32 v9, 0
	v_mov_b32_e32 v10, 0
	v_mov_b32_e32 v11, 0
	v_mov_b32_e32 v12, 0
	v_mov_b32_e32 v13, 0
	v_mov_b32_e32 v14, 0
	v_mov_b32_e32 v15, 0
	v_mov_b32_e32 v16, 0
	v_mov_b32_e32 v17, 0
	v_mov_b32_e32 v18, 0
	v_mov_b32_e32 v19, 0
	v_mov_b32_e32 v20, 0
	v_mov_b32_e32 v21, 0
	v_mov_b32_e32 v22, 0
	v_mov_b32_e32 v23, 0
	v_mov_b32_e32 v24, 0
	v_mov_b32_e32 v25, 0
	v_mov_b32_e32 v26, 0
	v_mov_b32_e32 v27, 0
; #define LAS __attribute__((address_space(3)))
;     ...
;   f32x4 acc[4][8];
; #pragma unroll
;   for (int i = 0; i < 4; i++)
; #pragma unroll
;     for (int j = 0; j < 8; j++) acc[i][j] = (f32x4){0.f, 0.f, 0.f, 0.f};
;   const int nk = (nk_part < 0) ? (K >> 5) : nk_part;
;   const int lrow = tid >> 2, lpc = tid & 3;
;   const int lch = lpc ^ ((0x78 >> (((lrow >> 2) & 3) * 2)) & 3);
;   const u16* ga = A + (size_t)(m0 + lrow) * lda + kbeg + lch * 8;
;   const u16* gb = Bt + (size_t)(n0 + lrow) * K + kbeg + lch * 8;
;   const size_t ga1 = (size_t)64 * lda, gb1 = (size_t)64 * K;
;   const unsigned lds0 = (unsigned)(uintptr_t)(LAS char*)smem + (unsigned)__builtin_amdgcn_readfirstlane(wid) * 1024u;
;     ...
;   __syncthreads();
;   G2_STAGE(0); G2_STAGE(1);
;   const int fsw = (0x78 >> (((r16 >> 2) & 3) * 2)) & 3;
;   const int aoff = (wm * 128 + r16) * 64 + ((quad ^ fsw) << 4);
;   const int boff = 16384 + (wn * 64 + r16) * 64 + ((quad ^ fsw) << 4);
;   for (int kt = 0; kt < nk; kt++) {
;     if (kt + 1 < nk) asm volatile("s_waitcnt vmcnt(6)" ::: "memory");
;     else asm volatile("s_waitcnt vmcnt(0)" ::: "memory");
;     __builtin_amdgcn_s_barrier();
;     asm volatile("" ::: "memory");
;     if (kt + 2 < nk) G2_STAGE(kt + 2);
;     const char* cS = smem + (kt % 3) * 24576;
;     bf16x8 xa[8], wb[4];
; #pragma unroll
;     for (int f = 0; f < 8; f++) xa[f] = *(const bf16x8*)(cS + aoff + f * 1024);
; #pragma unroll
;     for (int f = 0; f < 4; f++) wb[f] = *(const bf16x8*)(cS + boff + f * 1024);
; #pragma unroll
;     for (int nf = 0; nf < 4; nf++)
; #pragma unroll
;       for (int mf = 0; mf < 8; mf++)
;         acc[nf][mf] = __builtin_amdgcn_mfma_f32_16x16x32_bf16(wb[nf], xa[mf], acc[nf][mf], 0, 0, 0);
	v_mov_b32_e32 v28, 0
	v_mov_b32_e32 v29, 0
	v_mov_b32_e32 v30, 0
	v_mov_b32_e32 v31, 0
	v_mov_b32_e32 v32, 0
	v_mov_b32_e32 v33, 0
	v_mov_b32_e32 v34, 0
	v_mov_b32_e32 v35, 0
	v_mov_b32_e32 v36, 0
	v_mov_b32_e32 v37, 0
	v_mov_b32_e32 v38, 0
	v_mov_b32_e32 v39, 0
	v_mov_b32_e32 v40, 0
	v_mov_b32_e32 v41, 0
	v_mov_b32_e32 v42, 0
	v_mov_b32_e32 v43, 0
	v_mov_b32_e32 v44, 0
	v_mov_b32_e32 v45, 0
	v_mov_b32_e32 v46, 0
	v_mov_b32_e32 v47, 0
	v_mov_b32_e32 v48, 0
	v_mov_b32_e32 v49, 0
	v_mov_b32_e32 v50, 0
	v_mov_b32_e32 v51, 0
	v_mov_b32_e32 v52, 0
	v_mov_b32_e32 v53, 0
	v_mov_b32_e32 v54, 0
	v_mov_b32_e32 v55, 0
	v_mov_b32_e32 v56, 0
	v_mov_b32_e32 v57, 0
	v_mov_b32_e32 v58, 0
	v_mov_b32_e32 v59, 0
	v_mov_b32_e32 v60, 0
	v_mov_b32_e32 v61, 0
	v_mov_b32_e32 v62, 0
	v_mov_b32_e32 v63, 0
	v_mov_b32_e32 v64, 0
	v_mov_b32_e32 v65, 0
	v_mov_b32_e32 v66, 0
	v_mov_b32_e32 v67, 0
	v_mov_b32_e32 v68, 0
	v_mov_b32_e32 v69, 0
	v_mov_b32_e32 v70, 0
	v_mov_b32_e32 v71, 0
	v_mov_b32_e32 v72, 0
	v_mov_b32_e32 v73, 0
	v_mov_b32_e32 v74, 0
	v_mov_b32_e32 v75, 0
	v_mov_b32_e32 v76, 0
	v_mov_b32_e32 v77, 0
	v_mov_b32_e32 v78, 0
	v_mov_b32_e32 v79, 0
	v_mov_b32_e32 v80, 0
	v_mov_b32_e32 v81, 0
	v_mov_b32_e32 v82, 0
	v_mov_b32_e32 v83, 0
	v_mov_b32_e32 v84, 0
	v_mov_b32_e32 v85, 0
	v_mov_b32_e32 v86, 0
	v_mov_b32_e32 v87, 0
	v_mov_b32_e32 v88, 0
	v_mov_b32_e32 v89, 0
	v_mov_b32_e32 v90, 0
	v_mov_b32_e32 v91, 0
	v_mov_b32_e32 v92, 0
	v_mov_b32_e32 v93, 0
	v_mov_b32_e32 v94, 0
	v_mov_b32_e32 v95, 0
	v_mov_b32_e32 v96, 0
	v_mov_b32_e32 v97, 0
	v_mov_b32_e32 v98, 0
	v_mov_b32_e32 v99, 0
	v_mov_b32_e32 v100, 0
	v_mov_b32_e32 v101, 0
	v_mov_b32_e32 v102, 0
	v_mov_b32_e32 v103, 0
	v_mov_b32_e32 v104, 0
	v_mov_b32_e32 v105, 0
	v_mov_b32_e32 v106, 0
	v_mov_b32_e32 v107, 0
	v_mov_b32_e32 v108, 0
	v_mov_b32_e32 v109, 0
	v_mov_b32_e32 v110, 0
	v_mov_b32_e32 v111, 0
	v_mov_b32_e32 v112, 0
	v_mov_b32_e32 v113, 0
	v_mov_b32_e32 v114, 0
	v_mov_b32_e32 v115, 0
	v_mov_b32_e32 v116, 0
	v_mov_b32_e32 v117, 0
	v_mov_b32_e32 v118, 0
	v_mov_b32_e32 v119, 0
	v_mov_b32_e32 v120, 0
	v_mov_b32_e32 v121, 0
	v_mov_b32_e32 v122, 0
	v_mov_b32_e32 v123, 0
	v_mov_b32_e32 v124, 0
	v_mov_b32_e32 v125, 0
	v_mov_b32_e32 v126, 0
	v_mov_b32_e32 v127, 0
	v_mov_b32_e32 v128, 0
	v_mov_b32_e32 v129, 0
	s_waitcnt vmcnt(12)
	s_barrier
	ds_read_b128 v[146:149], v136 offset:0
	ds_read_b128 v[152:155], v136 offset:1024
	ds_read_b128 v[156:159], v136 offset:2048
	ds_read_b128 v[162:165], v136 offset:3072
	ds_read_b128 v[166:169], v136 offset:4096
	ds_read_b128 v[170:173], v136 offset:5120
	ds_read_b128 v[176:179], v136 offset:6144
	ds_read_b128 v[180:183], v136 offset:7168
	ds_read_b128 v[184:187], v137 offset:16384
	ds_read_b128 v[188:191], v137 offset:17408
	ds_read_b128 v[192:195], v137 offset:18432
	ds_read_b128 v[196:199], v137 offset:19456
	s_movk_i32 s40, 0x6000
	s_mov_b32 s41, 0
	s_movk_i32 s39, 2
	.p2align 6
.Lt8_loop:
	.p2align 3
	s_waitcnt vmcnt(6) lgkmcnt(0)
	s_barrier
	s_setprio 1
	v_add_u32_e32 v144, s40, v136
	v_mfma_f32_16x16x32_bf16 v[126:129], v[184:187], v[146:149], v[126:129]
	ds_read_b128 v[200:203], v144 offset:0
	v_mfma_f32_16x16x32_bf16 v[122:125], v[184:187], v[152:155], v[122:125]
	ds_read_b128 v[204:207], v144 offset:1024
	v_mfma_f32_16x16x32_bf16 v[118:121], v[184:187], v[156:159], v[118:121]
	ds_read_b128 v[208:211], v144 offset:2048
	v_mfma_f32_16x16x32_bf16 v[114:117], v[184:187], v[162:165], v[114:117]
	ds_read_b128 v[212:215], v144 offset:3072
	v_mfma_f32_16x16x32_bf16 v[110:113], v[184:187], v[166:169], v[110:113]
	ds_read_b128 v[216:219], v144 offset:4096
	v_mfma_f32_16x16x32_bf16 v[106:109], v[184:187], v[170:173], v[106:109]
	ds_read_b128 v[220:223], v144 offset:5120
	v_mfma_f32_16x16x32_bf16 v[102:105], v[184:187], v[176:179], v[102:105]
	ds_read_b128 v[224:227], v144 offset:6144
	v_mfma_f32_16x16x32_bf16 v[98:101], v[184:187], v[180:183], v[98:101]
	ds_read_b128 v[228:231], v144 offset:7168
	v_mfma_f32_16x16x32_bf16 v[94:97], v[188:191], v[146:149], v[94:97]
	v_add_u32_e64 v144, s40, v137
	v_mfma_f32_16x16x32_bf16 v[90:93], v[188:191], v[152:155], v[90:93]
	v_mfma_f32_16x16x32_bf16 v[86:89], v[188:191], v[156:159], v[86:89]
	ds_read_b128 v[232:235], v144 offset:16384
	v_mfma_f32_16x16x32_bf16 v[82:85], v[188:191], v[162:165], v[82:85]
	ds_read_b128 v[236:239], v144 offset:17408
	v_mfma_f32_16x16x32_bf16 v[78:81], v[188:191], v[166:169], v[78:81]
	ds_read_b128 v[240:243], v144 offset:18432
	v_mfma_f32_16x16x32_bf16 v[74:77], v[188:191], v[170:173], v[74:77]
	ds_read_b128 v[244:247], v144 offset:19456
	v_mfma_f32_16x16x32_bf16 v[70:73], v[188:191], v[176:179], v[70:73]
	s_add_i32 s42, s46, s41
	s_mov_b32 m0, s42
	v_lshl_add_u64 v[142:143], v[132:133], 0, s[2:3]
	v_mfma_f32_16x16x32_bf16 v[66:69], v[188:191], v[180:183], v[66:69]
	global_load_lds_dwordx4 v[132:133], off
	s_add_i32 m0, m0, 0x1000
	v_mfma_f32_16x16x32_bf16 v[62:65], v[192:195], v[146:149], v[62:65]
	v_mfma_f32_16x16x32_bf16 v[58:61], v[192:195], v[152:155], v[58:61]
	v_mfma_f32_16x16x32_bf16 v[54:57], v[192:195], v[156:159], v[54:57]
	global_load_lds_dwordx4 v[142:143], off
	v_lshl_add_u64 v[142:143], v[142:143], 0, s[2:3]
	s_add_i32 m0, m0, 0x1000
	v_mfma_f32_16x16x32_bf16 v[50:53], v[192:195], v[162:165], v[50:53]
	v_mfma_f32_16x16x32_bf16 v[46:49], v[192:195], v[166:169], v[46:49]
	v_mfma_f32_16x16x32_bf16 v[42:45], v[192:195], v[170:173], v[42:45]
	global_load_lds_dwordx4 v[142:143], off
	v_lshl_add_u64 v[142:143], v[142:143], 0, s[2:3]
	s_add_i32 m0, m0, 0x1000
	v_mfma_f32_16x16x32_bf16 v[38:41], v[192:195], v[176:179], v[38:41]
	v_mfma_f32_16x16x32_bf16 v[34:37], v[192:195], v[180:183], v[34:37]
	v_mfma_f32_16x16x32_bf16 v[30:33], v[196:199], v[146:149], v[30:33]
	global_load_lds_dwordx4 v[142:143], off
	s_add_i32 m0, m0, 0x1000
	v_lshl_add_u64 v[142:143], v[134:135], 0, s[2:3]
	v_mfma_f32_16x16x32_bf16 v[26:29], v[196:199], v[152:155], v[26:29]
	v_mfma_f32_16x16x32_bf16 v[22:25], v[196:199], v[156:159], v[22:25]
	v_mfma_f32_16x16x32_bf16 v[18:21], v[196:199], v[162:165], v[18:21]
	global_load_lds_dwordx4 v[134:135], off
	s_add_i32 m0, m0, 0x1000
	v_lshl_add_u64 v[132:133], v[132:133], 0, s[12:13]
	v_mfma_f32_16x16x32_bf16 v[14:17], v[196:199], v[166:169], v[14:17]
	v_mfma_f32_16x16x32_bf16 v[10:13], v[196:199], v[170:173], v[10:13]
	v_mfma_f32_16x16x32_bf16 v[6:9], v[196:199], v[176:179], v[6:9]
	global_load_lds_dwordx4 v[142:143], off
	v_lshl_add_u64 v[134:135], v[134:135], 0, s[4:5]
	v_mfma_f32_16x16x32_bf16 v[2:5], v[196:199], v[180:183], v[2:5]
	s_setprio 0
	s_mov_b32 s41, s40
	s_add_i32 s40, s40, 0x6000
	s_cmp_eq_u32 s40, 0x12000
	s_cselect_b32 s40, 0, s40
	s_nop 0
	.p2align 3
	s_waitcnt vmcnt(6) lgkmcnt(0)
	s_barrier
;     ...
;   for (int kt = 0; kt < nk; kt++) {
;     if (kt + 1 < nk) asm volatile("s_waitcnt vmcnt(6)" ::: "memory");
;     else asm volatile("s_waitcnt vmcnt(0)" ::: "memory");
;     __builtin_amdgcn_s_barrier();
;     asm volatile("" ::: "memory");
;     if (kt + 2 < nk) G2_STAGE(kt + 2);
;     const char* cS = smem + (kt % 3) * 24576;
;     bf16x8 xa[8], wb[4];
; #pragma unroll
;     for (int f = 0; f < 8; f++) xa[f] = *(const bf16x8*)(cS + aoff + f * 1024);
; #pragma unroll
;     for (int f = 0; f < 4; f++) wb[f] = *(const bf16x8*)(cS + boff + f * 1024);
; #pragma unroll
;     for (int nf = 0; nf < 4; nf++)
; #pragma unroll
;       for (int mf = 0; mf < 8; mf++)
;         acc[nf][mf] = __builtin_amdgcn_mfma_f32_16x16x32_bf16(wb[nf], xa[mf], acc[nf][mf], 0, 0, 0);
;   }
	s_setprio 1
	v_add_u32_e32 v144, s40, v136
	v_mfma_f32_16x16x32_bf16 v[126:129], v[232:235], v[200:203], v[126:129]
	ds_read_b128 v[146:149], v144 offset:0
	v_mfma_f32_16x16x32_bf16 v[122:125], v[232:235], v[204:207], v[122:125]
	ds_read_b128 v[152:155], v144 offset:1024
	v_mfma_f32_16x16x32_bf16 v[118:121], v[232:235], v[208:211], v[118:121]
	ds_read_b128 v[156:159], v144 offset:2048
	v_mfma_f32_16x16x32_bf16 v[114:117], v[232:235], v[212:215], v[114:117]
	ds_read_b128 v[162:165], v144 offset:3072
	v_mfma_f32_16x16x32_bf16 v[110:113], v[232:235], v[216:219], v[110:113]
	ds_read_b128 v[166:169], v144 offset:4096
	v_mfma_f32_16x16x32_bf16 v[106:109], v[232:235], v[220:223], v[106:109]
	ds_read_b128 v[170:173], v144 offset:5120
	v_mfma_f32_16x16x32_bf16 v[102:105], v[232:235], v[224:227], v[102:105]
	ds_read_b128 v[176:179], v144 offset:6144
	v_mfma_f32_16x16x32_bf16 v[98:101], v[232:235], v[228:231], v[98:101]
	ds_read_b128 v[180:183], v144 offset:7168
	v_mfma_f32_16x16x32_bf16 v[94:97], v[236:239], v[200:203], v[94:97]
	v_add_u32_e64 v144, s40, v137
	v_mfma_f32_16x16x32_bf16 v[90:93], v[236:239], v[204:207], v[90:93]
	v_mfma_f32_16x16x32_bf16 v[86:89], v[236:239], v[208:211], v[86:89]
	ds_read_b128 v[184:187], v144 offset:16384
	v_mfma_f32_16x16x32_bf16 v[82:85], v[236:239], v[212:215], v[82:85]
	ds_read_b128 v[188:191], v144 offset:17408
	v_mfma_f32_16x16x32_bf16 v[78:81], v[236:239], v[216:219], v[78:81]
	ds_read_b128 v[192:195], v144 offset:18432
	v_mfma_f32_16x16x32_bf16 v[74:77], v[236:239], v[220:223], v[74:77]
	ds_read_b128 v[196:199], v144 offset:19456
	v_mfma_f32_16x16x32_bf16 v[70:73], v[236:239], v[224:227], v[70:73]
	s_add_i32 s42, s46, s41
	s_mov_b32 m0, s42
	v_lshl_add_u64 v[142:143], v[132:133], 0, s[2:3]
	v_mfma_f32_16x16x32_bf16 v[66:69], v[236:239], v[228:231], v[66:69]
	global_load_lds_dwordx4 v[132:133], off
	s_add_i32 m0, m0, 0x1000
	v_mfma_f32_16x16x32_bf16 v[62:65], v[240:243], v[200:203], v[62:65]
	v_mfma_f32_16x16x32_bf16 v[58:61], v[240:243], v[204:207], v[58:61]
	v_mfma_f32_16x16x32_bf16 v[54:57], v[240:243], v[208:211], v[54:57]
	global_load_lds_dwordx4 v[142:143], off
	v_lshl_add_u64 v[142:143], v[142:143], 0, s[2:3]
	s_add_i32 m0, m0, 0x1000
	v_mfma_f32_16x16x32_bf16 v[50:53], v[240:243], v[212:215], v[50:53]
	v_mfma_f32_16x16x32_bf16 v[46:49], v[240:243], v[216:219], v[46:49]
	v_mfma_f32_16x16x32_bf16 v[42:45], v[240:243], v[220:223], v[42:45]
	global_load_lds_dwordx4 v[142:143], off
	v_lshl_add_u64 v[142:143], v[142:143], 0, s[2:3]
	s_add_i32 m0, m0, 0x1000
	v_mfma_f32_16x16x32_bf16 v[38:41], v[240:243], v[224:227], v[38:41]
	v_mfma_f32_16x16x32_bf16 v[34:37], v[240:243], v[228:231], v[34:37]
	v_mfma_f32_16x16x32_bf16 v[30:33], v[244:247], v[200:203], v[30:33]
	global_load_lds_dwordx4 v[142:143], off
	s_add_i32 m0, m0, 0x1000
	v_lshl_add_u64 v[142:143], v[134:135], 0, s[2:3]
	v_mfma_f32_16x16x32_bf16 v[26:29], v[244:247], v[204:207], v[26:29]
	v_mfma_f32_16x16x32_bf16 v[22:25], v[244:247], v[208:211], v[22:25]
	v_mfma_f32_16x16x32_bf16 v[18:21], v[244:247], v[212:215], v[18:21]
	global_load_lds_dwordx4 v[134:135], off
	s_add_i32 m0, m0, 0x1000
	v_lshl_add_u64 v[132:133], v[132:133], 0, s[12:13]
	v_mfma_f32_16x16x32_bf16 v[14:17], v[244:247], v[216:219], v[14:17]
	v_mfma_f32_16x16x32_bf16 v[10:13], v[244:247], v[220:223], v[10:13]
	v_mfma_f32_16x16x32_bf16 v[6:9], v[244:247], v[224:227], v[6:9]
	global_load_lds_dwordx4 v[142:143], off
	v_lshl_add_u64 v[134:135], v[134:135], 0, s[4:5]
	v_mfma_f32_16x16x32_bf16 v[2:5], v[244:247], v[228:231], v[2:5]
	s_setprio 0
	s_mov_b32 s41, s40
	s_add_i32 s40, s40, 0x6000
	s_cmp_eq_u32 s40, 0x12000
	s_cselect_b32 s40, 0, s40
	s_nop 0
	s_sub_i32 s39, s39, 1
	s_cmp_lg_u32 s39, 0
	s_cbranch_scc1 .Lt8_loop
	.p2align 3
	s_waitcnt vmcnt(6) lgkmcnt(0)
	s_barrier
	s_setprio 1
	v_add_u32_e32 v144, s40, v136
	v_mfma_f32_16x16x32_bf16 v[126:129], v[184:187], v[146:149], v[126:129]
	ds_read_b128 v[200:203], v144 offset:0
	v_mfma_f32_16x16x32_bf16 v[122:125], v[184:187], v[152:155], v[122:125]
	ds_read_b128 v[204:207], v144 offset:1024
	v_mfma_f32_16x16x32_bf16 v[118:121], v[184:187], v[156:159], v[118:121]
	ds_read_b128 v[208:211], v144 offset:2048
	v_mfma_f32_16x16x32_bf16 v[114:117], v[184:187], v[162:165], v[114:117]
	ds_read_b128 v[212:215], v144 offset:3072
	v_mfma_f32_16x16x32_bf16 v[110:113], v[184:187], v[166:169], v[110:113]
	ds_read_b128 v[216:219], v144 offset:4096
	v_mfma_f32_16x16x32_bf16 v[106:109], v[184:187], v[170:173], v[106:109]
	ds_read_b128 v[220:223], v144 offset:5120
	v_mfma_f32_16x16x32_bf16 v[102:105], v[184:187], v[176:179], v[102:105]
	ds_read_b128 v[224:227], v144 offset:6144
	v_mfma_f32_16x16x32_bf16 v[98:101], v[184:187], v[180:183], v[98:101]
	ds_read_b128 v[228:231], v144 offset:7168
	v_mfma_f32_16x16x32_bf16 v[94:97], v[188:191], v[146:149], v[94:97]
	v_add_u32_e64 v144, s40, v137
	v_mfma_f32_16x16x32_bf16 v[90:93], v[188:191], v[152:155], v[90:93]
	v_mfma_f32_16x16x32_bf16 v[86:89], v[188:191], v[156:159], v[86:89]
	ds_read_b128 v[232:235], v144 offset:16384
	v_mfma_f32_16x16x32_bf16 v[82:85], v[188:191], v[162:165], v[82:85]
	ds_read_b128 v[236:239], v144 offset:17408
	v_mfma_f32_16x16x32_bf16 v[78:81], v[188:191], v[166:169], v[78:81]
	ds_read_b128 v[240:243], v144 offset:18432
	v_mfma_f32_16x16x32_bf16 v[74:77], v[188:191], v[170:173], v[74:77]
	ds_read_b128 v[244:247], v144 offset:19456
	v_mfma_f32_16x16x32_bf16 v[70:73], v[188:191], v[176:179], v[70:73]
	s_add_i32 s42, s46, s41
	s_mov_b32 m0, s42
	v_lshl_add_u64 v[142:143], v[132:133], 0, s[2:3]
	v_mfma_f32_16x16x32_bf16 v[66:69], v[188:191], v[180:183], v[66:69]
	global_load_lds_dwordx4 v[132:133], off
;     ...
;   for (int kt = 0; kt < nk; kt++) {
;     if (kt + 1 < nk) asm volatile("s_waitcnt vmcnt(6)" ::: "memory");
;     else asm volatile("s_waitcnt vmcnt(0)" ::: "memory");
;     __builtin_amdgcn_s_barrier();
;     asm volatile("" ::: "memory");
;     if (kt + 2 < nk) G2_STAGE(kt + 2);
;     const char* cS = smem + (kt % 3) * 24576;
;     bf16x8 xa[8], wb[4];
; #pragma unroll
;     for (int f = 0; f < 8; f++) xa[f] = *(const bf16x8*)(cS + aoff + f * 1024);
; #pragma unroll
;     for (int f = 0; f < 4; f++) wb[f] = *(const bf16x8*)(cS + boff + f * 1024);
; #pragma unroll
;     for (int nf = 0; nf < 4; nf++)
; #pragma unroll
;       for (int mf = 0; mf < 8; mf++)
;         acc[nf][mf] = __builtin_amdgcn_mfma_f32_16x16x32_bf16(wb[nf], xa[mf], acc[nf][mf], 0, 0, 0);
;   }
	s_add_i32 m0, m0, 0x1000
	v_mfma_f32_16x16x32_bf16 v[62:65], v[192:195], v[146:149], v[62:65]
	v_mfma_f32_16x16x32_bf16 v[58:61], v[192:195], v[152:155], v[58:61]
	v_mfma_f32_16x16x32_bf16 v[54:57], v[192:195], v[156:159], v[54:57]
	global_load_lds_dwordx4 v[142:143], off
	v_lshl_add_u64 v[142:143], v[142:143], 0, s[2:3]
	s_add_i32 m0, m0, 0x1000
	v_mfma_f32_16x16x32_bf16 v[50:53], v[192:195], v[162:165], v[50:53]
	v_mfma_f32_16x16x32_bf16 v[46:49], v[192:195], v[166:169], v[46:49]
	v_mfma_f32_16x16x32_bf16 v[42:45], v[192:195], v[170:173], v[42:45]
	global_load_lds_dwordx4 v[142:143], off
	v_lshl_add_u64 v[142:143], v[142:143], 0, s[2:3]
	s_add_i32 m0, m0, 0x1000
	v_mfma_f32_16x16x32_bf16 v[38:41], v[192:195], v[176:179], v[38:41]
	v_mfma_f32_16x16x32_bf16 v[34:37], v[192:195], v[180:183], v[34:37]
	v_mfma_f32_16x16x32_bf16 v[30:33], v[196:199], v[146:149], v[30:33]
	global_load_lds_dwordx4 v[142:143], off
	s_add_i32 m0, m0, 0x1000
	v_lshl_add_u64 v[142:143], v[134:135], 0, s[2:3]
	v_mfma_f32_16x16x32_bf16 v[26:29], v[196:199], v[152:155], v[26:29]
	v_mfma_f32_16x16x32_bf16 v[22:25], v[196:199], v[156:159], v[22:25]
	v_mfma_f32_16x16x32_bf16 v[18:21], v[196:199], v[162:165], v[18:21]
	global_load_lds_dwordx4 v[134:135], off
	s_add_i32 m0, m0, 0x1000
	v_lshl_add_u64 v[132:133], v[132:133], 0, s[12:13]
	v_mfma_f32_16x16x32_bf16 v[14:17], v[196:199], v[166:169], v[14:17]
	v_mfma_f32_16x16x32_bf16 v[10:13], v[196:199], v[170:173], v[10:13]
	v_mfma_f32_16x16x32_bf16 v[6:9], v[196:199], v[176:179], v[6:9]
	global_load_lds_dwordx4 v[142:143], off
	v_lshl_add_u64 v[134:135], v[134:135], 0, s[4:5]
	v_mfma_f32_16x16x32_bf16 v[2:5], v[196:199], v[180:183], v[2:5]
	s_setprio 0
	s_mov_b32 s41, s40
	s_add_i32 s40, s40, 0x6000
	s_cmp_eq_u32 s40, 0x12000
	s_cselect_b32 s40, 0, s40
	s_nop 0
	.p2align 3
	s_waitcnt vmcnt(6) lgkmcnt(0)
	s_barrier
	s_setprio 1
	v_add_u32_e32 v144, s40, v136
	v_mfma_f32_16x16x32_bf16 v[126:129], v[232:235], v[200:203], v[126:129]
	ds_read_b128 v[146:149], v144 offset:0
	v_mfma_f32_16x16x32_bf16 v[122:125], v[232:235], v[204:207], v[122:125]
	ds_read_b128 v[152:155], v144 offset:1024
	v_mfma_f32_16x16x32_bf16 v[118:121], v[232:235], v[208:211], v[118:121]
	ds_read_b128 v[156:159], v144 offset:2048
	v_mfma_f32_16x16x32_bf16 v[114:117], v[232:235], v[212:215], v[114:117]
	ds_read_b128 v[162:165], v144 offset:3072
	v_mfma_f32_16x16x32_bf16 v[110:113], v[232:235], v[216:219], v[110:113]
	ds_read_b128 v[166:169], v144 offset:4096
	v_mfma_f32_16x16x32_bf16 v[106:109], v[232:235], v[220:223], v[106:109]
	ds_read_b128 v[170:173], v144 offset:5120
	v_mfma_f32_16x16x32_bf16 v[102:105], v[232:235], v[224:227], v[102:105]
	ds_read_b128 v[176:179], v144 offset:6144
	v_mfma_f32_16x16x32_bf16 v[98:101], v[232:235], v[228:231], v[98:101]
	ds_read_b128 v[180:183], v144 offset:7168
	v_mfma_f32_16x16x32_bf16 v[94:97], v[236:239], v[200:203], v[94:97]
	v_add_u32_e64 v144, s40, v137
	v_mfma_f32_16x16x32_bf16 v[90:93], v[236:239], v[204:207], v[90:93]
	v_mfma_f32_16x16x32_bf16 v[86:89], v[236:239], v[208:211], v[86:89]
	ds_read_b128 v[184:187], v144 offset:16384
	v_mfma_f32_16x16x32_bf16 v[82:85], v[236:239], v[212:215], v[82:85]
	ds_read_b128 v[188:191], v144 offset:17408
	v_mfma_f32_16x16x32_bf16 v[78:81], v[236:239], v[216:219], v[78:81]
	ds_read_b128 v[192:195], v144 offset:18432
	v_mfma_f32_16x16x32_bf16 v[74:77], v[236:239], v[220:223], v[74:77]
	ds_read_b128 v[196:199], v144 offset:19456
	v_mfma_f32_16x16x32_bf16 v[70:73], v[236:239], v[224:227], v[70:73]
	v_mfma_f32_16x16x32_bf16 v[66:69], v[236:239], v[228:231], v[66:69]
	v_mfma_f32_16x16x32_bf16 v[62:65], v[240:243], v[200:203], v[62:65]
	v_mfma_f32_16x16x32_bf16 v[58:61], v[240:243], v[204:207], v[58:61]
	v_mfma_f32_16x16x32_bf16 v[54:57], v[240:243], v[208:211], v[54:57]
	v_mfma_f32_16x16x32_bf16 v[50:53], v[240:243], v[212:215], v[50:53]
	v_mfma_f32_16x16x32_bf16 v[46:49], v[240:243], v[216:219], v[46:49]
	v_mfma_f32_16x16x32_bf16 v[42:45], v[240:243], v[220:223], v[42:45]
	v_mfma_f32_16x16x32_bf16 v[38:41], v[240:243], v[224:227], v[38:41]
	v_mfma_f32_16x16x32_bf16 v[34:37], v[240:243], v[228:231], v[34:37]
	v_mfma_f32_16x16x32_bf16 v[30:33], v[244:247], v[200:203], v[30:33]
	v_mfma_f32_16x16x32_bf16 v[26:29], v[244:247], v[204:207], v[26:29]
	v_mfma_f32_16x16x32_bf16 v[22:25], v[244:247], v[208:211], v[22:25]
	v_mfma_f32_16x16x32_bf16 v[18:21], v[244:247], v[212:215], v[18:21]
	v_mfma_f32_16x16x32_bf16 v[14:17], v[244:247], v[216:219], v[14:17]
	v_mfma_f32_16x16x32_bf16 v[10:13], v[244:247], v[220:223], v[10:13]
	v_mfma_f32_16x16x32_bf16 v[6:9], v[244:247], v[224:227], v[6:9]
	v_mfma_f32_16x16x32_bf16 v[2:5], v[244:247], v[228:231], v[2:5]
	s_setprio 0
	s_mov_b32 s41, s40
	s_add_i32 s40, s40, 0x6000
	s_cmp_eq_u32 s40, 0x12000
	s_cselect_b32 s40, 0, s40
	s_nop 0
	.p2align 3
	s_waitcnt vmcnt(0) lgkmcnt(0)
	s_barrier
; DEVI float blo(unsigned u) { return __uint_as_float(u << 16); }
; DEVI float bhi(unsigned u) { return __uint_as_float(u & 0xffff0000u); }
;     ...
;   for (int kt = 0; kt < nk; kt++) {
;     if (kt + 1 < nk) asm volatile("s_waitcnt vmcnt(6)" ::: "memory");
;     else asm volatile("s_waitcnt vmcnt(0)" ::: "memory");
;     __builtin_amdgcn_s_barrier();
;     asm volatile("" ::: "memory");
;     if (kt + 2 < nk) G2_STAGE(kt + 2);
;     const char* cS = smem + (kt % 3) * 24576;
;     bf16x8 xa[8], wb[4];
; #pragma unroll
;     for (int f = 0; f < 8; f++) xa[f] = *(const bf16x8*)(cS + aoff + f * 1024);
; #pragma unroll
;     for (int f = 0; f < 4; f++) wb[f] = *(const bf16x8*)(cS + boff + f * 1024);
; #pragma unroll
;     for (int nf = 0; nf < 4; nf++)
; #pragma unroll
;       for (int mf = 0; mf < 8; mf++)
;         acc[nf][mf] = __builtin_amdgcn_mfma_f32_16x16x32_bf16(wb[nf], xa[mf], acc[nf][mf], 0, 0, 0);
;     ...
;         const int col = n0 + wn * 64 + nf * 16 + quad * 4;
;         f32x4 a = acc[nf][mf];
;         if (EPI == EPI_RESID || EPI == EPI_RESID_ATOMIC) {
;           f32x4 x = a;
;           if (EPI == EPI_RESID || kpart == 0) {
;             const u32x2 xr = *(const u32x2*)((const u16*)(p.ws + WS_XB) + (size_t)row * 1024 + col);
;             x[0] += ALPHA * blo(xr[0]); x[1] += ALPHA * bhi(xr[0]); x[2] += ALPHA * blo(xr[1]); x[3] += ALPHA * bhi(xr[1]);
;           }
;           if (EPI == EPI_RESID) *(f32x4*)((float*)(p.ws + WS_XF) + (size_t)row * 1024 + col) = x;
	s_setprio 1
	v_add_u32_e32 v144, s40, v136
	v_mfma_f32_16x16x32_bf16 v[126:129], v[184:187], v[146:149], v[126:129]
	ds_read_b128 v[200:203], v144 offset:0
	v_mfma_f32_16x16x32_bf16 v[122:125], v[184:187], v[152:155], v[122:125]
	ds_read_b128 v[204:207], v144 offset:1024
	v_mfma_f32_16x16x32_bf16 v[118:121], v[184:187], v[156:159], v[118:121]
	ds_read_b128 v[208:211], v144 offset:2048
	v_mfma_f32_16x16x32_bf16 v[114:117], v[184:187], v[162:165], v[114:117]
	ds_read_b128 v[212:215], v144 offset:3072
	v_mfma_f32_16x16x32_bf16 v[110:113], v[184:187], v[166:169], v[110:113]
	ds_read_b128 v[216:219], v144 offset:4096
	v_mfma_f32_16x16x32_bf16 v[106:109], v[184:187], v[170:173], v[106:109]
	ds_read_b128 v[220:223], v144 offset:5120
	v_mfma_f32_16x16x32_bf16 v[102:105], v[184:187], v[176:179], v[102:105]
	ds_read_b128 v[224:227], v144 offset:6144
	v_mfma_f32_16x16x32_bf16 v[98:101], v[184:187], v[180:183], v[98:101]
	ds_read_b128 v[228:231], v144 offset:7168
	v_mfma_f32_16x16x32_bf16 v[94:97], v[188:191], v[146:149], v[94:97]
	v_add_u32_e64 v144, s40, v137
	v_mfma_f32_16x16x32_bf16 v[90:93], v[188:191], v[152:155], v[90:93]
	v_mfma_f32_16x16x32_bf16 v[86:89], v[188:191], v[156:159], v[86:89]
	ds_read_b128 v[232:235], v144 offset:16384
	v_mfma_f32_16x16x32_bf16 v[82:85], v[188:191], v[162:165], v[82:85]
	ds_read_b128 v[236:239], v144 offset:17408
	v_mfma_f32_16x16x32_bf16 v[78:81], v[188:191], v[166:169], v[78:81]
	ds_read_b128 v[240:243], v144 offset:18432
	v_mfma_f32_16x16x32_bf16 v[74:77], v[188:191], v[170:173], v[74:77]
	ds_read_b128 v[244:247], v144 offset:19456
	v_mfma_f32_16x16x32_bf16 v[70:73], v[188:191], v[176:179], v[70:73]
	v_mfma_f32_16x16x32_bf16 v[66:69], v[188:191], v[180:183], v[66:69]
	v_mfma_f32_16x16x32_bf16 v[62:65], v[192:195], v[146:149], v[62:65]
	v_mfma_f32_16x16x32_bf16 v[58:61], v[192:195], v[152:155], v[58:61]
	v_mfma_f32_16x16x32_bf16 v[54:57], v[192:195], v[156:159], v[54:57]
	v_mfma_f32_16x16x32_bf16 v[50:53], v[192:195], v[162:165], v[50:53]
	v_mfma_f32_16x16x32_bf16 v[46:49], v[192:195], v[166:169], v[46:49]
	v_mfma_f32_16x16x32_bf16 v[42:45], v[192:195], v[170:173], v[42:45]
	v_mfma_f32_16x16x32_bf16 v[38:41], v[192:195], v[176:179], v[38:41]
	v_mfma_f32_16x16x32_bf16 v[34:37], v[192:195], v[180:183], v[34:37]
	v_mfma_f32_16x16x32_bf16 v[30:33], v[196:199], v[146:149], v[30:33]
	v_mfma_f32_16x16x32_bf16 v[26:29], v[196:199], v[152:155], v[26:29]
	v_mfma_f32_16x16x32_bf16 v[22:25], v[196:199], v[156:159], v[22:25]
	v_mfma_f32_16x16x32_bf16 v[18:21], v[196:199], v[162:165], v[18:21]
	v_mfma_f32_16x16x32_bf16 v[14:17], v[196:199], v[166:169], v[14:17]
	v_mfma_f32_16x16x32_bf16 v[10:13], v[196:199], v[170:173], v[10:13]
	v_mfma_f32_16x16x32_bf16 v[6:9], v[196:199], v[176:179], v[6:9]
	v_mfma_f32_16x16x32_bf16 v[2:5], v[196:199], v[180:183], v[2:5]
	s_setprio 0
	s_mov_b32 s41, s40
	s_add_i32 s40, s40, 0x6000
	s_cmp_eq_u32 s40, 0x12000
	s_cselect_b32 s40, 0, s40
	s_nop 0
	s_mov_b32 s4, 0x8000
	s_mov_b32 s5, 0
	s_mov_b32 s10, 0x10000
	s_mov_b32 s11, 0
	s_mov_b32 s44, 0x3fd744fd
	.p2align 3
	s_waitcnt lgkmcnt(0)
	s_nop 0
	v_mfma_f32_16x16x32_bf16 v[126:129], v[232:235], v[200:203], v[126:129]
	v_mfma_f32_16x16x32_bf16 v[122:125], v[232:235], v[204:207], v[122:125]
	v_mfma_f32_16x16x32_bf16 v[118:121], v[232:235], v[208:211], v[118:121]
	v_mfma_f32_16x16x32_bf16 v[114:117], v[232:235], v[212:215], v[114:117]
	v_mfma_f32_16x16x32_bf16 v[110:113], v[232:235], v[216:219], v[110:113]
	global_load_dwordx4 v[146:149], v[138:139], off offset:0
	v_mfma_f32_16x16x32_bf16 v[106:109], v[232:235], v[220:223], v[106:109]
	v_mfma_f32_16x16x32_bf16 v[102:105], v[232:235], v[224:227], v[102:105]
	global_load_dwordx4 v[152:155], v[138:139], off offset:64
	v_mfma_f32_16x16x32_bf16 v[98:101], v[232:235], v[228:231], v[98:101]
	v_lshl_add_u64 v[138:139], v[138:139], 0, s[4:5]
	v_mfma_f32_16x16x32_bf16 v[94:97], v[236:239], v[200:203], v[94:97]
	global_load_dwordx4 v[156:159], v[138:139], off offset:0
	v_mfma_f32_16x16x32_bf16 v[90:93], v[236:239], v[204:207], v[90:93]
	v_mfma_f32_16x16x32_bf16 v[86:89], v[236:239], v[208:211], v[86:89]
	global_load_dwordx4 v[162:165], v[138:139], off offset:64
	v_mfma_f32_16x16x32_bf16 v[82:85], v[236:239], v[212:215], v[82:85]
	v_lshl_add_u64 v[138:139], v[138:139], 0, s[4:5]
	v_mfma_f32_16x16x32_bf16 v[78:81], v[236:239], v[216:219], v[78:81]
	global_load_dwordx4 v[166:169], v[138:139], off offset:0
	v_mfma_f32_16x16x32_bf16 v[74:77], v[236:239], v[220:223], v[74:77]
	v_mfma_f32_16x16x32_bf16 v[70:73], v[236:239], v[224:227], v[70:73]
	global_load_dwordx4 v[170:173], v[138:139], off offset:64
	v_mfma_f32_16x16x32_bf16 v[66:69], v[236:239], v[228:231], v[66:69]
	v_lshl_add_u64 v[138:139], v[138:139], 0, s[4:5]
	v_mfma_f32_16x16x32_bf16 v[62:65], v[240:243], v[200:203], v[62:65]
	global_load_dwordx4 v[176:179], v[138:139], off offset:0
	v_mfma_f32_16x16x32_bf16 v[58:61], v[240:243], v[204:207], v[58:61]
	v_mfma_f32_16x16x32_bf16 v[54:57], v[240:243], v[208:211], v[54:57]
	global_load_dwordx4 v[180:183], v[138:139], off offset:64
	v_mfma_f32_16x16x32_bf16 v[50:53], v[240:243], v[212:215], v[50:53]
	v_lshl_add_u64 v[138:139], v[138:139], 0, s[4:5]
	v_mfma_f32_16x16x32_bf16 v[46:49], v[240:243], v[216:219], v[46:49]
	global_load_dwordx4 v[184:187], v[138:139], off offset:0
	v_mfma_f32_16x16x32_bf16 v[42:45], v[240:243], v[220:223], v[42:45]
	v_mfma_f32_16x16x32_bf16 v[38:41], v[240:243], v[224:227], v[38:41]
	global_load_dwordx4 v[188:191], v[138:139], off offset:64
	v_mfma_f32_16x16x32_bf16 v[34:37], v[240:243], v[228:231], v[34:37]
	v_lshl_add_u64 v[138:139], v[138:139], 0, s[4:5]
	v_mfma_f32_16x16x32_bf16 v[30:33], v[244:247], v[200:203], v[30:33]
	global_load_dwordx4 v[192:195], v[138:139], off offset:0
	v_mfma_f32_16x16x32_bf16 v[26:29], v[244:247], v[204:207], v[26:29]
	v_mfma_f32_16x16x32_bf16 v[22:25], v[244:247], v[208:211], v[22:25]
	global_load_dwordx4 v[196:199], v[138:139], off offset:64
	v_mfma_f32_16x16x32_bf16 v[18:21], v[244:247], v[212:215], v[18:21]
	v_lshl_add_u64 v[138:139], v[138:139], 0, s[4:5]
	v_mfma_f32_16x16x32_bf16 v[14:17], v[244:247], v[216:219], v[14:17]
	v_mfma_f32_16x16x32_bf16 v[10:13], v[244:247], v[220:223], v[10:13]
	v_mfma_f32_16x16x32_bf16 v[6:9], v[244:247], v[224:227], v[6:9]
	v_mfma_f32_16x16x32_bf16 v[2:5], v[244:247], v[228:231], v[2:5]
	s_mov_b32 m0, s43
	global_load_dwordx4 v[200:203], v[138:139], off offset:0
	global_load_dwordx4 v[204:207], v[138:139], off offset:64
	v_lshl_add_u64 v[138:139], v[138:139], 0, s[4:5]
	global_load_dwordx4 v[208:211], v[138:139], off offset:0
	global_load_dwordx4 v[212:215], v[138:139], off offset:64
	v_lshl_add_u64 v[138:139], v[138:139], 0, s[4:5]
	s_nop 7
	s_waitcnt vmcnt(15)
; DEVI float blo(unsigned u) { return __uint_as_float(u << 16); }
; DEVI float bhi(unsigned u) { return __uint_as_float(u & 0xffff0000u); }
;     ...
;         if (EPI == EPI_RESID || EPI == EPI_RESID_ATOMIC) {
;           f32x4 x = a;
;           if (EPI == EPI_RESID || kpart == 0) {
;             const u32x2 xr = *(const u32x2*)((const u16*)(p.ws + WS_XB) + (size_t)row * 1024 + col);
;             x[0] += ALPHA * blo(xr[0]); x[1] += ALPHA * bhi(xr[0]); x[2] += ALPHA * blo(xr[1]); x[3] += ALPHA * bhi(xr[1]);
;           }
;           if (EPI == EPI_RESID) *(f32x4*)((float*)(p.ws + WS_XF) + (size_t)row * 1024 + col) = x;
	v_permlane16_swap_b32_e32 v146, v148
	v_permlane16_swap_b32_e32 v147, v149
	v_lshlrev_b32_e32 v216, 16, v146
	v_and_b32_e32 v146, 0xffff0000, v146
	v_lshlrev_b32_e32 v217, 16, v147
	v_and_b32_e32 v147, 0xffff0000, v147
	v_fmac_f32_e32 v126, s44, v216
	v_fmac_f32_e32 v127, s44, v146
	v_fmac_f32_e32 v128, s44, v217
	v_fmac_f32_e32 v129, s44, v147
	global_store_dwordx4 v[140:141], v[126:129], off offset:0
	v_lshlrev_b32_e32 v216, 16, v148
	v_and_b32_e32 v148, 0xffff0000, v148
	v_lshlrev_b32_e32 v217, 16, v149
	v_and_b32_e32 v149, 0xffff0000, v149
	v_fmac_f32_e32 v94, s44, v216
	v_fmac_f32_e32 v95, s44, v148
	v_fmac_f32_e32 v96, s44, v217
	v_fmac_f32_e32 v97, s44, v149
	global_store_dwordx4 v[140:141], v[94:97], off offset:64
	s_waitcnt vmcnt(16)
	v_permlane16_swap_b32_e32 v152, v154
	v_permlane16_swap_b32_e32 v153, v155
	v_lshlrev_b32_e32 v216, 16, v152
	v_and_b32_e32 v152, 0xffff0000, v152
	v_lshlrev_b32_e32 v217, 16, v153
	v_and_b32_e32 v153, 0xffff0000, v153
	v_fmac_f32_e32 v62, s44, v216
	v_fmac_f32_e32 v63, s44, v152
	v_fmac_f32_e32 v64, s44, v217
	v_fmac_f32_e32 v65, s44, v153
	global_store_dwordx4 v[140:141], v[62:65], off offset:128
	v_lshlrev_b32_e32 v216, 16, v154
	v_and_b32_e32 v154, 0xffff0000, v154
	v_lshlrev_b32_e32 v217, 16, v155
	v_and_b32_e32 v155, 0xffff0000, v155
	v_fmac_f32_e32 v30, s44, v216
	v_fmac_f32_e32 v31, s44, v154
	v_fmac_f32_e32 v32, s44, v217
	v_fmac_f32_e32 v33, s44, v155
	global_store_dwordx4 v[140:141], v[30:33], off offset:192
	v_lshl_add_u64 v[140:141], v[140:141], 0, s[10:11]
	s_waitcnt vmcnt(17)
	v_permlane16_swap_b32_e32 v156, v158
	v_permlane16_swap_b32_e32 v157, v159
	v_lshlrev_b32_e32 v216, 16, v156
	v_and_b32_e32 v156, 0xffff0000, v156
	v_lshlrev_b32_e32 v217, 16, v157
	v_and_b32_e32 v157, 0xffff0000, v157
	v_fmac_f32_e32 v122, s44, v216
	v_fmac_f32_e32 v123, s44, v156
	v_fmac_f32_e32 v124, s44, v217
	v_fmac_f32_e32 v125, s44, v157
	global_store_dwordx4 v[140:141], v[122:125], off offset:0
	v_lshlrev_b32_e32 v216, 16, v158
	v_and_b32_e32 v158, 0xffff0000, v158
	v_lshlrev_b32_e32 v217, 16, v159
	v_and_b32_e32 v159, 0xffff0000, v159
	v_fmac_f32_e32 v90, s44, v216
	v_fmac_f32_e32 v91, s44, v158
	v_fmac_f32_e32 v92, s44, v217
	v_fmac_f32_e32 v93, s44, v159
	global_store_dwordx4 v[140:141], v[90:93], off offset:64
	s_waitcnt vmcnt(18)
	v_permlane16_swap_b32_e32 v162, v164
	v_permlane16_swap_b32_e32 v163, v165
	v_lshlrev_b32_e32 v216, 16, v162
	v_and_b32_e32 v162, 0xffff0000, v162
	v_lshlrev_b32_e32 v217, 16, v163
	v_and_b32_e32 v163, 0xffff0000, v163
	v_fmac_f32_e32 v58, s44, v216
	v_fmac_f32_e32 v59, s44, v162
	v_fmac_f32_e32 v60, s44, v217
	v_fmac_f32_e32 v61, s44, v163
	global_store_dwordx4 v[140:141], v[58:61], off offset:128
	v_lshlrev_b32_e32 v216, 16, v164
	v_and_b32_e32 v164, 0xffff0000, v164
	v_lshlrev_b32_e32 v217, 16, v165
	v_and_b32_e32 v165, 0xffff0000, v165
	v_fmac_f32_e32 v26, s44, v216
	v_fmac_f32_e32 v27, s44, v164
	v_fmac_f32_e32 v28, s44, v217
	v_fmac_f32_e32 v29, s44, v165
	global_store_dwordx4 v[140:141], v[26:29], off offset:192
	v_lshl_add_u64 v[140:141], v[140:141], 0, s[10:11]
	s_waitcnt vmcnt(19)
	v_permlane16_swap_b32_e32 v166, v168
	v_permlane16_swap_b32_e32 v167, v169
	v_lshlrev_b32_e32 v216, 16, v166
	v_and_b32_e32 v166, 0xffff0000, v166
	v_lshlrev_b32_e32 v217, 16, v167
	v_and_b32_e32 v167, 0xffff0000, v167
	v_fmac_f32_e32 v118, s44, v216
	v_fmac_f32_e32 v119, s44, v166
	v_fmac_f32_e32 v120, s44, v217
	v_fmac_f32_e32 v121, s44, v167
	global_store_dwordx4 v[140:141], v[118:121], off offset:0
	v_lshlrev_b32_e32 v216, 16, v168
	v_and_b32_e32 v168, 0xffff0000, v168
	v_lshlrev_b32_e32 v217, 16, v169
	v_and_b32_e32 v169, 0xffff0000, v169
	v_fmac_f32_e32 v86, s44, v216
	v_fmac_f32_e32 v87, s44, v168
	v_fmac_f32_e32 v88, s44, v217
	v_fmac_f32_e32 v89, s44, v169
	global_store_dwordx4 v[140:141], v[86:89], off offset:64
	s_waitcnt vmcnt(20)
	v_permlane16_swap_b32_e32 v170, v172
	v_permlane16_swap_b32_e32 v171, v173
	v_lshlrev_b32_e32 v216, 16, v170
	v_and_b32_e32 v170, 0xffff0000, v170
	v_lshlrev_b32_e32 v217, 16, v171
	v_and_b32_e32 v171, 0xffff0000, v171
	v_fmac_f32_e32 v54, s44, v216
	v_fmac_f32_e32 v55, s44, v170
	v_fmac_f32_e32 v56, s44, v217
	v_fmac_f32_e32 v57, s44, v171
	global_store_dwordx4 v[140:141], v[54:57], off offset:128
	v_lshlrev_b32_e32 v216, 16, v172
	v_and_b32_e32 v172, 0xffff0000, v172
	v_lshlrev_b32_e32 v217, 16, v173
	v_and_b32_e32 v173, 0xffff0000, v173
	v_fmac_f32_e32 v22, s44, v216
	v_fmac_f32_e32 v23, s44, v172
	v_fmac_f32_e32 v24, s44, v217
	v_fmac_f32_e32 v25, s44, v173
	global_store_dwordx4 v[140:141], v[22:25], off offset:192
	v_lshl_add_u64 v[140:141], v[140:141], 0, s[10:11]
	s_waitcnt vmcnt(21)
	v_permlane16_swap_b32_e32 v176, v178
	v_permlane16_swap_b32_e32 v177, v179
	v_lshlrev_b32_e32 v216, 16, v176
	v_and_b32_e32 v176, 0xffff0000, v176
	v_lshlrev_b32_e32 v217, 16, v177
	v_and_b32_e32 v177, 0xffff0000, v177
	v_fmac_f32_e32 v114, s44, v216
	v_fmac_f32_e32 v115, s44, v176
	v_fmac_f32_e32 v116, s44, v217
	v_fmac_f32_e32 v117, s44, v177
	global_store_dwordx4 v[140:141], v[114:117], off offset:0
	v_lshlrev_b32_e32 v216, 16, v178
	v_and_b32_e32 v178, 0xffff0000, v178
	v_lshlrev_b32_e32 v217, 16, v179
	v_and_b32_e32 v179, 0xffff0000, v179
	v_fmac_f32_e32 v82, s44, v216
	v_fmac_f32_e32 v83, s44, v178
	v_fmac_f32_e32 v84, s44, v217
	v_fmac_f32_e32 v85, s44, v179
	global_store_dwordx4 v[140:141], v[82:85], off offset:64
	s_waitcnt vmcnt(22)
; DEVI float blo(unsigned u) { return __uint_as_float(u << 16); }
; DEVI float bhi(unsigned u) { return __uint_as_float(u & 0xffff0000u); }
; DEVI int xcd_first_tile() { return (blockIdx.x & 7) * (gridDim.x >> 3) + (blockIdx.x >> 3); }
;     ...
;         if (EPI == EPI_RESID || EPI == EPI_RESID_ATOMIC) {
;           f32x4 x = a;
;           if (EPI == EPI_RESID || kpart == 0) {
;             const u32x2 xr = *(const u32x2*)((const u16*)(p.ws + WS_XB) + (size_t)row * 1024 + col);
;             x[0] += ALPHA * blo(xr[0]); x[1] += ALPHA * bhi(xr[0]); x[2] += ALPHA * blo(xr[1]); x[3] += ALPHA * bhi(xr[1]);
;           }
;           if (EPI == EPI_RESID) *(f32x4*)((float*)(p.ws + WS_XF) + (size_t)row * 1024 + col) = x;
; DEVI void run_phase(const Params& p, int ph, char* smem) {
;     ...
;       for (int t = xcd_first_tile(); t < 512 + 16 * 2; t += xcd_tile_step()) {
	v_permlane16_swap_b32_e32 v180, v182
	v_permlane16_swap_b32_e32 v181, v183
	v_lshlrev_b32_e32 v216, 16, v180
	v_and_b32_e32 v180, 0xffff0000, v180
	v_lshlrev_b32_e32 v217, 16, v181
	v_and_b32_e32 v181, 0xffff0000, v181
	v_fmac_f32_e32 v50, s44, v216
	v_fmac_f32_e32 v51, s44, v180
	v_fmac_f32_e32 v52, s44, v217
	v_fmac_f32_e32 v53, s44, v181
	global_store_dwordx4 v[140:141], v[50:53], off offset:128
	v_lshlrev_b32_e32 v216, 16, v182
	v_and_b32_e32 v182, 0xffff0000, v182
	v_lshlrev_b32_e32 v217, 16, v183
	v_and_b32_e32 v183, 0xffff0000, v183
	v_fmac_f32_e32 v18, s44, v216
	v_fmac_f32_e32 v19, s44, v182
	v_fmac_f32_e32 v20, s44, v217
	v_fmac_f32_e32 v21, s44, v183
	global_store_dwordx4 v[140:141], v[18:21], off offset:192
	v_lshl_add_u64 v[140:141], v[140:141], 0, s[10:11]
	s_waitcnt vmcnt(23)
	v_permlane16_swap_b32_e32 v184, v186
	v_permlane16_swap_b32_e32 v185, v187
	v_lshlrev_b32_e32 v216, 16, v184
	v_and_b32_e32 v184, 0xffff0000, v184
	v_lshlrev_b32_e32 v217, 16, v185
	v_and_b32_e32 v185, 0xffff0000, v185
	v_fmac_f32_e32 v110, s44, v216
	v_fmac_f32_e32 v111, s44, v184
	v_fmac_f32_e32 v112, s44, v217
	v_fmac_f32_e32 v113, s44, v185
	global_store_dwordx4 v[140:141], v[110:113], off offset:0
	v_lshlrev_b32_e32 v216, 16, v186
	v_and_b32_e32 v186, 0xffff0000, v186
	v_lshlrev_b32_e32 v217, 16, v187
	v_and_b32_e32 v187, 0xffff0000, v187
	v_fmac_f32_e32 v78, s44, v216
	v_fmac_f32_e32 v79, s44, v186
	v_fmac_f32_e32 v80, s44, v217
	v_fmac_f32_e32 v81, s44, v187
	global_store_dwordx4 v[140:141], v[78:81], off offset:64
	s_waitcnt vmcnt(24)
	v_permlane16_swap_b32_e32 v188, v190
	v_permlane16_swap_b32_e32 v189, v191
	v_lshlrev_b32_e32 v216, 16, v188
	v_and_b32_e32 v188, 0xffff0000, v188
	v_lshlrev_b32_e32 v217, 16, v189
	v_and_b32_e32 v189, 0xffff0000, v189
	v_fmac_f32_e32 v46, s44, v216
	v_fmac_f32_e32 v47, s44, v188
	v_fmac_f32_e32 v48, s44, v217
	v_fmac_f32_e32 v49, s44, v189
	global_store_dwordx4 v[140:141], v[46:49], off offset:128
	v_lshlrev_b32_e32 v216, 16, v190
	v_and_b32_e32 v190, 0xffff0000, v190
	v_lshlrev_b32_e32 v217, 16, v191
	v_and_b32_e32 v191, 0xffff0000, v191
	v_fmac_f32_e32 v14, s44, v216
	v_fmac_f32_e32 v15, s44, v190
	v_fmac_f32_e32 v16, s44, v217
	v_fmac_f32_e32 v17, s44, v191
	global_store_dwordx4 v[140:141], v[14:17], off offset:192
	v_lshl_add_u64 v[140:141], v[140:141], 0, s[10:11]
	s_waitcnt vmcnt(25)
	v_permlane16_swap_b32_e32 v192, v194
	v_permlane16_swap_b32_e32 v193, v195
	v_lshlrev_b32_e32 v216, 16, v192
	v_and_b32_e32 v192, 0xffff0000, v192
	v_lshlrev_b32_e32 v217, 16, v193
	v_and_b32_e32 v193, 0xffff0000, v193
	v_fmac_f32_e32 v106, s44, v216
	v_fmac_f32_e32 v107, s44, v192
	v_fmac_f32_e32 v108, s44, v217
	v_fmac_f32_e32 v109, s44, v193
	global_store_dwordx4 v[140:141], v[106:109], off offset:0
	v_lshlrev_b32_e32 v216, 16, v194
	v_and_b32_e32 v194, 0xffff0000, v194
	v_lshlrev_b32_e32 v217, 16, v195
	v_and_b32_e32 v195, 0xffff0000, v195
	v_fmac_f32_e32 v74, s44, v216
	v_fmac_f32_e32 v75, s44, v194
	v_fmac_f32_e32 v76, s44, v217
	v_fmac_f32_e32 v77, s44, v195
	global_store_dwordx4 v[140:141], v[74:77], off offset:64
	s_waitcnt vmcnt(26)
	v_permlane16_swap_b32_e32 v196, v198
	v_permlane16_swap_b32_e32 v197, v199
	v_lshlrev_b32_e32 v216, 16, v196
	v_and_b32_e32 v196, 0xffff0000, v196
	v_lshlrev_b32_e32 v217, 16, v197
	v_and_b32_e32 v197, 0xffff0000, v197
	v_fmac_f32_e32 v42, s44, v216
	v_fmac_f32_e32 v43, s44, v196
	v_fmac_f32_e32 v44, s44, v217
	v_fmac_f32_e32 v45, s44, v197
	global_store_dwordx4 v[140:141], v[42:45], off offset:128
	v_lshlrev_b32_e32 v216, 16, v198
	v_and_b32_e32 v198, 0xffff0000, v198
	v_lshlrev_b32_e32 v217, 16, v199
	v_and_b32_e32 v199, 0xffff0000, v199
	v_fmac_f32_e32 v10, s44, v216
	v_fmac_f32_e32 v11, s44, v198
	v_fmac_f32_e32 v12, s44, v217
	v_fmac_f32_e32 v13, s44, v199
	global_store_dwordx4 v[140:141], v[10:13], off offset:192
	v_lshl_add_u64 v[140:141], v[140:141], 0, s[10:11]
	s_waitcnt vmcnt(27)
	v_permlane16_swap_b32_e32 v200, v202
	v_permlane16_swap_b32_e32 v201, v203
	v_lshlrev_b32_e32 v216, 16, v200
	v_and_b32_e32 v200, 0xffff0000, v200
	v_lshlrev_b32_e32 v217, 16, v201
	v_and_b32_e32 v201, 0xffff0000, v201
	v_fmac_f32_e32 v102, s44, v216
	v_fmac_f32_e32 v103, s44, v200
	v_fmac_f32_e32 v104, s44, v217
	v_fmac_f32_e32 v105, s44, v201
	global_store_dwordx4 v[140:141], v[102:105], off offset:0
	v_lshlrev_b32_e32 v216, 16, v202
	v_and_b32_e32 v202, 0xffff0000, v202
	v_lshlrev_b32_e32 v217, 16, v203
	v_and_b32_e32 v203, 0xffff0000, v203
	v_fmac_f32_e32 v70, s44, v216
	v_fmac_f32_e32 v71, s44, v202
	v_fmac_f32_e32 v72, s44, v217
	v_fmac_f32_e32 v73, s44, v203
	global_store_dwordx4 v[140:141], v[70:73], off offset:64
	s_waitcnt vmcnt(28)
	v_permlane16_swap_b32_e32 v204, v206
	v_permlane16_swap_b32_e32 v205, v207
	v_lshlrev_b32_e32 v216, 16, v204
	v_and_b32_e32 v204, 0xffff0000, v204
	v_lshlrev_b32_e32 v217, 16, v205
	v_and_b32_e32 v205, 0xffff0000, v205
	v_fmac_f32_e32 v38, s44, v216
	v_fmac_f32_e32 v39, s44, v204
	v_fmac_f32_e32 v40, s44, v217
	v_fmac_f32_e32 v41, s44, v205
	global_store_dwordx4 v[140:141], v[38:41], off offset:128
	v_lshlrev_b32_e32 v216, 16, v206
	v_and_b32_e32 v206, 0xffff0000, v206
	v_lshlrev_b32_e32 v217, 16, v207
	v_and_b32_e32 v207, 0xffff0000, v207
	v_fmac_f32_e32 v6, s44, v216
	v_fmac_f32_e32 v7, s44, v206
	v_fmac_f32_e32 v8, s44, v217
	v_fmac_f32_e32 v9, s44, v207
	global_store_dwordx4 v[140:141], v[6:9], off offset:192
	v_lshl_add_u64 v[140:141], v[140:141], 0, s[10:11]
	s_waitcnt vmcnt(29)
	v_permlane16_swap_b32_e32 v208, v210
	v_permlane16_swap_b32_e32 v209, v211
	v_lshlrev_b32_e32 v216, 16, v208
	v_and_b32_e32 v208, 0xffff0000, v208
	v_lshlrev_b32_e32 v217, 16, v209
	v_and_b32_e32 v209, 0xffff0000, v209
	v_fmac_f32_e32 v98, s44, v216
	v_fmac_f32_e32 v99, s44, v208
	v_fmac_f32_e32 v100, s44, v217
	v_fmac_f32_e32 v101, s44, v209
	global_store_dwordx4 v[140:141], v[98:101], off offset:0
	v_lshlrev_b32_e32 v216, 16, v210
	v_and_b32_e32 v210, 0xffff0000, v210
	v_lshlrev_b32_e32 v217, 16, v211
	v_and_b32_e32 v211, 0xffff0000, v211
	v_fmac_f32_e32 v66, s44, v216
	v_fmac_f32_e32 v67, s44, v210
	v_fmac_f32_e32 v68, s44, v217
	v_fmac_f32_e32 v69, s44, v211
	global_store_dwordx4 v[140:141], v[66:69], off offset:64
	s_waitcnt vmcnt(30)
	v_permlane16_swap_b32_e32 v212, v214
	v_permlane16_swap_b32_e32 v213, v215
	v_lshlrev_b32_e32 v216, 16, v212
	v_and_b32_e32 v212, 0xffff0000, v212
	v_lshlrev_b32_e32 v217, 16, v213
	v_and_b32_e32 v213, 0xffff0000, v213
	v_fmac_f32_e32 v34, s44, v216
	v_fmac_f32_e32 v35, s44, v212
	v_fmac_f32_e32 v36, s44, v217
	v_fmac_f32_e32 v37, s44, v213
	global_store_dwordx4 v[140:141], v[34:37], off offset:128
	v_lshlrev_b32_e32 v216, 16, v214
	v_and_b32_e32 v214, 0xffff0000, v214
	v_lshlrev_b32_e32 v217, 16, v215
	v_and_b32_e32 v215, 0xffff0000, v215
	v_fmac_f32_e32 v2, s44, v216
	v_fmac_f32_e32 v3, s44, v214
	v_fmac_f32_e32 v4, s44, v217
	v_fmac_f32_e32 v5, s44, v215
	global_store_dwordx4 v[140:141], v[2:5], off offset:192
	v_readlane_b32 s39, v250, 7
	s_cmpk_lg_u32 s39, 0x200
	s_cbranch_scc1 .LBB0_146
; DEVI int xcd_first_tile() { return (blockIdx.x & 7) * (gridDim.x >> 3) + (blockIdx.x >> 3); }
; DEVI void run_phase(const Params& p, int ph, char* smem) {
;     ...
;       for (int t = xcd_first_tile(); t < 512 + 16 * 2; t += xcd_tile_step()) {
	v_readlane_b32 s40, v250, 0
	s_lshr_b32 s41, s40, 3
	s_and_b32 s40, s40, 7
	s_mul_i32 s40, s40, 4
	s_add_i32 s40, s40, s41
	s_cmp_lt_u32 s41, 4
	s_cselect_b32 s38, s40, 0x4000
	s_branch .LBB0_146

; #define LAS __attribute__((address_space(3)))
;     ...
;   const int nk = (nk_part < 0) ? (K >> 5) : nk_part;
;   const int lrow = tid >> 2, lpc = tid & 3;
;   const int lch = lpc ^ ((0x78 >> (((lrow >> 2) & 3) * 2)) & 3);
;   const u16* ga = A + (size_t)(m0 + lrow) * lda + kbeg + lch * 8;
;   const u16* gb = Bt + (size_t)(n0 + lrow) * K + kbeg + lch * 8;
;   const size_t ga1 = (size_t)64 * lda, gb1 = (size_t)64 * K;
;   const unsigned lds0 = (unsigned)(uintptr_t)(LAS char*)smem + (unsigned)__builtin_amdgcn_readfirstlane(wid) * 1024u;
;     ...
;   __syncthreads();
;   G2_STAGE(0); G2_STAGE(1);
; DEVI void run_phase(const Params& p, int ph, char* smem) {
;     ...
;           const int u_ = t - 512, tl_ = u_ / 8, q_ = u_ - tl_ * 8;
;           gemm_tile256<EPI_RESID_ATOMIC>(p, mix, 1024, Bt, 1024, (64 + (tl_ & 1)) * 256, (tl_ >> 1) * 128, nullptr, 0, smem, q_ * 128, 4, q_);
.LBB0_758:
	s_cmpk_gt_i32 s39, 0x1ff
	s_mov_b64 s[2:3], -1
	s_cbranch_scc0 .LBB0_812
	s_sub_i32 s43, s39, 512
	s_lshr_b32 s42, s43, 3
	s_and_b32 s98, s43, 7
	s_lshr_b32 s15, s42, 1
	s_and_b32 s42, s42, 1
	s_add_i32 s42, s42, 64
	v_readlane_b32 s2, v250, 5
	v_readlane_b32 s3, v250, 6
	v_readlane_b32 s43, v254, 62
	s_mul_i32 s1, s42, 0x80000
	s_add_u32 s4, s2, s1
	s_addc_u32 s5, s3, 0
	s_add_u32 s4, s4, 0xb580000
	s_addc_u32 s5, s5, 0
	s_mul_i32 s1, s43, 0x200000
	s_mul_i32 s14, s15, 0x40000
	s_add_i32 s1, s1, s14
	s_add_u32 s10, s2, s1
	s_addc_u32 s11, s3, 0
	s_add_u32 s10, s10, 0x15e00000
	s_addc_u32 s11, s11, 0
	s_mul_i32 s1, s98, 256
	s_add_u32 s4, s4, s1
	s_addc_u32 s5, s5, 0
	s_mul_i32 s1, s98, 512
	s_add_u32 s10, s10, s1
	s_addc_u32 s11, s11, 0
	s_movk_i32 s0, 0x78
	v_lshrrev_b32_e32 v0, 2, v145
	v_and_b32_e32 v131, 3, v145
	v_bfe_u32 v136, v145, 4, 2
	v_lshlrev_b32_e32 v136, 1, v136
	v_lshrrev_b32_e64 v136, v136, s0
	v_and_b32_e32 v136, 3, v136
	v_xor_b32_e32 v131, v131, v136
	v_lshlrev_b32_e32 v131, 4, v131
	s_movk_i32 s14, 0x800
	v_mad_u32_u24 v0, v0, s14, v131
	v_bfe_u32 v137, v145, 2, 1
	s_movk_i32 s14, 0x7c0
	v_mul_u32_u24_e32 v136, s14, v137
	v_sub_u32_e32 v136, v0, v136
	v_mov_b32_e32 v137, 0
	v_lshl_add_u64 v[134:135], s[10:11], 0, v[136:137]
	v_bfe_u32 v137, v145, 2, 1
	s_mov_b32 s12, 64
	s_mov_b32 s13, 0
	v_lshl_add_u64 v[132:133], s[4:5], 0, v[0:1]
	v_bfe_u32 v136, v145, 2, 2
	v_lshlrev_b32_e32 v136, 1, v136
	v_lshrrev_b32_e64 v136, v136, s0
	v_and_b32_e32 v136, 3, v136
	v_bfe_u32 v137, v145, 4, 2
	v_xor_b32_e32 v136, v136, v137
	v_lshlrev_b32_e32 v136, 4, v136
	v_and_b32_e32 v131, 15, v145
	v_lshl_or_b32 v136, v131, 6, v136
	v_bfe_u32 v137, v145, 6, 1
	v_lshl_or_b32 v137, v137, 12, v136
	v_lshrrev_b32_e32 v0, 7, v145
	v_lshl_or_b32 v136, v0, 13, v136
	v_and_b32_e32 v140, 1, v131
	v_lshl_or_b32 v131, v0, 7, v131
	v_bfe_u32 v0, v145, 4, 2
	v_lshlrev_b32_e32 v0, 3, v0
	v_bfe_u32 v141, v145, 6, 1
	s_lshl_b32 s1, s42, 19
	s_lshl_b32 s14, s15, 8
	s_add_i32 s1, s1, s14
	s_add_u32 s4, s2, s1
	s_addc_u32 s5, s3, 0
	s_add_u32 s4, s4, 0x4200000
	s_addc_u32 s5, s5, 0
	v_lshlrev_b32_e32 v138, 11, v131
	v_lshl_add_u32 v138, v141, 7, v138
	v_bfe_u32 v139, v145, 4, 1
	v_lshl_add_u32 v138, v139, 5, v138
	v_bfe_u32 v139, v145, 5, 1
	v_lshl_add_u32 v138, v139, 4, v138
	v_mov_b32_e32 v139, 0
	v_lshl_add_u64 v[138:139], s[4:5], 0, v[138:139]
	s_and_b32 s1, s42, 1
	s_lshl_b32 s1, s1, 20
	s_lshl_b32 s14, s98, 21
	s_add_i32 s1, s1, s14
	s_lshl_b32 s14, s15, 9
	s_add_i32 s1, s1, s14
	s_add_u32 s10, s2, s1
	s_addc_u32 s11, s3, 0
	s_add_u32 s10, s10, 0x1dcc0000
	s_addc_u32 s11, s11, 0
	v_lshlrev_b32_e32 v140, 12, v131
	v_lshl_add_u32 v140, v141, 8, v140
	v_lshl_add_u32 v140, v0, 1, v140
	v_mov_b32_e32 v141, 0
	v_lshl_add_u64 v[140:141], s[10:11], 0, v[140:141]
	s_mov_b32 s2, 0x20000
	s_mov_b32 s3, 0
	v_lshrrev_b32_e32 v0, 6, v145
	v_lshlrev_b32_e32 v0, 10, v0
	s_nop 0
	v_readfirstlane_b32 s43, v0
	s_mov_b32 s40, m0
	s_mov_b32 s4, 128
	s_mov_b32 s5, 0
	s_barrier
	s_add_i32 s15, s43, 0x0
	s_mov_b32 m0, s15
	v_lshl_add_u64 v[142:143], v[132:133], 0, s[2:3]
	global_load_lds_dwordx4 v[132:133], off
	s_add_i32 m0, m0, 0x1000
	s_nop 0
	global_load_lds_dwordx4 v[142:143], off
	v_lshl_add_u64 v[142:143], v[142:143], 0, s[2:3]
	s_add_i32 m0, m0, 0x1000
	s_nop 0
	global_load_lds_dwordx4 v[142:143], off
	v_lshl_add_u64 v[142:143], v[142:143], 0, s[2:3]
	s_add_i32 m0, m0, 0x1000
	s_nop 0
	global_load_lds_dwordx4 v[142:143], off
	s_add_i32 m0, m0, 0x1000
	v_lshl_add_u64 v[142:143], v[134:135], 0, s[2:3]
	s_nop 0
	global_load_lds_dwordx4 v[134:135], off
	s_add_i32 m0, m0, 0x1000
	v_lshl_add_u64 v[132:133], v[132:133], 0, s[12:13]
	s_nop 0
	global_load_lds_dwordx4 v[142:143], off
	v_lshl_add_u64 v[134:135], v[134:135], 0, s[4:5]
	s_nop 0
	s_add_i32 s15, s43, 0x6000
	s_mov_b32 m0, s15
	v_lshl_add_u64 v[142:143], v[132:133], 0, s[2:3]
	global_load_lds_dwordx4 v[132:133], off
	s_add_i32 m0, m0, 0x1000
	s_nop 0
	global_load_lds_dwordx4 v[142:143], off
	v_lshl_add_u64 v[142:143], v[142:143], 0, s[2:3]
	s_add_i32 m0, m0, 0x1000
	s_nop 0
	global_load_lds_dwordx4 v[142:143], off
	v_lshl_add_u64 v[142:143], v[142:143], 0, s[2:3]
	s_add_i32 m0, m0, 0x1000
	s_nop 0
	global_load_lds_dwordx4 v[142:143], off
	s_add_i32 m0, m0, 0x1000
	v_lshl_add_u64 v[142:143], v[134:135], 0, s[2:3]
	s_nop 0
	global_load_lds_dwordx4 v[134:135], off
	s_add_i32 m0, m0, 0x1000
	v_lshl_add_u64 v[132:133], v[132:133], 0, s[12:13]
	s_nop 0
	global_load_lds_dwordx4 v[142:143], off
	v_lshl_add_u64 v[134:135], v[134:135], 0, s[4:5]
	s_nop 0
	s_add_i32 s15, s43, 0xc000
	s_mov_b32 m0, s15
	v_lshl_add_u64 v[142:143], v[132:133], 0, s[2:3]
	global_load_lds_dwordx4 v[132:133], off
	s_add_i32 m0, m0, 0x1000
	s_nop 0
	global_load_lds_dwordx4 v[142:143], off
	v_lshl_add_u64 v[142:143], v[142:143], 0, s[2:3]
	s_add_i32 m0, m0, 0x1000
	s_nop 0
	global_load_lds_dwordx4 v[142:143], off
	v_lshl_add_u64 v[142:143], v[142:143], 0, s[2:3]
	s_add_i32 m0, m0, 0x1000
	s_nop 0
	global_load_lds_dwordx4 v[142:143], off
	s_add_i32 m0, m0, 0x1000
	v_lshl_add_u64 v[142:143], v[134:135], 0, s[2:3]
	s_nop 0
	global_load_lds_dwordx4 v[134:135], off
	s_add_i32 m0, m0, 0x1000
	v_lshl_add_u64 v[132:133], v[132:133], 0, s[12:13]
	s_nop 0
	global_load_lds_dwordx4 v[142:143], off
	v_lshl_add_u64 v[134:135], v[134:135], 0, s[4:5]
	s_nop 0
	v_mov_b32_e32 v2, 0
	v_mov_b32_e32 v3, 0
	v_mov_b32_e32 v4, 0
	v_mov_b32_e32 v5, 0
	v_mov_b32_e32 v6, 0
	v_mov_b32_e32 v7, 0
	v_mov_b32_e32 v8, 0
	v_mov_b32_e32 v9, 0
	v_mov_b32_e32 v10, 0
	v_mov_b32_e32 v11, 0
	v_mov_b32_e32 v12, 0
	v_mov_b32_e32 v13, 0
	v_mov_b32_e32 v14, 0
	v_mov_b32_e32 v15, 0
; #define LAS __attribute__((address_space(3)))
;     ...
;   f32x4 acc[4][8];
; #pragma unroll
;   for (int i = 0; i < 4; i++)
; #pragma unroll
;     for (int j = 0; j < 8; j++) acc[i][j] = (f32x4){0.f, 0.f, 0.f, 0.f};
;   const int nk = (nk_part < 0) ? (K >> 5) : nk_part;
;   const int lrow = tid >> 2, lpc = tid & 3;
;   const int lch = lpc ^ ((0x78 >> (((lrow >> 2) & 3) * 2)) & 3);
;   const u16* ga = A + (size_t)(m0 + lrow) * lda + kbeg + lch * 8;
;   const u16* gb = Bt + (size_t)(n0 + lrow) * K + kbeg + lch * 8;
;   const size_t ga1 = (size_t)64 * lda, gb1 = (size_t)64 * K;
;   const unsigned lds0 = (unsigned)(uintptr_t)(LAS char*)smem + (unsigned)__builtin_amdgcn_readfirstlane(wid) * 1024u;
;     ...
;   __syncthreads();
;   G2_STAGE(0); G2_STAGE(1);
;   const int fsw = (0x78 >> (((r16 >> 2) & 3) * 2)) & 3;
;   const int aoff = (wm * 128 + r16) * 64 + ((quad ^ fsw) << 4);
;   const int boff = 16384 + (wn * 64 + r16) * 64 + ((quad ^ fsw) << 4);
;   for (int kt = 0; kt < nk; kt++) {
;     if (kt + 1 < nk) asm volatile("s_waitcnt vmcnt(6)" ::: "memory");
;     else asm volatile("s_waitcnt vmcnt(0)" ::: "memory");
;     __builtin_amdgcn_s_barrier();
;     asm volatile("" ::: "memory");
;     if (kt + 2 < nk) G2_STAGE(kt + 2);
;     const char* cS = smem + (kt % 3) * 24576;
;     bf16x8 xa[8], wb[4];
; #pragma unroll
;     for (int f = 0; f < 8; f++) xa[f] = *(const bf16x8*)(cS + aoff + f * 1024);
; #pragma unroll
;     for (int f = 0; f < 4; f++) wb[f] = *(const bf16x8*)(cS + boff + f * 1024);
; #pragma unroll
;     for (int nf = 0; nf < 4; nf++)
; #pragma unroll
;       for (int mf = 0; mf < 8; mf++)
;         acc[nf][mf] = __builtin_amdgcn_mfma_f32_16x16x32_bf16(wb[nf], xa[mf], acc[nf][mf], 0, 0, 0);
	v_mov_b32_e32 v16, 0
	v_mov_b32_e32 v17, 0
	v_mov_b32_e32 v18, 0
	v_mov_b32_e32 v19, 0
	v_mov_b32_e32 v20, 0
	v_mov_b32_e32 v21, 0
	v_mov_b32_e32 v22, 0
	v_mov_b32_e32 v23, 0
	v_mov_b32_e32 v24, 0
	v_mov_b32_e32 v25, 0
	v_mov_b32_e32 v26, 0
	v_mov_b32_e32 v27, 0
	v_mov_b32_e32 v28, 0
	v_mov_b32_e32 v29, 0
	v_mov_b32_e32 v30, 0
	v_mov_b32_e32 v31, 0
	v_mov_b32_e32 v32, 0
	v_mov_b32_e32 v33, 0
	v_mov_b32_e32 v34, 0
	v_mov_b32_e32 v35, 0
	v_mov_b32_e32 v36, 0
	v_mov_b32_e32 v37, 0
	v_mov_b32_e32 v38, 0
	v_mov_b32_e32 v39, 0
	v_mov_b32_e32 v40, 0
	v_mov_b32_e32 v41, 0
	v_mov_b32_e32 v42, 0
	v_mov_b32_e32 v43, 0
	v_mov_b32_e32 v44, 0
	v_mov_b32_e32 v45, 0
	v_mov_b32_e32 v46, 0
	v_mov_b32_e32 v47, 0
	v_mov_b32_e32 v48, 0
	v_mov_b32_e32 v49, 0
	v_mov_b32_e32 v50, 0
	v_mov_b32_e32 v51, 0
	v_mov_b32_e32 v52, 0
	v_mov_b32_e32 v53, 0
	v_mov_b32_e32 v54, 0
	v_mov_b32_e32 v55, 0
	v_mov_b32_e32 v56, 0
	v_mov_b32_e32 v57, 0
	v_mov_b32_e32 v58, 0
	v_mov_b32_e32 v59, 0
	v_mov_b32_e32 v60, 0
	v_mov_b32_e32 v61, 0
	v_mov_b32_e32 v62, 0
	v_mov_b32_e32 v63, 0
	v_mov_b32_e32 v64, 0
	v_mov_b32_e32 v65, 0
	v_mov_b32_e32 v66, 0
	v_mov_b32_e32 v67, 0
	v_mov_b32_e32 v68, 0
	v_mov_b32_e32 v69, 0
	v_mov_b32_e32 v70, 0
	v_mov_b32_e32 v71, 0
	v_mov_b32_e32 v72, 0
	v_mov_b32_e32 v73, 0
	v_mov_b32_e32 v74, 0
	v_mov_b32_e32 v75, 0
	v_mov_b32_e32 v76, 0
	v_mov_b32_e32 v77, 0
	v_mov_b32_e32 v78, 0
	v_mov_b32_e32 v79, 0
	v_mov_b32_e32 v80, 0
	v_mov_b32_e32 v81, 0
	v_mov_b32_e32 v82, 0
	v_mov_b32_e32 v83, 0
	v_mov_b32_e32 v84, 0
	v_mov_b32_e32 v85, 0
	v_mov_b32_e32 v86, 0
	v_mov_b32_e32 v87, 0
	v_mov_b32_e32 v88, 0
	v_mov_b32_e32 v89, 0
	v_mov_b32_e32 v90, 0
	v_mov_b32_e32 v91, 0
	v_mov_b32_e32 v92, 0
	v_mov_b32_e32 v93, 0
	v_mov_b32_e32 v94, 0
	v_mov_b32_e32 v95, 0
	v_mov_b32_e32 v96, 0
	v_mov_b32_e32 v97, 0
	v_mov_b32_e32 v98, 0
	v_mov_b32_e32 v99, 0
	v_mov_b32_e32 v100, 0
	v_mov_b32_e32 v101, 0
	v_mov_b32_e32 v102, 0
	v_mov_b32_e32 v103, 0
	v_mov_b32_e32 v104, 0
	v_mov_b32_e32 v105, 0
	v_mov_b32_e32 v106, 0
	v_mov_b32_e32 v107, 0
	v_mov_b32_e32 v108, 0
	v_mov_b32_e32 v109, 0
	v_mov_b32_e32 v110, 0
	v_mov_b32_e32 v111, 0
	v_mov_b32_e32 v112, 0
	v_mov_b32_e32 v113, 0
	v_mov_b32_e32 v114, 0
	v_mov_b32_e32 v115, 0
	v_mov_b32_e32 v116, 0
	v_mov_b32_e32 v117, 0
	v_mov_b32_e32 v118, 0
	v_mov_b32_e32 v119, 0
	v_mov_b32_e32 v120, 0
	v_mov_b32_e32 v121, 0
	v_mov_b32_e32 v122, 0
	v_mov_b32_e32 v123, 0
	v_mov_b32_e32 v124, 0
	v_mov_b32_e32 v125, 0
	v_mov_b32_e32 v126, 0
	v_mov_b32_e32 v127, 0
	v_mov_b32_e32 v128, 0
	v_mov_b32_e32 v129, 0
	s_waitcnt vmcnt(12)
	s_barrier
	ds_read_b128 v[146:149], v136 offset:0
	ds_read_b128 v[152:155], v136 offset:1024
	ds_read_b128 v[156:159], v136 offset:2048
	ds_read_b128 v[162:165], v136 offset:3072
	ds_read_b128 v[166:169], v136 offset:4096
	ds_read_b128 v[170:173], v136 offset:5120
	ds_read_b128 v[176:179], v136 offset:6144
	ds_read_b128 v[180:183], v136 offset:7168
	ds_read_b128 v[184:187], v137 offset:16384
	ds_read_b128 v[188:191], v137 offset:17408
	ds_read_b128 v[192:195], v137 offset:18432
	ds_read_b128 v[196:199], v137 offset:19456
	s_movk_i32 s1, 0x6000
	s_mov_b32 s14, 0
	.p2align 3
	s_waitcnt vmcnt(6) lgkmcnt(0)
	s_barrier
	s_setprio 1
	v_add_u32_e32 v144, s1, v136
	v_mfma_f32_16x16x32_bf16 v[126:129], v[184:187], v[146:149], v[126:129]
	ds_read_b128 v[200:203], v144 offset:0
	v_mfma_f32_16x16x32_bf16 v[122:125], v[184:187], v[152:155], v[122:125]
	ds_read_b128 v[204:207], v144 offset:1024
	v_mfma_f32_16x16x32_bf16 v[118:121], v[184:187], v[156:159], v[118:121]
	ds_read_b128 v[208:211], v144 offset:2048
	v_mfma_f32_16x16x32_bf16 v[114:117], v[184:187], v[162:165], v[114:117]
	ds_read_b128 v[212:215], v144 offset:3072
	v_mfma_f32_16x16x32_bf16 v[110:113], v[184:187], v[166:169], v[110:113]
	ds_read_b128 v[216:219], v144 offset:4096
	v_mfma_f32_16x16x32_bf16 v[106:109], v[184:187], v[170:173], v[106:109]
	ds_read_b128 v[220:223], v144 offset:5120
	v_mfma_f32_16x16x32_bf16 v[102:105], v[184:187], v[176:179], v[102:105]
	ds_read_b128 v[224:227], v144 offset:6144
	v_mfma_f32_16x16x32_bf16 v[98:101], v[184:187], v[180:183], v[98:101]
	ds_read_b128 v[228:231], v144 offset:7168
	v_mfma_f32_16x16x32_bf16 v[94:97], v[188:191], v[146:149], v[94:97]
	v_add_u32_e64 v144, s1, v137
	v_mfma_f32_16x16x32_bf16 v[90:93], v[188:191], v[152:155], v[90:93]
	v_mfma_f32_16x16x32_bf16 v[86:89], v[188:191], v[156:159], v[86:89]
	ds_read_b128 v[232:235], v144 offset:16384
	v_mfma_f32_16x16x32_bf16 v[82:85], v[188:191], v[162:165], v[82:85]
	ds_read_b128 v[236:239], v144 offset:17408
	v_mfma_f32_16x16x32_bf16 v[78:81], v[188:191], v[166:169], v[78:81]
	ds_read_b128 v[240:243], v144 offset:18432
	v_mfma_f32_16x16x32_bf16 v[74:77], v[188:191], v[170:173], v[74:77]
	ds_read_b128 v[244:247], v144 offset:19456
	v_mfma_f32_16x16x32_bf16 v[70:73], v[188:191], v[176:179], v[70:73]
	s_add_i32 s15, s43, s14
	s_mov_b32 m0, s15
	v_lshl_add_u64 v[142:143], v[132:133], 0, s[2:3]
	v_mfma_f32_16x16x32_bf16 v[66:69], v[188:191], v[180:183], v[66:69]
	global_load_lds_dwordx4 v[132:133], off
	s_add_i32 m0, m0, 0x1000
	v_mfma_f32_16x16x32_bf16 v[62:65], v[192:195], v[146:149], v[62:65]
	v_mfma_f32_16x16x32_bf16 v[58:61], v[192:195], v[152:155], v[58:61]
	v_mfma_f32_16x16x32_bf16 v[54:57], v[192:195], v[156:159], v[54:57]
	global_load_lds_dwordx4 v[142:143], off
	v_lshl_add_u64 v[142:143], v[142:143], 0, s[2:3]
	s_add_i32 m0, m0, 0x1000
	v_mfma_f32_16x16x32_bf16 v[50:53], v[192:195], v[162:165], v[50:53]
	v_mfma_f32_16x16x32_bf16 v[46:49], v[192:195], v[166:169], v[46:49]
	v_mfma_f32_16x16x32_bf16 v[42:45], v[192:195], v[170:173], v[42:45]
	global_load_lds_dwordx4 v[142:143], off
	v_lshl_add_u64 v[142:143], v[142:143], 0, s[2:3]
	s_add_i32 m0, m0, 0x1000
	v_mfma_f32_16x16x32_bf16 v[38:41], v[192:195], v[176:179], v[38:41]
	v_mfma_f32_16x16x32_bf16 v[34:37], v[192:195], v[180:183], v[34:37]
	v_mfma_f32_16x16x32_bf16 v[30:33], v[196:199], v[146:149], v[30:33]
	global_load_lds_dwordx4 v[142:143], off
	s_add_i32 m0, m0, 0x1000
	v_lshl_add_u64 v[142:143], v[134:135], 0, s[2:3]
	v_mfma_f32_16x16x32_bf16 v[26:29], v[196:199], v[152:155], v[26:29]
	v_mfma_f32_16x16x32_bf16 v[22:25], v[196:199], v[156:159], v[22:25]
	v_mfma_f32_16x16x32_bf16 v[18:21], v[196:199], v[162:165], v[18:21]
	global_load_lds_dwordx4 v[134:135], off
	s_add_i32 m0, m0, 0x1000
	v_lshl_add_u64 v[132:133], v[132:133], 0, s[12:13]
	v_mfma_f32_16x16x32_bf16 v[14:17], v[196:199], v[166:169], v[14:17]
	v_mfma_f32_16x16x32_bf16 v[10:13], v[196:199], v[170:173], v[10:13]
	v_mfma_f32_16x16x32_bf16 v[6:9], v[196:199], v[176:179], v[6:9]
	global_load_lds_dwordx4 v[142:143], off
	v_lshl_add_u64 v[134:135], v[134:135], 0, s[4:5]
	v_mfma_f32_16x16x32_bf16 v[2:5], v[196:199], v[180:183], v[2:5]
	s_setprio 0
	s_mov_b32 s14, s1
	s_add_i32 s1, s1, 0x6000
	s_cmp_eq_u32 s1, 0x12000
	s_cselect_b32 s1, 0, s1
	s_nop 0
	.p2align 3
	s_waitcnt vmcnt(6) lgkmcnt(0)
	s_barrier
;     ...
;   for (int kt = 0; kt < nk; kt++) {
;     if (kt + 1 < nk) asm volatile("s_waitcnt vmcnt(6)" ::: "memory");
;     else asm volatile("s_waitcnt vmcnt(0)" ::: "memory");
;     __builtin_amdgcn_s_barrier();
;     asm volatile("" ::: "memory");
;     if (kt + 2 < nk) G2_STAGE(kt + 2);
;     const char* cS = smem + (kt % 3) * 24576;
;     bf16x8 xa[8], wb[4];
; #pragma unroll
;     for (int f = 0; f < 8; f++) xa[f] = *(const bf16x8*)(cS + aoff + f * 1024);
; #pragma unroll
;     for (int f = 0; f < 4; f++) wb[f] = *(const bf16x8*)(cS + boff + f * 1024);
; #pragma unroll
;     for (int nf = 0; nf < 4; nf++)
; #pragma unroll
;       for (int mf = 0; mf < 8; mf++)
;         acc[nf][mf] = __builtin_amdgcn_mfma_f32_16x16x32_bf16(wb[nf], xa[mf], acc[nf][mf], 0, 0, 0);
	s_setprio 1
	v_add_u32_e32 v144, s1, v136
	v_mfma_f32_16x16x32_bf16 v[126:129], v[232:235], v[200:203], v[126:129]
	ds_read_b128 v[146:149], v144 offset:0
	v_mfma_f32_16x16x32_bf16 v[122:125], v[232:235], v[204:207], v[122:125]
	ds_read_b128 v[152:155], v144 offset:1024
	v_mfma_f32_16x16x32_bf16 v[118:121], v[232:235], v[208:211], v[118:121]
	ds_read_b128 v[156:159], v144 offset:2048
	v_mfma_f32_16x16x32_bf16 v[114:117], v[232:235], v[212:215], v[114:117]
	ds_read_b128 v[162:165], v144 offset:3072
	v_mfma_f32_16x16x32_bf16 v[110:113], v[232:235], v[216:219], v[110:113]
	ds_read_b128 v[166:169], v144 offset:4096
	v_mfma_f32_16x16x32_bf16 v[106:109], v[232:235], v[220:223], v[106:109]
	ds_read_b128 v[170:173], v144 offset:5120
	v_mfma_f32_16x16x32_bf16 v[102:105], v[232:235], v[224:227], v[102:105]
	ds_read_b128 v[176:179], v144 offset:6144
	v_mfma_f32_16x16x32_bf16 v[98:101], v[232:235], v[228:231], v[98:101]
	ds_read_b128 v[180:183], v144 offset:7168
	v_mfma_f32_16x16x32_bf16 v[94:97], v[236:239], v[200:203], v[94:97]
	v_add_u32_e64 v144, s1, v137
	v_mfma_f32_16x16x32_bf16 v[90:93], v[236:239], v[204:207], v[90:93]
	v_mfma_f32_16x16x32_bf16 v[86:89], v[236:239], v[208:211], v[86:89]
	ds_read_b128 v[184:187], v144 offset:16384
	v_mfma_f32_16x16x32_bf16 v[82:85], v[236:239], v[212:215], v[82:85]
	ds_read_b128 v[188:191], v144 offset:17408
	v_mfma_f32_16x16x32_bf16 v[78:81], v[236:239], v[216:219], v[78:81]
	ds_read_b128 v[192:195], v144 offset:18432
	v_mfma_f32_16x16x32_bf16 v[74:77], v[236:239], v[220:223], v[74:77]
	ds_read_b128 v[196:199], v144 offset:19456
	v_mfma_f32_16x16x32_bf16 v[70:73], v[236:239], v[224:227], v[70:73]
	v_mfma_f32_16x16x32_bf16 v[66:69], v[236:239], v[228:231], v[66:69]
	v_mfma_f32_16x16x32_bf16 v[62:65], v[240:243], v[200:203], v[62:65]
	v_mfma_f32_16x16x32_bf16 v[58:61], v[240:243], v[204:207], v[58:61]
	v_mfma_f32_16x16x32_bf16 v[54:57], v[240:243], v[208:211], v[54:57]
	v_mfma_f32_16x16x32_bf16 v[50:53], v[240:243], v[212:215], v[50:53]
	v_mfma_f32_16x16x32_bf16 v[46:49], v[240:243], v[216:219], v[46:49]
	v_mfma_f32_16x16x32_bf16 v[42:45], v[240:243], v[220:223], v[42:45]
	v_mfma_f32_16x16x32_bf16 v[38:41], v[240:243], v[224:227], v[38:41]
	v_mfma_f32_16x16x32_bf16 v[34:37], v[240:243], v[228:231], v[34:37]
	v_mfma_f32_16x16x32_bf16 v[30:33], v[244:247], v[200:203], v[30:33]
	v_mfma_f32_16x16x32_bf16 v[26:29], v[244:247], v[204:207], v[26:29]
	v_mfma_f32_16x16x32_bf16 v[22:25], v[244:247], v[208:211], v[22:25]
	v_mfma_f32_16x16x32_bf16 v[18:21], v[244:247], v[212:215], v[18:21]
	v_mfma_f32_16x16x32_bf16 v[14:17], v[244:247], v[216:219], v[14:17]
	v_mfma_f32_16x16x32_bf16 v[10:13], v[244:247], v[220:223], v[10:13]
	v_mfma_f32_16x16x32_bf16 v[6:9], v[244:247], v[224:227], v[6:9]
	v_mfma_f32_16x16x32_bf16 v[2:5], v[244:247], v[228:231], v[2:5]
	s_setprio 0
	s_mov_b32 s14, s1
	s_add_i32 s1, s1, 0x6000
	s_cmp_eq_u32 s1, 0x12000
	s_cselect_b32 s1, 0, s1
	s_nop 0
	.p2align 3
	s_waitcnt vmcnt(0) lgkmcnt(0)
	s_barrier
	s_setprio 1
	v_add_u32_e32 v144, s1, v136
	v_mfma_f32_16x16x32_bf16 v[126:129], v[184:187], v[146:149], v[126:129]
	ds_read_b128 v[200:203], v144 offset:0
	v_mfma_f32_16x16x32_bf16 v[122:125], v[184:187], v[152:155], v[122:125]
	ds_read_b128 v[204:207], v144 offset:1024
	v_mfma_f32_16x16x32_bf16 v[118:121], v[184:187], v[156:159], v[118:121]
	ds_read_b128 v[208:211], v144 offset:2048
	v_mfma_f32_16x16x32_bf16 v[114:117], v[184:187], v[162:165], v[114:117]
	ds_read_b128 v[212:215], v144 offset:3072
	v_mfma_f32_16x16x32_bf16 v[110:113], v[184:187], v[166:169], v[110:113]
	ds_read_b128 v[216:219], v144 offset:4096
	v_mfma_f32_16x16x32_bf16 v[106:109], v[184:187], v[170:173], v[106:109]
	ds_read_b128 v[220:223], v144 offset:5120
	v_mfma_f32_16x16x32_bf16 v[102:105], v[184:187], v[176:179], v[102:105]
	ds_read_b128 v[224:227], v144 offset:6144
	v_mfma_f32_16x16x32_bf16 v[98:101], v[184:187], v[180:183], v[98:101]
	ds_read_b128 v[228:231], v144 offset:7168
	v_mfma_f32_16x16x32_bf16 v[94:97], v[188:191], v[146:149], v[94:97]
	v_add_u32_e64 v144, s1, v137
	v_mfma_f32_16x16x32_bf16 v[90:93], v[188:191], v[152:155], v[90:93]
	v_mfma_f32_16x16x32_bf16 v[86:89], v[188:191], v[156:159], v[86:89]
	ds_read_b128 v[232:235], v144 offset:16384
	v_mfma_f32_16x16x32_bf16 v[82:85], v[188:191], v[162:165], v[82:85]
	ds_read_b128 v[236:239], v144 offset:17408
	v_mfma_f32_16x16x32_bf16 v[78:81], v[188:191], v[166:169], v[78:81]
	ds_read_b128 v[240:243], v144 offset:18432
	v_mfma_f32_16x16x32_bf16 v[74:77], v[188:191], v[170:173], v[74:77]
	ds_read_b128 v[244:247], v144 offset:19456
	v_mfma_f32_16x16x32_bf16 v[70:73], v[188:191], v[176:179], v[70:73]
	v_mfma_f32_16x16x32_bf16 v[66:69], v[188:191], v[180:183], v[66:69]
	v_mfma_f32_16x16x32_bf16 v[62:65], v[192:195], v[146:149], v[62:65]
	v_mfma_f32_16x16x32_bf16 v[58:61], v[192:195], v[152:155], v[58:61]
	v_mfma_f32_16x16x32_bf16 v[54:57], v[192:195], v[156:159], v[54:57]
	v_mfma_f32_16x16x32_bf16 v[50:53], v[192:195], v[162:165], v[50:53]
	v_mfma_f32_16x16x32_bf16 v[46:49], v[192:195], v[166:169], v[46:49]
	v_mfma_f32_16x16x32_bf16 v[42:45], v[192:195], v[170:173], v[42:45]
	v_mfma_f32_16x16x32_bf16 v[38:41], v[192:195], v[176:179], v[38:41]
	v_mfma_f32_16x16x32_bf16 v[34:37], v[192:195], v[180:183], v[34:37]
	v_mfma_f32_16x16x32_bf16 v[30:33], v[196:199], v[146:149], v[30:33]
	v_mfma_f32_16x16x32_bf16 v[26:29], v[196:199], v[152:155], v[26:29]
	v_mfma_f32_16x16x32_bf16 v[22:25], v[196:199], v[156:159], v[22:25]
	v_mfma_f32_16x16x32_bf16 v[18:21], v[196:199], v[162:165], v[18:21]
	v_mfma_f32_16x16x32_bf16 v[14:17], v[196:199], v[166:169], v[14:17]
	v_mfma_f32_16x16x32_bf16 v[10:13], v[196:199], v[170:173], v[10:13]
	v_mfma_f32_16x16x32_bf16 v[6:9], v[196:199], v[176:179], v[6:9]
	v_mfma_f32_16x16x32_bf16 v[2:5], v[196:199], v[180:183], v[2:5]
	s_setprio 0
	s_mov_b32 s14, s1
	s_add_i32 s1, s1, 0x6000
	s_cmp_eq_u32 s1, 0x12000
	s_cselect_b32 s1, 0, s1
	s_nop 0
	s_mov_b32 s4, 0x8000
	s_mov_b32 s5, 0
	s_mov_b32 s10, 0x10000
	s_mov_b32 s11, 0
	s_mov_b32 s41, 0x3fd744fd
	.p2align 3
	s_waitcnt lgkmcnt(0)
; DEVI float blo(unsigned u) { return __uint_as_float(u << 16); }
; DEVI float bhi(unsigned u) { return __uint_as_float(u & 0xffff0000u); }
;     ...
;     for (int nf = 0; nf < 4; nf++)
; #pragma unroll
;       for (int mf = 0; mf < 8; mf++)
;         acc[nf][mf] = __builtin_amdgcn_mfma_f32_16x16x32_bf16(wb[nf], xa[mf], acc[nf][mf], 0, 0, 0);
;     ...
;         if (EPI == EPI_RESID || EPI == EPI_RESID_ATOMIC) {
;           f32x4 x = a;
;           if (EPI == EPI_RESID || kpart == 0) {
;             const u32x2 xr = *(const u32x2*)((const u16*)(p.ws + WS_XB) + (size_t)row * 1024 + col);
;             x[0] += ALPHA * blo(xr[0]); x[1] += ALPHA * bhi(xr[0]); x[2] += ALPHA * blo(xr[1]); x[3] += ALPHA * bhi(xr[1]);
;           }
;           if (EPI == EPI_RESID) *(f32x4*)((float*)(p.ws + WS_XF) + (size_t)row * 1024 + col) = x;
;           else *(f32x4*)((float*)(p.ws + WS_SLAB) + ((size_t)kpart * 512 + (row - T_P)) * 1024 + col) = x;
	s_nop 0
	v_mfma_f32_16x16x32_bf16 v[126:129], v[232:235], v[200:203], v[126:129]
	v_mfma_f32_16x16x32_bf16 v[122:125], v[232:235], v[204:207], v[122:125]
	v_mfma_f32_16x16x32_bf16 v[118:121], v[232:235], v[208:211], v[118:121]
	v_mfma_f32_16x16x32_bf16 v[114:117], v[232:235], v[212:215], v[114:117]
	v_mfma_f32_16x16x32_bf16 v[110:113], v[232:235], v[216:219], v[110:113]
	v_mfma_f32_16x16x32_bf16 v[106:109], v[232:235], v[220:223], v[106:109]
	v_mfma_f32_16x16x32_bf16 v[102:105], v[232:235], v[224:227], v[102:105]
	v_mfma_f32_16x16x32_bf16 v[98:101], v[232:235], v[228:231], v[98:101]
	v_mfma_f32_16x16x32_bf16 v[94:97], v[236:239], v[200:203], v[94:97]
	v_mfma_f32_16x16x32_bf16 v[90:93], v[236:239], v[204:207], v[90:93]
	v_mfma_f32_16x16x32_bf16 v[86:89], v[236:239], v[208:211], v[86:89]
	v_mfma_f32_16x16x32_bf16 v[82:85], v[236:239], v[212:215], v[82:85]
	v_mfma_f32_16x16x32_bf16 v[78:81], v[236:239], v[216:219], v[78:81]
	v_mfma_f32_16x16x32_bf16 v[74:77], v[236:239], v[220:223], v[74:77]
	v_mfma_f32_16x16x32_bf16 v[70:73], v[236:239], v[224:227], v[70:73]
	v_mfma_f32_16x16x32_bf16 v[66:69], v[236:239], v[228:231], v[66:69]
	v_mfma_f32_16x16x32_bf16 v[62:65], v[240:243], v[200:203], v[62:65]
	v_mfma_f32_16x16x32_bf16 v[58:61], v[240:243], v[204:207], v[58:61]
	v_mfma_f32_16x16x32_bf16 v[54:57], v[240:243], v[208:211], v[54:57]
	v_mfma_f32_16x16x32_bf16 v[50:53], v[240:243], v[212:215], v[50:53]
	v_mfma_f32_16x16x32_bf16 v[46:49], v[240:243], v[216:219], v[46:49]
	v_mfma_f32_16x16x32_bf16 v[42:45], v[240:243], v[220:223], v[42:45]
	v_mfma_f32_16x16x32_bf16 v[38:41], v[240:243], v[224:227], v[38:41]
	v_mfma_f32_16x16x32_bf16 v[34:37], v[240:243], v[228:231], v[34:37]
	v_mfma_f32_16x16x32_bf16 v[30:33], v[244:247], v[200:203], v[30:33]
	v_mfma_f32_16x16x32_bf16 v[26:29], v[244:247], v[204:207], v[26:29]
	v_mfma_f32_16x16x32_bf16 v[22:25], v[244:247], v[208:211], v[22:25]
	v_mfma_f32_16x16x32_bf16 v[18:21], v[244:247], v[212:215], v[18:21]
	v_mfma_f32_16x16x32_bf16 v[14:17], v[244:247], v[216:219], v[14:17]
	v_mfma_f32_16x16x32_bf16 v[10:13], v[244:247], v[220:223], v[10:13]
	v_mfma_f32_16x16x32_bf16 v[6:9], v[244:247], v[224:227], v[6:9]
	v_mfma_f32_16x16x32_bf16 v[2:5], v[244:247], v[228:231], v[2:5]
	s_mov_b32 m0, s40
	s_cmp_eq_u32 s98, 0
	s_cbranch_scc1 .Lta4_first
	s_nop 7
	global_store_dwordx4 v[140:141], v[126:129], off offset:0
	global_store_dwordx4 v[140:141], v[94:97], off offset:64
	global_store_dwordx4 v[140:141], v[62:65], off offset:128
	global_store_dwordx4 v[140:141], v[30:33], off offset:192
	v_lshl_add_u64 v[140:141], v[140:141], 0, s[10:11]
	global_store_dwordx4 v[140:141], v[122:125], off offset:0
	global_store_dwordx4 v[140:141], v[90:93], off offset:64
	global_store_dwordx4 v[140:141], v[58:61], off offset:128
	global_store_dwordx4 v[140:141], v[26:29], off offset:192
	v_lshl_add_u64 v[140:141], v[140:141], 0, s[10:11]
	global_store_dwordx4 v[140:141], v[118:121], off offset:0
	global_store_dwordx4 v[140:141], v[86:89], off offset:64
	global_store_dwordx4 v[140:141], v[54:57], off offset:128
	global_store_dwordx4 v[140:141], v[22:25], off offset:192
	v_lshl_add_u64 v[140:141], v[140:141], 0, s[10:11]
	global_store_dwordx4 v[140:141], v[114:117], off offset:0
	global_store_dwordx4 v[140:141], v[82:85], off offset:64
	global_store_dwordx4 v[140:141], v[50:53], off offset:128
	global_store_dwordx4 v[140:141], v[18:21], off offset:192
	v_lshl_add_u64 v[140:141], v[140:141], 0, s[10:11]
	global_store_dwordx4 v[140:141], v[110:113], off offset:0
	global_store_dwordx4 v[140:141], v[78:81], off offset:64
	global_store_dwordx4 v[140:141], v[46:49], off offset:128
	global_store_dwordx4 v[140:141], v[14:17], off offset:192
	v_lshl_add_u64 v[140:141], v[140:141], 0, s[10:11]
	global_store_dwordx4 v[140:141], v[106:109], off offset:0
	global_store_dwordx4 v[140:141], v[74:77], off offset:64
	global_store_dwordx4 v[140:141], v[42:45], off offset:128
	global_store_dwordx4 v[140:141], v[10:13], off offset:192
	v_lshl_add_u64 v[140:141], v[140:141], 0, s[10:11]
	global_store_dwordx4 v[140:141], v[102:105], off offset:0
	global_store_dwordx4 v[140:141], v[70:73], off offset:64
	global_store_dwordx4 v[140:141], v[38:41], off offset:128
	global_store_dwordx4 v[140:141], v[6:9], off offset:192
	v_lshl_add_u64 v[140:141], v[140:141], 0, s[10:11]
	global_store_dwordx4 v[140:141], v[98:101], off offset:0
	global_store_dwordx4 v[140:141], v[66:69], off offset:64
	global_store_dwordx4 v[140:141], v[34:37], off offset:128
	global_store_dwordx4 v[140:141], v[2:5], off offset:192
	s_branch .LBB0_757

; #define LAS __attribute__((address_space(3)))
; DEVI int tidx() { int t = threadIdx.x; asm volatile("" : "+v"(t)); return t; }
;   const int tid = tidx(), lane = tid & 63, wid = tid >> 6;
;   const int wm = wid >> 1, wn = wid & 1, r16 = lane & 15, quad = lane >> 4;
;   f32x4 acc[4][8];
; #pragma unroll
;   for (int i = 0; i < 4; i++)
; #pragma unroll
;     for (int j = 0; j < 8; j++) acc[i][j] = (f32x4){0.f, 0.f, 0.f, 0.f};
;   const int nk = (nk_part < 0) ? (K >> 5) : nk_part;
;   const int lrow = tid >> 2, lpc = tid & 3;
;   const int lch = lpc ^ ((0x78 >> (((lrow >> 2) & 3) * 2)) & 3);
;   const u16* ga = A + (size_t)(m0 + lrow) * lda + kbeg + lch * 8;
;   const u16* gb = Bt + (size_t)(n0 + lrow) * K + kbeg + lch * 8;
;   const size_t ga1 = (size_t)64 * lda, gb1 = (size_t)64 * K;
;   const unsigned lds0 = (unsigned)(uintptr_t)(LAS char*)smem + (unsigned)__builtin_amdgcn_readfirstlane(wid) * 1024u;
;     ...
;   __syncthreads();
;   G2_STAGE(0); G2_STAGE(1);
; DEVI void tile_coords(int T, int MT, int NT, int& mt, int& nt) {
;   const int full = MT >> 3, band = T / (8 * NT);
;   if (band < full) { const int r = T - band * 8 * NT; nt = r >> 3; mt = band * 8 + (r & 7); }
.LBB0_812:
	s_and_b64 vcc, exec, s[2:3]
	s_cbranch_vccz .LBB0_757
	s_lshr_b32 s46, s39, 6
	s_and_b32 s47, s39, 63
	s_lshr_b32 s43, s47, 3
	s_and_b32 s47, s47, 7
	s_lshl_b32 s46, s46, 3
	s_add_i32 s46, s46, s47
	v_readlane_b32 s2, v250, 5
	v_readlane_b32 s3, v250, 6
	v_readlane_b32 s47, v254, 62
	s_mul_i32 s41, s46, 0x80000
	s_add_u32 s4, s2, s41
	s_addc_u32 s5, s3, 0
	s_add_u32 s4, s4, 0xb580000
	s_addc_u32 s5, s5, 0
	s_mul_i32 s41, s47, 0x200000
	s_mul_i32 s42, s43, 0x40000
	s_add_i32 s41, s41, s42
	s_add_u32 s10, s2, s41
	s_addc_u32 s11, s3, 0
	s_add_u32 s10, s10, 0x15e00000
	s_addc_u32 s11, s11, 0
	s_movk_i32 s40, 0x78
	v_lshrrev_b32_e32 v0, 2, v145
	v_and_b32_e32 v131, 3, v145
	v_bfe_u32 v136, v145, 4, 2
	v_lshlrev_b32_e32 v136, 1, v136
	v_lshrrev_b32_e64 v136, v136, s40
	v_and_b32_e32 v136, 3, v136
	v_xor_b32_e32 v131, v131, v136
	v_lshlrev_b32_e32 v131, 4, v131
	s_movk_i32 s42, 0x800
	v_mad_u32_u24 v0, v0, s42, v131
	v_bfe_u32 v137, v145, 2, 1
	s_movk_i32 s42, 0x7c0
	v_mul_u32_u24_e32 v136, s42, v137
	v_sub_u32_e32 v136, v0, v136
	v_mov_b32_e32 v137, 0
	v_lshl_add_u64 v[134:135], s[10:11], 0, v[136:137]
	v_bfe_u32 v137, v145, 2, 1
	s_mov_b32 s12, 64
	s_mov_b32 s13, 0
	v_lshl_add_u64 v[132:133], s[4:5], 0, v[0:1]
	v_bfe_u32 v136, v145, 2, 2
	v_lshlrev_b32_e32 v136, 1, v136
	v_lshrrev_b32_e64 v136, v136, s40
	v_and_b32_e32 v136, 3, v136
	v_bfe_u32 v137, v145, 4, 2
	v_xor_b32_e32 v136, v136, v137
	v_lshlrev_b32_e32 v136, 4, v136
	v_and_b32_e32 v131, 15, v145
	v_lshl_or_b32 v136, v131, 6, v136
	v_bfe_u32 v137, v145, 6, 1
	v_lshl_or_b32 v137, v137, 12, v136
	v_lshrrev_b32_e32 v0, 7, v145
	v_lshl_or_b32 v136, v0, 13, v136
	v_and_b32_e32 v140, 1, v131
	v_lshl_or_b32 v131, v0, 7, v131
	v_bfe_u32 v0, v145, 4, 2
	v_lshlrev_b32_e32 v0, 3, v0
	v_bfe_u32 v141, v145, 6, 1
	s_lshl_b32 s41, s46, 19
	s_lshl_b32 s42, s43, 9
	s_add_i32 s41, s41, s42
	s_add_u32 s4, s2, s41
	s_addc_u32 s5, s3, 0
	s_add_u32 s4, s4, 0x4200000
	s_addc_u32 s5, s5, 0
	v_lshlrev_b32_e32 v138, 11, v131
	v_lshl_add_u32 v138, v141, 8, v138
	v_bfe_u32 v139, v145, 4, 1
	v_lshl_add_u32 v138, v139, 5, v138
	v_bfe_u32 v139, v145, 5, 1
	v_lshl_add_u32 v138, v139, 4, v138
	s_movk_i32 s42, 1984
	v_mul_u32_u24_e32 v139, s42, v140
	v_sub_u32_e32 v138, v138, v139
	v_mov_b32_e32 v139, 0
	v_lshl_add_u64 v[138:139], s[4:5], 0, v[138:139]
	s_lshl_b32 s41, s46, 20
	s_lshl_b32 s42, s43, 9
	s_add_i32 s41, s41, s42
	s_add_u32 s10, s2, s41
	s_addc_u32 s11, s3, 0
	v_lshlrev_b32_e32 v140, 12, v131
	v_lshl_add_u32 v140, v141, 8, v140
	v_lshl_add_u32 v140, v0, 1, v140
	v_mov_b32_e32 v141, 0
	v_lshl_add_u64 v[140:141], s[10:11], 0, v[140:141]
	s_mov_b32 s2, 0x20000
	s_mov_b32 s3, 0
	v_lshrrev_b32_e32 v0, 6, v145
	v_lshlrev_b32_e32 v0, 10, v0
	s_nop 0
	v_readfirstlane_b32 s47, v0
	s_mov_b32 s44, m0
	s_mov_b32 s4, 128
	s_mov_b32 s5, 0
	s_barrier
	s_add_i32 s43, s47, 0x0
	s_mov_b32 m0, s43
	v_lshl_add_u64 v[142:143], v[132:133], 0, s[2:3]
	global_load_lds_dwordx4 v[132:133], off
	s_add_i32 m0, m0, 0x1000
	s_nop 0
	global_load_lds_dwordx4 v[142:143], off
	v_lshl_add_u64 v[142:143], v[142:143], 0, s[2:3]
	s_add_i32 m0, m0, 0x1000
	s_nop 0
	global_load_lds_dwordx4 v[142:143], off
	v_lshl_add_u64 v[142:143], v[142:143], 0, s[2:3]
	s_add_i32 m0, m0, 0x1000
	s_nop 0
	global_load_lds_dwordx4 v[142:143], off
	s_add_i32 m0, m0, 0x1000
	v_lshl_add_u64 v[142:143], v[134:135], 0, s[2:3]
	s_nop 0
	global_load_lds_dwordx4 v[134:135], off
	s_add_i32 m0, m0, 0x1000
	v_lshl_add_u64 v[132:133], v[132:133], 0, s[12:13]
	s_nop 0
	global_load_lds_dwordx4 v[142:143], off
	v_lshl_add_u64 v[134:135], v[134:135], 0, s[4:5]
	s_nop 0
	s_add_i32 s43, s47, 0x6000
	s_mov_b32 m0, s43
	v_lshl_add_u64 v[142:143], v[132:133], 0, s[2:3]
	global_load_lds_dwordx4 v[132:133], off
	s_add_i32 m0, m0, 0x1000
	s_nop 0
	global_load_lds_dwordx4 v[142:143], off
	v_lshl_add_u64 v[142:143], v[142:143], 0, s[2:3]
	s_add_i32 m0, m0, 0x1000
	s_nop 0
	global_load_lds_dwordx4 v[142:143], off
	v_lshl_add_u64 v[142:143], v[142:143], 0, s[2:3]
	s_add_i32 m0, m0, 0x1000
	s_nop 0
	global_load_lds_dwordx4 v[142:143], off
	s_add_i32 m0, m0, 0x1000
	v_lshl_add_u64 v[142:143], v[134:135], 0, s[2:3]
	s_nop 0
	global_load_lds_dwordx4 v[134:135], off
	s_add_i32 m0, m0, 0x1000
	v_lshl_add_u64 v[132:133], v[132:133], 0, s[12:13]
	s_nop 0
	global_load_lds_dwordx4 v[142:143], off
	v_lshl_add_u64 v[134:135], v[134:135], 0, s[4:5]
	s_nop 0
	s_add_i32 s43, s47, 0xc000
	s_mov_b32 m0, s43
	v_lshl_add_u64 v[142:143], v[132:133], 0, s[2:3]
	global_load_lds_dwordx4 v[132:133], off
	s_add_i32 m0, m0, 0x1000
	s_nop 0
	global_load_lds_dwordx4 v[142:143], off
	v_lshl_add_u64 v[142:143], v[142:143], 0, s[2:3]
	s_add_i32 m0, m0, 0x1000
	s_nop 0
	global_load_lds_dwordx4 v[142:143], off
	v_lshl_add_u64 v[142:143], v[142:143], 0, s[2:3]
	s_add_i32 m0, m0, 0x1000
	s_nop 0
	global_load_lds_dwordx4 v[142:143], off
	s_add_i32 m0, m0, 0x1000
	v_lshl_add_u64 v[142:143], v[134:135], 0, s[2:3]
	s_nop 0
	global_load_lds_dwordx4 v[134:135], off
	s_add_i32 m0, m0, 0x1000
	v_lshl_add_u64 v[132:133], v[132:133], 0, s[12:13]
	s_nop 0
	global_load_lds_dwordx4 v[142:143], off
	v_lshl_add_u64 v[134:135], v[134:135], 0, s[4:5]
	s_nop 0
	v_mov_b32_e32 v2, 0
	v_mov_b32_e32 v3, 0
	v_mov_b32_e32 v4, 0
	v_mov_b32_e32 v5, 0
	v_mov_b32_e32 v6, 0
	v_mov_b32_e32 v7, 0
	v_mov_b32_e32 v8, 0
	v_mov_b32_e32 v9, 0
	v_mov_b32_e32 v10, 0
	v_mov_b32_e32 v11, 0
	v_mov_b32_e32 v12, 0
	v_mov_b32_e32 v13, 0
	v_mov_b32_e32 v14, 0
	v_mov_b32_e32 v15, 0
	v_mov_b32_e32 v16, 0
	v_mov_b32_e32 v17, 0
	v_mov_b32_e32 v18, 0
	v_mov_b32_e32 v19, 0
	v_mov_b32_e32 v20, 0
	v_mov_b32_e32 v21, 0
	v_mov_b32_e32 v22, 0
	v_mov_b32_e32 v23, 0
;     ...
;   __syncthreads();
;   G2_STAGE(0); G2_STAGE(1);
;   const int fsw = (0x78 >> (((r16 >> 2) & 3) * 2)) & 3;
;   const int aoff = (wm * 128 + r16) * 64 + ((quad ^ fsw) << 4);
;   const int boff = 16384 + (wn * 64 + r16) * 64 + ((quad ^ fsw) << 4);
;   for (int kt = 0; kt < nk; kt++) {
;     if (kt + 1 < nk) asm volatile("s_waitcnt vmcnt(6)" ::: "memory");
;     else asm volatile("s_waitcnt vmcnt(0)" ::: "memory");
;     __builtin_amdgcn_s_barrier();
;     asm volatile("" ::: "memory");
;     if (kt + 2 < nk) G2_STAGE(kt + 2);
;     const char* cS = smem + (kt % 3) * 24576;
;     bf16x8 xa[8], wb[4];
; #pragma unroll
;     for (int f = 0; f < 8; f++) xa[f] = *(const bf16x8*)(cS + aoff + f * 1024);
; #pragma unroll
;     for (int f = 0; f < 4; f++) wb[f] = *(const bf16x8*)(cS + boff + f * 1024);
; #pragma unroll
;     for (int nf = 0; nf < 4; nf++)
; #pragma unroll
;       for (int mf = 0; mf < 8; mf++)
;         acc[nf][mf] = __builtin_amdgcn_mfma_f32_16x16x32_bf16(wb[nf], xa[mf], acc[nf][mf], 0, 0, 0);
	v_mov_b32_e32 v24, 0
	v_mov_b32_e32 v25, 0
	v_mov_b32_e32 v26, 0
	v_mov_b32_e32 v27, 0
	v_mov_b32_e32 v28, 0
	v_mov_b32_e32 v29, 0
	v_mov_b32_e32 v30, 0
	v_mov_b32_e32 v31, 0
	v_mov_b32_e32 v32, 0
	v_mov_b32_e32 v33, 0
	v_mov_b32_e32 v34, 0
	v_mov_b32_e32 v35, 0
	v_mov_b32_e32 v36, 0
	v_mov_b32_e32 v37, 0
	v_mov_b32_e32 v38, 0
	v_mov_b32_e32 v39, 0
	v_mov_b32_e32 v40, 0
	v_mov_b32_e32 v41, 0
	v_mov_b32_e32 v42, 0
	v_mov_b32_e32 v43, 0
	v_mov_b32_e32 v44, 0
	v_mov_b32_e32 v45, 0
	v_mov_b32_e32 v46, 0
	v_mov_b32_e32 v47, 0
	v_mov_b32_e32 v48, 0
	v_mov_b32_e32 v49, 0
	v_mov_b32_e32 v50, 0
	v_mov_b32_e32 v51, 0
	v_mov_b32_e32 v52, 0
	v_mov_b32_e32 v53, 0
	v_mov_b32_e32 v54, 0
	v_mov_b32_e32 v55, 0
	v_mov_b32_e32 v56, 0
	v_mov_b32_e32 v57, 0
	v_mov_b32_e32 v58, 0
	v_mov_b32_e32 v59, 0
	v_mov_b32_e32 v60, 0
	v_mov_b32_e32 v61, 0
	v_mov_b32_e32 v62, 0
	v_mov_b32_e32 v63, 0
	v_mov_b32_e32 v64, 0
	v_mov_b32_e32 v65, 0
	v_mov_b32_e32 v66, 0
	v_mov_b32_e32 v67, 0
	v_mov_b32_e32 v68, 0
	v_mov_b32_e32 v69, 0
	v_mov_b32_e32 v70, 0
	v_mov_b32_e32 v71, 0
	v_mov_b32_e32 v72, 0
	v_mov_b32_e32 v73, 0
	v_mov_b32_e32 v74, 0
	v_mov_b32_e32 v75, 0
	v_mov_b32_e32 v76, 0
	v_mov_b32_e32 v77, 0
	v_mov_b32_e32 v78, 0
	v_mov_b32_e32 v79, 0
	v_mov_b32_e32 v80, 0
	v_mov_b32_e32 v81, 0
	v_mov_b32_e32 v82, 0
	v_mov_b32_e32 v83, 0
	v_mov_b32_e32 v84, 0
	v_mov_b32_e32 v85, 0
	v_mov_b32_e32 v86, 0
	v_mov_b32_e32 v87, 0
	v_mov_b32_e32 v88, 0
	v_mov_b32_e32 v89, 0
	v_mov_b32_e32 v90, 0
	v_mov_b32_e32 v91, 0
	v_mov_b32_e32 v92, 0
	v_mov_b32_e32 v93, 0
	v_mov_b32_e32 v94, 0
	v_mov_b32_e32 v95, 0
	v_mov_b32_e32 v96, 0
	v_mov_b32_e32 v97, 0
	v_mov_b32_e32 v98, 0
	v_mov_b32_e32 v99, 0
	v_mov_b32_e32 v100, 0
	v_mov_b32_e32 v101, 0
	v_mov_b32_e32 v102, 0
	v_mov_b32_e32 v103, 0
	v_mov_b32_e32 v104, 0
	v_mov_b32_e32 v105, 0
	v_mov_b32_e32 v106, 0
	v_mov_b32_e32 v107, 0
	v_mov_b32_e32 v108, 0
	v_mov_b32_e32 v109, 0
	v_mov_b32_e32 v110, 0
	v_mov_b32_e32 v111, 0
	v_mov_b32_e32 v112, 0
	v_mov_b32_e32 v113, 0
	v_mov_b32_e32 v114, 0
	v_mov_b32_e32 v115, 0
	v_mov_b32_e32 v116, 0
	v_mov_b32_e32 v117, 0
	v_mov_b32_e32 v118, 0
	v_mov_b32_e32 v119, 0
	v_mov_b32_e32 v120, 0
	v_mov_b32_e32 v121, 0
	v_mov_b32_e32 v122, 0
	v_mov_b32_e32 v123, 0
	v_mov_b32_e32 v124, 0
	v_mov_b32_e32 v125, 0
	v_mov_b32_e32 v126, 0
	v_mov_b32_e32 v127, 0
	v_mov_b32_e32 v128, 0
	v_mov_b32_e32 v129, 0
	s_waitcnt vmcnt(12)
	s_barrier
	ds_read_b128 v[146:149], v136 offset:0
	ds_read_b128 v[152:155], v136 offset:1024
	ds_read_b128 v[156:159], v136 offset:2048
	ds_read_b128 v[162:165], v136 offset:3072
	ds_read_b128 v[166:169], v136 offset:4096
	ds_read_b128 v[170:173], v136 offset:5120
	ds_read_b128 v[176:179], v136 offset:6144
	ds_read_b128 v[180:183], v136 offset:7168
	ds_read_b128 v[184:187], v137 offset:16384
	ds_read_b128 v[188:191], v137 offset:17408
	ds_read_b128 v[192:195], v137 offset:18432
	ds_read_b128 v[196:199], v137 offset:19456
	s_movk_i32 s41, 0x6000
	s_mov_b32 s42, 0
	s_movk_i32 s40, 14
	.p2align 6
.Lt4_loop:
	.p2align 3
	s_waitcnt vmcnt(6) lgkmcnt(0)
	s_barrier
	s_setprio 1
	v_add_u32_e32 v144, s41, v136
	v_mfma_f32_16x16x32_bf16 v[126:129], v[184:187], v[146:149], v[126:129]
	ds_read_b128 v[200:203], v144 offset:0
	v_mfma_f32_16x16x32_bf16 v[122:125], v[184:187], v[152:155], v[122:125]
	ds_read_b128 v[204:207], v144 offset:1024
	v_mfma_f32_16x16x32_bf16 v[118:121], v[184:187], v[156:159], v[118:121]
	ds_read_b128 v[208:211], v144 offset:2048
	v_mfma_f32_16x16x32_bf16 v[114:117], v[184:187], v[162:165], v[114:117]
	ds_read_b128 v[212:215], v144 offset:3072
	v_mfma_f32_16x16x32_bf16 v[110:113], v[184:187], v[166:169], v[110:113]
	ds_read_b128 v[216:219], v144 offset:4096
	v_mfma_f32_16x16x32_bf16 v[106:109], v[184:187], v[170:173], v[106:109]
	ds_read_b128 v[220:223], v144 offset:5120
	v_mfma_f32_16x16x32_bf16 v[102:105], v[184:187], v[176:179], v[102:105]
	ds_read_b128 v[224:227], v144 offset:6144
	v_mfma_f32_16x16x32_bf16 v[98:101], v[184:187], v[180:183], v[98:101]
	ds_read_b128 v[228:231], v144 offset:7168
	v_mfma_f32_16x16x32_bf16 v[94:97], v[188:191], v[146:149], v[94:97]
	v_add_u32_e64 v144, s41, v137
	v_mfma_f32_16x16x32_bf16 v[90:93], v[188:191], v[152:155], v[90:93]
	v_mfma_f32_16x16x32_bf16 v[86:89], v[188:191], v[156:159], v[86:89]
	ds_read_b128 v[232:235], v144 offset:16384
	v_mfma_f32_16x16x32_bf16 v[82:85], v[188:191], v[162:165], v[82:85]
	ds_read_b128 v[236:239], v144 offset:17408
	v_mfma_f32_16x16x32_bf16 v[78:81], v[188:191], v[166:169], v[78:81]
	ds_read_b128 v[240:243], v144 offset:18432
	v_mfma_f32_16x16x32_bf16 v[74:77], v[188:191], v[170:173], v[74:77]
	ds_read_b128 v[244:247], v144 offset:19456
	v_mfma_f32_16x16x32_bf16 v[70:73], v[188:191], v[176:179], v[70:73]
	s_add_i32 s43, s47, s42
	s_mov_b32 m0, s43
	v_lshl_add_u64 v[142:143], v[132:133], 0, s[2:3]
	v_mfma_f32_16x16x32_bf16 v[66:69], v[188:191], v[180:183], v[66:69]
	global_load_lds_dwordx4 v[132:133], off
	s_add_i32 m0, m0, 0x1000
	v_mfma_f32_16x16x32_bf16 v[62:65], v[192:195], v[146:149], v[62:65]
	v_mfma_f32_16x16x32_bf16 v[58:61], v[192:195], v[152:155], v[58:61]
	v_mfma_f32_16x16x32_bf16 v[54:57], v[192:195], v[156:159], v[54:57]
	global_load_lds_dwordx4 v[142:143], off
	v_lshl_add_u64 v[142:143], v[142:143], 0, s[2:3]
	s_add_i32 m0, m0, 0x1000
	v_mfma_f32_16x16x32_bf16 v[50:53], v[192:195], v[162:165], v[50:53]
	v_mfma_f32_16x16x32_bf16 v[46:49], v[192:195], v[166:169], v[46:49]
	v_mfma_f32_16x16x32_bf16 v[42:45], v[192:195], v[170:173], v[42:45]
	global_load_lds_dwordx4 v[142:143], off
	v_lshl_add_u64 v[142:143], v[142:143], 0, s[2:3]
	s_add_i32 m0, m0, 0x1000
	v_mfma_f32_16x16x32_bf16 v[38:41], v[192:195], v[176:179], v[38:41]
	v_mfma_f32_16x16x32_bf16 v[34:37], v[192:195], v[180:183], v[34:37]
	v_mfma_f32_16x16x32_bf16 v[30:33], v[196:199], v[146:149], v[30:33]
	global_load_lds_dwordx4 v[142:143], off
	s_add_i32 m0, m0, 0x1000
	v_lshl_add_u64 v[142:143], v[134:135], 0, s[2:3]
	v_mfma_f32_16x16x32_bf16 v[26:29], v[196:199], v[152:155], v[26:29]
	v_mfma_f32_16x16x32_bf16 v[22:25], v[196:199], v[156:159], v[22:25]
	v_mfma_f32_16x16x32_bf16 v[18:21], v[196:199], v[162:165], v[18:21]
	global_load_lds_dwordx4 v[134:135], off
	s_add_i32 m0, m0, 0x1000
	v_lshl_add_u64 v[132:133], v[132:133], 0, s[12:13]
	v_mfma_f32_16x16x32_bf16 v[14:17], v[196:199], v[166:169], v[14:17]
	v_mfma_f32_16x16x32_bf16 v[10:13], v[196:199], v[170:173], v[10:13]
	v_mfma_f32_16x16x32_bf16 v[6:9], v[196:199], v[176:179], v[6:9]
	global_load_lds_dwordx4 v[142:143], off
	v_lshl_add_u64 v[134:135], v[134:135], 0, s[4:5]
	v_mfma_f32_16x16x32_bf16 v[2:5], v[196:199], v[180:183], v[2:5]
	s_setprio 0
	s_mov_b32 s42, s41
	s_add_i32 s41, s41, 0x6000
	s_cmp_eq_u32 s41, 0x12000
	s_cselect_b32 s41, 0, s41
	s_nop 0
	.p2align 3
	s_waitcnt vmcnt(6) lgkmcnt(0)
	s_barrier
;     ...
;   for (int kt = 0; kt < nk; kt++) {
;     if (kt + 1 < nk) asm volatile("s_waitcnt vmcnt(6)" ::: "memory");
;     else asm volatile("s_waitcnt vmcnt(0)" ::: "memory");
;     __builtin_amdgcn_s_barrier();
;     asm volatile("" ::: "memory");
;     if (kt + 2 < nk) G2_STAGE(kt + 2);
;     const char* cS = smem + (kt % 3) * 24576;
;     bf16x8 xa[8], wb[4];
; #pragma unroll
;     for (int f = 0; f < 8; f++) xa[f] = *(const bf16x8*)(cS + aoff + f * 1024);
; #pragma unroll
;     for (int f = 0; f < 4; f++) wb[f] = *(const bf16x8*)(cS + boff + f * 1024);
; #pragma unroll
;     for (int nf = 0; nf < 4; nf++)
; #pragma unroll
;       for (int mf = 0; mf < 8; mf++)
;         acc[nf][mf] = __builtin_amdgcn_mfma_f32_16x16x32_bf16(wb[nf], xa[mf], acc[nf][mf], 0, 0, 0);
	s_setprio 1
	v_add_u32_e32 v144, s41, v136
	v_mfma_f32_16x16x32_bf16 v[126:129], v[232:235], v[200:203], v[126:129]
	ds_read_b128 v[146:149], v144 offset:0
	v_mfma_f32_16x16x32_bf16 v[122:125], v[232:235], v[204:207], v[122:125]
	ds_read_b128 v[152:155], v144 offset:1024
	v_mfma_f32_16x16x32_bf16 v[118:121], v[232:235], v[208:211], v[118:121]
	ds_read_b128 v[156:159], v144 offset:2048
	v_mfma_f32_16x16x32_bf16 v[114:117], v[232:235], v[212:215], v[114:117]
	ds_read_b128 v[162:165], v144 offset:3072
	v_mfma_f32_16x16x32_bf16 v[110:113], v[232:235], v[216:219], v[110:113]
	ds_read_b128 v[166:169], v144 offset:4096
	v_mfma_f32_16x16x32_bf16 v[106:109], v[232:235], v[220:223], v[106:109]
	ds_read_b128 v[170:173], v144 offset:5120
	v_mfma_f32_16x16x32_bf16 v[102:105], v[232:235], v[224:227], v[102:105]
	ds_read_b128 v[176:179], v144 offset:6144
	v_mfma_f32_16x16x32_bf16 v[98:101], v[232:235], v[228:231], v[98:101]
	ds_read_b128 v[180:183], v144 offset:7168
	v_mfma_f32_16x16x32_bf16 v[94:97], v[236:239], v[200:203], v[94:97]
	v_add_u32_e64 v144, s41, v137
	v_mfma_f32_16x16x32_bf16 v[90:93], v[236:239], v[204:207], v[90:93]
	v_mfma_f32_16x16x32_bf16 v[86:89], v[236:239], v[208:211], v[86:89]
	ds_read_b128 v[184:187], v144 offset:16384
	v_mfma_f32_16x16x32_bf16 v[82:85], v[236:239], v[212:215], v[82:85]
	ds_read_b128 v[188:191], v144 offset:17408
	v_mfma_f32_16x16x32_bf16 v[78:81], v[236:239], v[216:219], v[78:81]
	ds_read_b128 v[192:195], v144 offset:18432
	v_mfma_f32_16x16x32_bf16 v[74:77], v[236:239], v[220:223], v[74:77]
	ds_read_b128 v[196:199], v144 offset:19456
	v_mfma_f32_16x16x32_bf16 v[70:73], v[236:239], v[224:227], v[70:73]
	s_add_i32 s43, s47, s42
	s_mov_b32 m0, s43
	v_lshl_add_u64 v[142:143], v[132:133], 0, s[2:3]
	v_mfma_f32_16x16x32_bf16 v[66:69], v[236:239], v[228:231], v[66:69]
	global_load_lds_dwordx4 v[132:133], off
	s_add_i32 m0, m0, 0x1000
	v_mfma_f32_16x16x32_bf16 v[62:65], v[240:243], v[200:203], v[62:65]
	v_mfma_f32_16x16x32_bf16 v[58:61], v[240:243], v[204:207], v[58:61]
	v_mfma_f32_16x16x32_bf16 v[54:57], v[240:243], v[208:211], v[54:57]
	global_load_lds_dwordx4 v[142:143], off
	v_lshl_add_u64 v[142:143], v[142:143], 0, s[2:3]
	s_add_i32 m0, m0, 0x1000
	v_mfma_f32_16x16x32_bf16 v[50:53], v[240:243], v[212:215], v[50:53]
	v_mfma_f32_16x16x32_bf16 v[46:49], v[240:243], v[216:219], v[46:49]
	v_mfma_f32_16x16x32_bf16 v[42:45], v[240:243], v[220:223], v[42:45]
	global_load_lds_dwordx4 v[142:143], off
	v_lshl_add_u64 v[142:143], v[142:143], 0, s[2:3]
	s_add_i32 m0, m0, 0x1000
	v_mfma_f32_16x16x32_bf16 v[38:41], v[240:243], v[224:227], v[38:41]
	v_mfma_f32_16x16x32_bf16 v[34:37], v[240:243], v[228:231], v[34:37]
	v_mfma_f32_16x16x32_bf16 v[30:33], v[244:247], v[200:203], v[30:33]
	global_load_lds_dwordx4 v[142:143], off
	s_add_i32 m0, m0, 0x1000
	v_lshl_add_u64 v[142:143], v[134:135], 0, s[2:3]
	v_mfma_f32_16x16x32_bf16 v[26:29], v[244:247], v[204:207], v[26:29]
	v_mfma_f32_16x16x32_bf16 v[22:25], v[244:247], v[208:211], v[22:25]
	v_mfma_f32_16x16x32_bf16 v[18:21], v[244:247], v[212:215], v[18:21]
	global_load_lds_dwordx4 v[134:135], off
	s_add_i32 m0, m0, 0x1000
	v_lshl_add_u64 v[132:133], v[132:133], 0, s[12:13]
	v_mfma_f32_16x16x32_bf16 v[14:17], v[244:247], v[216:219], v[14:17]
	v_mfma_f32_16x16x32_bf16 v[10:13], v[244:247], v[220:223], v[10:13]
	v_mfma_f32_16x16x32_bf16 v[6:9], v[244:247], v[224:227], v[6:9]
	global_load_lds_dwordx4 v[142:143], off
	v_lshl_add_u64 v[134:135], v[134:135], 0, s[4:5]
	v_mfma_f32_16x16x32_bf16 v[2:5], v[244:247], v[228:231], v[2:5]
	s_setprio 0
	s_mov_b32 s42, s41
	s_add_i32 s41, s41, 0x6000
	s_cmp_eq_u32 s41, 0x12000
	s_cselect_b32 s41, 0, s41
	s_nop 0
	s_sub_i32 s40, s40, 1
	s_cmp_lg_u32 s40, 0
	s_cbranch_scc1 .Lt4_loop
	.p2align 3
	s_waitcnt vmcnt(6) lgkmcnt(0)
	s_barrier
	s_setprio 1
	v_add_u32_e32 v144, s41, v136
	v_mfma_f32_16x16x32_bf16 v[126:129], v[184:187], v[146:149], v[126:129]
	ds_read_b128 v[200:203], v144 offset:0
	v_mfma_f32_16x16x32_bf16 v[122:125], v[184:187], v[152:155], v[122:125]
	ds_read_b128 v[204:207], v144 offset:1024
	v_mfma_f32_16x16x32_bf16 v[118:121], v[184:187], v[156:159], v[118:121]
	ds_read_b128 v[208:211], v144 offset:2048
	v_mfma_f32_16x16x32_bf16 v[114:117], v[184:187], v[162:165], v[114:117]
	ds_read_b128 v[212:215], v144 offset:3072
	v_mfma_f32_16x16x32_bf16 v[110:113], v[184:187], v[166:169], v[110:113]
	ds_read_b128 v[216:219], v144 offset:4096
	v_mfma_f32_16x16x32_bf16 v[106:109], v[184:187], v[170:173], v[106:109]
	ds_read_b128 v[220:223], v144 offset:5120
	v_mfma_f32_16x16x32_bf16 v[102:105], v[184:187], v[176:179], v[102:105]
	ds_read_b128 v[224:227], v144 offset:6144
	v_mfma_f32_16x16x32_bf16 v[98:101], v[184:187], v[180:183], v[98:101]
	ds_read_b128 v[228:231], v144 offset:7168
	v_mfma_f32_16x16x32_bf16 v[94:97], v[188:191], v[146:149], v[94:97]
	v_add_u32_e64 v144, s41, v137
	v_mfma_f32_16x16x32_bf16 v[90:93], v[188:191], v[152:155], v[90:93]
	v_mfma_f32_16x16x32_bf16 v[86:89], v[188:191], v[156:159], v[86:89]
	ds_read_b128 v[232:235], v144 offset:16384
	v_mfma_f32_16x16x32_bf16 v[82:85], v[188:191], v[162:165], v[82:85]
	ds_read_b128 v[236:239], v144 offset:17408
	v_mfma_f32_16x16x32_bf16 v[78:81], v[188:191], v[166:169], v[78:81]
	ds_read_b128 v[240:243], v144 offset:18432
	v_mfma_f32_16x16x32_bf16 v[74:77], v[188:191], v[170:173], v[74:77]
	ds_read_b128 v[244:247], v144 offset:19456
	v_mfma_f32_16x16x32_bf16 v[70:73], v[188:191], v[176:179], v[70:73]
	s_add_i32 s43, s47, s42
	s_mov_b32 m0, s43
	v_lshl_add_u64 v[142:143], v[132:133], 0, s[2:3]
	v_mfma_f32_16x16x32_bf16 v[66:69], v[188:191], v[180:183], v[66:69]
	global_load_lds_dwordx4 v[132:133], off
;     ...
;   for (int kt = 0; kt < nk; kt++) {
;     if (kt + 1 < nk) asm volatile("s_waitcnt vmcnt(6)" ::: "memory");
;     else asm volatile("s_waitcnt vmcnt(0)" ::: "memory");
;     __builtin_amdgcn_s_barrier();
;     asm volatile("" ::: "memory");
;     if (kt + 2 < nk) G2_STAGE(kt + 2);
;     const char* cS = smem + (kt % 3) * 24576;
;     bf16x8 xa[8], wb[4];
; #pragma unroll
;     for (int f = 0; f < 8; f++) xa[f] = *(const bf16x8*)(cS + aoff + f * 1024);
; #pragma unroll
;     for (int f = 0; f < 4; f++) wb[f] = *(const bf16x8*)(cS + boff + f * 1024);
; #pragma unroll
;     for (int nf = 0; nf < 4; nf++)
; #pragma unroll
;       for (int mf = 0; mf < 8; mf++)
;         acc[nf][mf] = __builtin_amdgcn_mfma_f32_16x16x32_bf16(wb[nf], xa[mf], acc[nf][mf], 0, 0, 0);
	s_add_i32 m0, m0, 0x1000
	v_mfma_f32_16x16x32_bf16 v[62:65], v[192:195], v[146:149], v[62:65]
	v_mfma_f32_16x16x32_bf16 v[58:61], v[192:195], v[152:155], v[58:61]
	v_mfma_f32_16x16x32_bf16 v[54:57], v[192:195], v[156:159], v[54:57]
	global_load_lds_dwordx4 v[142:143], off
	v_lshl_add_u64 v[142:143], v[142:143], 0, s[2:3]
	s_add_i32 m0, m0, 0x1000
	v_mfma_f32_16x16x32_bf16 v[50:53], v[192:195], v[162:165], v[50:53]
	v_mfma_f32_16x16x32_bf16 v[46:49], v[192:195], v[166:169], v[46:49]
	v_mfma_f32_16x16x32_bf16 v[42:45], v[192:195], v[170:173], v[42:45]
	global_load_lds_dwordx4 v[142:143], off
	v_lshl_add_u64 v[142:143], v[142:143], 0, s[2:3]
	s_add_i32 m0, m0, 0x1000
	v_mfma_f32_16x16x32_bf16 v[38:41], v[192:195], v[176:179], v[38:41]
	v_mfma_f32_16x16x32_bf16 v[34:37], v[192:195], v[180:183], v[34:37]
	v_mfma_f32_16x16x32_bf16 v[30:33], v[196:199], v[146:149], v[30:33]
	global_load_lds_dwordx4 v[142:143], off
	s_add_i32 m0, m0, 0x1000
	v_lshl_add_u64 v[142:143], v[134:135], 0, s[2:3]
	v_mfma_f32_16x16x32_bf16 v[26:29], v[196:199], v[152:155], v[26:29]
	v_mfma_f32_16x16x32_bf16 v[22:25], v[196:199], v[156:159], v[22:25]
	v_mfma_f32_16x16x32_bf16 v[18:21], v[196:199], v[162:165], v[18:21]
	global_load_lds_dwordx4 v[134:135], off
	s_add_i32 m0, m0, 0x1000
	v_lshl_add_u64 v[132:133], v[132:133], 0, s[12:13]
	v_mfma_f32_16x16x32_bf16 v[14:17], v[196:199], v[166:169], v[14:17]
	v_mfma_f32_16x16x32_bf16 v[10:13], v[196:199], v[170:173], v[10:13]
	v_mfma_f32_16x16x32_bf16 v[6:9], v[196:199], v[176:179], v[6:9]
	global_load_lds_dwordx4 v[142:143], off
	v_lshl_add_u64 v[134:135], v[134:135], 0, s[4:5]
	v_mfma_f32_16x16x32_bf16 v[2:5], v[196:199], v[180:183], v[2:5]
	s_setprio 0
	s_mov_b32 s42, s41
	s_add_i32 s41, s41, 0x6000
	s_cmp_eq_u32 s41, 0x12000
	s_cselect_b32 s41, 0, s41
	s_nop 0
	.p2align 3
	s_waitcnt vmcnt(6) lgkmcnt(0)
	s_barrier
	s_setprio 1
	v_add_u32_e32 v144, s41, v136
	v_mfma_f32_16x16x32_bf16 v[126:129], v[232:235], v[200:203], v[126:129]
	ds_read_b128 v[146:149], v144 offset:0
	v_mfma_f32_16x16x32_bf16 v[122:125], v[232:235], v[204:207], v[122:125]
	ds_read_b128 v[152:155], v144 offset:1024
	v_mfma_f32_16x16x32_bf16 v[118:121], v[232:235], v[208:211], v[118:121]
	ds_read_b128 v[156:159], v144 offset:2048
	v_mfma_f32_16x16x32_bf16 v[114:117], v[232:235], v[212:215], v[114:117]
	ds_read_b128 v[162:165], v144 offset:3072
	v_mfma_f32_16x16x32_bf16 v[110:113], v[232:235], v[216:219], v[110:113]
	ds_read_b128 v[166:169], v144 offset:4096
	v_mfma_f32_16x16x32_bf16 v[106:109], v[232:235], v[220:223], v[106:109]
	ds_read_b128 v[170:173], v144 offset:5120
	v_mfma_f32_16x16x32_bf16 v[102:105], v[232:235], v[224:227], v[102:105]
	ds_read_b128 v[176:179], v144 offset:6144
	v_mfma_f32_16x16x32_bf16 v[98:101], v[232:235], v[228:231], v[98:101]
	ds_read_b128 v[180:183], v144 offset:7168
	v_mfma_f32_16x16x32_bf16 v[94:97], v[236:239], v[200:203], v[94:97]
	v_add_u32_e64 v144, s41, v137
	v_mfma_f32_16x16x32_bf16 v[90:93], v[236:239], v[204:207], v[90:93]
	v_mfma_f32_16x16x32_bf16 v[86:89], v[236:239], v[208:211], v[86:89]
	ds_read_b128 v[184:187], v144 offset:16384
	v_mfma_f32_16x16x32_bf16 v[82:85], v[236:239], v[212:215], v[82:85]
	ds_read_b128 v[188:191], v144 offset:17408
	v_mfma_f32_16x16x32_bf16 v[78:81], v[236:239], v[216:219], v[78:81]
	ds_read_b128 v[192:195], v144 offset:18432
	v_mfma_f32_16x16x32_bf16 v[74:77], v[236:239], v[220:223], v[74:77]
	ds_read_b128 v[196:199], v144 offset:19456
	v_mfma_f32_16x16x32_bf16 v[70:73], v[236:239], v[224:227], v[70:73]
	v_mfma_f32_16x16x32_bf16 v[66:69], v[236:239], v[228:231], v[66:69]
	v_mfma_f32_16x16x32_bf16 v[62:65], v[240:243], v[200:203], v[62:65]
	v_mfma_f32_16x16x32_bf16 v[58:61], v[240:243], v[204:207], v[58:61]
	v_mfma_f32_16x16x32_bf16 v[54:57], v[240:243], v[208:211], v[54:57]
	v_mfma_f32_16x16x32_bf16 v[50:53], v[240:243], v[212:215], v[50:53]
	v_mfma_f32_16x16x32_bf16 v[46:49], v[240:243], v[216:219], v[46:49]
	v_mfma_f32_16x16x32_bf16 v[42:45], v[240:243], v[220:223], v[42:45]
	v_mfma_f32_16x16x32_bf16 v[38:41], v[240:243], v[224:227], v[38:41]
	v_mfma_f32_16x16x32_bf16 v[34:37], v[240:243], v[228:231], v[34:37]
	v_mfma_f32_16x16x32_bf16 v[30:33], v[244:247], v[200:203], v[30:33]
	v_mfma_f32_16x16x32_bf16 v[26:29], v[244:247], v[204:207], v[26:29]
	v_mfma_f32_16x16x32_bf16 v[22:25], v[244:247], v[208:211], v[22:25]
	v_mfma_f32_16x16x32_bf16 v[18:21], v[244:247], v[212:215], v[18:21]
	v_mfma_f32_16x16x32_bf16 v[14:17], v[244:247], v[216:219], v[14:17]
	v_mfma_f32_16x16x32_bf16 v[10:13], v[244:247], v[220:223], v[10:13]
	v_mfma_f32_16x16x32_bf16 v[6:9], v[244:247], v[224:227], v[6:9]
	v_mfma_f32_16x16x32_bf16 v[2:5], v[244:247], v[228:231], v[2:5]
	s_setprio 0
	s_mov_b32 s42, s41
	s_add_i32 s41, s41, 0x6000
	s_cmp_eq_u32 s41, 0x12000
	s_cselect_b32 s41, 0, s41
	s_nop 0
	.p2align 3
	s_waitcnt vmcnt(0) lgkmcnt(0)
	s_barrier
; DEVI float blo(unsigned u) { return __uint_as_float(u << 16); }
; DEVI float bhi(unsigned u) { return __uint_as_float(u & 0xffff0000u); }
;     ...
;   for (int kt = 0; kt < nk; kt++) {
;     if (kt + 1 < nk) asm volatile("s_waitcnt vmcnt(6)" ::: "memory");
;     else asm volatile("s_waitcnt vmcnt(0)" ::: "memory");
;     __builtin_amdgcn_s_barrier();
;     asm volatile("" ::: "memory");
;     if (kt + 2 < nk) G2_STAGE(kt + 2);
;     const char* cS = smem + (kt % 3) * 24576;
;     bf16x8 xa[8], wb[4];
; #pragma unroll
;     for (int f = 0; f < 8; f++) xa[f] = *(const bf16x8*)(cS + aoff + f * 1024);
; #pragma unroll
;     for (int f = 0; f < 4; f++) wb[f] = *(const bf16x8*)(cS + boff + f * 1024);
; #pragma unroll
;     for (int nf = 0; nf < 4; nf++)
; #pragma unroll
;       for (int mf = 0; mf < 8; mf++)
;         acc[nf][mf] = __builtin_amdgcn_mfma_f32_16x16x32_bf16(wb[nf], xa[mf], acc[nf][mf], 0, 0, 0);
;     ...
;         if (EPI == EPI_RESID || EPI == EPI_RESID_ATOMIC) {
;           f32x4 x = a;
;           if (EPI == EPI_RESID || kpart == 0) {
;             const u32x2 xr = *(const u32x2*)((const u16*)(p.ws + WS_XB) + (size_t)row * 1024 + col);
;             x[0] += ALPHA * blo(xr[0]); x[1] += ALPHA * bhi(xr[0]); x[2] += ALPHA * blo(xr[1]); x[3] += ALPHA * bhi(xr[1]);
;           }
;           if (EPI == EPI_RESID) *(f32x4*)((float*)(p.ws + WS_XF) + (size_t)row * 1024 + col) = x;
	s_setprio 1
	v_add_u32_e32 v144, s41, v136
	v_mfma_f32_16x16x32_bf16 v[126:129], v[184:187], v[146:149], v[126:129]
	ds_read_b128 v[200:203], v144 offset:0
	v_mfma_f32_16x16x32_bf16 v[122:125], v[184:187], v[152:155], v[122:125]
	ds_read_b128 v[204:207], v144 offset:1024
	v_mfma_f32_16x16x32_bf16 v[118:121], v[184:187], v[156:159], v[118:121]
	ds_read_b128 v[208:211], v144 offset:2048
	v_mfma_f32_16x16x32_bf16 v[114:117], v[184:187], v[162:165], v[114:117]
	ds_read_b128 v[212:215], v144 offset:3072
	v_mfma_f32_16x16x32_bf16 v[110:113], v[184:187], v[166:169], v[110:113]
	ds_read_b128 v[216:219], v144 offset:4096
	v_mfma_f32_16x16x32_bf16 v[106:109], v[184:187], v[170:173], v[106:109]
	ds_read_b128 v[220:223], v144 offset:5120
	v_mfma_f32_16x16x32_bf16 v[102:105], v[184:187], v[176:179], v[102:105]
	ds_read_b128 v[224:227], v144 offset:6144
	v_mfma_f32_16x16x32_bf16 v[98:101], v[184:187], v[180:183], v[98:101]
	ds_read_b128 v[228:231], v144 offset:7168
	v_mfma_f32_16x16x32_bf16 v[94:97], v[188:191], v[146:149], v[94:97]
	v_add_u32_e64 v144, s41, v137
	v_mfma_f32_16x16x32_bf16 v[90:93], v[188:191], v[152:155], v[90:93]
	v_mfma_f32_16x16x32_bf16 v[86:89], v[188:191], v[156:159], v[86:89]
	ds_read_b128 v[232:235], v144 offset:16384
	v_mfma_f32_16x16x32_bf16 v[82:85], v[188:191], v[162:165], v[82:85]
	ds_read_b128 v[236:239], v144 offset:17408
	v_mfma_f32_16x16x32_bf16 v[78:81], v[188:191], v[166:169], v[78:81]
	ds_read_b128 v[240:243], v144 offset:18432
	v_mfma_f32_16x16x32_bf16 v[74:77], v[188:191], v[170:173], v[74:77]
	ds_read_b128 v[244:247], v144 offset:19456
	v_mfma_f32_16x16x32_bf16 v[70:73], v[188:191], v[176:179], v[70:73]
	v_mfma_f32_16x16x32_bf16 v[66:69], v[188:191], v[180:183], v[66:69]
	v_mfma_f32_16x16x32_bf16 v[62:65], v[192:195], v[146:149], v[62:65]
	v_mfma_f32_16x16x32_bf16 v[58:61], v[192:195], v[152:155], v[58:61]
	v_mfma_f32_16x16x32_bf16 v[54:57], v[192:195], v[156:159], v[54:57]
	v_mfma_f32_16x16x32_bf16 v[50:53], v[192:195], v[162:165], v[50:53]
	v_mfma_f32_16x16x32_bf16 v[46:49], v[192:195], v[166:169], v[46:49]
	v_mfma_f32_16x16x32_bf16 v[42:45], v[192:195], v[170:173], v[42:45]
	v_mfma_f32_16x16x32_bf16 v[38:41], v[192:195], v[176:179], v[38:41]
	v_mfma_f32_16x16x32_bf16 v[34:37], v[192:195], v[180:183], v[34:37]
	v_mfma_f32_16x16x32_bf16 v[30:33], v[196:199], v[146:149], v[30:33]
	v_mfma_f32_16x16x32_bf16 v[26:29], v[196:199], v[152:155], v[26:29]
	v_mfma_f32_16x16x32_bf16 v[22:25], v[196:199], v[156:159], v[22:25]
	v_mfma_f32_16x16x32_bf16 v[18:21], v[196:199], v[162:165], v[18:21]
	v_mfma_f32_16x16x32_bf16 v[14:17], v[196:199], v[166:169], v[14:17]
	v_mfma_f32_16x16x32_bf16 v[10:13], v[196:199], v[170:173], v[10:13]
	v_mfma_f32_16x16x32_bf16 v[6:9], v[196:199], v[176:179], v[6:9]
	v_mfma_f32_16x16x32_bf16 v[2:5], v[196:199], v[180:183], v[2:5]
	s_setprio 0
	s_mov_b32 s42, s41
	s_add_i32 s41, s41, 0x6000
	s_cmp_eq_u32 s41, 0x12000
	s_cselect_b32 s41, 0, s41
	s_nop 0
	s_mov_b32 s4, 0x8000
	s_mov_b32 s5, 0
	s_mov_b32 s10, 0x10000
	s_mov_b32 s11, 0
	s_mov_b32 s45, 0x3fd744fd
	.p2align 3
	s_waitcnt lgkmcnt(0)
	s_nop 0
	v_mfma_f32_16x16x32_bf16 v[126:129], v[232:235], v[200:203], v[126:129]
	v_mfma_f32_16x16x32_bf16 v[122:125], v[232:235], v[204:207], v[122:125]
	v_mfma_f32_16x16x32_bf16 v[118:121], v[232:235], v[208:211], v[118:121]
	v_mfma_f32_16x16x32_bf16 v[114:117], v[232:235], v[212:215], v[114:117]
	v_mfma_f32_16x16x32_bf16 v[110:113], v[232:235], v[216:219], v[110:113]
	global_load_dwordx4 v[146:149], v[138:139], off offset:0
	v_mfma_f32_16x16x32_bf16 v[106:109], v[232:235], v[220:223], v[106:109]
	v_mfma_f32_16x16x32_bf16 v[102:105], v[232:235], v[224:227], v[102:105]
	global_load_dwordx4 v[152:155], v[138:139], off offset:128
	v_mfma_f32_16x16x32_bf16 v[98:101], v[232:235], v[228:231], v[98:101]
	v_lshl_add_u64 v[138:139], v[138:139], 0, s[4:5]
	v_mfma_f32_16x16x32_bf16 v[94:97], v[236:239], v[200:203], v[94:97]
	global_load_dwordx4 v[156:159], v[138:139], off offset:0
	v_mfma_f32_16x16x32_bf16 v[90:93], v[236:239], v[204:207], v[90:93]
	v_mfma_f32_16x16x32_bf16 v[86:89], v[236:239], v[208:211], v[86:89]
	global_load_dwordx4 v[162:165], v[138:139], off offset:128
	v_mfma_f32_16x16x32_bf16 v[82:85], v[236:239], v[212:215], v[82:85]
	v_lshl_add_u64 v[138:139], v[138:139], 0, s[4:5]
	v_mfma_f32_16x16x32_bf16 v[78:81], v[236:239], v[216:219], v[78:81]
	global_load_dwordx4 v[166:169], v[138:139], off offset:0
	v_mfma_f32_16x16x32_bf16 v[74:77], v[236:239], v[220:223], v[74:77]
	v_mfma_f32_16x16x32_bf16 v[70:73], v[236:239], v[224:227], v[70:73]
	global_load_dwordx4 v[170:173], v[138:139], off offset:128
	v_mfma_f32_16x16x32_bf16 v[66:69], v[236:239], v[228:231], v[66:69]
	v_lshl_add_u64 v[138:139], v[138:139], 0, s[4:5]
	v_mfma_f32_16x16x32_bf16 v[62:65], v[240:243], v[200:203], v[62:65]
	global_load_dwordx4 v[176:179], v[138:139], off offset:0
	v_mfma_f32_16x16x32_bf16 v[58:61], v[240:243], v[204:207], v[58:61]
	v_mfma_f32_16x16x32_bf16 v[54:57], v[240:243], v[208:211], v[54:57]
	global_load_dwordx4 v[180:183], v[138:139], off offset:128
	v_mfma_f32_16x16x32_bf16 v[50:53], v[240:243], v[212:215], v[50:53]
	v_lshl_add_u64 v[138:139], v[138:139], 0, s[4:5]
	v_mfma_f32_16x16x32_bf16 v[46:49], v[240:243], v[216:219], v[46:49]
	global_load_dwordx4 v[184:187], v[138:139], off offset:0
	v_mfma_f32_16x16x32_bf16 v[42:45], v[240:243], v[220:223], v[42:45]
	v_mfma_f32_16x16x32_bf16 v[38:41], v[240:243], v[224:227], v[38:41]
	global_load_dwordx4 v[188:191], v[138:139], off offset:128
	v_mfma_f32_16x16x32_bf16 v[34:37], v[240:243], v[228:231], v[34:37]
	v_lshl_add_u64 v[138:139], v[138:139], 0, s[4:5]
	v_mfma_f32_16x16x32_bf16 v[30:33], v[244:247], v[200:203], v[30:33]
	global_load_dwordx4 v[192:195], v[138:139], off offset:0
	v_mfma_f32_16x16x32_bf16 v[26:29], v[244:247], v[204:207], v[26:29]
	v_mfma_f32_16x16x32_bf16 v[22:25], v[244:247], v[208:211], v[22:25]
	global_load_dwordx4 v[196:199], v[138:139], off offset:128
	v_mfma_f32_16x16x32_bf16 v[18:21], v[244:247], v[212:215], v[18:21]
	v_lshl_add_u64 v[138:139], v[138:139], 0, s[4:5]
	v_mfma_f32_16x16x32_bf16 v[14:17], v[244:247], v[216:219], v[14:17]
	v_mfma_f32_16x16x32_bf16 v[10:13], v[244:247], v[220:223], v[10:13]
	v_mfma_f32_16x16x32_bf16 v[6:9], v[244:247], v[224:227], v[6:9]
	v_mfma_f32_16x16x32_bf16 v[2:5], v[244:247], v[228:231], v[2:5]
	s_mov_b32 m0, s44
	global_load_dwordx4 v[200:203], v[138:139], off offset:0
	global_load_dwordx4 v[204:207], v[138:139], off offset:128
	v_lshl_add_u64 v[138:139], v[138:139], 0, s[4:5]
	global_load_dwordx4 v[208:211], v[138:139], off offset:0
	global_load_dwordx4 v[212:215], v[138:139], off offset:128
	v_lshl_add_u64 v[138:139], v[138:139], 0, s[4:5]
	s_nop 7
	s_waitcnt vmcnt(15)
; DEVI float blo(unsigned u) { return __uint_as_float(u << 16); }
; DEVI float bhi(unsigned u) { return __uint_as_float(u & 0xffff0000u); }
;     ...
;         if (EPI == EPI_RESID || EPI == EPI_RESID_ATOMIC) {
;           f32x4 x = a;
;           if (EPI == EPI_RESID || kpart == 0) {
;             const u32x2 xr = *(const u32x2*)((const u16*)(p.ws + WS_XB) + (size_t)row * 1024 + col);
;             x[0] += ALPHA * blo(xr[0]); x[1] += ALPHA * bhi(xr[0]); x[2] += ALPHA * blo(xr[1]); x[3] += ALPHA * bhi(xr[1]);
;           }
;           if (EPI == EPI_RESID) *(f32x4*)((float*)(p.ws + WS_XF) + (size_t)row * 1024 + col) = x;
	v_permlane16_swap_b32_e32 v146, v148
	v_permlane16_swap_b32_e32 v147, v149
	v_lshlrev_b32_e32 v216, 16, v146
	v_and_b32_e32 v146, 0xffff0000, v146
	v_lshlrev_b32_e32 v217, 16, v147
	v_and_b32_e32 v147, 0xffff0000, v147
	v_fmac_f32_e32 v126, s45, v216
	v_fmac_f32_e32 v127, s45, v146
	v_fmac_f32_e32 v128, s45, v217
	v_fmac_f32_e32 v129, s45, v147
	global_store_dwordx4 v[140:141], v[126:129], off offset:0
	v_lshlrev_b32_e32 v216, 16, v148
	v_and_b32_e32 v148, 0xffff0000, v148
	v_lshlrev_b32_e32 v217, 16, v149
	v_and_b32_e32 v149, 0xffff0000, v149
	v_fmac_f32_e32 v94, s45, v216
	v_fmac_f32_e32 v95, s45, v148
	v_fmac_f32_e32 v96, s45, v217
	v_fmac_f32_e32 v97, s45, v149
	global_store_dwordx4 v[140:141], v[94:97], off offset:64
	s_waitcnt vmcnt(16)
	v_permlane16_swap_b32_e32 v152, v154
	v_permlane16_swap_b32_e32 v153, v155
	v_lshlrev_b32_e32 v216, 16, v152
	v_and_b32_e32 v152, 0xffff0000, v152
	v_lshlrev_b32_e32 v217, 16, v153
	v_and_b32_e32 v153, 0xffff0000, v153
	v_fmac_f32_e32 v62, s45, v216
	v_fmac_f32_e32 v63, s45, v152
	v_fmac_f32_e32 v64, s45, v217
	v_fmac_f32_e32 v65, s45, v153
	global_store_dwordx4 v[140:141], v[62:65], off offset:128
	v_lshlrev_b32_e32 v216, 16, v154
	v_and_b32_e32 v154, 0xffff0000, v154
	v_lshlrev_b32_e32 v217, 16, v155
	v_and_b32_e32 v155, 0xffff0000, v155
	v_fmac_f32_e32 v30, s45, v216
	v_fmac_f32_e32 v31, s45, v154
	v_fmac_f32_e32 v32, s45, v217
	v_fmac_f32_e32 v33, s45, v155
	global_store_dwordx4 v[140:141], v[30:33], off offset:192
	v_lshl_add_u64 v[140:141], v[140:141], 0, s[10:11]
	s_waitcnt vmcnt(17)
	v_permlane16_swap_b32_e32 v156, v158
	v_permlane16_swap_b32_e32 v157, v159
	v_lshlrev_b32_e32 v216, 16, v156
	v_and_b32_e32 v156, 0xffff0000, v156
	v_lshlrev_b32_e32 v217, 16, v157
	v_and_b32_e32 v157, 0xffff0000, v157
	v_fmac_f32_e32 v122, s45, v216
	v_fmac_f32_e32 v123, s45, v156
	v_fmac_f32_e32 v124, s45, v217
	v_fmac_f32_e32 v125, s45, v157
	global_store_dwordx4 v[140:141], v[122:125], off offset:0
	v_lshlrev_b32_e32 v216, 16, v158
	v_and_b32_e32 v158, 0xffff0000, v158
	v_lshlrev_b32_e32 v217, 16, v159
	v_and_b32_e32 v159, 0xffff0000, v159
	v_fmac_f32_e32 v90, s45, v216
	v_fmac_f32_e32 v91, s45, v158
	v_fmac_f32_e32 v92, s45, v217
	v_fmac_f32_e32 v93, s45, v159
	global_store_dwordx4 v[140:141], v[90:93], off offset:64
	s_waitcnt vmcnt(18)
	v_permlane16_swap_b32_e32 v162, v164
	v_permlane16_swap_b32_e32 v163, v165
	v_lshlrev_b32_e32 v216, 16, v162
	v_and_b32_e32 v162, 0xffff0000, v162
	v_lshlrev_b32_e32 v217, 16, v163
	v_and_b32_e32 v163, 0xffff0000, v163
	v_fmac_f32_e32 v58, s45, v216
	v_fmac_f32_e32 v59, s45, v162
	v_fmac_f32_e32 v60, s45, v217
	v_fmac_f32_e32 v61, s45, v163
	global_store_dwordx4 v[140:141], v[58:61], off offset:128
	v_lshlrev_b32_e32 v216, 16, v164
	v_and_b32_e32 v164, 0xffff0000, v164
	v_lshlrev_b32_e32 v217, 16, v165
	v_and_b32_e32 v165, 0xffff0000, v165
	v_fmac_f32_e32 v26, s45, v216
	v_fmac_f32_e32 v27, s45, v164
	v_fmac_f32_e32 v28, s45, v217
	v_fmac_f32_e32 v29, s45, v165
	global_store_dwordx4 v[140:141], v[26:29], off offset:192
	v_lshl_add_u64 v[140:141], v[140:141], 0, s[10:11]
	s_waitcnt vmcnt(19)
	v_permlane16_swap_b32_e32 v166, v168
	v_permlane16_swap_b32_e32 v167, v169
	v_lshlrev_b32_e32 v216, 16, v166
	v_and_b32_e32 v166, 0xffff0000, v166
	v_lshlrev_b32_e32 v217, 16, v167
	v_and_b32_e32 v167, 0xffff0000, v167
	v_fmac_f32_e32 v118, s45, v216
	v_fmac_f32_e32 v119, s45, v166
	v_fmac_f32_e32 v120, s45, v217
	v_fmac_f32_e32 v121, s45, v167
	global_store_dwordx4 v[140:141], v[118:121], off offset:0
	v_lshlrev_b32_e32 v216, 16, v168
	v_and_b32_e32 v168, 0xffff0000, v168
	v_lshlrev_b32_e32 v217, 16, v169
	v_and_b32_e32 v169, 0xffff0000, v169
	v_fmac_f32_e32 v86, s45, v216
	v_fmac_f32_e32 v87, s45, v168
	v_fmac_f32_e32 v88, s45, v217
	v_fmac_f32_e32 v89, s45, v169
	global_store_dwordx4 v[140:141], v[86:89], off offset:64
	s_waitcnt vmcnt(20)
	v_permlane16_swap_b32_e32 v170, v172
	v_permlane16_swap_b32_e32 v171, v173
	v_lshlrev_b32_e32 v216, 16, v170
	v_and_b32_e32 v170, 0xffff0000, v170
	v_lshlrev_b32_e32 v217, 16, v171
	v_and_b32_e32 v171, 0xffff0000, v171
	v_fmac_f32_e32 v54, s45, v216
	v_fmac_f32_e32 v55, s45, v170
	v_fmac_f32_e32 v56, s45, v217
	v_fmac_f32_e32 v57, s45, v171
	global_store_dwordx4 v[140:141], v[54:57], off offset:128
	v_lshlrev_b32_e32 v216, 16, v172
	v_and_b32_e32 v172, 0xffff0000, v172
	v_lshlrev_b32_e32 v217, 16, v173
	v_and_b32_e32 v173, 0xffff0000, v173
	v_fmac_f32_e32 v22, s45, v216
	v_fmac_f32_e32 v23, s45, v172
	v_fmac_f32_e32 v24, s45, v217
	v_fmac_f32_e32 v25, s45, v173
	global_store_dwordx4 v[140:141], v[22:25], off offset:192
	v_lshl_add_u64 v[140:141], v[140:141], 0, s[10:11]
	s_waitcnt vmcnt(21)
	v_permlane16_swap_b32_e32 v176, v178
	v_permlane16_swap_b32_e32 v177, v179
	v_lshlrev_b32_e32 v216, 16, v176
	v_and_b32_e32 v176, 0xffff0000, v176
	v_lshlrev_b32_e32 v217, 16, v177
	v_and_b32_e32 v177, 0xffff0000, v177
	v_fmac_f32_e32 v114, s45, v216
	v_fmac_f32_e32 v115, s45, v176
	v_fmac_f32_e32 v116, s45, v217
	v_fmac_f32_e32 v117, s45, v177
	global_store_dwordx4 v[140:141], v[114:117], off offset:0
	v_lshlrev_b32_e32 v216, 16, v178
	v_and_b32_e32 v178, 0xffff0000, v178
	v_lshlrev_b32_e32 v217, 16, v179
	v_and_b32_e32 v179, 0xffff0000, v179
	v_fmac_f32_e32 v82, s45, v216
	v_fmac_f32_e32 v83, s45, v178
	v_fmac_f32_e32 v84, s45, v217
	v_fmac_f32_e32 v85, s45, v179
	global_store_dwordx4 v[140:141], v[82:85], off offset:64
	s_waitcnt vmcnt(22)
; DEVI float blo(unsigned u) { return __uint_as_float(u << 16); }
; DEVI float bhi(unsigned u) { return __uint_as_float(u & 0xffff0000u); }
;     ...
;         if (EPI == EPI_RESID || EPI == EPI_RESID_ATOMIC) {
;           f32x4 x = a;
;           if (EPI == EPI_RESID || kpart == 0) {
;             const u32x2 xr = *(const u32x2*)((const u16*)(p.ws + WS_XB) + (size_t)row * 1024 + col);
;             x[0] += ALPHA * blo(xr[0]); x[1] += ALPHA * bhi(xr[0]); x[2] += ALPHA * blo(xr[1]); x[3] += ALPHA * bhi(xr[1]);
;           }
;           if (EPI == EPI_RESID) *(f32x4*)((float*)(p.ws + WS_XF) + (size_t)row * 1024 + col) = x;
	v_permlane16_swap_b32_e32 v180, v182
	v_permlane16_swap_b32_e32 v181, v183
	v_lshlrev_b32_e32 v216, 16, v180
	v_and_b32_e32 v180, 0xffff0000, v180
	v_lshlrev_b32_e32 v217, 16, v181
	v_and_b32_e32 v181, 0xffff0000, v181
	v_fmac_f32_e32 v50, s45, v216
	v_fmac_f32_e32 v51, s45, v180
	v_fmac_f32_e32 v52, s45, v217
	v_fmac_f32_e32 v53, s45, v181
	global_store_dwordx4 v[140:141], v[50:53], off offset:128
	v_lshlrev_b32_e32 v216, 16, v182
	v_and_b32_e32 v182, 0xffff0000, v182
	v_lshlrev_b32_e32 v217, 16, v183
	v_and_b32_e32 v183, 0xffff0000, v183
	v_fmac_f32_e32 v18, s45, v216
	v_fmac_f32_e32 v19, s45, v182
	v_fmac_f32_e32 v20, s45, v217
	v_fmac_f32_e32 v21, s45, v183
	global_store_dwordx4 v[140:141], v[18:21], off offset:192
	v_lshl_add_u64 v[140:141], v[140:141], 0, s[10:11]
	s_waitcnt vmcnt(23)
	v_permlane16_swap_b32_e32 v184, v186
	v_permlane16_swap_b32_e32 v185, v187
	v_lshlrev_b32_e32 v216, 16, v184
	v_and_b32_e32 v184, 0xffff0000, v184
	v_lshlrev_b32_e32 v217, 16, v185
	v_and_b32_e32 v185, 0xffff0000, v185
	v_fmac_f32_e32 v110, s45, v216
	v_fmac_f32_e32 v111, s45, v184
	v_fmac_f32_e32 v112, s45, v217
	v_fmac_f32_e32 v113, s45, v185
	global_store_dwordx4 v[140:141], v[110:113], off offset:0
	v_lshlrev_b32_e32 v216, 16, v186
	v_and_b32_e32 v186, 0xffff0000, v186
	v_lshlrev_b32_e32 v217, 16, v187
	v_and_b32_e32 v187, 0xffff0000, v187
	v_fmac_f32_e32 v78, s45, v216
	v_fmac_f32_e32 v79, s45, v186
	v_fmac_f32_e32 v80, s45, v217
	v_fmac_f32_e32 v81, s45, v187
	global_store_dwordx4 v[140:141], v[78:81], off offset:64
	s_waitcnt vmcnt(24)
	v_permlane16_swap_b32_e32 v188, v190
	v_permlane16_swap_b32_e32 v189, v191
	v_lshlrev_b32_e32 v216, 16, v188
	v_and_b32_e32 v188, 0xffff0000, v188
	v_lshlrev_b32_e32 v217, 16, v189
	v_and_b32_e32 v189, 0xffff0000, v189
	v_fmac_f32_e32 v46, s45, v216
	v_fmac_f32_e32 v47, s45, v188
	v_fmac_f32_e32 v48, s45, v217
	v_fmac_f32_e32 v49, s45, v189
	global_store_dwordx4 v[140:141], v[46:49], off offset:128
	v_lshlrev_b32_e32 v216, 16, v190
	v_and_b32_e32 v190, 0xffff0000, v190
	v_lshlrev_b32_e32 v217, 16, v191
	v_and_b32_e32 v191, 0xffff0000, v191
	v_fmac_f32_e32 v14, s45, v216
	v_fmac_f32_e32 v15, s45, v190
	v_fmac_f32_e32 v16, s45, v217
	v_fmac_f32_e32 v17, s45, v191
	global_store_dwordx4 v[140:141], v[14:17], off offset:192
	v_lshl_add_u64 v[140:141], v[140:141], 0, s[10:11]
	s_waitcnt vmcnt(25)
	v_permlane16_swap_b32_e32 v192, v194
	v_permlane16_swap_b32_e32 v193, v195
	v_lshlrev_b32_e32 v216, 16, v192
	v_and_b32_e32 v192, 0xffff0000, v192
	v_lshlrev_b32_e32 v217, 16, v193
	v_and_b32_e32 v193, 0xffff0000, v193
	v_fmac_f32_e32 v106, s45, v216
	v_fmac_f32_e32 v107, s45, v192
	v_fmac_f32_e32 v108, s45, v217
	v_fmac_f32_e32 v109, s45, v193
	global_store_dwordx4 v[140:141], v[106:109], off offset:0
	v_lshlrev_b32_e32 v216, 16, v194
	v_and_b32_e32 v194, 0xffff0000, v194
	v_lshlrev_b32_e32 v217, 16, v195
	v_and_b32_e32 v195, 0xffff0000, v195
	v_fmac_f32_e32 v74, s45, v216
	v_fmac_f32_e32 v75, s45, v194
	v_fmac_f32_e32 v76, s45, v217
	v_fmac_f32_e32 v77, s45, v195
	global_store_dwordx4 v[140:141], v[74:77], off offset:64
	s_waitcnt vmcnt(26)
	v_permlane16_swap_b32_e32 v196, v198
	v_permlane16_swap_b32_e32 v197, v199
	v_lshlrev_b32_e32 v216, 16, v196
	v_and_b32_e32 v196, 0xffff0000, v196
	v_lshlrev_b32_e32 v217, 16, v197
	v_and_b32_e32 v197, 0xffff0000, v197
	v_fmac_f32_e32 v42, s45, v216
	v_fmac_f32_e32 v43, s45, v196
	v_fmac_f32_e32 v44, s45, v217
	v_fmac_f32_e32 v45, s45, v197
	global_store_dwordx4 v[140:141], v[42:45], off offset:128
	v_lshlrev_b32_e32 v216, 16, v198
	v_and_b32_e32 v198, 0xffff0000, v198
	v_lshlrev_b32_e32 v217, 16, v199
	v_and_b32_e32 v199, 0xffff0000, v199
	v_fmac_f32_e32 v10, s45, v216
	v_fmac_f32_e32 v11, s45, v198
	v_fmac_f32_e32 v12, s45, v217
	v_fmac_f32_e32 v13, s45, v199
	global_store_dwordx4 v[140:141], v[10:13], off offset:192
	v_lshl_add_u64 v[140:141], v[140:141], 0, s[10:11]
	s_waitcnt vmcnt(27)
	v_permlane16_swap_b32_e32 v200, v202
	v_permlane16_swap_b32_e32 v201, v203
	v_lshlrev_b32_e32 v216, 16, v200
	v_and_b32_e32 v200, 0xffff0000, v200
	v_lshlrev_b32_e32 v217, 16, v201
	v_and_b32_e32 v201, 0xffff0000, v201
	v_fmac_f32_e32 v102, s45, v216
	v_fmac_f32_e32 v103, s45, v200
	v_fmac_f32_e32 v104, s45, v217
	v_fmac_f32_e32 v105, s45, v201
	global_store_dwordx4 v[140:141], v[102:105], off offset:0
	v_lshlrev_b32_e32 v216, 16, v202
	v_and_b32_e32 v202, 0xffff0000, v202
	v_lshlrev_b32_e32 v217, 16, v203
	v_and_b32_e32 v203, 0xffff0000, v203
	v_fmac_f32_e32 v70, s45, v216
	v_fmac_f32_e32 v71, s45, v202
	v_fmac_f32_e32 v72, s45, v217
	v_fmac_f32_e32 v73, s45, v203
	global_store_dwordx4 v[140:141], v[70:73], off offset:64
	s_waitcnt vmcnt(28)
	v_permlane16_swap_b32_e32 v204, v206
	v_permlane16_swap_b32_e32 v205, v207
	v_lshlrev_b32_e32 v216, 16, v204
	v_and_b32_e32 v204, 0xffff0000, v204
	v_lshlrev_b32_e32 v217, 16, v205
	v_and_b32_e32 v205, 0xffff0000, v205
	v_fmac_f32_e32 v38, s45, v216
	v_fmac_f32_e32 v39, s45, v204
	v_fmac_f32_e32 v40, s45, v217
	v_fmac_f32_e32 v41, s45, v205
	global_store_dwordx4 v[140:141], v[38:41], off offset:128
	v_lshlrev_b32_e32 v216, 16, v206
	v_and_b32_e32 v206, 0xffff0000, v206
	v_lshlrev_b32_e32 v217, 16, v207
	v_and_b32_e32 v207, 0xffff0000, v207
	v_fmac_f32_e32 v6, s45, v216
	v_fmac_f32_e32 v7, s45, v206
	v_fmac_f32_e32 v8, s45, v217
	v_fmac_f32_e32 v9, s45, v207
	global_store_dwordx4 v[140:141], v[6:9], off offset:192
	v_lshl_add_u64 v[140:141], v[140:141], 0, s[10:11]
	s_waitcnt vmcnt(29)
	v_permlane16_swap_b32_e32 v208, v210
	v_permlane16_swap_b32_e32 v209, v211
	v_lshlrev_b32_e32 v216, 16, v208
	v_and_b32_e32 v208, 0xffff0000, v208
	v_lshlrev_b32_e32 v217, 16, v209
	v_and_b32_e32 v209, 0xffff0000, v209
	v_fmac_f32_e32 v98, s45, v216
	v_fmac_f32_e32 v99, s45, v208
	v_fmac_f32_e32 v100, s45, v217
	v_fmac_f32_e32 v101, s45, v209
	global_store_dwordx4 v[140:141], v[98:101], off offset:0
	v_lshlrev_b32_e32 v216, 16, v210
	v_and_b32_e32 v210, 0xffff0000, v210
	v_lshlrev_b32_e32 v217, 16, v211
	v_and_b32_e32 v211, 0xffff0000, v211
	v_fmac_f32_e32 v66, s45, v216
	v_fmac_f32_e32 v67, s45, v210
	v_fmac_f32_e32 v68, s45, v217
	v_fmac_f32_e32 v69, s45, v211
	global_store_dwordx4 v[140:141], v[66:69], off offset:64
	s_waitcnt vmcnt(30)
	v_permlane16_swap_b32_e32 v212, v214
	v_permlane16_swap_b32_e32 v213, v215
	v_lshlrev_b32_e32 v216, 16, v212
	v_and_b32_e32 v212, 0xffff0000, v212
	v_lshlrev_b32_e32 v217, 16, v213
	v_and_b32_e32 v213, 0xffff0000, v213
	v_fmac_f32_e32 v34, s45, v216
	v_fmac_f32_e32 v35, s45, v212
	v_fmac_f32_e32 v36, s45, v217
	v_fmac_f32_e32 v37, s45, v213
	global_store_dwordx4 v[140:141], v[34:37], off offset:128
	v_lshlrev_b32_e32 v216, 16, v214
	v_and_b32_e32 v214, 0xffff0000, v214
	v_lshlrev_b32_e32 v217, 16, v215
	v_and_b32_e32 v215, 0xffff0000, v215
	v_fmac_f32_e32 v2, s45, v216
	v_fmac_f32_e32 v3, s45, v214
	v_fmac_f32_e32 v4, s45, v217
	v_fmac_f32_e32 v5, s45, v215
	global_store_dwordx4 v[140:141], v[2:5], off offset:192
	v_readlane_b32 s40, v250, 7
	s_cmpk_lg_u32 s40, 0x200
	s_cbranch_scc1 .LBB0_757
; DEVI int xcd_first_tile() { return (blockIdx.x & 7) * (gridDim.x >> 3) + (blockIdx.x >> 3); }
; DEVI void run_phase(const Params& p, int ph, char* smem) {
;     ...
;       for (int t = xcd_first_tile(); t < 512 + 16 * 8; t += xcd_tile_step()) {
;         if (t < 512) {
;           int mt_, nt_; tile_coords(t, 64, 8, mt_, nt_);
;           gemm_tile256<EPI_RESID>(p, mix, 1024, Bt, 1024, mt_ * 256, nt_ * 128, nullptr, 0, smem);
;         } else {
;           const int u_ = t - 512, tl_ = u_ / 8, q_ = u_ - tl_ * 8;
;           gemm_tile256<EPI_RESID_ATOMIC>(p, mix, 1024, Bt, 1024, (64 + (tl_ & 1)) * 256, (tl_ >> 1) * 128, nullptr, 0, smem, q_ * 128, 4, q_);
;         }
	v_readlane_b32 s41, v250, 0
	s_lshr_b32 s42, s41, 3
	s_and_b32 s41, s41, 7
	s_mul_i32 s41, s41, 16
	s_add_i32 s41, s41, s42
	s_cmp_lt_u32 s42, 16
	s_cselect_b32 s39, s41, 0x4000
	s_branch .LBB0_757

; #define LAS __attribute__((address_space(3)))
; DEVI int tidx() { int t = threadIdx.x; asm volatile("" : "+v"(t)); return t; }
; DEVI int xcd_first_tile() { return (blockIdx.x & 7) * (gridDim.x >> 3) + (blockIdx.x >> 3); }
;   const int tid = tidx(), lane = tid & 63, wid = tid >> 6;
;   const int wm = wid >> 1, wn = wid & 1, r16 = lane & 15, quad = lane >> 4;
;   f32x4 acc[4][8];
; #pragma unroll
;   for (int i = 0; i < 4; i++)
; #pragma unroll
;     for (int j = 0; j < 8; j++) acc[i][j] = (f32x4){0.f, 0.f, 0.f, 0.f};
;   const int nk = (nk_part < 0) ? (K >> 5) : nk_part;
;   const int lrow = tid >> 2, lpc = tid & 3;
;   const int lch = lpc ^ ((0x78 >> (((lrow >> 2) & 3) * 2)) & 3);
;   const u16* ga = A + (size_t)(m0 + lrow) * lda + kbeg + lch * 8;
;   const u16* gb = Bt + (size_t)(n0 + lrow) * K + kbeg + lch * 8;
;   const size_t ga1 = (size_t)64 * lda, gb1 = (size_t)64 * K;
;   const unsigned lds0 = (unsigned)(uintptr_t)(LAS char*)smem + (unsigned)__builtin_amdgcn_readfirstlane(wid) * 1024u;
;     ...
;   __syncthreads();
;   G2_STAGE(0); G2_STAGE(1);
; DEVI void run_phase(const Params& p, int ph, char* smem) {
;     ...
;       for (int t = xcd_first_tile(); t < n1 + n2; t += xcd_tile_step()) {
;         if (t < n1) { int mt_, nt_; tile_coords(t, 66, 20, mt_, nt_); gemm_tile256<EPI_BF16>(p, xb, 1024, Bt, 1024, mt_ * 256, nt_ * 128, proj, DIN, smem); }
.Lt0_crd:
	s_cmp_lt_u32 s43, 64
	s_cselect_b32 s42, 1, 0
	v_readlane_b32 s2, v250, 5
	v_readlane_b32 s3, v250, 6
	v_readlane_b32 s44, v254, 62
	s_mul_i32 s38, s43, 0x80000
	s_add_u32 s8, s2, s38
	s_addc_u32 s9, s3, 0
	s_add_u32 s8, s8, 0x4200000
	s_addc_u32 s9, s9, 0
	s_mul_i32 s38, s44, 0x500000
	s_mul_i32 s39, s40, 0x40000
	s_add_i32 s38, s38, s39
	s_add_u32 s10, s2, s38
	s_addc_u32 s11, s3, 0
	s_add_u32 s10, s10, 0x14a00000
	s_addc_u32 s11, s11, 0
	s_movk_i32 s15, 0x78
	v_lshrrev_b32_e32 v0, 2, v145
	v_and_b32_e32 v131, 3, v145
	v_bfe_u32 v136, v145, 4, 2
	v_lshlrev_b32_e32 v136, 1, v136
	v_lshrrev_b32_e64 v136, v136, s15
	v_and_b32_e32 v136, 3, v136
	v_xor_b32_e32 v131, v131, v136
	v_lshlrev_b32_e32 v131, 4, v131
	s_movk_i32 s39, 0x800
	v_mad_u32_u24 v0, v0, s39, v131
	v_bfe_u32 v137, v145, 2, 1
	s_movk_i32 s39, 0x7c0
	v_mul_u32_u24_e32 v136, s39, v137
	v_sub_u32_e32 v136, v0, v136
	v_mov_b32_e32 v137, 0
	v_lshl_add_u64 v[134:135], s[10:11], 0, v[136:137]
	v_bfe_u32 v137, v145, 2, 1
	s_mul_i32 s39, s42, 0x7c0
	v_mul_u32_u24_e32 v136, s39, v137
	v_sub_u32_e32 v0, v0, v136
	s_lshl_b32 s36, s42, 6
	s_add_i32 s36, s36, 64
	s_mov_b32 s37, 0
	v_lshl_add_u64 v[132:133], s[8:9], 0, v[0:1]
	v_bfe_u32 v136, v145, 2, 2
	v_lshlrev_b32_e32 v136, 1, v136
	v_lshrrev_b32_e64 v136, v136, s15
	v_and_b32_e32 v136, 3, v136
	v_bfe_u32 v137, v145, 4, 2
	v_xor_b32_e32 v136, v136, v137
	v_lshlrev_b32_e32 v136, 4, v136
	v_and_b32_e32 v131, 15, v145
	v_lshl_or_b32 v136, v131, 6, v136
	v_bfe_u32 v137, v145, 6, 1
	v_lshl_or_b32 v137, v137, 12, v136
	v_lshrrev_b32_e32 v0, 7, v145
	v_lshl_or_b32 v136, v0, 13, v136
	v_and_b32_e32 v140, 1, v131
	v_lshl_or_b32 v131, v0, 7, v131
	v_bfe_u32 v0, v145, 4, 1
	v_lshlrev_b32_e32 v0, 5, v0
	v_bfe_u32 v141, v145, 5, 1
	v_lshl_or_b32 v0, v141, 4, v0
	v_bfe_u32 v141, v145, 6, 1
	s_mul_i32 s38, s43, 0x140000
	s_lshl_b32 s39, s40, 8
	s_add_i32 s38, s38, s39
	s_add_u32 s10, s2, s38
	s_addc_u32 s11, s3, 0
	s_add_u32 s10, s10, 0x6300000
	s_addc_u32 s11, s11, 0
	s_movk_i32 s39, 5120
	v_mad_u32_u24 v138, v131, s39, v0
	v_lshl_add_u32 v138, v141, 7, v138
	v_mov_b32_e32 v139, 0
	v_lshl_add_u64 v[140:141], s[10:11], 0, v[138:139]
	s_mov_b32 s2, 0x20000
	s_mov_b32 s3, 0
	v_lshrrev_b32_e32 v0, 6, v145
	v_lshlrev_b32_e32 v0, 10, v0
	s_nop 0
	v_readfirstlane_b32 s44, v0
	s_mov_b32 s41, m0
	s_mov_b32 s8, 128
	s_mov_b32 s9, 0
	s_barrier
	s_add_i32 s40, s44, 0x0
	s_mov_b32 m0, s40
	v_lshl_add_u64 v[142:143], v[132:133], 0, s[2:3]
	global_load_lds_dwordx4 v[132:133], off
	s_add_i32 m0, m0, 0x1000
	s_nop 0
	global_load_lds_dwordx4 v[142:143], off
	v_lshl_add_u64 v[142:143], v[142:143], 0, s[2:3]
	s_add_i32 m0, m0, 0x1000
	s_nop 0
	global_load_lds_dwordx4 v[142:143], off
	v_lshl_add_u64 v[142:143], v[142:143], 0, s[2:3]
	s_add_i32 m0, m0, 0x1000
	s_nop 0
	global_load_lds_dwordx4 v[142:143], off
	s_add_i32 m0, m0, 0x1000
	v_lshl_add_u64 v[142:143], v[134:135], 0, s[2:3]
	s_nop 0
	global_load_lds_dwordx4 v[134:135], off
	s_add_i32 m0, m0, 0x1000
	v_lshl_add_u64 v[132:133], v[132:133], 0, s[36:37]
	s_nop 0
	global_load_lds_dwordx4 v[142:143], off
	v_lshl_add_u64 v[134:135], v[134:135], 0, s[8:9]
	s_nop 0
	s_add_i32 s40, s44, 0x6000
	s_mov_b32 m0, s40
	v_lshl_add_u64 v[142:143], v[132:133], 0, s[2:3]
	global_load_lds_dwordx4 v[132:133], off
	s_add_i32 m0, m0, 0x1000
	s_nop 0
	global_load_lds_dwordx4 v[142:143], off
	v_lshl_add_u64 v[142:143], v[142:143], 0, s[2:3]
	s_add_i32 m0, m0, 0x1000
	s_nop 0
	global_load_lds_dwordx4 v[142:143], off
	v_lshl_add_u64 v[142:143], v[142:143], 0, s[2:3]
	s_add_i32 m0, m0, 0x1000
	s_nop 0
	global_load_lds_dwordx4 v[142:143], off
	s_add_i32 m0, m0, 0x1000
	v_lshl_add_u64 v[142:143], v[134:135], 0, s[2:3]
	s_nop 0
	global_load_lds_dwordx4 v[134:135], off
	s_add_i32 m0, m0, 0x1000
	v_lshl_add_u64 v[132:133], v[132:133], 0, s[36:37]
	s_nop 0
	global_load_lds_dwordx4 v[142:143], off
	v_lshl_add_u64 v[134:135], v[134:135], 0, s[8:9]
	s_nop 0
	s_add_i32 s40, s44, 0xc000
	s_mov_b32 m0, s40
	v_lshl_add_u64 v[142:143], v[132:133], 0, s[2:3]
	global_load_lds_dwordx4 v[132:133], off
	s_add_i32 m0, m0, 0x1000
	s_nop 0
	global_load_lds_dwordx4 v[142:143], off
	v_lshl_add_u64 v[142:143], v[142:143], 0, s[2:3]
	s_add_i32 m0, m0, 0x1000
	s_nop 0
	global_load_lds_dwordx4 v[142:143], off
	v_lshl_add_u64 v[142:143], v[142:143], 0, s[2:3]
	s_add_i32 m0, m0, 0x1000
	s_nop 0
	global_load_lds_dwordx4 v[142:143], off
	s_add_i32 m0, m0, 0x1000
	v_lshl_add_u64 v[142:143], v[134:135], 0, s[2:3]
	s_nop 0
	global_load_lds_dwordx4 v[134:135], off
	s_add_i32 m0, m0, 0x1000
	v_lshl_add_u64 v[132:133], v[132:133], 0, s[36:37]
	s_nop 0
	global_load_lds_dwordx4 v[142:143], off
	v_lshl_add_u64 v[134:135], v[134:135], 0, s[8:9]
	s_nop 0
	v_mov_b32_e32 v2, 0
	v_mov_b32_e32 v3, 0
	v_mov_b32_e32 v4, 0
	v_mov_b32_e32 v5, 0
	v_mov_b32_e32 v6, 0
	v_mov_b32_e32 v7, 0
	v_mov_b32_e32 v8, 0
	v_mov_b32_e32 v9, 0
	v_mov_b32_e32 v10, 0
	v_mov_b32_e32 v11, 0
	v_mov_b32_e32 v12, 0
	v_mov_b32_e32 v13, 0
	v_mov_b32_e32 v14, 0
	v_mov_b32_e32 v15, 0
	v_mov_b32_e32 v16, 0
	v_mov_b32_e32 v17, 0
	v_mov_b32_e32 v18, 0
	v_mov_b32_e32 v19, 0
	v_mov_b32_e32 v20, 0
	v_mov_b32_e32 v21, 0
	v_mov_b32_e32 v22, 0
	v_mov_b32_e32 v23, 0
	v_mov_b32_e32 v24, 0
	v_mov_b32_e32 v25, 0
	v_mov_b32_e32 v26, 0
	v_mov_b32_e32 v27, 0
	v_mov_b32_e32 v28, 0
	v_mov_b32_e32 v29, 0
	v_mov_b32_e32 v30, 0
	v_mov_b32_e32 v31, 0
	v_mov_b32_e32 v32, 0
	v_mov_b32_e32 v33, 0
	v_mov_b32_e32 v34, 0
	v_mov_b32_e32 v35, 0
	v_mov_b32_e32 v36, 0
	v_mov_b32_e32 v37, 0
	v_mov_b32_e32 v38, 0
	v_mov_b32_e32 v39, 0
	v_mov_b32_e32 v40, 0
	v_mov_b32_e32 v41, 0
	v_mov_b32_e32 v42, 0
	v_mov_b32_e32 v43, 0
	v_mov_b32_e32 v44, 0
;     ...
;   __syncthreads();
;   G2_STAGE(0); G2_STAGE(1);
;   const int fsw = (0x78 >> (((r16 >> 2) & 3) * 2)) & 3;
;   const int aoff = (wm * 128 + r16) * 64 + ((quad ^ fsw) << 4);
;   const int boff = 16384 + (wn * 64 + r16) * 64 + ((quad ^ fsw) << 4);
;   for (int kt = 0; kt < nk; kt++) {
;     if (kt + 1 < nk) asm volatile("s_waitcnt vmcnt(6)" ::: "memory");
;     else asm volatile("s_waitcnt vmcnt(0)" ::: "memory");
;     __builtin_amdgcn_s_barrier();
;     asm volatile("" ::: "memory");
;     if (kt + 2 < nk) G2_STAGE(kt + 2);
;     const char* cS = smem + (kt % 3) * 24576;
;     bf16x8 xa[8], wb[4];
; #pragma unroll
;     for (int f = 0; f < 8; f++) xa[f] = *(const bf16x8*)(cS + aoff + f * 1024);
; #pragma unroll
;     for (int f = 0; f < 4; f++) wb[f] = *(const bf16x8*)(cS + boff + f * 1024);
; #pragma unroll
;     for (int nf = 0; nf < 4; nf++)
; #pragma unroll
;       for (int mf = 0; mf < 8; mf++)
;         acc[nf][mf] = __builtin_amdgcn_mfma_f32_16x16x32_bf16(wb[nf], xa[mf], acc[nf][mf], 0, 0, 0);
	v_mov_b32_e32 v45, 0
	v_mov_b32_e32 v46, 0
	v_mov_b32_e32 v47, 0
	v_mov_b32_e32 v48, 0
	v_mov_b32_e32 v49, 0
	v_mov_b32_e32 v50, 0
	v_mov_b32_e32 v51, 0
	v_mov_b32_e32 v52, 0
	v_mov_b32_e32 v53, 0
	v_mov_b32_e32 v54, 0
	v_mov_b32_e32 v55, 0
	v_mov_b32_e32 v56, 0
	v_mov_b32_e32 v57, 0
	v_mov_b32_e32 v58, 0
	v_mov_b32_e32 v59, 0
	v_mov_b32_e32 v60, 0
	v_mov_b32_e32 v61, 0
	v_mov_b32_e32 v62, 0
	v_mov_b32_e32 v63, 0
	v_mov_b32_e32 v64, 0
	v_mov_b32_e32 v65, 0
	v_mov_b32_e32 v66, 0
	v_mov_b32_e32 v67, 0
	v_mov_b32_e32 v68, 0
	v_mov_b32_e32 v69, 0
	v_mov_b32_e32 v70, 0
	v_mov_b32_e32 v71, 0
	v_mov_b32_e32 v72, 0
	v_mov_b32_e32 v73, 0
	v_mov_b32_e32 v74, 0
	v_mov_b32_e32 v75, 0
	v_mov_b32_e32 v76, 0
	v_mov_b32_e32 v77, 0
	v_mov_b32_e32 v78, 0
	v_mov_b32_e32 v79, 0
	v_mov_b32_e32 v80, 0
	v_mov_b32_e32 v81, 0
	v_mov_b32_e32 v82, 0
	v_mov_b32_e32 v83, 0
	v_mov_b32_e32 v84, 0
	v_mov_b32_e32 v85, 0
	v_mov_b32_e32 v86, 0
	v_mov_b32_e32 v87, 0
	v_mov_b32_e32 v88, 0
	v_mov_b32_e32 v89, 0
	v_mov_b32_e32 v90, 0
	v_mov_b32_e32 v91, 0
	v_mov_b32_e32 v92, 0
	v_mov_b32_e32 v93, 0
	v_mov_b32_e32 v94, 0
	v_mov_b32_e32 v95, 0
	v_mov_b32_e32 v96, 0
	v_mov_b32_e32 v97, 0
	v_mov_b32_e32 v98, 0
	v_mov_b32_e32 v99, 0
	v_mov_b32_e32 v100, 0
	v_mov_b32_e32 v101, 0
	v_mov_b32_e32 v102, 0
	v_mov_b32_e32 v103, 0
	v_mov_b32_e32 v104, 0
	v_mov_b32_e32 v105, 0
	v_mov_b32_e32 v106, 0
	v_mov_b32_e32 v107, 0
	v_mov_b32_e32 v108, 0
	v_mov_b32_e32 v109, 0
	v_mov_b32_e32 v110, 0
	v_mov_b32_e32 v111, 0
	v_mov_b32_e32 v112, 0
	v_mov_b32_e32 v113, 0
	v_mov_b32_e32 v114, 0
	v_mov_b32_e32 v115, 0
	v_mov_b32_e32 v116, 0
	v_mov_b32_e32 v117, 0
	v_mov_b32_e32 v118, 0
	v_mov_b32_e32 v119, 0
	v_mov_b32_e32 v120, 0
	v_mov_b32_e32 v121, 0
	v_mov_b32_e32 v122, 0
	v_mov_b32_e32 v123, 0
	v_mov_b32_e32 v124, 0
	v_mov_b32_e32 v125, 0
	v_mov_b32_e32 v126, 0
	v_mov_b32_e32 v127, 0
	v_mov_b32_e32 v128, 0
	v_mov_b32_e32 v129, 0
	s_waitcnt vmcnt(12)
	s_barrier
	ds_read_b128 v[146:149], v136 offset:0
	ds_read_b128 v[152:155], v136 offset:1024
	ds_read_b128 v[156:159], v136 offset:2048
	ds_read_b128 v[162:165], v136 offset:3072
	ds_read_b128 v[166:169], v136 offset:4096
	ds_read_b128 v[170:173], v136 offset:5120
	ds_read_b128 v[176:179], v136 offset:6144
	ds_read_b128 v[180:183], v136 offset:7168
	ds_read_b128 v[184:187], v137 offset:16384
	ds_read_b128 v[188:191], v137 offset:17408
	ds_read_b128 v[192:195], v137 offset:18432
	ds_read_b128 v[196:199], v137 offset:19456
	s_movk_i32 s38, 0x6000
	s_mov_b32 s39, 0
	s_movk_i32 s15, 14
	.p2align 6
.Lt0_loop:
	.p2align 3
	s_waitcnt vmcnt(6) lgkmcnt(0)
	s_barrier
	s_setprio 1
	v_add_u32_e32 v144, s38, v136
	v_mfma_f32_16x16x32_bf16 v[126:129], v[184:187], v[146:149], v[126:129]
	ds_read_b128 v[200:203], v144 offset:0
	v_mfma_f32_16x16x32_bf16 v[122:125], v[184:187], v[152:155], v[122:125]
	ds_read_b128 v[204:207], v144 offset:1024
	v_mfma_f32_16x16x32_bf16 v[118:121], v[184:187], v[156:159], v[118:121]
	ds_read_b128 v[208:211], v144 offset:2048
	v_mfma_f32_16x16x32_bf16 v[114:117], v[184:187], v[162:165], v[114:117]
	ds_read_b128 v[212:215], v144 offset:3072
	v_mfma_f32_16x16x32_bf16 v[110:113], v[184:187], v[166:169], v[110:113]
	ds_read_b128 v[216:219], v144 offset:4096
	v_mfma_f32_16x16x32_bf16 v[106:109], v[184:187], v[170:173], v[106:109]
	ds_read_b128 v[220:223], v144 offset:5120
	v_mfma_f32_16x16x32_bf16 v[102:105], v[184:187], v[176:179], v[102:105]
	ds_read_b128 v[224:227], v144 offset:6144
	v_mfma_f32_16x16x32_bf16 v[98:101], v[184:187], v[180:183], v[98:101]
	ds_read_b128 v[228:231], v144 offset:7168
	v_mfma_f32_16x16x32_bf16 v[94:97], v[188:191], v[146:149], v[94:97]
	v_add_u32_e64 v144, s38, v137
	v_mfma_f32_16x16x32_bf16 v[90:93], v[188:191], v[152:155], v[90:93]
	v_mfma_f32_16x16x32_bf16 v[86:89], v[188:191], v[156:159], v[86:89]
	ds_read_b128 v[232:235], v144 offset:16384
	v_mfma_f32_16x16x32_bf16 v[82:85], v[188:191], v[162:165], v[82:85]
	ds_read_b128 v[236:239], v144 offset:17408
	v_mfma_f32_16x16x32_bf16 v[78:81], v[188:191], v[166:169], v[78:81]
	ds_read_b128 v[240:243], v144 offset:18432
	v_mfma_f32_16x16x32_bf16 v[74:77], v[188:191], v[170:173], v[74:77]
	ds_read_b128 v[244:247], v144 offset:19456
	v_mfma_f32_16x16x32_bf16 v[70:73], v[188:191], v[176:179], v[70:73]
	s_add_i32 s40, s44, s39
	s_mov_b32 m0, s40
	v_lshl_add_u64 v[142:143], v[132:133], 0, s[2:3]
	v_mfma_f32_16x16x32_bf16 v[66:69], v[188:191], v[180:183], v[66:69]
	global_load_lds_dwordx4 v[132:133], off
	s_add_i32 m0, m0, 0x1000
	v_mfma_f32_16x16x32_bf16 v[62:65], v[192:195], v[146:149], v[62:65]
	v_mfma_f32_16x16x32_bf16 v[58:61], v[192:195], v[152:155], v[58:61]
	v_mfma_f32_16x16x32_bf16 v[54:57], v[192:195], v[156:159], v[54:57]
	global_load_lds_dwordx4 v[142:143], off
	v_lshl_add_u64 v[142:143], v[142:143], 0, s[2:3]
	s_add_i32 m0, m0, 0x1000
	v_mfma_f32_16x16x32_bf16 v[50:53], v[192:195], v[162:165], v[50:53]
	v_mfma_f32_16x16x32_bf16 v[46:49], v[192:195], v[166:169], v[46:49]
	v_mfma_f32_16x16x32_bf16 v[42:45], v[192:195], v[170:173], v[42:45]
	global_load_lds_dwordx4 v[142:143], off
	v_lshl_add_u64 v[142:143], v[142:143], 0, s[2:3]
	s_add_i32 m0, m0, 0x1000
	v_mfma_f32_16x16x32_bf16 v[38:41], v[192:195], v[176:179], v[38:41]
	v_mfma_f32_16x16x32_bf16 v[34:37], v[192:195], v[180:183], v[34:37]
	v_mfma_f32_16x16x32_bf16 v[30:33], v[196:199], v[146:149], v[30:33]
	global_load_lds_dwordx4 v[142:143], off
	s_add_i32 m0, m0, 0x1000
	v_lshl_add_u64 v[142:143], v[134:135], 0, s[2:3]
	v_mfma_f32_16x16x32_bf16 v[26:29], v[196:199], v[152:155], v[26:29]
	v_mfma_f32_16x16x32_bf16 v[22:25], v[196:199], v[156:159], v[22:25]
	v_mfma_f32_16x16x32_bf16 v[18:21], v[196:199], v[162:165], v[18:21]
	global_load_lds_dwordx4 v[134:135], off
	s_add_i32 m0, m0, 0x1000
	v_lshl_add_u64 v[132:133], v[132:133], 0, s[36:37]
	v_mfma_f32_16x16x32_bf16 v[14:17], v[196:199], v[166:169], v[14:17]
	v_mfma_f32_16x16x32_bf16 v[10:13], v[196:199], v[170:173], v[10:13]
	v_mfma_f32_16x16x32_bf16 v[6:9], v[196:199], v[176:179], v[6:9]
	global_load_lds_dwordx4 v[142:143], off
	v_lshl_add_u64 v[134:135], v[134:135], 0, s[8:9]
	v_mfma_f32_16x16x32_bf16 v[2:5], v[196:199], v[180:183], v[2:5]
	s_setprio 0
	s_mov_b32 s39, s38
	s_add_i32 s38, s38, 0x6000
	s_cmp_eq_u32 s38, 0x12000
	s_cselect_b32 s38, 0, s38
	s_nop 0
	.p2align 3
	s_waitcnt vmcnt(6) lgkmcnt(0)
	s_barrier
;     ...
;   for (int kt = 0; kt < nk; kt++) {
;     if (kt + 1 < nk) asm volatile("s_waitcnt vmcnt(6)" ::: "memory");
;     else asm volatile("s_waitcnt vmcnt(0)" ::: "memory");
;     __builtin_amdgcn_s_barrier();
;     asm volatile("" ::: "memory");
;     if (kt + 2 < nk) G2_STAGE(kt + 2);
;     const char* cS = smem + (kt % 3) * 24576;
;     bf16x8 xa[8], wb[4];
; #pragma unroll
;     for (int f = 0; f < 8; f++) xa[f] = *(const bf16x8*)(cS + aoff + f * 1024);
; #pragma unroll
;     for (int f = 0; f < 4; f++) wb[f] = *(const bf16x8*)(cS + boff + f * 1024);
; #pragma unroll
;     for (int nf = 0; nf < 4; nf++)
; #pragma unroll
;       for (int mf = 0; mf < 8; mf++)
;         acc[nf][mf] = __builtin_amdgcn_mfma_f32_16x16x32_bf16(wb[nf], xa[mf], acc[nf][mf], 0, 0, 0);
	s_setprio 1
	v_add_u32_e32 v144, s38, v136
	v_mfma_f32_16x16x32_bf16 v[126:129], v[232:235], v[200:203], v[126:129]
	ds_read_b128 v[146:149], v144 offset:0
	v_mfma_f32_16x16x32_bf16 v[122:125], v[232:235], v[204:207], v[122:125]
	ds_read_b128 v[152:155], v144 offset:1024
	v_mfma_f32_16x16x32_bf16 v[118:121], v[232:235], v[208:211], v[118:121]
	ds_read_b128 v[156:159], v144 offset:2048
	v_mfma_f32_16x16x32_bf16 v[114:117], v[232:235], v[212:215], v[114:117]
	ds_read_b128 v[162:165], v144 offset:3072
	v_mfma_f32_16x16x32_bf16 v[110:113], v[232:235], v[216:219], v[110:113]
	ds_read_b128 v[166:169], v144 offset:4096
	v_mfma_f32_16x16x32_bf16 v[106:109], v[232:235], v[220:223], v[106:109]
	ds_read_b128 v[170:173], v144 offset:5120
	v_mfma_f32_16x16x32_bf16 v[102:105], v[232:235], v[224:227], v[102:105]
	ds_read_b128 v[176:179], v144 offset:6144
	v_mfma_f32_16x16x32_bf16 v[98:101], v[232:235], v[228:231], v[98:101]
	ds_read_b128 v[180:183], v144 offset:7168
	v_mfma_f32_16x16x32_bf16 v[94:97], v[236:239], v[200:203], v[94:97]
	v_add_u32_e64 v144, s38, v137
	v_mfma_f32_16x16x32_bf16 v[90:93], v[236:239], v[204:207], v[90:93]
	v_mfma_f32_16x16x32_bf16 v[86:89], v[236:239], v[208:211], v[86:89]
	ds_read_b128 v[184:187], v144 offset:16384
	v_mfma_f32_16x16x32_bf16 v[82:85], v[236:239], v[212:215], v[82:85]
	ds_read_b128 v[188:191], v144 offset:17408
	v_mfma_f32_16x16x32_bf16 v[78:81], v[236:239], v[216:219], v[78:81]
	ds_read_b128 v[192:195], v144 offset:18432
	v_mfma_f32_16x16x32_bf16 v[74:77], v[236:239], v[220:223], v[74:77]
	ds_read_b128 v[196:199], v144 offset:19456
	v_mfma_f32_16x16x32_bf16 v[70:73], v[236:239], v[224:227], v[70:73]
	s_add_i32 s40, s44, s39
	s_mov_b32 m0, s40
	v_lshl_add_u64 v[142:143], v[132:133], 0, s[2:3]
	v_mfma_f32_16x16x32_bf16 v[66:69], v[236:239], v[228:231], v[66:69]
	global_load_lds_dwordx4 v[132:133], off
	s_add_i32 m0, m0, 0x1000
	v_mfma_f32_16x16x32_bf16 v[62:65], v[240:243], v[200:203], v[62:65]
	v_mfma_f32_16x16x32_bf16 v[58:61], v[240:243], v[204:207], v[58:61]
	v_mfma_f32_16x16x32_bf16 v[54:57], v[240:243], v[208:211], v[54:57]
	global_load_lds_dwordx4 v[142:143], off
	v_lshl_add_u64 v[142:143], v[142:143], 0, s[2:3]
	s_add_i32 m0, m0, 0x1000
	v_mfma_f32_16x16x32_bf16 v[50:53], v[240:243], v[212:215], v[50:53]
	v_mfma_f32_16x16x32_bf16 v[46:49], v[240:243], v[216:219], v[46:49]
	v_mfma_f32_16x16x32_bf16 v[42:45], v[240:243], v[220:223], v[42:45]
	global_load_lds_dwordx4 v[142:143], off
	v_lshl_add_u64 v[142:143], v[142:143], 0, s[2:3]
	s_add_i32 m0, m0, 0x1000
	v_mfma_f32_16x16x32_bf16 v[38:41], v[240:243], v[224:227], v[38:41]
	v_mfma_f32_16x16x32_bf16 v[34:37], v[240:243], v[228:231], v[34:37]
	v_mfma_f32_16x16x32_bf16 v[30:33], v[244:247], v[200:203], v[30:33]
	global_load_lds_dwordx4 v[142:143], off
	s_add_i32 m0, m0, 0x1000
	v_lshl_add_u64 v[142:143], v[134:135], 0, s[2:3]
	v_mfma_f32_16x16x32_bf16 v[26:29], v[244:247], v[204:207], v[26:29]
	v_mfma_f32_16x16x32_bf16 v[22:25], v[244:247], v[208:211], v[22:25]
	v_mfma_f32_16x16x32_bf16 v[18:21], v[244:247], v[212:215], v[18:21]
	global_load_lds_dwordx4 v[134:135], off
	s_add_i32 m0, m0, 0x1000
	v_lshl_add_u64 v[132:133], v[132:133], 0, s[36:37]
	v_mfma_f32_16x16x32_bf16 v[14:17], v[244:247], v[216:219], v[14:17]
	v_mfma_f32_16x16x32_bf16 v[10:13], v[244:247], v[220:223], v[10:13]
	v_mfma_f32_16x16x32_bf16 v[6:9], v[244:247], v[224:227], v[6:9]
	global_load_lds_dwordx4 v[142:143], off
	v_lshl_add_u64 v[134:135], v[134:135], 0, s[8:9]
	v_mfma_f32_16x16x32_bf16 v[2:5], v[244:247], v[228:231], v[2:5]
	s_setprio 0
	s_mov_b32 s39, s38
	s_add_i32 s38, s38, 0x6000
	s_cmp_eq_u32 s38, 0x12000
	s_cselect_b32 s38, 0, s38
	s_nop 0
	s_sub_i32 s15, s15, 1
	s_cmp_lg_u32 s15, 0
	s_cbranch_scc1 .Lt0_loop
	.p2align 3
	s_waitcnt vmcnt(6) lgkmcnt(0)
	s_barrier
	s_setprio 1
	v_add_u32_e32 v144, s38, v136
	v_mfma_f32_16x16x32_bf16 v[126:129], v[184:187], v[146:149], v[126:129]
	ds_read_b128 v[200:203], v144 offset:0
	v_mfma_f32_16x16x32_bf16 v[122:125], v[184:187], v[152:155], v[122:125]
	ds_read_b128 v[204:207], v144 offset:1024
	v_mfma_f32_16x16x32_bf16 v[118:121], v[184:187], v[156:159], v[118:121]
	ds_read_b128 v[208:211], v144 offset:2048
	v_mfma_f32_16x16x32_bf16 v[114:117], v[184:187], v[162:165], v[114:117]
	ds_read_b128 v[212:215], v144 offset:3072
	v_mfma_f32_16x16x32_bf16 v[110:113], v[184:187], v[166:169], v[110:113]
	ds_read_b128 v[216:219], v144 offset:4096
	v_mfma_f32_16x16x32_bf16 v[106:109], v[184:187], v[170:173], v[106:109]
	ds_read_b128 v[220:223], v144 offset:5120
	v_mfma_f32_16x16x32_bf16 v[102:105], v[184:187], v[176:179], v[102:105]
	ds_read_b128 v[224:227], v144 offset:6144
	v_mfma_f32_16x16x32_bf16 v[98:101], v[184:187], v[180:183], v[98:101]
	ds_read_b128 v[228:231], v144 offset:7168
	v_mfma_f32_16x16x32_bf16 v[94:97], v[188:191], v[146:149], v[94:97]
	v_add_u32_e64 v144, s38, v137
	v_mfma_f32_16x16x32_bf16 v[90:93], v[188:191], v[152:155], v[90:93]
	v_mfma_f32_16x16x32_bf16 v[86:89], v[188:191], v[156:159], v[86:89]
	ds_read_b128 v[232:235], v144 offset:16384
	v_mfma_f32_16x16x32_bf16 v[82:85], v[188:191], v[162:165], v[82:85]
	ds_read_b128 v[236:239], v144 offset:17408
	v_mfma_f32_16x16x32_bf16 v[78:81], v[188:191], v[166:169], v[78:81]
	ds_read_b128 v[240:243], v144 offset:18432
	v_mfma_f32_16x16x32_bf16 v[74:77], v[188:191], v[170:173], v[74:77]
	ds_read_b128 v[244:247], v144 offset:19456
	v_mfma_f32_16x16x32_bf16 v[70:73], v[188:191], v[176:179], v[70:73]
	s_add_i32 s40, s44, s39
	s_mov_b32 m0, s40
	v_lshl_add_u64 v[142:143], v[132:133], 0, s[2:3]
	v_mfma_f32_16x16x32_bf16 v[66:69], v[188:191], v[180:183], v[66:69]
	global_load_lds_dwordx4 v[132:133], off
;     ...
;   for (int kt = 0; kt < nk; kt++) {
;     if (kt + 1 < nk) asm volatile("s_waitcnt vmcnt(6)" ::: "memory");
;     else asm volatile("s_waitcnt vmcnt(0)" ::: "memory");
;     __builtin_amdgcn_s_barrier();
;     asm volatile("" ::: "memory");
;     if (kt + 2 < nk) G2_STAGE(kt + 2);
;     const char* cS = smem + (kt % 3) * 24576;
;     bf16x8 xa[8], wb[4];
; #pragma unroll
;     for (int f = 0; f < 8; f++) xa[f] = *(const bf16x8*)(cS + aoff + f * 1024);
; #pragma unroll
;     for (int f = 0; f < 4; f++) wb[f] = *(const bf16x8*)(cS + boff + f * 1024);
; #pragma unroll
;     for (int nf = 0; nf < 4; nf++)
; #pragma unroll
;       for (int mf = 0; mf < 8; mf++)
;         acc[nf][mf] = __builtin_amdgcn_mfma_f32_16x16x32_bf16(wb[nf], xa[mf], acc[nf][mf], 0, 0, 0);
	s_add_i32 m0, m0, 0x1000
	v_mfma_f32_16x16x32_bf16 v[62:65], v[192:195], v[146:149], v[62:65]
	v_mfma_f32_16x16x32_bf16 v[58:61], v[192:195], v[152:155], v[58:61]
	v_mfma_f32_16x16x32_bf16 v[54:57], v[192:195], v[156:159], v[54:57]
	global_load_lds_dwordx4 v[142:143], off
	v_lshl_add_u64 v[142:143], v[142:143], 0, s[2:3]
	s_add_i32 m0, m0, 0x1000
	v_mfma_f32_16x16x32_bf16 v[50:53], v[192:195], v[162:165], v[50:53]
	v_mfma_f32_16x16x32_bf16 v[46:49], v[192:195], v[166:169], v[46:49]
	v_mfma_f32_16x16x32_bf16 v[42:45], v[192:195], v[170:173], v[42:45]
	global_load_lds_dwordx4 v[142:143], off
	v_lshl_add_u64 v[142:143], v[142:143], 0, s[2:3]
	s_add_i32 m0, m0, 0x1000
	v_mfma_f32_16x16x32_bf16 v[38:41], v[192:195], v[176:179], v[38:41]
	v_mfma_f32_16x16x32_bf16 v[34:37], v[192:195], v[180:183], v[34:37]
	v_mfma_f32_16x16x32_bf16 v[30:33], v[196:199], v[146:149], v[30:33]
	global_load_lds_dwordx4 v[142:143], off
	s_add_i32 m0, m0, 0x1000
	v_lshl_add_u64 v[142:143], v[134:135], 0, s[2:3]
	v_mfma_f32_16x16x32_bf16 v[26:29], v[196:199], v[152:155], v[26:29]
	v_mfma_f32_16x16x32_bf16 v[22:25], v[196:199], v[156:159], v[22:25]
	v_mfma_f32_16x16x32_bf16 v[18:21], v[196:199], v[162:165], v[18:21]
	global_load_lds_dwordx4 v[134:135], off
	s_add_i32 m0, m0, 0x1000
	v_lshl_add_u64 v[132:133], v[132:133], 0, s[36:37]
	v_mfma_f32_16x16x32_bf16 v[14:17], v[196:199], v[166:169], v[14:17]
	v_mfma_f32_16x16x32_bf16 v[10:13], v[196:199], v[170:173], v[10:13]
	v_mfma_f32_16x16x32_bf16 v[6:9], v[196:199], v[176:179], v[6:9]
	global_load_lds_dwordx4 v[142:143], off
	v_lshl_add_u64 v[134:135], v[134:135], 0, s[8:9]
	v_mfma_f32_16x16x32_bf16 v[2:5], v[196:199], v[180:183], v[2:5]
	s_setprio 0
	s_mov_b32 s39, s38
	s_add_i32 s38, s38, 0x6000
	s_cmp_eq_u32 s38, 0x12000
	s_cselect_b32 s38, 0, s38
	s_nop 0
	.p2align 3
	s_waitcnt vmcnt(6) lgkmcnt(0)
	s_barrier
	s_setprio 1
	v_add_u32_e32 v144, s38, v136
	v_mfma_f32_16x16x32_bf16 v[126:129], v[232:235], v[200:203], v[126:129]
	ds_read_b128 v[146:149], v144 offset:0
	v_mfma_f32_16x16x32_bf16 v[122:125], v[232:235], v[204:207], v[122:125]
	ds_read_b128 v[152:155], v144 offset:1024
	v_mfma_f32_16x16x32_bf16 v[118:121], v[232:235], v[208:211], v[118:121]
	ds_read_b128 v[156:159], v144 offset:2048
	v_mfma_f32_16x16x32_bf16 v[114:117], v[232:235], v[212:215], v[114:117]
	ds_read_b128 v[162:165], v144 offset:3072
	v_mfma_f32_16x16x32_bf16 v[110:113], v[232:235], v[216:219], v[110:113]
	ds_read_b128 v[166:169], v144 offset:4096
	v_mfma_f32_16x16x32_bf16 v[106:109], v[232:235], v[220:223], v[106:109]
	ds_read_b128 v[170:173], v144 offset:5120
	v_mfma_f32_16x16x32_bf16 v[102:105], v[232:235], v[224:227], v[102:105]
	ds_read_b128 v[176:179], v144 offset:6144
	v_mfma_f32_16x16x32_bf16 v[98:101], v[232:235], v[228:231], v[98:101]
	ds_read_b128 v[180:183], v144 offset:7168
	v_mfma_f32_16x16x32_bf16 v[94:97], v[236:239], v[200:203], v[94:97]
	v_add_u32_e64 v144, s38, v137
	v_mfma_f32_16x16x32_bf16 v[90:93], v[236:239], v[204:207], v[90:93]
	v_mfma_f32_16x16x32_bf16 v[86:89], v[236:239], v[208:211], v[86:89]
	ds_read_b128 v[184:187], v144 offset:16384
	v_mfma_f32_16x16x32_bf16 v[82:85], v[236:239], v[212:215], v[82:85]
	ds_read_b128 v[188:191], v144 offset:17408
	v_mfma_f32_16x16x32_bf16 v[78:81], v[236:239], v[216:219], v[78:81]
	ds_read_b128 v[192:195], v144 offset:18432
	v_mfma_f32_16x16x32_bf16 v[74:77], v[236:239], v[220:223], v[74:77]
	ds_read_b128 v[196:199], v144 offset:19456
	v_mfma_f32_16x16x32_bf16 v[70:73], v[236:239], v[224:227], v[70:73]
	v_mfma_f32_16x16x32_bf16 v[66:69], v[236:239], v[228:231], v[66:69]
	v_mfma_f32_16x16x32_bf16 v[62:65], v[240:243], v[200:203], v[62:65]
	v_mfma_f32_16x16x32_bf16 v[58:61], v[240:243], v[204:207], v[58:61]
	v_mfma_f32_16x16x32_bf16 v[54:57], v[240:243], v[208:211], v[54:57]
	v_mfma_f32_16x16x32_bf16 v[50:53], v[240:243], v[212:215], v[50:53]
	v_mfma_f32_16x16x32_bf16 v[46:49], v[240:243], v[216:219], v[46:49]
	v_mfma_f32_16x16x32_bf16 v[42:45], v[240:243], v[220:223], v[42:45]
	v_mfma_f32_16x16x32_bf16 v[38:41], v[240:243], v[224:227], v[38:41]
	v_mfma_f32_16x16x32_bf16 v[34:37], v[240:243], v[228:231], v[34:37]
	v_mfma_f32_16x16x32_bf16 v[30:33], v[244:247], v[200:203], v[30:33]
	v_mfma_f32_16x16x32_bf16 v[26:29], v[244:247], v[204:207], v[26:29]
	v_mfma_f32_16x16x32_bf16 v[22:25], v[244:247], v[208:211], v[22:25]
	v_mfma_f32_16x16x32_bf16 v[18:21], v[244:247], v[212:215], v[18:21]
	v_mfma_f32_16x16x32_bf16 v[14:17], v[244:247], v[216:219], v[14:17]
	v_mfma_f32_16x16x32_bf16 v[10:13], v[244:247], v[220:223], v[10:13]
	v_mfma_f32_16x16x32_bf16 v[6:9], v[244:247], v[224:227], v[6:9]
	v_mfma_f32_16x16x32_bf16 v[2:5], v[244:247], v[228:231], v[2:5]
	s_setprio 0
	s_mov_b32 s39, s38
	s_add_i32 s38, s38, 0x6000
	s_cmp_eq_u32 s38, 0x12000
	s_cselect_b32 s38, 0, s38
	s_nop 0
	.p2align 3
	s_waitcnt vmcnt(0) lgkmcnt(0)
	s_barrier
;     ...
;   for (int kt = 0; kt < nk; kt++) {
;     if (kt + 1 < nk) asm volatile("s_waitcnt vmcnt(6)" ::: "memory");
;     else asm volatile("s_waitcnt vmcnt(0)" ::: "memory");
;     __builtin_amdgcn_s_barrier();
;     asm volatile("" ::: "memory");
;     if (kt + 2 < nk) G2_STAGE(kt + 2);
;     const char* cS = smem + (kt % 3) * 24576;
;     bf16x8 xa[8], wb[4];
; #pragma unroll
;     for (int f = 0; f < 8; f++) xa[f] = *(const bf16x8*)(cS + aoff + f * 1024);
; #pragma unroll
;     for (int f = 0; f < 4; f++) wb[f] = *(const bf16x8*)(cS + boff + f * 1024);
; #pragma unroll
;     for (int nf = 0; nf < 4; nf++)
; #pragma unroll
;       for (int mf = 0; mf < 8; mf++)
;         acc[nf][mf] = __builtin_amdgcn_mfma_f32_16x16x32_bf16(wb[nf], xa[mf], acc[nf][mf], 0, 0, 0);
	s_setprio 1
	v_add_u32_e32 v144, s38, v136
	v_mfma_f32_16x16x32_bf16 v[126:129], v[184:187], v[146:149], v[126:129]
	ds_read_b128 v[200:203], v144 offset:0
	v_mfma_f32_16x16x32_bf16 v[122:125], v[184:187], v[152:155], v[122:125]
	ds_read_b128 v[204:207], v144 offset:1024
	v_mfma_f32_16x16x32_bf16 v[118:121], v[184:187], v[156:159], v[118:121]
	ds_read_b128 v[208:211], v144 offset:2048
	v_mfma_f32_16x16x32_bf16 v[114:117], v[184:187], v[162:165], v[114:117]
	ds_read_b128 v[212:215], v144 offset:3072
	v_mfma_f32_16x16x32_bf16 v[110:113], v[184:187], v[166:169], v[110:113]
	ds_read_b128 v[216:219], v144 offset:4096
	v_mfma_f32_16x16x32_bf16 v[106:109], v[184:187], v[170:173], v[106:109]
	ds_read_b128 v[220:223], v144 offset:5120
	v_mfma_f32_16x16x32_bf16 v[102:105], v[184:187], v[176:179], v[102:105]
	ds_read_b128 v[224:227], v144 offset:6144
	v_mfma_f32_16x16x32_bf16 v[98:101], v[184:187], v[180:183], v[98:101]
	ds_read_b128 v[228:231], v144 offset:7168
	v_mfma_f32_16x16x32_bf16 v[94:97], v[188:191], v[146:149], v[94:97]
	v_add_u32_e64 v144, s38, v137
	v_mfma_f32_16x16x32_bf16 v[90:93], v[188:191], v[152:155], v[90:93]
	v_mfma_f32_16x16x32_bf16 v[86:89], v[188:191], v[156:159], v[86:89]
	ds_read_b128 v[232:235], v144 offset:16384
	v_mfma_f32_16x16x32_bf16 v[82:85], v[188:191], v[162:165], v[82:85]
	ds_read_b128 v[236:239], v144 offset:17408
	v_mfma_f32_16x16x32_bf16 v[78:81], v[188:191], v[166:169], v[78:81]
	ds_read_b128 v[240:243], v144 offset:18432
	v_mfma_f32_16x16x32_bf16 v[74:77], v[188:191], v[170:173], v[74:77]
	ds_read_b128 v[244:247], v144 offset:19456
	v_mfma_f32_16x16x32_bf16 v[70:73], v[188:191], v[176:179], v[70:73]
	v_mfma_f32_16x16x32_bf16 v[66:69], v[188:191], v[180:183], v[66:69]
	v_mfma_f32_16x16x32_bf16 v[62:65], v[192:195], v[146:149], v[62:65]
	v_mfma_f32_16x16x32_bf16 v[58:61], v[192:195], v[152:155], v[58:61]
	v_mfma_f32_16x16x32_bf16 v[54:57], v[192:195], v[156:159], v[54:57]
	v_mfma_f32_16x16x32_bf16 v[50:53], v[192:195], v[162:165], v[50:53]
	v_mfma_f32_16x16x32_bf16 v[46:49], v[192:195], v[166:169], v[46:49]
	v_mfma_f32_16x16x32_bf16 v[42:45], v[192:195], v[170:173], v[42:45]
	v_mfma_f32_16x16x32_bf16 v[38:41], v[192:195], v[176:179], v[38:41]
	v_mfma_f32_16x16x32_bf16 v[34:37], v[192:195], v[180:183], v[34:37]
	v_mfma_f32_16x16x32_bf16 v[30:33], v[196:199], v[146:149], v[30:33]
	v_mfma_f32_16x16x32_bf16 v[26:29], v[196:199], v[152:155], v[26:29]
	v_mfma_f32_16x16x32_bf16 v[22:25], v[196:199], v[156:159], v[22:25]
	v_mfma_f32_16x16x32_bf16 v[18:21], v[196:199], v[162:165], v[18:21]
	v_mfma_f32_16x16x32_bf16 v[14:17], v[196:199], v[166:169], v[14:17]
	v_mfma_f32_16x16x32_bf16 v[10:13], v[196:199], v[170:173], v[10:13]
	v_mfma_f32_16x16x32_bf16 v[6:9], v[196:199], v[176:179], v[6:9]
	v_mfma_f32_16x16x32_bf16 v[2:5], v[196:199], v[180:183], v[2:5]
	s_setprio 0
	s_mov_b32 s39, s38
	s_add_i32 s38, s38, 0x6000
	s_cmp_eq_u32 s38, 0x12000
	s_cselect_b32 s38, 0, s38
	s_nop 0
	.p2align 3
	s_waitcnt lgkmcnt(0)
; DEVI unsigned pack2(float a, float b) { return __builtin_bit_cast(unsigned, __builtin_convertvector((f32x2_t){a, b}, bf16x2_t)); }
;     ...
;     for (int nf = 0; nf < 4; nf++)
; #pragma unroll
;       for (int mf = 0; mf < 8; mf++)
;         acc[nf][mf] = __builtin_amdgcn_mfma_f32_16x16x32_bf16(wb[nf], xa[mf], acc[nf][mf], 0, 0, 0);
;     ...
;         } else {
;           u32x2 pk; pk[0] = pack2(a[0], a[1]); pk[1] = pack2(a[2], a[3]);
;           *(u32x2*)(outb + (size_t)row * ldc + col) = pk;
;         }
	s_nop 0
	v_mfma_f32_16x16x32_bf16 v[126:129], v[232:235], v[200:203], v[126:129]
	v_mfma_f32_16x16x32_bf16 v[122:125], v[232:235], v[204:207], v[122:125]
	v_mfma_f32_16x16x32_bf16 v[118:121], v[232:235], v[208:211], v[118:121]
	v_mfma_f32_16x16x32_bf16 v[114:117], v[232:235], v[212:215], v[114:117]
	v_mfma_f32_16x16x32_bf16 v[110:113], v[232:235], v[216:219], v[110:113]
	v_mfma_f32_16x16x32_bf16 v[106:109], v[232:235], v[220:223], v[106:109]
	v_mfma_f32_16x16x32_bf16 v[102:105], v[232:235], v[224:227], v[102:105]
	v_mfma_f32_16x16x32_bf16 v[98:101], v[232:235], v[228:231], v[98:101]
	v_mfma_f32_16x16x32_bf16 v[94:97], v[236:239], v[200:203], v[94:97]
	v_mfma_f32_16x16x32_bf16 v[90:93], v[236:239], v[204:207], v[90:93]
	v_mfma_f32_16x16x32_bf16 v[86:89], v[236:239], v[208:211], v[86:89]
	v_mfma_f32_16x16x32_bf16 v[82:85], v[236:239], v[212:215], v[82:85]
	v_mfma_f32_16x16x32_bf16 v[78:81], v[236:239], v[216:219], v[78:81]
	v_mfma_f32_16x16x32_bf16 v[74:77], v[236:239], v[220:223], v[74:77]
	v_mfma_f32_16x16x32_bf16 v[70:73], v[236:239], v[224:227], v[70:73]
	v_mfma_f32_16x16x32_bf16 v[66:69], v[236:239], v[228:231], v[66:69]
	v_mfma_f32_16x16x32_bf16 v[62:65], v[240:243], v[200:203], v[62:65]
	v_mfma_f32_16x16x32_bf16 v[58:61], v[240:243], v[204:207], v[58:61]
	v_mfma_f32_16x16x32_bf16 v[54:57], v[240:243], v[208:211], v[54:57]
	v_mfma_f32_16x16x32_bf16 v[50:53], v[240:243], v[212:215], v[50:53]
	v_mfma_f32_16x16x32_bf16 v[46:49], v[240:243], v[216:219], v[46:49]
	v_mfma_f32_16x16x32_bf16 v[42:45], v[240:243], v[220:223], v[42:45]
	v_mfma_f32_16x16x32_bf16 v[38:41], v[240:243], v[224:227], v[38:41]
	v_mfma_f32_16x16x32_bf16 v[34:37], v[240:243], v[228:231], v[34:37]
	v_mfma_f32_16x16x32_bf16 v[30:33], v[244:247], v[200:203], v[30:33]
	v_mfma_f32_16x16x32_bf16 v[26:29], v[244:247], v[204:207], v[26:29]
	v_mfma_f32_16x16x32_bf16 v[22:25], v[244:247], v[208:211], v[22:25]
	v_mfma_f32_16x16x32_bf16 v[18:21], v[244:247], v[212:215], v[18:21]
	v_mfma_f32_16x16x32_bf16 v[14:17], v[244:247], v[216:219], v[14:17]
	v_mfma_f32_16x16x32_bf16 v[10:13], v[244:247], v[220:223], v[10:13]
	v_mfma_f32_16x16x32_bf16 v[6:9], v[244:247], v[224:227], v[6:9]
	v_mfma_f32_16x16x32_bf16 v[2:5], v[244:247], v[228:231], v[2:5]
	s_mov_b32 m0, s41
	s_mov_b32 s8, 0x14000
	s_mov_b32 s9, 0
	s_nop 7
	v_cvt_pk_bf16_f32 v126, v126, v127
	v_cvt_pk_bf16_f32 v127, v128, v129
	v_cvt_pk_bf16_f32 v128, v94, v95
	v_cvt_pk_bf16_f32 v129, v96, v97
	v_cvt_pk_bf16_f32 v62, v62, v63
	v_cvt_pk_bf16_f32 v63, v64, v65
	v_cvt_pk_bf16_f32 v64, v30, v31
	v_cvt_pk_bf16_f32 v65, v32, v33
	v_permlane16_swap_b32_e32 v126, v128
	v_permlane16_swap_b32_e32 v127, v129
	v_permlane16_swap_b32_e32 v62, v64
	v_permlane16_swap_b32_e32 v63, v65
	global_store_dwordx4 v[140:141], v[126:129], off offset:0
	global_store_dwordx4 v[140:141], v[62:65], off offset:64
	v_lshl_add_u64 v[140:141], v[140:141], 0, s[8:9]
	v_cvt_pk_bf16_f32 v122, v122, v123
	v_cvt_pk_bf16_f32 v123, v124, v125
	v_cvt_pk_bf16_f32 v124, v90, v91
	v_cvt_pk_bf16_f32 v125, v92, v93
	v_cvt_pk_bf16_f32 v58, v58, v59
	v_cvt_pk_bf16_f32 v59, v60, v61
	v_cvt_pk_bf16_f32 v60, v26, v27
	v_cvt_pk_bf16_f32 v61, v28, v29
	v_permlane16_swap_b32_e32 v122, v124
	v_permlane16_swap_b32_e32 v123, v125
	v_permlane16_swap_b32_e32 v58, v60
	v_permlane16_swap_b32_e32 v59, v61
	global_store_dwordx4 v[140:141], v[122:125], off offset:0
	global_store_dwordx4 v[140:141], v[58:61], off offset:64
	v_lshl_add_u64 v[140:141], v[140:141], 0, s[8:9]
	v_cvt_pk_bf16_f32 v118, v118, v119
	v_cvt_pk_bf16_f32 v119, v120, v121
	v_cvt_pk_bf16_f32 v120, v86, v87
	v_cvt_pk_bf16_f32 v121, v88, v89
	v_cvt_pk_bf16_f32 v54, v54, v55
	v_cvt_pk_bf16_f32 v55, v56, v57
	v_cvt_pk_bf16_f32 v56, v22, v23
	v_cvt_pk_bf16_f32 v57, v24, v25
	v_permlane16_swap_b32_e32 v118, v120
	v_permlane16_swap_b32_e32 v119, v121
	v_permlane16_swap_b32_e32 v54, v56
	v_permlane16_swap_b32_e32 v55, v57
	global_store_dwordx4 v[140:141], v[118:121], off offset:0
	global_store_dwordx4 v[140:141], v[54:57], off offset:64
	v_lshl_add_u64 v[140:141], v[140:141], 0, s[8:9]
	v_cvt_pk_bf16_f32 v114, v114, v115
	v_cvt_pk_bf16_f32 v115, v116, v117
	v_cvt_pk_bf16_f32 v116, v82, v83
	v_cvt_pk_bf16_f32 v117, v84, v85
	v_cvt_pk_bf16_f32 v50, v50, v51
	v_cvt_pk_bf16_f32 v51, v52, v53
	v_cvt_pk_bf16_f32 v52, v18, v19
	v_cvt_pk_bf16_f32 v53, v20, v21
	v_permlane16_swap_b32_e32 v114, v116
	v_permlane16_swap_b32_e32 v115, v117
	v_permlane16_swap_b32_e32 v50, v52
	v_permlane16_swap_b32_e32 v51, v53
	global_store_dwordx4 v[140:141], v[114:117], off offset:0
	global_store_dwordx4 v[140:141], v[50:53], off offset:64
	v_lshl_add_u64 v[140:141], v[140:141], 0, s[8:9]
	v_cvt_pk_bf16_f32 v110, v110, v111
	v_cvt_pk_bf16_f32 v111, v112, v113
	v_cvt_pk_bf16_f32 v112, v78, v79
	v_cvt_pk_bf16_f32 v113, v80, v81
	v_cvt_pk_bf16_f32 v46, v46, v47
	v_cvt_pk_bf16_f32 v47, v48, v49
	v_cvt_pk_bf16_f32 v48, v14, v15
	v_cvt_pk_bf16_f32 v49, v16, v17
	v_permlane16_swap_b32_e32 v110, v112
	v_permlane16_swap_b32_e32 v111, v113
	v_permlane16_swap_b32_e32 v46, v48
	v_permlane16_swap_b32_e32 v47, v49
	global_store_dwordx4 v[140:141], v[110:113], off offset:0
	global_store_dwordx4 v[140:141], v[46:49], off offset:64
	v_lshl_add_u64 v[140:141], v[140:141], 0, s[8:9]
	v_cvt_pk_bf16_f32 v106, v106, v107
	v_cvt_pk_bf16_f32 v107, v108, v109
	v_cvt_pk_bf16_f32 v108, v74, v75
	v_cvt_pk_bf16_f32 v109, v76, v77
	v_cvt_pk_bf16_f32 v42, v42, v43
	v_cvt_pk_bf16_f32 v43, v44, v45
	v_cvt_pk_bf16_f32 v44, v10, v11
	v_cvt_pk_bf16_f32 v45, v12, v13
	v_permlane16_swap_b32_e32 v106, v108
	v_permlane16_swap_b32_e32 v107, v109
	v_permlane16_swap_b32_e32 v42, v44
	v_permlane16_swap_b32_e32 v43, v45
	global_store_dwordx4 v[140:141], v[106:109], off offset:0
	global_store_dwordx4 v[140:141], v[42:45], off offset:64
	v_lshl_add_u64 v[140:141], v[140:141], 0, s[8:9]
	v_cvt_pk_bf16_f32 v102, v102, v103
	v_cvt_pk_bf16_f32 v103, v104, v105
	v_cvt_pk_bf16_f32 v104, v70, v71
	v_cvt_pk_bf16_f32 v105, v72, v73
	v_cvt_pk_bf16_f32 v38, v38, v39
	v_cvt_pk_bf16_f32 v39, v40, v41
	v_cvt_pk_bf16_f32 v40, v6, v7
	v_cvt_pk_bf16_f32 v41, v8, v9
	v_permlane16_swap_b32_e32 v102, v104
	v_permlane16_swap_b32_e32 v103, v105
	v_permlane16_swap_b32_e32 v38, v40
	v_permlane16_swap_b32_e32 v39, v41
	global_store_dwordx4 v[140:141], v[102:105], off offset:0
	global_store_dwordx4 v[140:141], v[38:41], off offset:64
	v_lshl_add_u64 v[140:141], v[140:141], 0, s[8:9]
	v_cvt_pk_bf16_f32 v98, v98, v99
	v_cvt_pk_bf16_f32 v99, v100, v101
	v_cvt_pk_bf16_f32 v100, v66, v67
	v_cvt_pk_bf16_f32 v101, v68, v69
	v_cvt_pk_bf16_f32 v34, v34, v35
	v_cvt_pk_bf16_f32 v35, v36, v37
	v_cvt_pk_bf16_f32 v36, v2, v3
	v_cvt_pk_bf16_f32 v37, v4, v5
	v_permlane16_swap_b32_e32 v98, v100
	v_permlane16_swap_b32_e32 v99, v101
	v_permlane16_swap_b32_e32 v34, v36
	v_permlane16_swap_b32_e32 v35, v37
	global_store_dwordx4 v[140:141], v[98:101], off offset:0
	global_store_dwordx4 v[140:141], v[34:37], off offset:64
	s_branch .LBB0_886
